# lever 4: one static s_setprio 1 for waves 4-7 at entry, all per-segment s_setprio flips deleted
# baseline (speedup 1.0000x reference)
_Z8yoco_fwd6Params:
	s_load_dwordx8 s[36:43], s[0:1], 0x40
	s_load_dword s66, s[0:1], 0x68
	s_load_dwordx2 s[92:93], s[0:1], 0x60
	s_add_u32 s6, s0, 0x60
	v_and_b32_e32 v170, 0x3ff, v0
	s_mov_b32 s85, s2
	s_addc_u32 s7, s1, 0
	v_cmp_gt_u32_e32 vcc, 4, v170
	s_and_saveexec_b64 s[4:5], vcc
	v_lshl_add_u32 v1, v170, 2, 0
	v_add_u32_e32 v1, 0x20000, v1
	v_mov_b32_e32 v2, 0
	ds_write_b32 v1, v2
	s_or_b64 exec, exec, s[4:5]
	s_waitcnt lgkmcnt(0)
	s_mov_b32 s100, 0
	v_readfirstlane_b32 s33, v170
	s_nop 3
	s_lshr_b32 s33, s33, 6
	s_cmp_ge_u32 s33, 4
	s_cbranch_scc0 .Lprio_done
	s_setprio 1
.Lprio_done:
	s_add_u32 s2, s42, 0xdc00000
	s_addc_u32 s3, s43, 0
	v_writelane_b32 v252, s2, 0
	s_barrier
	s_nop 0
	v_writelane_b32 v252, s3, 1
	s_getreg_b32 s2, hwreg(HW_REG_XCC_ID, 0, 4)
	v_cmp_eq_u32_e64 s[8:9], 0, v170
	s_mov_b64 s[4:5], exec
	s_nop 0
	v_writelane_b32 v252, s8, 2
	s_nop 1
	v_writelane_b32 v252, s9, 3
	s_and_b64 s[8:9], s[4:5], s[8:9]
	s_mov_b64 exec, s[8:9]
	s_cbranch_execz .LBB0_5
	s_mov_b64 s[8:9], exec
	v_mbcnt_lo_u32_b32 v1, s8, 0
	v_mbcnt_hi_u32_b32 v1, s9, v1
	v_cmp_eq_u32_e32 vcc, 0, v1
	s_and_b64 s[10:11], exec, vcc
	s_mov_b64 exec, s[10:11]
	s_cbranch_execz .LBB0_5
	s_lshl_b32 s2, s2, 8
	s_and_b32 s2, s2, 0xf00
	s_bcnt1_i32_b64 s3, s[8:9]
	v_mov_b32_e32 v1, s2
	v_mov_b32_e32 v2, s3
	v_readlane_b32 s2, v252, 0
	v_readlane_b32 s3, v252, 1
	s_nop 4
	global_atomic_add v1, v2, s[2:3] offset:1024

.LBB0_93:
	ds_read_b128 v[152:155], v146
	ds_read_b128 v[156:159], v146 offset:1024
	ds_read_b128 v[160:163], v146 offset:2048
	ds_read_b128 v[164:167], v146 offset:3072
	ds_read_b128 v[172:175], v147
	ds_read_b128 v[176:179], v147 offset:1024
	ds_read_b128 v[180:183], v147 offset:2048
	ds_read_b128 v[184:187], v147 offset:3072
	s_add_u32 s16, s12, s14
	s_addc_u32 s17, s13, s15
	s_add_u32 s16, s16, 0x9800100
	s_addc_u32 s17, s17, 0
	s_add_u32 s48, s26, s14
	s_addc_u32 s49, s27, s15
	s_cmpk_eq_i32 s14, 0x300
	s_cselect_b32 s17, s7, s17
	s_cselect_b32 s16, s6, s16
	s_cselect_b32 s49, s5, s49
	s_cselect_b32 s48, s4, s48
	s_mov_b32 m0, s29
	v_lshl_add_u64 v[168:169], v[140:141], 0, s[14:15]
	ds_read_b128 v[188:191], v148
	ds_read_b128 v[192:195], v148 offset:1024
	ds_read_b128 v[196:199], v148 offset:2048
	ds_read_b128 v[200:203], v148 offset:3072
	ds_read_b128 v[204:207], v148 offset:4096
	ds_read_b128 v[208:211], v148 offset:5120
	ds_read_b128 v[212:215], v148 offset:6144
	ds_read_b128 v[216:219], v148 offset:7168
	global_load_lds_dwordx4 v[168:169], off
	v_lshl_add_u64 v[168:169], v[142:143], 0, s[14:15]
	s_mov_b32 m0, s30
	s_nop 0
	global_load_lds_dwordx4 v[168:169], off
	s_waitcnt vmcnt(8)
	s_waitcnt lgkmcnt(0)
	v_mfma_f32_16x16x32_f16 v[124:127], v[152:155], v[188:191], v[124:127]
	v_mfma_f32_16x16x32_f16 v[120:123], v[160:163], v[188:191], v[120:123]
	v_mfma_f32_16x16x32_f16 v[112:115], v[152:155], v[196:199], v[112:115]
	v_mfma_f32_16x16x32_f16 v[104:107], v[160:163], v[196:199], v[104:107]
	s_barrier
	s_waitcnt lgkmcnt(0)
	v_mfma_f32_16x16x32_f16 v[96:99], v[152:155], v[204:207], v[96:99]
	v_mfma_f32_16x16x32_f16 v[88:91], v[160:163], v[204:207], v[88:91]
	v_mfma_f32_16x16x32_f16 v[80:83], v[152:155], v[212:215], v[80:83]
	v_mfma_f32_16x16x32_f16 v[72:75], v[160:163], v[212:215], v[72:75]
	v_mfma_f32_16x16x32_f16 v[124:127], v[156:159], v[192:195], v[124:127]
	v_mfma_f32_16x16x32_f16 v[120:123], v[164:167], v[192:195], v[120:123]
	v_mfma_f32_16x16x32_f16 v[112:115], v[156:159], v[200:203], v[112:115]
	v_mfma_f32_16x16x32_f16 v[104:107], v[164:167], v[200:203], v[104:107]
	v_mfma_f32_16x16x32_f16 v[96:99], v[156:159], v[208:211], v[96:99]
	v_mfma_f32_16x16x32_f16 v[88:91], v[164:167], v[208:211], v[88:91]
	v_mfma_f32_16x16x32_f16 v[80:83], v[156:159], v[216:219], v[80:83]
	v_mfma_f32_16x16x32_f16 v[72:75], v[164:167], v[216:219], v[72:75]
	v_mfma_f32_16x16x32_f16 v[116:119], v[172:175], v[188:191], v[116:119]
	v_mfma_f32_16x16x32_f16 v[108:111], v[180:183], v[188:191], v[108:111]
	v_mfma_f32_16x16x32_f16 v[100:103], v[172:175], v[196:199], v[100:103]
	v_mfma_f32_16x16x32_f16 v[92:95], v[180:183], v[196:199], v[92:95]
	v_mfma_f32_16x16x32_f16 v[84:87], v[172:175], v[204:207], v[84:87]
	v_mfma_f32_16x16x32_f16 v[76:79], v[180:183], v[204:207], v[76:79]
	v_mfma_f32_16x16x32_f16 v[68:71], v[172:175], v[212:215], v[68:71]
	v_mfma_f32_16x16x32_f16 v[64:67], v[180:183], v[212:215], v[64:67]
	v_mfma_f32_16x16x32_f16 v[116:119], v[176:179], v[192:195], v[116:119]
	v_mfma_f32_16x16x32_f16 v[108:111], v[184:187], v[192:195], v[108:111]
	v_mfma_f32_16x16x32_f16 v[100:103], v[176:179], v[200:203], v[100:103]
	v_mfma_f32_16x16x32_f16 v[92:95], v[184:187], v[200:203], v[92:95]
	v_mfma_f32_16x16x32_f16 v[84:87], v[176:179], v[208:211], v[84:87]
	v_mfma_f32_16x16x32_f16 v[76:79], v[184:187], v[208:211], v[76:79]
	v_mfma_f32_16x16x32_f16 v[68:71], v[176:179], v[216:219], v[68:71]
	v_mfma_f32_16x16x32_f16 v[64:67], v[184:187], v[216:219], v[64:67]
	s_barrier
	s_mov_b32 m0, s31
	v_lshl_add_u64 v[168:169], s[48:49], 0, v[134:135]
	ds_read_b128 v[188:191], v148 offset:16384
	ds_read_b128 v[192:195], v148 offset:17408
	ds_read_b128 v[196:199], v148 offset:18432
	ds_read_b128 v[200:203], v148 offset:19456
	ds_read_b128 v[204:207], v148 offset:20480
	ds_read_b128 v[208:211], v148 offset:21504
	ds_read_b128 v[212:215], v148 offset:22528
	ds_read_b128 v[216:219], v148 offset:23552
	global_load_lds_dwordx4 v[168:169], off
	v_lshl_add_u64 v[220:221], s[48:49], 0, v[128:129]
	s_mov_b32 m0, s33
	v_lshl_add_u64 v[222:223], s[48:49], 0, v[136:137]
	global_load_lds_dwordx4 v[220:221], off
	s_mov_b32 m0, s34
	v_lshl_add_u64 v[224:225], s[48:49], 0, v[130:131]
	global_load_lds_dwordx4 v[222:223], off
	s_mov_b32 m0, s35
	v_lshl_add_u64 v[226:227], s[16:17], 0, v[138:139]
	global_load_lds_dwordx4 v[224:225], off
	s_mov_b32 m0, s1
	v_lshl_add_u64 v[228:229], s[16:17], 0, v[132:133]
	global_load_lds_dwordx4 v[226:227], off
	s_mov_b32 m0, s3
	s_nop 0
	global_load_lds_dwordx4 v[228:229], off
	s_waitcnt vmcnt(8)
	s_waitcnt lgkmcnt(0)
	v_mfma_f32_16x16x32_f16 v[60:63], v[152:155], v[188:191], v[60:63]
	v_mfma_f32_16x16x32_f16 v[56:59], v[160:163], v[188:191], v[56:59]
	v_mfma_f32_16x16x32_f16 v[52:55], v[152:155], v[196:199], v[52:55]
	v_mfma_f32_16x16x32_f16 v[44:47], v[160:163], v[196:199], v[44:47]
	s_barrier
	s_waitcnt lgkmcnt(0)
	v_mfma_f32_16x16x32_f16 v[36:39], v[152:155], v[204:207], v[36:39]
	v_mfma_f32_16x16x32_f16 v[28:31], v[160:163], v[204:207], v[28:31]
	v_mfma_f32_16x16x32_f16 v[20:23], v[152:155], v[212:215], v[20:23]
	v_mfma_f32_16x16x32_f16 v[12:15], v[160:163], v[212:215], v[12:15]
	v_mfma_f32_16x16x32_f16 v[60:63], v[156:159], v[192:195], v[60:63]
	v_mfma_f32_16x16x32_f16 v[56:59], v[164:167], v[192:195], v[56:59]
	v_mfma_f32_16x16x32_f16 v[52:55], v[156:159], v[200:203], v[52:55]
	v_mfma_f32_16x16x32_f16 v[44:47], v[164:167], v[200:203], v[44:47]
	v_mfma_f32_16x16x32_f16 v[36:39], v[156:159], v[208:211], v[36:39]
	v_mfma_f32_16x16x32_f16 v[28:31], v[164:167], v[208:211], v[28:31]
	v_mfma_f32_16x16x32_f16 v[20:23], v[156:159], v[216:219], v[20:23]
	v_mfma_f32_16x16x32_f16 v[12:15], v[164:167], v[216:219], v[12:15]
	v_mfma_f32_16x16x32_f16 v[48:51], v[172:175], v[188:191], v[48:51]
	v_mfma_f32_16x16x32_f16 v[40:43], v[180:183], v[188:191], v[40:43]
	v_mfma_f32_16x16x32_f16 v[32:35], v[172:175], v[196:199], v[32:35]
	v_mfma_f32_16x16x32_f16 v[24:27], v[180:183], v[196:199], v[24:27]
	v_mfma_f32_16x16x32_f16 v[16:19], v[172:175], v[204:207], v[16:19]
	v_mfma_f32_16x16x32_f16 v[8:11], v[180:183], v[204:207], v[8:11]
	v_mfma_f32_16x16x32_f16 v[4:7], v[172:175], v[212:215], v[4:7]
	v_mfma_f32_16x16x32_f16 v[0:3], v[180:183], v[212:215], v[0:3]
	v_mfma_f32_16x16x32_f16 v[48:51], v[176:179], v[192:195], v[48:51]
	v_mfma_f32_16x16x32_f16 v[40:43], v[184:187], v[192:195], v[40:43]
	v_mfma_f32_16x16x32_f16 v[32:35], v[176:179], v[200:203], v[32:35]
	v_mfma_f32_16x16x32_f16 v[24:27], v[184:187], v[200:203], v[24:27]
	v_mfma_f32_16x16x32_f16 v[16:19], v[176:179], v[208:211], v[16:19]
	v_mfma_f32_16x16x32_f16 v[8:11], v[184:187], v[208:211], v[8:11]
	v_mfma_f32_16x16x32_f16 v[4:7], v[176:179], v[216:219], v[4:7]
	v_mfma_f32_16x16x32_f16 v[0:3], v[184:187], v[216:219], v[0:3]
	s_barrier
	ds_read_b128 v[152:155], v149
	ds_read_b128 v[156:159], v149 offset:1024
	ds_read_b128 v[160:163], v149 offset:2048
	ds_read_b128 v[164:167], v149 offset:3072
	ds_read_b128 v[172:175], v150
	ds_read_b128 v[176:179], v150 offset:1024
	ds_read_b128 v[180:183], v150 offset:2048
	ds_read_b128 v[184:187], v150 offset:3072
	s_add_u32 s16, s16, 0x20000
	s_addc_u32 s17, s17, 0
	s_mov_b32 m0, s21
	v_lshl_add_u64 v[230:231], s[16:17], 0, v[138:139]
	ds_read_b128 v[188:191], v148 offset:32768
	ds_read_b128 v[192:195], v148 offset:33792
	ds_read_b128 v[196:199], v148 offset:34816
	ds_read_b128 v[200:203], v148 offset:35840
	ds_read_b128 v[204:207], v148 offset:36864
	ds_read_b128 v[208:211], v148 offset:37888
	ds_read_b128 v[212:215], v148 offset:38912
	ds_read_b128 v[216:219], v148 offset:39936
	global_load_lds_dwordx4 v[230:231], off
	v_lshl_add_u64 v[230:231], s[16:17], 0, v[132:133]
	s_mov_b32 m0, s22
	s_nop 0
	global_load_lds_dwordx4 v[230:231], off
	s_waitcnt vmcnt(8)
	s_waitcnt lgkmcnt(0)
	v_mfma_f32_16x16x32_f16 v[124:127], v[152:155], v[188:191], v[124:127]
	v_mfma_f32_16x16x32_f16 v[120:123], v[160:163], v[188:191], v[120:123]
	v_mfma_f32_16x16x32_f16 v[112:115], v[152:155], v[196:199], v[112:115]
	v_mfma_f32_16x16x32_f16 v[104:107], v[160:163], v[196:199], v[104:107]
	s_barrier
	s_waitcnt lgkmcnt(0)
	v_mfma_f32_16x16x32_f16 v[96:99], v[152:155], v[204:207], v[96:99]
	v_mfma_f32_16x16x32_f16 v[88:91], v[160:163], v[204:207], v[88:91]
	v_mfma_f32_16x16x32_f16 v[80:83], v[152:155], v[212:215], v[80:83]
	v_mfma_f32_16x16x32_f16 v[72:75], v[160:163], v[212:215], v[72:75]
	v_mfma_f32_16x16x32_f16 v[124:127], v[156:159], v[192:195], v[124:127]
	v_mfma_f32_16x16x32_f16 v[120:123], v[164:167], v[192:195], v[120:123]
	v_mfma_f32_16x16x32_f16 v[112:115], v[156:159], v[200:203], v[112:115]
	v_mfma_f32_16x16x32_f16 v[104:107], v[164:167], v[200:203], v[104:107]
	v_mfma_f32_16x16x32_f16 v[96:99], v[156:159], v[208:211], v[96:99]
	v_mfma_f32_16x16x32_f16 v[88:91], v[164:167], v[208:211], v[88:91]
	v_mfma_f32_16x16x32_f16 v[80:83], v[156:159], v[216:219], v[80:83]
	v_mfma_f32_16x16x32_f16 v[72:75], v[164:167], v[216:219], v[72:75]
	v_mfma_f32_16x16x32_f16 v[116:119], v[172:175], v[188:191], v[116:119]
	v_mfma_f32_16x16x32_f16 v[108:111], v[180:183], v[188:191], v[108:111]
	v_mfma_f32_16x16x32_f16 v[100:103], v[172:175], v[196:199], v[100:103]
	v_mfma_f32_16x16x32_f16 v[92:95], v[180:183], v[196:199], v[92:95]
	v_mfma_f32_16x16x32_f16 v[84:87], v[172:175], v[204:207], v[84:87]
	v_mfma_f32_16x16x32_f16 v[76:79], v[180:183], v[204:207], v[76:79]
	v_mfma_f32_16x16x32_f16 v[68:71], v[172:175], v[212:215], v[68:71]
	v_mfma_f32_16x16x32_f16 v[64:67], v[180:183], v[212:215], v[64:67]
	v_mfma_f32_16x16x32_f16 v[116:119], v[176:179], v[192:195], v[116:119]
	v_mfma_f32_16x16x32_f16 v[108:111], v[184:187], v[192:195], v[108:111]
	v_mfma_f32_16x16x32_f16 v[100:103], v[176:179], v[200:203], v[100:103]
	v_mfma_f32_16x16x32_f16 v[92:95], v[184:187], v[200:203], v[92:95]
	v_mfma_f32_16x16x32_f16 v[84:87], v[176:179], v[208:211], v[84:87]
	v_mfma_f32_16x16x32_f16 v[76:79], v[184:187], v[208:211], v[76:79]
	v_mfma_f32_16x16x32_f16 v[68:71], v[176:179], v[216:219], v[68:71]
	v_mfma_f32_16x16x32_f16 v[64:67], v[184:187], v[216:219], v[64:67]
	s_barrier
	s_mov_b32 m0, s44
	v_lshl_add_u64 v[168:169], v[168:169], 0, s[8:9]
	ds_read_b128 v[188:191], v148 offset:49152
	ds_read_b128 v[192:195], v148 offset:50176
	ds_read_b128 v[196:199], v148 offset:51200
	ds_read_b128 v[200:203], v148 offset:52224
	ds_read_b128 v[204:207], v148 offset:53248
	ds_read_b128 v[208:211], v148 offset:54272
	ds_read_b128 v[212:215], v148 offset:55296
	ds_read_b128 v[216:219], v148 offset:56320
	global_load_lds_dwordx4 v[168:169], off
	v_lshl_add_u64 v[168:169], v[220:221], 0, s[8:9]
	s_mov_b32 m0, s45
	s_nop 0
	global_load_lds_dwordx4 v[168:169], off
	v_lshl_add_u64 v[168:169], v[222:223], 0, s[8:9]
	s_mov_b32 m0, s46
	s_nop 0
	global_load_lds_dwordx4 v[168:169], off
	v_lshl_add_u64 v[168:169], v[224:225], 0, s[8:9]
	s_mov_b32 m0, s47
	s_nop 0
	global_load_lds_dwordx4 v[168:169], off
	v_lshl_add_u64 v[168:169], v[226:227], 0, s[8:9]
	s_mov_b32 m0, s24
	s_nop 0
	global_load_lds_dwordx4 v[168:169], off
	v_lshl_add_u64 v[168:169], v[228:229], 0, s[8:9]
	s_mov_b32 m0, s25
	s_nop 0
	global_load_lds_dwordx4 v[168:169], off
	s_waitcnt vmcnt(8)
	s_waitcnt lgkmcnt(0)
	v_mfma_f32_16x16x32_f16 v[60:63], v[152:155], v[188:191], v[60:63]
	v_mfma_f32_16x16x32_f16 v[56:59], v[160:163], v[188:191], v[56:59]
	v_mfma_f32_16x16x32_f16 v[52:55], v[152:155], v[196:199], v[52:55]
	v_mfma_f32_16x16x32_f16 v[44:47], v[160:163], v[196:199], v[44:47]
	s_barrier
	s_waitcnt lgkmcnt(0)
	v_mfma_f32_16x16x32_f16 v[36:39], v[152:155], v[204:207], v[36:39]
	v_mfma_f32_16x16x32_f16 v[28:31], v[160:163], v[204:207], v[28:31]
	v_mfma_f32_16x16x32_f16 v[20:23], v[152:155], v[212:215], v[20:23]
	v_mfma_f32_16x16x32_f16 v[12:15], v[160:163], v[212:215], v[12:15]
	v_mfma_f32_16x16x32_f16 v[60:63], v[156:159], v[192:195], v[60:63]
	v_mfma_f32_16x16x32_f16 v[56:59], v[164:167], v[192:195], v[56:59]
	v_mfma_f32_16x16x32_f16 v[52:55], v[156:159], v[200:203], v[52:55]
	v_mfma_f32_16x16x32_f16 v[44:47], v[164:167], v[200:203], v[44:47]
	v_mfma_f32_16x16x32_f16 v[36:39], v[156:159], v[208:211], v[36:39]
	v_mfma_f32_16x16x32_f16 v[28:31], v[164:167], v[208:211], v[28:31]
	v_mfma_f32_16x16x32_f16 v[20:23], v[156:159], v[216:219], v[20:23]
	v_mfma_f32_16x16x32_f16 v[12:15], v[164:167], v[216:219], v[12:15]
	v_mfma_f32_16x16x32_f16 v[48:51], v[172:175], v[188:191], v[48:51]
	v_mfma_f32_16x16x32_f16 v[40:43], v[180:183], v[188:191], v[40:43]
	v_mfma_f32_16x16x32_f16 v[32:35], v[172:175], v[196:199], v[32:35]
	v_mfma_f32_16x16x32_f16 v[24:27], v[180:183], v[196:199], v[24:27]
	v_mfma_f32_16x16x32_f16 v[16:19], v[172:175], v[204:207], v[16:19]
	v_mfma_f32_16x16x32_f16 v[8:11], v[180:183], v[204:207], v[8:11]
	v_mfma_f32_16x16x32_f16 v[4:7], v[172:175], v[212:215], v[4:7]
	v_mfma_f32_16x16x32_f16 v[0:3], v[180:183], v[212:215], v[0:3]
	v_mfma_f32_16x16x32_f16 v[48:51], v[176:179], v[192:195], v[48:51]
	v_mfma_f32_16x16x32_f16 v[40:43], v[184:187], v[192:195], v[40:43]
	v_mfma_f32_16x16x32_f16 v[32:35], v[176:179], v[200:203], v[32:35]
	v_mfma_f32_16x16x32_f16 v[24:27], v[184:187], v[200:203], v[24:27]
	v_mfma_f32_16x16x32_f16 v[16:19], v[176:179], v[208:211], v[16:19]
	v_mfma_f32_16x16x32_f16 v[8:11], v[184:187], v[208:211], v[8:11]
	v_mfma_f32_16x16x32_f16 v[4:7], v[176:179], v[216:219], v[4:7]
	v_mfma_f32_16x16x32_f16 v[0:3], v[184:187], v[216:219], v[0:3]
	s_barrier
	s_add_i32 s28, s28, 2
	s_add_u32 s14, s14, 0x100
	s_addc_u32 s15, s15, 0
	s_cmp_gt_u32 s28, 5
	s_cbranch_scc0 .LBB0_93
	s_cmpk_lt_u32 s20, 0x100
	s_cbranch_scc0 .LBB0_96
	s_barrier

.LBB0_202:
	s_add_u32 s2, s6, 0xfffc0080
	s_addc_u32 s3, s7, -1
	s_add_i32 s66, 0, 0x10000
	s_cmp_eq_u32 s89, 12
	s_cselect_b32 s57, s20, s3
	s_cselect_b32 s56, s21, s2
	v_add_u32_e32 v148, s66, v151
	s_cselect_b32 s91, s49, s88
	s_cselect_b32 s90, s51, s62
	s_add_i32 s2, 0, 0x14000
	ds_read_b128 v[144:147], v148
	ds_read_b128 v[164:167], v148 offset:1024
	ds_read_b128 v[176:179], v148 offset:2048
	ds_read_b128 v[180:183], v148 offset:3072
	v_add_u32_e32 v148, s2, v151
	ds_read_b128 v[184:187], v148
	ds_read_b128 v[188:191], v148 offset:1024
	ds_read_b128 v[192:195], v148 offset:2048
	ds_read_b128 v[196:199], v148 offset:3072
	v_lshl_add_u64 v[148:149], s[6:7], 0, v[140:141]
	s_add_i32 m0, s17, 0xc000
	ds_read_b128 v[200:203], v153
	ds_read_b128 v[204:207], v153 offset:1024
	ds_read_b128 v[208:211], v153 offset:2048
	ds_read_b128 v[212:215], v153 offset:3072
	ds_read_b128 v[216:219], v153 offset:4096
	ds_read_b128 v[220:223], v153 offset:5120
	ds_read_b128 v[224:227], v153 offset:6144
	ds_read_b128 v[228:231], v153 offset:7168
	global_load_lds_dwordx4 v[148:149], off
	v_lshl_add_u64 v[148:149], s[6:7], 0, v[142:143]
	s_add_i32 m0, s17, 0xe000
	s_nop 0
	global_load_lds_dwordx4 v[148:149], off
	s_waitcnt vmcnt(8)
	s_waitcnt lgkmcnt(0)
	v_mfma_f32_16x16x32_f16 v[128:131], v[144:147], v[200:203], v[128:131]
	v_mfma_f32_16x16x32_f16 v[124:127], v[176:179], v[200:203], v[124:127]
	v_mfma_f32_16x16x32_f16 v[112:115], v[144:147], v[208:211], v[112:115]
	v_mfma_f32_16x16x32_f16 v[108:111], v[176:179], v[208:211], v[108:111]
	s_barrier
	s_waitcnt lgkmcnt(0)
	v_mfma_f32_16x16x32_f16 v[96:99], v[144:147], v[216:219], v[96:99]
	v_mfma_f32_16x16x32_f16 v[92:95], v[176:179], v[216:219], v[92:95]
	v_mfma_f32_16x16x32_f16 v[80:83], v[144:147], v[224:227], v[80:83]
	v_mfma_f32_16x16x32_f16 v[76:79], v[176:179], v[224:227], v[76:79]
	v_mfma_f32_16x16x32_f16 v[128:131], v[164:167], v[204:207], v[128:131]
	v_mfma_f32_16x16x32_f16 v[124:127], v[180:183], v[204:207], v[124:127]
	v_mfma_f32_16x16x32_f16 v[112:115], v[164:167], v[212:215], v[112:115]
	v_mfma_f32_16x16x32_f16 v[108:111], v[180:183], v[212:215], v[108:111]
	v_mfma_f32_16x16x32_f16 v[96:99], v[164:167], v[220:223], v[96:99]
	v_mfma_f32_16x16x32_f16 v[92:95], v[180:183], v[220:223], v[92:95]
	v_mfma_f32_16x16x32_f16 v[80:83], v[164:167], v[228:231], v[80:83]
	v_mfma_f32_16x16x32_f16 v[76:79], v[180:183], v[228:231], v[76:79]
	v_mfma_f32_16x16x32_f16 v[120:123], v[184:187], v[200:203], v[120:123]
	v_mfma_f32_16x16x32_f16 v[116:119], v[192:195], v[200:203], v[116:119]
	v_mfma_f32_16x16x32_f16 v[104:107], v[184:187], v[208:211], v[104:107]
	v_mfma_f32_16x16x32_f16 v[100:103], v[192:195], v[208:211], v[100:103]
	v_mfma_f32_16x16x32_f16 v[88:91], v[184:187], v[216:219], v[88:91]
	v_mfma_f32_16x16x32_f16 v[84:87], v[192:195], v[216:219], v[84:87]
	v_mfma_f32_16x16x32_f16 v[72:75], v[184:187], v[224:227], v[72:75]
	v_mfma_f32_16x16x32_f16 v[68:71], v[192:195], v[224:227], v[68:71]
	v_mfma_f32_16x16x32_f16 v[120:123], v[188:191], v[204:207], v[120:123]
	v_mfma_f32_16x16x32_f16 v[116:119], v[196:199], v[204:207], v[116:119]
	v_mfma_f32_16x16x32_f16 v[104:107], v[188:191], v[212:215], v[104:107]
	v_mfma_f32_16x16x32_f16 v[100:103], v[196:199], v[212:215], v[100:103]
	v_mfma_f32_16x16x32_f16 v[88:91], v[188:191], v[220:223], v[88:91]
	v_mfma_f32_16x16x32_f16 v[84:87], v[196:199], v[220:223], v[84:87]
	v_mfma_f32_16x16x32_f16 v[72:75], v[188:191], v[228:231], v[72:75]
	v_mfma_f32_16x16x32_f16 v[68:71], v[196:199], v[228:231], v[68:71]
	s_barrier
	s_add_i32 s3, s66, s16
	v_lshl_add_u64 v[148:149], s[90:91], 0, v[2:3]
	s_mov_b32 m0, s3
	ds_read_b128 v[200:203], v153 offset:16384
	ds_read_b128 v[204:207], v153 offset:17408
	ds_read_b128 v[208:211], v153 offset:18432
	ds_read_b128 v[212:215], v153 offset:19456
	ds_read_b128 v[216:219], v153 offset:20480
	ds_read_b128 v[220:223], v153 offset:21504
	ds_read_b128 v[224:227], v153 offset:22528
	ds_read_b128 v[228:231], v153 offset:23552
	global_load_lds_dwordx4 v[148:149], off
	v_lshl_add_u64 v[154:155], s[90:91], 0, v[0:1]
	s_add_i32 m0, s3, 0x2000
	s_add_i32 s2, s2, s16
	global_load_lds_dwordx4 v[154:155], off
	v_lshl_add_u64 v[232:233], s[90:91], 0, v[136:137]
	s_mov_b32 m0, s2
	v_lshl_add_u64 v[234:235], s[90:91], 0, v[132:133]
	global_load_lds_dwordx4 v[232:233], off
	s_add_i32 m0, s2, 0x2000
	v_lshl_add_u64 v[236:237], s[56:57], 0, v[138:139]
	global_load_lds_dwordx4 v[234:235], off
	s_mov_b32 m0, s17
	v_lshl_add_u64 v[238:239], s[56:57], 0, v[134:135]
	global_load_lds_dwordx4 v[236:237], off
	s_mov_b32 m0, s28
	s_nop 0
	global_load_lds_dwordx4 v[238:239], off
	s_waitcnt vmcnt(8)
	s_waitcnt lgkmcnt(0)
	v_mfma_f32_16x16x32_f16 v[64:67], v[144:147], v[200:203], v[64:67]
	v_mfma_f32_16x16x32_f16 v[60:63], v[176:179], v[200:203], v[60:63]
	v_mfma_f32_16x16x32_f16 v[48:51], v[144:147], v[208:211], v[48:51]
	v_mfma_f32_16x16x32_f16 v[44:47], v[176:179], v[208:211], v[44:47]
	s_barrier
	s_waitcnt lgkmcnt(0)
	v_mfma_f32_16x16x32_f16 v[32:35], v[144:147], v[216:219], v[32:35]
	v_mfma_f32_16x16x32_f16 v[28:31], v[176:179], v[216:219], v[28:31]
	v_mfma_f32_16x16x32_f16 v[16:19], v[144:147], v[224:227], v[16:19]
	v_mfma_f32_16x16x32_f16 v[12:15], v[176:179], v[224:227], v[12:15]
	v_mfma_f32_16x16x32_f16 v[64:67], v[164:167], v[204:207], v[64:67]
	v_mfma_f32_16x16x32_f16 v[60:63], v[180:183], v[204:207], v[60:63]
	v_mfma_f32_16x16x32_f16 v[48:51], v[164:167], v[212:215], v[48:51]
	v_mfma_f32_16x16x32_f16 v[44:47], v[180:183], v[212:215], v[44:47]
	v_mfma_f32_16x16x32_f16 v[32:35], v[164:167], v[220:223], v[32:35]
	v_mfma_f32_16x16x32_f16 v[28:31], v[180:183], v[220:223], v[28:31]
	v_mfma_f32_16x16x32_f16 v[16:19], v[164:167], v[228:231], v[16:19]
	v_mfma_f32_16x16x32_f16 v[12:15], v[180:183], v[228:231], v[12:15]
	v_mfma_f32_16x16x32_f16 v[56:59], v[184:187], v[200:203], v[56:59]
	v_mfma_f32_16x16x32_f16 v[52:55], v[192:195], v[200:203], v[52:55]
	v_mfma_f32_16x16x32_f16 v[40:43], v[184:187], v[208:211], v[40:43]
	v_mfma_f32_16x16x32_f16 v[36:39], v[192:195], v[208:211], v[36:39]
	v_mfma_f32_16x16x32_f16 v[24:27], v[184:187], v[216:219], v[24:27]
	v_mfma_f32_16x16x32_f16 v[20:23], v[192:195], v[216:219], v[20:23]
	v_mfma_f32_16x16x32_f16 v[8:11], v[184:187], v[224:227], v[8:11]
	v_mfma_f32_16x16x32_f16 v[4:7], v[192:195], v[224:227], v[4:7]
	v_mfma_f32_16x16x32_f16 v[56:59], v[188:191], v[204:207], v[56:59]
	v_mfma_f32_16x16x32_f16 v[52:55], v[196:199], v[204:207], v[52:55]
	v_mfma_f32_16x16x32_f16 v[40:43], v[188:191], v[212:215], v[40:43]
	v_mfma_f32_16x16x32_f16 v[36:39], v[196:199], v[212:215], v[36:39]
	v_mfma_f32_16x16x32_f16 v[24:27], v[188:191], v[220:223], v[24:27]
	v_mfma_f32_16x16x32_f16 v[20:23], v[196:199], v[220:223], v[20:23]
	v_mfma_f32_16x16x32_f16 v[8:11], v[188:191], v[228:231], v[8:11]
	v_mfma_f32_16x16x32_f16 v[4:7], v[196:199], v[228:231], v[4:7]
	s_barrier
	s_add_i32 s2, 0, 0x18000
	s_add_i32 s3, 0, 0x1c000
	v_add_u32_e32 v180, s2, v151
	v_add_u32_e32 v196, s3, v151
	ds_read_b128 v[144:147], v180
	ds_read_b128 v[164:167], v180 offset:1024
	ds_read_b128 v[176:179], v180 offset:2048
	ds_read_b128 v[180:183], v180 offset:3072
	ds_read_b128 v[184:187], v196
	ds_read_b128 v[188:191], v196 offset:1024
	ds_read_b128 v[192:195], v196 offset:2048
	ds_read_b128 v[196:199], v196 offset:3072
	s_add_u32 s56, s56, 0x40000
	s_addc_u32 s57, s57, 0
	s_mov_b32 m0, s58
	v_lshl_add_u64 v[240:241], s[56:57], 0, v[138:139]
	ds_read_b128 v[200:203], v153 offset:32768
	ds_read_b128 v[204:207], v153 offset:33792
	ds_read_b128 v[208:211], v153 offset:34816
	ds_read_b128 v[212:215], v153 offset:35840
	ds_read_b128 v[216:219], v153 offset:36864
	ds_read_b128 v[220:223], v153 offset:37888
	ds_read_b128 v[224:227], v153 offset:38912
	ds_read_b128 v[228:231], v153 offset:39936
	global_load_lds_dwordx4 v[240:241], off
	v_lshl_add_u64 v[240:241], s[56:57], 0, v[134:135]
	s_mov_b32 m0, s59
	s_nop 0
	global_load_lds_dwordx4 v[240:241], off
	s_waitcnt vmcnt(8)
	s_waitcnt lgkmcnt(0)
	v_mfma_f32_16x16x32_f16 v[128:131], v[144:147], v[200:203], v[128:131]
	v_mfma_f32_16x16x32_f16 v[124:127], v[176:179], v[200:203], v[124:127]
	v_mfma_f32_16x16x32_f16 v[112:115], v[144:147], v[208:211], v[112:115]
	v_mfma_f32_16x16x32_f16 v[108:111], v[176:179], v[208:211], v[108:111]
	s_barrier
	s_waitcnt lgkmcnt(0)
	v_mfma_f32_16x16x32_f16 v[96:99], v[144:147], v[216:219], v[96:99]
	v_mfma_f32_16x16x32_f16 v[92:95], v[176:179], v[216:219], v[92:95]
	v_mfma_f32_16x16x32_f16 v[80:83], v[144:147], v[224:227], v[80:83]
	v_mfma_f32_16x16x32_f16 v[76:79], v[176:179], v[224:227], v[76:79]
	v_mfma_f32_16x16x32_f16 v[128:131], v[164:167], v[204:207], v[128:131]
	v_mfma_f32_16x16x32_f16 v[124:127], v[180:183], v[204:207], v[124:127]
	v_mfma_f32_16x16x32_f16 v[112:115], v[164:167], v[212:215], v[112:115]
	v_mfma_f32_16x16x32_f16 v[108:111], v[180:183], v[212:215], v[108:111]
	v_mfma_f32_16x16x32_f16 v[96:99], v[164:167], v[220:223], v[96:99]
	v_mfma_f32_16x16x32_f16 v[92:95], v[180:183], v[220:223], v[92:95]
	v_mfma_f32_16x16x32_f16 v[80:83], v[164:167], v[228:231], v[80:83]
	v_mfma_f32_16x16x32_f16 v[76:79], v[180:183], v[228:231], v[76:79]
	v_mfma_f32_16x16x32_f16 v[120:123], v[184:187], v[200:203], v[120:123]
	v_mfma_f32_16x16x32_f16 v[116:119], v[192:195], v[200:203], v[116:119]
	v_mfma_f32_16x16x32_f16 v[104:107], v[184:187], v[208:211], v[104:107]
	v_mfma_f32_16x16x32_f16 v[100:103], v[192:195], v[208:211], v[100:103]
	v_mfma_f32_16x16x32_f16 v[88:91], v[184:187], v[216:219], v[88:91]
	v_mfma_f32_16x16x32_f16 v[84:87], v[192:195], v[216:219], v[84:87]
	v_mfma_f32_16x16x32_f16 v[72:75], v[184:187], v[224:227], v[72:75]
	v_mfma_f32_16x16x32_f16 v[68:71], v[192:195], v[224:227], v[68:71]
	v_mfma_f32_16x16x32_f16 v[120:123], v[188:191], v[204:207], v[120:123]
	v_mfma_f32_16x16x32_f16 v[116:119], v[196:199], v[204:207], v[116:119]
	v_mfma_f32_16x16x32_f16 v[104:107], v[188:191], v[212:215], v[104:107]
	v_mfma_f32_16x16x32_f16 v[100:103], v[196:199], v[212:215], v[100:103]
	v_mfma_f32_16x16x32_f16 v[88:91], v[188:191], v[220:223], v[88:91]
	v_mfma_f32_16x16x32_f16 v[84:87], v[196:199], v[220:223], v[84:87]
	v_mfma_f32_16x16x32_f16 v[72:75], v[188:191], v[228:231], v[72:75]
	v_mfma_f32_16x16x32_f16 v[68:71], v[196:199], v[228:231], v[68:71]
	s_barrier
	s_add_i32 s2, s2, s16
	v_lshl_add_u64 v[148:149], v[148:149], 0, s[82:83]
	s_mov_b32 m0, s2
	ds_read_b128 v[200:203], v153 offset:49152
	ds_read_b128 v[204:207], v153 offset:50176
	ds_read_b128 v[208:211], v153 offset:51200
	ds_read_b128 v[212:215], v153 offset:52224
	ds_read_b128 v[216:219], v153 offset:53248
	ds_read_b128 v[220:223], v153 offset:54272
	ds_read_b128 v[224:227], v153 offset:55296
	ds_read_b128 v[228:231], v153 offset:56320
	global_load_lds_dwordx4 v[148:149], off
	v_lshl_add_u64 v[148:149], v[154:155], 0, s[82:83]
	s_add_i32 m0, s2, 0x2000
	s_add_i32 s2, s3, s16
	global_load_lds_dwordx4 v[148:149], off
	v_lshl_add_u64 v[148:149], v[232:233], 0, s[82:83]
	s_mov_b32 m0, s2
	s_nop 0
	global_load_lds_dwordx4 v[148:149], off
	v_lshl_add_u64 v[148:149], v[234:235], 0, s[82:83]
	s_add_i32 m0, s2, 0x2000
	s_nop 0
	global_load_lds_dwordx4 v[148:149], off
	v_lshl_add_u64 v[148:149], v[236:237], 0, s[82:83]
	s_mov_b32 m0, s60
	s_nop 0
	global_load_lds_dwordx4 v[148:149], off
	v_lshl_add_u64 v[148:149], v[238:239], 0, s[82:83]
	s_mov_b32 m0, s61
	s_nop 0
	global_load_lds_dwordx4 v[148:149], off
	s_waitcnt vmcnt(8)
	s_waitcnt lgkmcnt(0)
	v_mfma_f32_16x16x32_f16 v[64:67], v[144:147], v[200:203], v[64:67]
	v_mfma_f32_16x16x32_f16 v[60:63], v[176:179], v[200:203], v[60:63]
	v_mfma_f32_16x16x32_f16 v[48:51], v[144:147], v[208:211], v[48:51]
	v_mfma_f32_16x16x32_f16 v[44:47], v[176:179], v[208:211], v[44:47]
	s_barrier
	s_waitcnt lgkmcnt(0)
	v_mfma_f32_16x16x32_f16 v[32:35], v[144:147], v[216:219], v[32:35]
	v_mfma_f32_16x16x32_f16 v[28:31], v[176:179], v[216:219], v[28:31]
	v_mfma_f32_16x16x32_f16 v[16:19], v[144:147], v[224:227], v[16:19]
	v_mfma_f32_16x16x32_f16 v[12:15], v[176:179], v[224:227], v[12:15]
	v_mfma_f32_16x16x32_f16 v[64:67], v[164:167], v[204:207], v[64:67]
	v_mfma_f32_16x16x32_f16 v[60:63], v[180:183], v[204:207], v[60:63]
	v_mfma_f32_16x16x32_f16 v[48:51], v[164:167], v[212:215], v[48:51]
	v_mfma_f32_16x16x32_f16 v[44:47], v[180:183], v[212:215], v[44:47]
	v_mfma_f32_16x16x32_f16 v[32:35], v[164:167], v[220:223], v[32:35]
	v_mfma_f32_16x16x32_f16 v[28:31], v[180:183], v[220:223], v[28:31]
	v_mfma_f32_16x16x32_f16 v[16:19], v[164:167], v[228:231], v[16:19]
	v_mfma_f32_16x16x32_f16 v[12:15], v[180:183], v[228:231], v[12:15]
	v_mfma_f32_16x16x32_f16 v[56:59], v[184:187], v[200:203], v[56:59]
	v_mfma_f32_16x16x32_f16 v[52:55], v[192:195], v[200:203], v[52:55]
	v_mfma_f32_16x16x32_f16 v[40:43], v[184:187], v[208:211], v[40:43]
	v_mfma_f32_16x16x32_f16 v[36:39], v[192:195], v[208:211], v[36:39]
	v_mfma_f32_16x16x32_f16 v[24:27], v[184:187], v[216:219], v[24:27]
	v_mfma_f32_16x16x32_f16 v[20:23], v[192:195], v[216:219], v[20:23]
	v_mfma_f32_16x16x32_f16 v[8:11], v[184:187], v[224:227], v[8:11]
	v_mfma_f32_16x16x32_f16 v[4:7], v[192:195], v[224:227], v[4:7]
	v_mfma_f32_16x16x32_f16 v[56:59], v[188:191], v[204:207], v[56:59]
	v_mfma_f32_16x16x32_f16 v[52:55], v[196:199], v[204:207], v[52:55]
	v_mfma_f32_16x16x32_f16 v[40:43], v[188:191], v[212:215], v[40:43]
	v_mfma_f32_16x16x32_f16 v[36:39], v[196:199], v[212:215], v[36:39]
	v_mfma_f32_16x16x32_f16 v[24:27], v[188:191], v[220:223], v[24:27]
	v_mfma_f32_16x16x32_f16 v[20:23], v[196:199], v[220:223], v[20:23]
	v_mfma_f32_16x16x32_f16 v[8:11], v[188:191], v[228:231], v[8:11]
	v_mfma_f32_16x16x32_f16 v[4:7], v[196:199], v[228:231], v[4:7]
	s_barrier
	s_add_i32 s89, s89, 2
	s_add_u32 s6, s6, 0x100
	s_addc_u32 s7, s7, 0
	s_add_u32 s62, s62, 0x100
	s_addc_u32 s88, s88, 0
	s_cmp_gt_u32 s89, 13
	s_cbranch_scc0 .LBB0_202
	s_and_b64 vcc, exec, s[46:47]
	s_cbranch_vccz .LBB0_205
	s_barrier

.LBB0_426:
	s_add_u32 s3, s54, s58
	s_addc_u32 s60, s55, s59
	s_add_u32 s3, s3, 0x100
	s_addc_u32 s60, s60, 0
	s_add_u32 s66, s21, s58
	s_addc_u32 s67, s62, s59
	s_add_i32 s85, 0, 0x10000
	s_cmpk_eq_i32 s58, 0xf00
	s_cselect_b32 s61, s53, s60
	s_cselect_b32 s60, vcc_lo, s3
	v_add_u32_e32 v146, s85, v144
	s_cselect_b32 s67, s51, s67
	s_cselect_b32 s66, vcc_hi, s66
	s_add_i32 s3, 0, 0x14000
	ds_read_b128 v[150:153], v146
	ds_read_b128 v[164:167], v146 offset:1024
	ds_read_b128 v[178:181], v146 offset:2048
	ds_read_b128 v[182:185], v146 offset:3072
	v_add_u32_e32 v146, s3, v144
	ds_read_b128 v[186:189], v146
	ds_read_b128 v[190:193], v146 offset:1024
	ds_read_b128 v[194:197], v146 offset:2048
	ds_read_b128 v[198:201], v146 offset:3072
	v_lshl_add_u64 v[146:147], v[140:141], 0, s[58:59]
	s_add_i32 m0, s16, 0xc000
	ds_read_b128 v[202:205], v145
	ds_read_b128 v[206:209], v145 offset:1024
	ds_read_b128 v[210:213], v145 offset:2048
	ds_read_b128 v[214:217], v145 offset:3072
	ds_read_b128 v[218:221], v145 offset:4096
	ds_read_b128 v[222:225], v145 offset:5120
	ds_read_b128 v[226:229], v145 offset:6144
	ds_read_b128 v[230:233], v145 offset:7168
	global_load_lds_dwordx4 v[146:147], off
	v_lshl_add_u64 v[146:147], v[142:143], 0, s[58:59]
	s_add_i32 m0, s16, 0xe000
	s_nop 0
	global_load_lds_dwordx4 v[146:147], off
	s_waitcnt vmcnt(8)
	s_waitcnt lgkmcnt(0)
	v_mfma_f32_16x16x32_bf16 v[28:31], v[150:153], v[202:205], v[28:31]
	v_mfma_f32_16x16x32_bf16 v[20:23], v[178:181], v[202:205], v[20:23]
	v_mfma_f32_16x16x32_bf16 v[32:35], v[150:153], v[210:213], v[32:35]
	v_mfma_f32_16x16x32_bf16 v[24:27], v[178:181], v[210:213], v[24:27]
	s_barrier
	s_waitcnt lgkmcnt(0)
	v_mfma_f32_16x16x32_bf16 v[60:63], v[150:153], v[218:221], v[60:63]
	v_mfma_f32_16x16x32_bf16 v[52:55], v[178:181], v[218:221], v[52:55]
	v_mfma_f32_16x16x32_bf16 v[64:67], v[150:153], v[226:229], v[64:67]
	v_mfma_f32_16x16x32_bf16 v[56:59], v[178:181], v[226:229], v[56:59]
	v_mfma_f32_16x16x32_bf16 v[28:31], v[164:167], v[206:209], v[28:31]
	v_mfma_f32_16x16x32_bf16 v[20:23], v[182:185], v[206:209], v[20:23]
	v_mfma_f32_16x16x32_bf16 v[32:35], v[164:167], v[214:217], v[32:35]
	v_mfma_f32_16x16x32_bf16 v[24:27], v[182:185], v[214:217], v[24:27]
	v_mfma_f32_16x16x32_bf16 v[60:63], v[164:167], v[222:225], v[60:63]
	v_mfma_f32_16x16x32_bf16 v[52:55], v[182:185], v[222:225], v[52:55]
	v_mfma_f32_16x16x32_bf16 v[64:67], v[164:167], v[230:233], v[64:67]
	v_mfma_f32_16x16x32_bf16 v[56:59], v[182:185], v[230:233], v[56:59]
	v_mfma_f32_16x16x32_bf16 v[12:15], v[186:189], v[202:205], v[12:15]
	v_mfma_f32_16x16x32_bf16 v[4:7], v[194:197], v[202:205], v[4:7]
	v_mfma_f32_16x16x32_bf16 v[16:19], v[186:189], v[210:213], v[16:19]
	v_mfma_f32_16x16x32_bf16 v[8:11], v[194:197], v[210:213], v[8:11]
	v_mfma_f32_16x16x32_bf16 v[44:47], v[186:189], v[218:221], v[44:47]
	v_mfma_f32_16x16x32_bf16 v[36:39], v[194:197], v[218:221], v[36:39]
	v_mfma_f32_16x16x32_bf16 v[48:51], v[186:189], v[226:229], v[48:51]
	v_mfma_f32_16x16x32_bf16 v[40:43], v[194:197], v[226:229], v[40:43]
	v_mfma_f32_16x16x32_bf16 v[12:15], v[190:193], v[206:209], v[12:15]
	v_mfma_f32_16x16x32_bf16 v[4:7], v[198:201], v[206:209], v[4:7]
	v_mfma_f32_16x16x32_bf16 v[16:19], v[190:193], v[214:217], v[16:19]
	v_mfma_f32_16x16x32_bf16 v[8:11], v[198:201], v[214:217], v[8:11]
	v_mfma_f32_16x16x32_bf16 v[44:47], v[190:193], v[222:225], v[44:47]
	v_mfma_f32_16x16x32_bf16 v[36:39], v[198:201], v[222:225], v[36:39]
	v_mfma_f32_16x16x32_bf16 v[48:51], v[190:193], v[230:233], v[48:51]
	v_mfma_f32_16x16x32_bf16 v[40:43], v[198:201], v[230:233], v[40:43]
	s_barrier
	s_add_i32 s85, s85, s15
	v_lshl_add_u64 v[146:147], s[66:67], 0, v[2:3]
	s_mov_b32 m0, s85
	ds_read_b128 v[202:205], v145 offset:16384
	ds_read_b128 v[206:209], v145 offset:17408
	ds_read_b128 v[210:213], v145 offset:18432
	ds_read_b128 v[214:217], v145 offset:19456
	ds_read_b128 v[218:221], v145 offset:20480
	ds_read_b128 v[222:225], v145 offset:21504
	ds_read_b128 v[226:229], v145 offset:22528
	ds_read_b128 v[230:233], v145 offset:23552
	global_load_lds_dwordx4 v[146:147], off
	v_lshl_add_u64 v[154:155], s[66:67], 0, v[132:133]
	s_add_i32 m0, s85, 0x2000
	s_add_i32 s3, s3, s15
	global_load_lds_dwordx4 v[154:155], off
	v_lshl_add_u64 v[234:235], s[66:67], 0, v[134:135]
	s_mov_b32 m0, s3
	v_lshl_add_u64 v[236:237], s[66:67], 0, v[0:1]
	global_load_lds_dwordx4 v[234:235], off
	s_add_i32 m0, s3, 0x2000
	v_lshl_add_u64 v[238:239], s[60:61], 0, v[2:3]
	global_load_lds_dwordx4 v[236:237], off
	s_mov_b32 m0, s16
	v_lshl_add_u64 v[240:241], s[60:61], 0, v[132:133]
	global_load_lds_dwordx4 v[238:239], off
	s_mov_b32 m0, s17
	s_nop 0
	global_load_lds_dwordx4 v[240:241], off
	s_waitcnt vmcnt(8)
	s_waitcnt lgkmcnt(0)
	v_mfma_f32_16x16x32_bf16 v[92:95], v[150:153], v[202:205], v[92:95]
	v_mfma_f32_16x16x32_bf16 v[84:87], v[178:181], v[202:205], v[84:87]
	v_mfma_f32_16x16x32_bf16 v[96:99], v[150:153], v[210:213], v[96:99]
	v_mfma_f32_16x16x32_bf16 v[88:91], v[178:181], v[210:213], v[88:91]
	s_barrier
	s_waitcnt lgkmcnt(0)
	v_mfma_f32_16x16x32_bf16 v[124:127], v[150:153], v[218:221], v[124:127]
	v_mfma_f32_16x16x32_bf16 v[116:119], v[178:181], v[218:221], v[116:119]
	v_mfma_f32_16x16x32_bf16 v[128:131], v[150:153], v[226:229], v[128:131]
	v_mfma_f32_16x16x32_bf16 v[120:123], v[178:181], v[226:229], v[120:123]
	v_mfma_f32_16x16x32_bf16 v[92:95], v[164:167], v[206:209], v[92:95]
	v_mfma_f32_16x16x32_bf16 v[84:87], v[182:185], v[206:209], v[84:87]
	v_mfma_f32_16x16x32_bf16 v[96:99], v[164:167], v[214:217], v[96:99]
	v_mfma_f32_16x16x32_bf16 v[88:91], v[182:185], v[214:217], v[88:91]
	v_mfma_f32_16x16x32_bf16 v[124:127], v[164:167], v[222:225], v[124:127]
	v_mfma_f32_16x16x32_bf16 v[116:119], v[182:185], v[222:225], v[116:119]
	v_mfma_f32_16x16x32_bf16 v[128:131], v[164:167], v[230:233], v[128:131]
	v_mfma_f32_16x16x32_bf16 v[120:123], v[182:185], v[230:233], v[120:123]
	v_mfma_f32_16x16x32_bf16 v[76:79], v[186:189], v[202:205], v[76:79]
	v_mfma_f32_16x16x32_bf16 v[68:71], v[194:197], v[202:205], v[68:71]
	v_mfma_f32_16x16x32_bf16 v[80:83], v[186:189], v[210:213], v[80:83]
	v_mfma_f32_16x16x32_bf16 v[72:75], v[194:197], v[210:213], v[72:75]
	v_mfma_f32_16x16x32_bf16 v[108:111], v[186:189], v[218:221], v[108:111]
	v_mfma_f32_16x16x32_bf16 v[100:103], v[194:197], v[218:221], v[100:103]
	v_mfma_f32_16x16x32_bf16 v[112:115], v[186:189], v[226:229], v[112:115]
	v_mfma_f32_16x16x32_bf16 v[104:107], v[194:197], v[226:229], v[104:107]
	v_mfma_f32_16x16x32_bf16 v[76:79], v[190:193], v[206:209], v[76:79]
	v_mfma_f32_16x16x32_bf16 v[68:71], v[198:201], v[206:209], v[68:71]
	v_mfma_f32_16x16x32_bf16 v[80:83], v[190:193], v[214:217], v[80:83]
	v_mfma_f32_16x16x32_bf16 v[72:75], v[198:201], v[214:217], v[72:75]
	v_mfma_f32_16x16x32_bf16 v[108:111], v[190:193], v[222:225], v[108:111]
	v_mfma_f32_16x16x32_bf16 v[100:103], v[198:201], v[222:225], v[100:103]
	v_mfma_f32_16x16x32_bf16 v[112:115], v[190:193], v[230:233], v[112:115]
	v_mfma_f32_16x16x32_bf16 v[104:107], v[198:201], v[230:233], v[104:107]
	s_barrier
	s_add_i32 s3, 0, 0x18000
	v_add_u32_e32 v149, s3, v144
	s_add_i32 s66, 0, 0x1c000
	ds_read_b128 v[150:153], v149
	ds_read_b128 v[164:167], v149 offset:1024
	ds_read_b128 v[178:181], v149 offset:2048
	ds_read_b128 v[182:185], v149 offset:3072
	v_add_u32_e32 v149, s66, v144
	ds_read_b128 v[186:189], v149
	ds_read_b128 v[190:193], v149 offset:1024
	ds_read_b128 v[194:197], v149 offset:2048
	ds_read_b128 v[198:201], v149 offset:3072
	s_add_u32 s60, s60, 0x80000
	s_addc_u32 s61, s61, 0
	s_mov_b32 m0, s28
	v_lshl_add_u64 v[242:243], s[60:61], 0, v[2:3]
	ds_read_b128 v[202:205], v145 offset:32768
	ds_read_b128 v[206:209], v145 offset:33792
	ds_read_b128 v[210:213], v145 offset:34816
	ds_read_b128 v[214:217], v145 offset:35840
	ds_read_b128 v[218:221], v145 offset:36864
	ds_read_b128 v[222:225], v145 offset:37888
	ds_read_b128 v[226:229], v145 offset:38912
	ds_read_b128 v[230:233], v145 offset:39936
	global_load_lds_dwordx4 v[242:243], off
	v_lshl_add_u64 v[242:243], s[60:61], 0, v[132:133]
	s_mov_b32 m0, s95
	s_nop 0
	global_load_lds_dwordx4 v[242:243], off
	s_waitcnt vmcnt(8)
	s_waitcnt lgkmcnt(0)
	v_mfma_f32_16x16x32_bf16 v[28:31], v[150:153], v[202:205], v[28:31]
	v_mfma_f32_16x16x32_bf16 v[20:23], v[178:181], v[202:205], v[20:23]
	v_mfma_f32_16x16x32_bf16 v[32:35], v[150:153], v[210:213], v[32:35]
	v_mfma_f32_16x16x32_bf16 v[24:27], v[178:181], v[210:213], v[24:27]
	s_barrier
	s_waitcnt lgkmcnt(0)
	v_mfma_f32_16x16x32_bf16 v[60:63], v[150:153], v[218:221], v[60:63]
	v_mfma_f32_16x16x32_bf16 v[52:55], v[178:181], v[218:221], v[52:55]
	v_mfma_f32_16x16x32_bf16 v[64:67], v[150:153], v[226:229], v[64:67]
	v_mfma_f32_16x16x32_bf16 v[56:59], v[178:181], v[226:229], v[56:59]
	v_mfma_f32_16x16x32_bf16 v[28:31], v[164:167], v[206:209], v[28:31]
	v_mfma_f32_16x16x32_bf16 v[20:23], v[182:185], v[206:209], v[20:23]
	v_mfma_f32_16x16x32_bf16 v[32:35], v[164:167], v[214:217], v[32:35]
	v_mfma_f32_16x16x32_bf16 v[24:27], v[182:185], v[214:217], v[24:27]
	v_mfma_f32_16x16x32_bf16 v[60:63], v[164:167], v[222:225], v[60:63]
	v_mfma_f32_16x16x32_bf16 v[52:55], v[182:185], v[222:225], v[52:55]
	v_mfma_f32_16x16x32_bf16 v[64:67], v[164:167], v[230:233], v[64:67]
	v_mfma_f32_16x16x32_bf16 v[56:59], v[182:185], v[230:233], v[56:59]
	v_mfma_f32_16x16x32_bf16 v[12:15], v[186:189], v[202:205], v[12:15]
	v_mfma_f32_16x16x32_bf16 v[4:7], v[194:197], v[202:205], v[4:7]
	v_mfma_f32_16x16x32_bf16 v[16:19], v[186:189], v[210:213], v[16:19]
	v_mfma_f32_16x16x32_bf16 v[8:11], v[194:197], v[210:213], v[8:11]
	v_mfma_f32_16x16x32_bf16 v[44:47], v[186:189], v[218:221], v[44:47]
	v_mfma_f32_16x16x32_bf16 v[36:39], v[194:197], v[218:221], v[36:39]
	v_mfma_f32_16x16x32_bf16 v[48:51], v[186:189], v[226:229], v[48:51]
	v_mfma_f32_16x16x32_bf16 v[40:43], v[194:197], v[226:229], v[40:43]
	v_mfma_f32_16x16x32_bf16 v[12:15], v[190:193], v[206:209], v[12:15]
	v_mfma_f32_16x16x32_bf16 v[4:7], v[198:201], v[206:209], v[4:7]
	v_mfma_f32_16x16x32_bf16 v[16:19], v[190:193], v[214:217], v[16:19]
	v_mfma_f32_16x16x32_bf16 v[8:11], v[198:201], v[214:217], v[8:11]
	v_mfma_f32_16x16x32_bf16 v[44:47], v[190:193], v[222:225], v[44:47]
	v_mfma_f32_16x16x32_bf16 v[36:39], v[198:201], v[222:225], v[36:39]
	v_mfma_f32_16x16x32_bf16 v[48:51], v[190:193], v[230:233], v[48:51]
	v_mfma_f32_16x16x32_bf16 v[40:43], v[198:201], v[230:233], v[40:43]
	s_barrier
	s_add_i32 s3, s3, s15
	v_lshl_add_u64 v[146:147], v[146:147], 0, s[82:83]
	s_mov_b32 m0, s3
	ds_read_b128 v[202:205], v145 offset:49152
	ds_read_b128 v[206:209], v145 offset:50176
	ds_read_b128 v[210:213], v145 offset:51200
	ds_read_b128 v[214:217], v145 offset:52224
	ds_read_b128 v[218:221], v145 offset:53248
	ds_read_b128 v[222:225], v145 offset:54272
	ds_read_b128 v[226:229], v145 offset:55296
	ds_read_b128 v[230:233], v145 offset:56320
	global_load_lds_dwordx4 v[146:147], off
	v_lshl_add_u64 v[146:147], v[154:155], 0, s[82:83]
	s_add_i32 m0, s3, 0x2000
	s_add_i32 s3, s66, s15
	global_load_lds_dwordx4 v[146:147], off
	v_lshl_add_u64 v[146:147], v[234:235], 0, s[82:83]
	s_mov_b32 m0, s3
	s_nop 0
	global_load_lds_dwordx4 v[146:147], off
	v_lshl_add_u64 v[146:147], v[236:237], 0, s[82:83]
	s_add_i32 m0, s3, 0x2000
	s_nop 0
	global_load_lds_dwordx4 v[146:147], off
	v_lshl_add_u64 v[146:147], v[238:239], 0, s[82:83]
	s_mov_b32 m0, s97
	s_nop 0
	global_load_lds_dwordx4 v[146:147], off
	v_lshl_add_u64 v[146:147], v[240:241], 0, s[82:83]
	s_mov_b32 m0, s12
	s_nop 0
	global_load_lds_dwordx4 v[146:147], off
	s_waitcnt vmcnt(8)
	s_waitcnt lgkmcnt(0)
	v_mfma_f32_16x16x32_bf16 v[92:95], v[150:153], v[202:205], v[92:95]
	v_mfma_f32_16x16x32_bf16 v[84:87], v[178:181], v[202:205], v[84:87]
	v_mfma_f32_16x16x32_bf16 v[96:99], v[150:153], v[210:213], v[96:99]
	v_mfma_f32_16x16x32_bf16 v[88:91], v[178:181], v[210:213], v[88:91]
	s_barrier
	s_waitcnt lgkmcnt(0)
	v_mfma_f32_16x16x32_bf16 v[124:127], v[150:153], v[218:221], v[124:127]
	v_mfma_f32_16x16x32_bf16 v[116:119], v[178:181], v[218:221], v[116:119]
	v_mfma_f32_16x16x32_bf16 v[128:131], v[150:153], v[226:229], v[128:131]
	v_mfma_f32_16x16x32_bf16 v[120:123], v[178:181], v[226:229], v[120:123]
	v_mfma_f32_16x16x32_bf16 v[92:95], v[164:167], v[206:209], v[92:95]
	v_mfma_f32_16x16x32_bf16 v[84:87], v[182:185], v[206:209], v[84:87]
	v_mfma_f32_16x16x32_bf16 v[96:99], v[164:167], v[214:217], v[96:99]
	v_mfma_f32_16x16x32_bf16 v[88:91], v[182:185], v[214:217], v[88:91]
	v_mfma_f32_16x16x32_bf16 v[124:127], v[164:167], v[222:225], v[124:127]
	v_mfma_f32_16x16x32_bf16 v[116:119], v[182:185], v[222:225], v[116:119]
	v_mfma_f32_16x16x32_bf16 v[128:131], v[164:167], v[230:233], v[128:131]
	v_mfma_f32_16x16x32_bf16 v[120:123], v[182:185], v[230:233], v[120:123]
	v_mfma_f32_16x16x32_bf16 v[76:79], v[186:189], v[202:205], v[76:79]
	v_mfma_f32_16x16x32_bf16 v[68:71], v[194:197], v[202:205], v[68:71]
	v_mfma_f32_16x16x32_bf16 v[80:83], v[186:189], v[210:213], v[80:83]
	v_mfma_f32_16x16x32_bf16 v[72:75], v[194:197], v[210:213], v[72:75]
	v_mfma_f32_16x16x32_bf16 v[108:111], v[186:189], v[218:221], v[108:111]
	v_mfma_f32_16x16x32_bf16 v[100:103], v[194:197], v[218:221], v[100:103]
	v_mfma_f32_16x16x32_bf16 v[112:115], v[186:189], v[226:229], v[112:115]
	v_mfma_f32_16x16x32_bf16 v[104:107], v[194:197], v[226:229], v[104:107]
	v_mfma_f32_16x16x32_bf16 v[76:79], v[190:193], v[206:209], v[76:79]
	v_mfma_f32_16x16x32_bf16 v[68:71], v[198:201], v[206:209], v[68:71]
	v_mfma_f32_16x16x32_bf16 v[80:83], v[190:193], v[214:217], v[80:83]
	v_mfma_f32_16x16x32_bf16 v[72:75], v[198:201], v[214:217], v[72:75]
	v_mfma_f32_16x16x32_bf16 v[108:111], v[190:193], v[222:225], v[108:111]
	v_mfma_f32_16x16x32_bf16 v[100:103], v[198:201], v[222:225], v[100:103]
	v_mfma_f32_16x16x32_bf16 v[112:115], v[190:193], v[230:233], v[112:115]
	v_mfma_f32_16x16x32_bf16 v[104:107], v[198:201], v[230:233], v[104:107]
	s_barrier
	s_add_i32 s2, s2, 2
	s_add_u32 s58, s58, 0x100
	s_addc_u32 s59, s59, 0
	s_cmp_gt_u32 s2, 29
	s_cbranch_scc0 .LBB0_426
	s_and_b64 vcc, exec, s[48:49]
	s_cbranch_vccz .LBB0_429
	s_barrier

.LBB0_483:
	s_add_u32 s2, s52, s58
	s_addc_u32 s3, s53, s59
	s_add_u32 s2, s2, 0x100
	s_addc_u32 s3, s3, 0
	s_add_u32 s66, s20, s58
	s_addc_u32 s67, s21, s59
	s_add_i32 vcc_hi, 0, 0x10000
	s_cmpk_eq_i32 s58, 0xf00
	s_cselect_b32 s61, s51, s3
	s_cselect_b32 s60, s62, s2
	v_add_u32_e32 v146, vcc_hi, v144
	s_cselect_b32 s3, s49, s67
	s_cselect_b32 s2, s97, s66
	s_add_i32 s66, 0, 0x14000
	ds_read_b128 v[150:153], v146
	ds_read_b128 v[164:167], v146 offset:1024
	ds_read_b128 v[178:181], v146 offset:2048
	ds_read_b128 v[182:185], v146 offset:3072
	v_add_u32_e32 v146, s66, v144
	ds_read_b128 v[186:189], v146
	ds_read_b128 v[190:193], v146 offset:1024
	ds_read_b128 v[194:197], v146 offset:2048
	ds_read_b128 v[198:201], v146 offset:3072
	v_lshl_add_u64 v[146:147], v[140:141], 0, s[58:59]
	s_add_i32 m0, s16, 0xc000
	ds_read_b128 v[202:205], v145
	ds_read_b128 v[206:209], v145 offset:1024
	ds_read_b128 v[210:213], v145 offset:2048
	ds_read_b128 v[214:217], v145 offset:3072
	ds_read_b128 v[218:221], v145 offset:4096
	ds_read_b128 v[222:225], v145 offset:5120
	ds_read_b128 v[226:229], v145 offset:6144
	ds_read_b128 v[230:233], v145 offset:7168
	global_load_lds_dwordx4 v[146:147], off
	v_lshl_add_u64 v[146:147], v[142:143], 0, s[58:59]
	s_add_i32 m0, s16, 0xe000
	s_nop 0
	global_load_lds_dwordx4 v[146:147], off
	s_waitcnt vmcnt(8)
	s_waitcnt lgkmcnt(0)
	v_mfma_f32_16x16x32_bf16 v[28:31], v[150:153], v[202:205], v[28:31]
	v_mfma_f32_16x16x32_bf16 v[20:23], v[178:181], v[202:205], v[20:23]
	v_mfma_f32_16x16x32_bf16 v[32:35], v[150:153], v[210:213], v[32:35]
	v_mfma_f32_16x16x32_bf16 v[24:27], v[178:181], v[210:213], v[24:27]
	s_barrier
	s_waitcnt lgkmcnt(0)
	v_mfma_f32_16x16x32_bf16 v[60:63], v[150:153], v[218:221], v[60:63]
	v_mfma_f32_16x16x32_bf16 v[52:55], v[178:181], v[218:221], v[52:55]
	v_mfma_f32_16x16x32_bf16 v[64:67], v[150:153], v[226:229], v[64:67]
	v_mfma_f32_16x16x32_bf16 v[56:59], v[178:181], v[226:229], v[56:59]
	v_mfma_f32_16x16x32_bf16 v[28:31], v[164:167], v[206:209], v[28:31]
	v_mfma_f32_16x16x32_bf16 v[20:23], v[182:185], v[206:209], v[20:23]
	v_mfma_f32_16x16x32_bf16 v[32:35], v[164:167], v[214:217], v[32:35]
	v_mfma_f32_16x16x32_bf16 v[24:27], v[182:185], v[214:217], v[24:27]
	v_mfma_f32_16x16x32_bf16 v[60:63], v[164:167], v[222:225], v[60:63]
	v_mfma_f32_16x16x32_bf16 v[52:55], v[182:185], v[222:225], v[52:55]
	v_mfma_f32_16x16x32_bf16 v[64:67], v[164:167], v[230:233], v[64:67]
	v_mfma_f32_16x16x32_bf16 v[56:59], v[182:185], v[230:233], v[56:59]
	v_mfma_f32_16x16x32_bf16 v[12:15], v[186:189], v[202:205], v[12:15]
	v_mfma_f32_16x16x32_bf16 v[4:7], v[194:197], v[202:205], v[4:7]
	v_mfma_f32_16x16x32_bf16 v[16:19], v[186:189], v[210:213], v[16:19]
	v_mfma_f32_16x16x32_bf16 v[8:11], v[194:197], v[210:213], v[8:11]
	v_mfma_f32_16x16x32_bf16 v[44:47], v[186:189], v[218:221], v[44:47]
	v_mfma_f32_16x16x32_bf16 v[36:39], v[194:197], v[218:221], v[36:39]
	v_mfma_f32_16x16x32_bf16 v[48:51], v[186:189], v[226:229], v[48:51]
	v_mfma_f32_16x16x32_bf16 v[40:43], v[194:197], v[226:229], v[40:43]
	v_mfma_f32_16x16x32_bf16 v[12:15], v[190:193], v[206:209], v[12:15]
	v_mfma_f32_16x16x32_bf16 v[4:7], v[198:201], v[206:209], v[4:7]
	v_mfma_f32_16x16x32_bf16 v[16:19], v[190:193], v[214:217], v[16:19]
	v_mfma_f32_16x16x32_bf16 v[8:11], v[198:201], v[214:217], v[8:11]
	v_mfma_f32_16x16x32_bf16 v[44:47], v[190:193], v[222:225], v[44:47]
	v_mfma_f32_16x16x32_bf16 v[36:39], v[198:201], v[222:225], v[36:39]
	v_mfma_f32_16x16x32_bf16 v[48:51], v[190:193], v[230:233], v[48:51]
	v_mfma_f32_16x16x32_bf16 v[40:43], v[198:201], v[230:233], v[40:43]
	s_barrier
	s_add_i32 s67, vcc_hi, s15
	v_lshl_add_u64 v[146:147], s[2:3], 0, v[2:3]
	s_mov_b32 m0, s67
	ds_read_b128 v[202:205], v145 offset:16384
	ds_read_b128 v[206:209], v145 offset:17408
	ds_read_b128 v[210:213], v145 offset:18432
	ds_read_b128 v[214:217], v145 offset:19456
	ds_read_b128 v[218:221], v145 offset:20480
	ds_read_b128 v[222:225], v145 offset:21504
	ds_read_b128 v[226:229], v145 offset:22528
	ds_read_b128 v[230:233], v145 offset:23552
	global_load_lds_dwordx4 v[146:147], off
	v_lshl_add_u64 v[154:155], s[2:3], 0, v[132:133]
	s_add_i32 m0, s67, 0x2000
	s_add_i32 s66, s66, s15
	global_load_lds_dwordx4 v[154:155], off
	v_lshl_add_u64 v[234:235], s[2:3], 0, v[134:135]
	s_mov_b32 m0, s66
	v_lshl_add_u64 v[236:237], s[2:3], 0, v[0:1]
	global_load_lds_dwordx4 v[234:235], off
	s_add_i32 m0, s66, 0x2000
	v_lshl_add_u64 v[238:239], s[60:61], 0, v[2:3]
	global_load_lds_dwordx4 v[236:237], off
	s_mov_b32 m0, s16
	v_lshl_add_u64 v[240:241], s[60:61], 0, v[132:133]
	global_load_lds_dwordx4 v[238:239], off
	s_mov_b32 m0, s17
	s_nop 0
	global_load_lds_dwordx4 v[240:241], off
	s_waitcnt vmcnt(8)
	s_waitcnt lgkmcnt(0)
	v_mfma_f32_16x16x32_bf16 v[92:95], v[150:153], v[202:205], v[92:95]
	v_mfma_f32_16x16x32_bf16 v[84:87], v[178:181], v[202:205], v[84:87]
	v_mfma_f32_16x16x32_bf16 v[96:99], v[150:153], v[210:213], v[96:99]
	v_mfma_f32_16x16x32_bf16 v[88:91], v[178:181], v[210:213], v[88:91]
	s_barrier
	s_waitcnt lgkmcnt(0)
	v_mfma_f32_16x16x32_bf16 v[124:127], v[150:153], v[218:221], v[124:127]
	v_mfma_f32_16x16x32_bf16 v[116:119], v[178:181], v[218:221], v[116:119]
	v_mfma_f32_16x16x32_bf16 v[128:131], v[150:153], v[226:229], v[128:131]
	v_mfma_f32_16x16x32_bf16 v[120:123], v[178:181], v[226:229], v[120:123]
	v_mfma_f32_16x16x32_bf16 v[92:95], v[164:167], v[206:209], v[92:95]
	v_mfma_f32_16x16x32_bf16 v[84:87], v[182:185], v[206:209], v[84:87]
	v_mfma_f32_16x16x32_bf16 v[96:99], v[164:167], v[214:217], v[96:99]
	v_mfma_f32_16x16x32_bf16 v[88:91], v[182:185], v[214:217], v[88:91]
	v_mfma_f32_16x16x32_bf16 v[124:127], v[164:167], v[222:225], v[124:127]
	v_mfma_f32_16x16x32_bf16 v[116:119], v[182:185], v[222:225], v[116:119]
	v_mfma_f32_16x16x32_bf16 v[128:131], v[164:167], v[230:233], v[128:131]
	v_mfma_f32_16x16x32_bf16 v[120:123], v[182:185], v[230:233], v[120:123]
	v_mfma_f32_16x16x32_bf16 v[76:79], v[186:189], v[202:205], v[76:79]
	v_mfma_f32_16x16x32_bf16 v[68:71], v[194:197], v[202:205], v[68:71]
	v_mfma_f32_16x16x32_bf16 v[80:83], v[186:189], v[210:213], v[80:83]
	v_mfma_f32_16x16x32_bf16 v[72:75], v[194:197], v[210:213], v[72:75]
	v_mfma_f32_16x16x32_bf16 v[108:111], v[186:189], v[218:221], v[108:111]
	v_mfma_f32_16x16x32_bf16 v[100:103], v[194:197], v[218:221], v[100:103]
	v_mfma_f32_16x16x32_bf16 v[112:115], v[186:189], v[226:229], v[112:115]
	v_mfma_f32_16x16x32_bf16 v[104:107], v[194:197], v[226:229], v[104:107]
	v_mfma_f32_16x16x32_bf16 v[76:79], v[190:193], v[206:209], v[76:79]
	v_mfma_f32_16x16x32_bf16 v[68:71], v[198:201], v[206:209], v[68:71]
	v_mfma_f32_16x16x32_bf16 v[80:83], v[190:193], v[214:217], v[80:83]
	v_mfma_f32_16x16x32_bf16 v[72:75], v[198:201], v[214:217], v[72:75]
	v_mfma_f32_16x16x32_bf16 v[108:111], v[190:193], v[222:225], v[108:111]
	v_mfma_f32_16x16x32_bf16 v[100:103], v[198:201], v[222:225], v[100:103]
	v_mfma_f32_16x16x32_bf16 v[112:115], v[190:193], v[230:233], v[112:115]
	v_mfma_f32_16x16x32_bf16 v[104:107], v[198:201], v[230:233], v[104:107]
	s_barrier
	s_add_i32 s66, 0, 0x18000
	v_add_u32_e32 v149, s66, v144
	s_add_i32 s67, 0, 0x1c000
	ds_read_b128 v[150:153], v149
	ds_read_b128 v[164:167], v149 offset:1024
	ds_read_b128 v[178:181], v149 offset:2048
	ds_read_b128 v[182:185], v149 offset:3072
	v_add_u32_e32 v149, s67, v144
	ds_read_b128 v[186:189], v149
	ds_read_b128 v[190:193], v149 offset:1024
	ds_read_b128 v[194:197], v149 offset:2048
	ds_read_b128 v[198:201], v149 offset:3072
	s_add_u32 s2, s60, 0x80000
	s_addc_u32 s3, s61, 0
	s_mov_b32 m0, s28
	v_lshl_add_u64 v[242:243], s[2:3], 0, v[2:3]
	ds_read_b128 v[202:205], v145 offset:32768
	ds_read_b128 v[206:209], v145 offset:33792
	ds_read_b128 v[210:213], v145 offset:34816
	ds_read_b128 v[214:217], v145 offset:35840
	ds_read_b128 v[218:221], v145 offset:36864
	ds_read_b128 v[222:225], v145 offset:37888
	ds_read_b128 v[226:229], v145 offset:38912
	ds_read_b128 v[230:233], v145 offset:39936
	global_load_lds_dwordx4 v[242:243], off
	v_lshl_add_u64 v[242:243], s[2:3], 0, v[132:133]
	s_mov_b32 m0, s91
	s_nop 0
	global_load_lds_dwordx4 v[242:243], off
	s_waitcnt vmcnt(8)
	s_waitcnt lgkmcnt(0)
	v_mfma_f32_16x16x32_bf16 v[28:31], v[150:153], v[202:205], v[28:31]
	v_mfma_f32_16x16x32_bf16 v[20:23], v[178:181], v[202:205], v[20:23]
	v_mfma_f32_16x16x32_bf16 v[32:35], v[150:153], v[210:213], v[32:35]
	v_mfma_f32_16x16x32_bf16 v[24:27], v[178:181], v[210:213], v[24:27]
	s_barrier
	s_waitcnt lgkmcnt(0)
	v_mfma_f32_16x16x32_bf16 v[60:63], v[150:153], v[218:221], v[60:63]
	v_mfma_f32_16x16x32_bf16 v[52:55], v[178:181], v[218:221], v[52:55]
	v_mfma_f32_16x16x32_bf16 v[64:67], v[150:153], v[226:229], v[64:67]
	v_mfma_f32_16x16x32_bf16 v[56:59], v[178:181], v[226:229], v[56:59]
	v_mfma_f32_16x16x32_bf16 v[28:31], v[164:167], v[206:209], v[28:31]
	v_mfma_f32_16x16x32_bf16 v[20:23], v[182:185], v[206:209], v[20:23]
	v_mfma_f32_16x16x32_bf16 v[32:35], v[164:167], v[214:217], v[32:35]
	v_mfma_f32_16x16x32_bf16 v[24:27], v[182:185], v[214:217], v[24:27]
	v_mfma_f32_16x16x32_bf16 v[60:63], v[164:167], v[222:225], v[60:63]
	v_mfma_f32_16x16x32_bf16 v[52:55], v[182:185], v[222:225], v[52:55]
	v_mfma_f32_16x16x32_bf16 v[64:67], v[164:167], v[230:233], v[64:67]
	v_mfma_f32_16x16x32_bf16 v[56:59], v[182:185], v[230:233], v[56:59]
	v_mfma_f32_16x16x32_bf16 v[12:15], v[186:189], v[202:205], v[12:15]
	v_mfma_f32_16x16x32_bf16 v[4:7], v[194:197], v[202:205], v[4:7]
	v_mfma_f32_16x16x32_bf16 v[16:19], v[186:189], v[210:213], v[16:19]
	v_mfma_f32_16x16x32_bf16 v[8:11], v[194:197], v[210:213], v[8:11]
	v_mfma_f32_16x16x32_bf16 v[44:47], v[186:189], v[218:221], v[44:47]
	v_mfma_f32_16x16x32_bf16 v[36:39], v[194:197], v[218:221], v[36:39]
	v_mfma_f32_16x16x32_bf16 v[48:51], v[186:189], v[226:229], v[48:51]
	v_mfma_f32_16x16x32_bf16 v[40:43], v[194:197], v[226:229], v[40:43]
	v_mfma_f32_16x16x32_bf16 v[12:15], v[190:193], v[206:209], v[12:15]
	v_mfma_f32_16x16x32_bf16 v[4:7], v[198:201], v[206:209], v[4:7]
	v_mfma_f32_16x16x32_bf16 v[16:19], v[190:193], v[214:217], v[16:19]
	v_mfma_f32_16x16x32_bf16 v[8:11], v[198:201], v[214:217], v[8:11]
	v_mfma_f32_16x16x32_bf16 v[44:47], v[190:193], v[222:225], v[44:47]
	v_mfma_f32_16x16x32_bf16 v[36:39], v[198:201], v[222:225], v[36:39]
	v_mfma_f32_16x16x32_bf16 v[48:51], v[190:193], v[230:233], v[48:51]
	v_mfma_f32_16x16x32_bf16 v[40:43], v[198:201], v[230:233], v[40:43]
	s_barrier
	s_add_i32 s2, s66, s15
	v_lshl_add_u64 v[146:147], v[146:147], 0, s[82:83]
	s_mov_b32 m0, s2
	ds_read_b128 v[202:205], v145 offset:49152
	ds_read_b128 v[206:209], v145 offset:50176
	ds_read_b128 v[210:213], v145 offset:51200
	ds_read_b128 v[214:217], v145 offset:52224
	ds_read_b128 v[218:221], v145 offset:53248
	ds_read_b128 v[222:225], v145 offset:54272
	ds_read_b128 v[226:229], v145 offset:55296
	ds_read_b128 v[230:233], v145 offset:56320
	global_load_lds_dwordx4 v[146:147], off
	v_lshl_add_u64 v[146:147], v[154:155], 0, s[82:83]
	s_add_i32 m0, s2, 0x2000
	s_add_i32 s2, s67, s15
	global_load_lds_dwordx4 v[146:147], off
	v_lshl_add_u64 v[146:147], v[234:235], 0, s[82:83]
	s_mov_b32 m0, s2
	s_nop 0
	global_load_lds_dwordx4 v[146:147], off
	v_lshl_add_u64 v[146:147], v[236:237], 0, s[82:83]
	s_add_i32 m0, s2, 0x2000
	s_nop 0
	global_load_lds_dwordx4 v[146:147], off
	v_lshl_add_u64 v[146:147], v[238:239], 0, s[82:83]
	s_mov_b32 m0, s95
	s_nop 0
	global_load_lds_dwordx4 v[146:147], off
	v_lshl_add_u64 v[146:147], v[240:241], 0, s[82:83]
	s_mov_b32 m0, s12
	s_nop 0
	global_load_lds_dwordx4 v[146:147], off
	s_waitcnt vmcnt(8)
	s_waitcnt lgkmcnt(0)
	v_mfma_f32_16x16x32_bf16 v[92:95], v[150:153], v[202:205], v[92:95]
	v_mfma_f32_16x16x32_bf16 v[84:87], v[178:181], v[202:205], v[84:87]
	v_mfma_f32_16x16x32_bf16 v[96:99], v[150:153], v[210:213], v[96:99]
	v_mfma_f32_16x16x32_bf16 v[88:91], v[178:181], v[210:213], v[88:91]
	s_barrier
	s_waitcnt lgkmcnt(0)
	v_mfma_f32_16x16x32_bf16 v[124:127], v[150:153], v[218:221], v[124:127]
	v_mfma_f32_16x16x32_bf16 v[116:119], v[178:181], v[218:221], v[116:119]
	v_mfma_f32_16x16x32_bf16 v[128:131], v[150:153], v[226:229], v[128:131]
	v_mfma_f32_16x16x32_bf16 v[120:123], v[178:181], v[226:229], v[120:123]
	v_mfma_f32_16x16x32_bf16 v[92:95], v[164:167], v[206:209], v[92:95]
	v_mfma_f32_16x16x32_bf16 v[84:87], v[182:185], v[206:209], v[84:87]
	v_mfma_f32_16x16x32_bf16 v[96:99], v[164:167], v[214:217], v[96:99]
	v_mfma_f32_16x16x32_bf16 v[88:91], v[182:185], v[214:217], v[88:91]
	v_mfma_f32_16x16x32_bf16 v[124:127], v[164:167], v[222:225], v[124:127]
	v_mfma_f32_16x16x32_bf16 v[116:119], v[182:185], v[222:225], v[116:119]
	v_mfma_f32_16x16x32_bf16 v[128:131], v[164:167], v[230:233], v[128:131]
	v_mfma_f32_16x16x32_bf16 v[120:123], v[182:185], v[230:233], v[120:123]
	v_mfma_f32_16x16x32_bf16 v[76:79], v[186:189], v[202:205], v[76:79]
	v_mfma_f32_16x16x32_bf16 v[68:71], v[194:197], v[202:205], v[68:71]
	v_mfma_f32_16x16x32_bf16 v[80:83], v[186:189], v[210:213], v[80:83]
	v_mfma_f32_16x16x32_bf16 v[72:75], v[194:197], v[210:213], v[72:75]
	v_mfma_f32_16x16x32_bf16 v[108:111], v[186:189], v[218:221], v[108:111]
	v_mfma_f32_16x16x32_bf16 v[100:103], v[194:197], v[218:221], v[100:103]
	v_mfma_f32_16x16x32_bf16 v[112:115], v[186:189], v[226:229], v[112:115]
	v_mfma_f32_16x16x32_bf16 v[104:107], v[194:197], v[226:229], v[104:107]
	v_mfma_f32_16x16x32_bf16 v[76:79], v[190:193], v[206:209], v[76:79]
	v_mfma_f32_16x16x32_bf16 v[68:71], v[198:201], v[206:209], v[68:71]
	v_mfma_f32_16x16x32_bf16 v[80:83], v[190:193], v[214:217], v[80:83]
	v_mfma_f32_16x16x32_bf16 v[72:75], v[198:201], v[214:217], v[72:75]
	v_mfma_f32_16x16x32_bf16 v[108:111], v[190:193], v[222:225], v[108:111]
	v_mfma_f32_16x16x32_bf16 v[100:103], v[198:201], v[222:225], v[100:103]
	v_mfma_f32_16x16x32_bf16 v[112:115], v[190:193], v[230:233], v[112:115]
	v_mfma_f32_16x16x32_bf16 v[104:107], v[198:201], v[230:233], v[104:107]
	s_barrier
	s_add_i32 vcc_lo, vcc_lo, 2
	s_add_u32 s58, s58, 0x100
	s_addc_u32 s59, s59, 0
	s_cmp_gt_u32 vcc_lo, 29
	s_cbranch_scc0 .LBB0_483
	s_and_b64 vcc, exec, s[46:47]
	s_cbranch_vccz .LBB0_486
	s_barrier

.LBB0_589:
	ds_read_b128 v[156:159], v152
	ds_read_b128 v[160:163], v152 offset:1024
	ds_read_b128 v[164:167], v152 offset:2048
	ds_read_b128 v[172:175], v152 offset:3072
	ds_read_b128 v[176:179], v153
	ds_read_b128 v[180:183], v153 offset:1024
	ds_read_b128 v[184:187], v153 offset:2048
	ds_read_b128 v[188:191], v153 offset:3072
	s_add_u32 s2, s44, 0xfffc0080
	s_addc_u32 s3, s45, -1
	s_cmp_eq_u32 s54, 12
	s_cselect_b32 s47, s25, s3
	s_cselect_b32 s46, s50, s2
	s_cselect_b32 s57, s19, s53
	s_cselect_b32 s56, s51, s52
	v_lshl_add_u64 v[168:169], s[44:45], 0, v[142:143]
	s_add_i32 m0, s14, 0xc000
	ds_read_b128 v[192:195], v154
	ds_read_b128 v[196:199], v154 offset:1024
	ds_read_b128 v[200:203], v154 offset:2048
	ds_read_b128 v[204:207], v154 offset:3072
	ds_read_b128 v[208:211], v154 offset:4096
	ds_read_b128 v[212:215], v154 offset:5120
	ds_read_b128 v[216:219], v154 offset:6144
	ds_read_b128 v[220:223], v154 offset:7168
	global_load_lds_dwordx4 v[168:169], off
	v_lshl_add_u64 v[168:169], s[44:45], 0, v[144:145]
	s_add_i32 m0, s14, 0xe000
	s_nop 0
	global_load_lds_dwordx4 v[168:169], off
	s_waitcnt vmcnt(8)
	s_waitcnt lgkmcnt(0)
	v_mfma_f32_16x16x32_f16 v[124:127], v[156:159], v[192:195], v[124:127]
	v_mfma_f32_16x16x32_f16 v[120:123], v[164:167], v[192:195], v[120:123]
	v_mfma_f32_16x16x32_f16 v[116:119], v[156:159], v[200:203], v[116:119]
	v_mfma_f32_16x16x32_f16 v[108:111], v[164:167], v[200:203], v[108:111]
	s_barrier
	s_waitcnt lgkmcnt(0)
	v_mfma_f32_16x16x32_f16 v[100:103], v[156:159], v[208:211], v[100:103]
	v_mfma_f32_16x16x32_f16 v[92:95], v[164:167], v[208:211], v[92:95]
	v_mfma_f32_16x16x32_f16 v[84:87], v[156:159], v[216:219], v[84:87]
	v_mfma_f32_16x16x32_f16 v[76:79], v[164:167], v[216:219], v[76:79]
	v_mfma_f32_16x16x32_f16 v[124:127], v[160:163], v[196:199], v[124:127]
	v_mfma_f32_16x16x32_f16 v[120:123], v[172:175], v[196:199], v[120:123]
	v_mfma_f32_16x16x32_f16 v[116:119], v[160:163], v[204:207], v[116:119]
	v_mfma_f32_16x16x32_f16 v[108:111], v[172:175], v[204:207], v[108:111]
	v_mfma_f32_16x16x32_f16 v[100:103], v[160:163], v[212:215], v[100:103]
	v_mfma_f32_16x16x32_f16 v[92:95], v[172:175], v[212:215], v[92:95]
	v_mfma_f32_16x16x32_f16 v[84:87], v[160:163], v[220:223], v[84:87]
	v_mfma_f32_16x16x32_f16 v[76:79], v[172:175], v[220:223], v[76:79]
	v_mfma_f32_16x16x32_f16 v[112:115], v[176:179], v[192:195], v[112:115]
	v_mfma_f32_16x16x32_f16 v[104:107], v[184:187], v[192:195], v[104:107]
	v_mfma_f32_16x16x32_f16 v[96:99], v[176:179], v[200:203], v[96:99]
	v_mfma_f32_16x16x32_f16 v[88:91], v[184:187], v[200:203], v[88:91]
	v_mfma_f32_16x16x32_f16 v[80:83], v[176:179], v[208:211], v[80:83]
	v_mfma_f32_16x16x32_f16 v[72:75], v[184:187], v[208:211], v[72:75]
	v_mfma_f32_16x16x32_f16 v[68:71], v[176:179], v[216:219], v[68:71]
	v_mfma_f32_16x16x32_f16 v[64:67], v[184:187], v[216:219], v[64:67]
	v_mfma_f32_16x16x32_f16 v[112:115], v[180:183], v[196:199], v[112:115]
	v_mfma_f32_16x16x32_f16 v[104:107], v[188:191], v[196:199], v[104:107]
	v_mfma_f32_16x16x32_f16 v[96:99], v[180:183], v[204:207], v[96:99]
	v_mfma_f32_16x16x32_f16 v[88:91], v[188:191], v[204:207], v[88:91]
	v_mfma_f32_16x16x32_f16 v[80:83], v[180:183], v[212:215], v[80:83]
	v_mfma_f32_16x16x32_f16 v[72:75], v[188:191], v[212:215], v[72:75]
	v_mfma_f32_16x16x32_f16 v[68:71], v[180:183], v[220:223], v[68:71]
	v_mfma_f32_16x16x32_f16 v[64:67], v[188:191], v[220:223], v[64:67]
	s_barrier
	s_add_i32 s2, s29, s12
	v_lshl_add_u64 v[168:169], s[56:57], 0, v[134:135]
	s_mov_b32 m0, s2
	ds_read_b128 v[192:195], v154 offset:16384
	ds_read_b128 v[196:199], v154 offset:17408
	ds_read_b128 v[200:203], v154 offset:18432
	ds_read_b128 v[204:207], v154 offset:19456
	ds_read_b128 v[208:211], v154 offset:20480
	ds_read_b128 v[212:215], v154 offset:21504
	ds_read_b128 v[216:219], v154 offset:22528
	ds_read_b128 v[220:223], v154 offset:23552
	global_load_lds_dwordx4 v[168:169], off
	v_lshl_add_u64 v[224:225], s[56:57], 0, v[128:129]
	s_add_i32 m0, s2, 0x2000
	s_add_i32 s2, s48, s12
	global_load_lds_dwordx4 v[224:225], off
	v_lshl_add_u64 v[226:227], s[56:57], 0, v[136:137]
	s_mov_b32 m0, s2
	v_lshl_add_u64 v[228:229], s[56:57], 0, v[130:131]
	global_load_lds_dwordx4 v[226:227], off
	s_add_i32 m0, s2, 0x2000
	v_lshl_add_u64 v[230:231], s[46:47], 0, v[138:139]
	global_load_lds_dwordx4 v[228:229], off
	s_mov_b32 m0, s14
	v_lshl_add_u64 v[232:233], s[46:47], 0, v[132:133]
	global_load_lds_dwordx4 v[230:231], off
	s_mov_b32 m0, s15
	s_nop 0
	global_load_lds_dwordx4 v[232:233], off
	s_waitcnt vmcnt(8)
	s_waitcnt lgkmcnt(0)
	v_mfma_f32_16x16x32_f16 v[60:63], v[156:159], v[192:195], v[60:63]
	v_mfma_f32_16x16x32_f16 v[56:59], v[164:167], v[192:195], v[56:59]
	v_mfma_f32_16x16x32_f16 v[52:55], v[156:159], v[200:203], v[52:55]
	v_mfma_f32_16x16x32_f16 v[44:47], v[164:167], v[200:203], v[44:47]
	s_barrier
	s_waitcnt lgkmcnt(0)
	v_mfma_f32_16x16x32_f16 v[36:39], v[156:159], v[208:211], v[36:39]
	v_mfma_f32_16x16x32_f16 v[28:31], v[164:167], v[208:211], v[28:31]
	v_mfma_f32_16x16x32_f16 v[20:23], v[156:159], v[216:219], v[20:23]
	v_mfma_f32_16x16x32_f16 v[12:15], v[164:167], v[216:219], v[12:15]
	v_mfma_f32_16x16x32_f16 v[60:63], v[160:163], v[196:199], v[60:63]
	v_mfma_f32_16x16x32_f16 v[56:59], v[172:175], v[196:199], v[56:59]
	v_mfma_f32_16x16x32_f16 v[52:55], v[160:163], v[204:207], v[52:55]
	v_mfma_f32_16x16x32_f16 v[44:47], v[172:175], v[204:207], v[44:47]
	v_mfma_f32_16x16x32_f16 v[36:39], v[160:163], v[212:215], v[36:39]
	v_mfma_f32_16x16x32_f16 v[28:31], v[172:175], v[212:215], v[28:31]
	v_mfma_f32_16x16x32_f16 v[20:23], v[160:163], v[220:223], v[20:23]
	v_mfma_f32_16x16x32_f16 v[12:15], v[172:175], v[220:223], v[12:15]
	v_mfma_f32_16x16x32_f16 v[48:51], v[176:179], v[192:195], v[48:51]
	v_mfma_f32_16x16x32_f16 v[40:43], v[184:187], v[192:195], v[40:43]
	v_mfma_f32_16x16x32_f16 v[32:35], v[176:179], v[200:203], v[32:35]
	v_mfma_f32_16x16x32_f16 v[24:27], v[184:187], v[200:203], v[24:27]
	v_mfma_f32_16x16x32_f16 v[16:19], v[176:179], v[208:211], v[16:19]
	v_mfma_f32_16x16x32_f16 v[8:11], v[184:187], v[208:211], v[8:11]
	v_mfma_f32_16x16x32_f16 v[4:7], v[176:179], v[216:219], v[4:7]
	v_mfma_f32_16x16x32_f16 v[0:3], v[184:187], v[216:219], v[0:3]
	v_mfma_f32_16x16x32_f16 v[48:51], v[180:183], v[196:199], v[48:51]
	v_mfma_f32_16x16x32_f16 v[40:43], v[188:191], v[196:199], v[40:43]
	v_mfma_f32_16x16x32_f16 v[32:35], v[180:183], v[204:207], v[32:35]
	v_mfma_f32_16x16x32_f16 v[24:27], v[188:191], v[204:207], v[24:27]
	v_mfma_f32_16x16x32_f16 v[16:19], v[180:183], v[212:215], v[16:19]
	v_mfma_f32_16x16x32_f16 v[8:11], v[188:191], v[212:215], v[8:11]
	v_mfma_f32_16x16x32_f16 v[4:7], v[180:183], v[220:223], v[4:7]
	v_mfma_f32_16x16x32_f16 v[0:3], v[188:191], v[220:223], v[0:3]
	s_barrier
	s_add_i32 s2, 0, 0x18000
	s_add_i32 s3, 0, 0x1c000
	v_add_u32_e32 v172, s2, v151
	v_add_u32_e32 v188, s3, v151
	ds_read_b128 v[156:159], v172
	ds_read_b128 v[160:163], v172 offset:1024
	ds_read_b128 v[164:167], v172 offset:2048
	ds_read_b128 v[172:175], v172 offset:3072
	ds_read_b128 v[176:179], v188
	ds_read_b128 v[180:183], v188 offset:1024
	ds_read_b128 v[184:187], v188 offset:2048
	ds_read_b128 v[188:191], v188 offset:3072
	s_add_u32 s46, s46, 0x40000
	s_addc_u32 s47, s47, 0
	s_mov_b32 m0, s16
	v_lshl_add_u64 v[234:235], s[46:47], 0, v[138:139]
	ds_read_b128 v[192:195], v154 offset:32768
	ds_read_b128 v[196:199], v154 offset:33792
	ds_read_b128 v[200:203], v154 offset:34816
	ds_read_b128 v[204:207], v154 offset:35840
	ds_read_b128 v[208:211], v154 offset:36864
	ds_read_b128 v[212:215], v154 offset:37888
	ds_read_b128 v[216:219], v154 offset:38912
	ds_read_b128 v[220:223], v154 offset:39936
	global_load_lds_dwordx4 v[234:235], off
	v_lshl_add_u64 v[234:235], s[46:47], 0, v[132:133]
	s_mov_b32 m0, s17
	s_nop 0
	global_load_lds_dwordx4 v[234:235], off
	s_waitcnt vmcnt(8)
	s_waitcnt lgkmcnt(0)
	v_mfma_f32_16x16x32_f16 v[124:127], v[156:159], v[192:195], v[124:127]
	v_mfma_f32_16x16x32_f16 v[120:123], v[164:167], v[192:195], v[120:123]
	v_mfma_f32_16x16x32_f16 v[116:119], v[156:159], v[200:203], v[116:119]
	v_mfma_f32_16x16x32_f16 v[108:111], v[164:167], v[200:203], v[108:111]
	s_barrier
	s_waitcnt lgkmcnt(0)
	v_mfma_f32_16x16x32_f16 v[100:103], v[156:159], v[208:211], v[100:103]
	v_mfma_f32_16x16x32_f16 v[92:95], v[164:167], v[208:211], v[92:95]
	v_mfma_f32_16x16x32_f16 v[84:87], v[156:159], v[216:219], v[84:87]
	v_mfma_f32_16x16x32_f16 v[76:79], v[164:167], v[216:219], v[76:79]
	v_mfma_f32_16x16x32_f16 v[124:127], v[160:163], v[196:199], v[124:127]
	v_mfma_f32_16x16x32_f16 v[120:123], v[172:175], v[196:199], v[120:123]
	v_mfma_f32_16x16x32_f16 v[116:119], v[160:163], v[204:207], v[116:119]
	v_mfma_f32_16x16x32_f16 v[108:111], v[172:175], v[204:207], v[108:111]
	v_mfma_f32_16x16x32_f16 v[100:103], v[160:163], v[212:215], v[100:103]
	v_mfma_f32_16x16x32_f16 v[92:95], v[172:175], v[212:215], v[92:95]
	v_mfma_f32_16x16x32_f16 v[84:87], v[160:163], v[220:223], v[84:87]
	v_mfma_f32_16x16x32_f16 v[76:79], v[172:175], v[220:223], v[76:79]
	v_mfma_f32_16x16x32_f16 v[112:115], v[176:179], v[192:195], v[112:115]
	v_mfma_f32_16x16x32_f16 v[104:107], v[184:187], v[192:195], v[104:107]
	v_mfma_f32_16x16x32_f16 v[96:99], v[176:179], v[200:203], v[96:99]
	v_mfma_f32_16x16x32_f16 v[88:91], v[184:187], v[200:203], v[88:91]
	v_mfma_f32_16x16x32_f16 v[80:83], v[176:179], v[208:211], v[80:83]
	v_mfma_f32_16x16x32_f16 v[72:75], v[184:187], v[208:211], v[72:75]
	v_mfma_f32_16x16x32_f16 v[68:71], v[176:179], v[216:219], v[68:71]
	v_mfma_f32_16x16x32_f16 v[64:67], v[184:187], v[216:219], v[64:67]
	v_mfma_f32_16x16x32_f16 v[112:115], v[180:183], v[196:199], v[112:115]
	v_mfma_f32_16x16x32_f16 v[104:107], v[188:191], v[196:199], v[104:107]
	v_mfma_f32_16x16x32_f16 v[96:99], v[180:183], v[204:207], v[96:99]
	v_mfma_f32_16x16x32_f16 v[88:91], v[188:191], v[204:207], v[88:91]
	v_mfma_f32_16x16x32_f16 v[80:83], v[180:183], v[212:215], v[80:83]
	v_mfma_f32_16x16x32_f16 v[72:75], v[188:191], v[212:215], v[72:75]
	v_mfma_f32_16x16x32_f16 v[68:71], v[180:183], v[220:223], v[68:71]
	v_mfma_f32_16x16x32_f16 v[64:67], v[188:191], v[220:223], v[64:67]
	s_barrier
	s_add_i32 s2, s2, s12
	v_lshl_add_u64 v[168:169], v[168:169], 0, s[6:7]
	s_mov_b32 m0, s2
	ds_read_b128 v[192:195], v154 offset:49152
	ds_read_b128 v[196:199], v154 offset:50176
	ds_read_b128 v[200:203], v154 offset:51200
	ds_read_b128 v[204:207], v154 offset:52224
	ds_read_b128 v[208:211], v154 offset:53248
	ds_read_b128 v[212:215], v154 offset:54272
	ds_read_b128 v[216:219], v154 offset:55296
	ds_read_b128 v[220:223], v154 offset:56320
	global_load_lds_dwordx4 v[168:169], off
	v_lshl_add_u64 v[168:169], v[224:225], 0, s[6:7]
	s_add_i32 m0, s2, 0x2000
	s_add_i32 s2, s3, s12
	global_load_lds_dwordx4 v[168:169], off
	v_lshl_add_u64 v[168:169], v[226:227], 0, s[6:7]
	s_mov_b32 m0, s2
	s_nop 0
	global_load_lds_dwordx4 v[168:169], off
	v_lshl_add_u64 v[168:169], v[228:229], 0, s[6:7]
	s_add_i32 m0, s2, 0x2000
	s_nop 0
	global_load_lds_dwordx4 v[168:169], off
	v_lshl_add_u64 v[168:169], v[230:231], 0, s[6:7]
	s_mov_b32 m0, s20
	s_nop 0
	global_load_lds_dwordx4 v[168:169], off
	v_lshl_add_u64 v[168:169], v[232:233], 0, s[6:7]
	s_mov_b32 m0, s21
	s_nop 0
	global_load_lds_dwordx4 v[168:169], off
	s_waitcnt vmcnt(8)
	s_waitcnt lgkmcnt(0)
	v_mfma_f32_16x16x32_f16 v[60:63], v[156:159], v[192:195], v[60:63]
	v_mfma_f32_16x16x32_f16 v[56:59], v[164:167], v[192:195], v[56:59]
	v_mfma_f32_16x16x32_f16 v[52:55], v[156:159], v[200:203], v[52:55]
	v_mfma_f32_16x16x32_f16 v[44:47], v[164:167], v[200:203], v[44:47]
	s_barrier
	s_waitcnt lgkmcnt(0)
	v_mfma_f32_16x16x32_f16 v[36:39], v[156:159], v[208:211], v[36:39]
	v_mfma_f32_16x16x32_f16 v[28:31], v[164:167], v[208:211], v[28:31]
	v_mfma_f32_16x16x32_f16 v[20:23], v[156:159], v[216:219], v[20:23]
	v_mfma_f32_16x16x32_f16 v[12:15], v[164:167], v[216:219], v[12:15]
	v_mfma_f32_16x16x32_f16 v[60:63], v[160:163], v[196:199], v[60:63]
	v_mfma_f32_16x16x32_f16 v[56:59], v[172:175], v[196:199], v[56:59]
	v_mfma_f32_16x16x32_f16 v[52:55], v[160:163], v[204:207], v[52:55]
	v_mfma_f32_16x16x32_f16 v[44:47], v[172:175], v[204:207], v[44:47]
	v_mfma_f32_16x16x32_f16 v[36:39], v[160:163], v[212:215], v[36:39]
	v_mfma_f32_16x16x32_f16 v[28:31], v[172:175], v[212:215], v[28:31]
	v_mfma_f32_16x16x32_f16 v[20:23], v[160:163], v[220:223], v[20:23]
	v_mfma_f32_16x16x32_f16 v[12:15], v[172:175], v[220:223], v[12:15]
	v_mfma_f32_16x16x32_f16 v[48:51], v[176:179], v[192:195], v[48:51]
	v_mfma_f32_16x16x32_f16 v[40:43], v[184:187], v[192:195], v[40:43]
	v_mfma_f32_16x16x32_f16 v[32:35], v[176:179], v[200:203], v[32:35]
	v_mfma_f32_16x16x32_f16 v[24:27], v[184:187], v[200:203], v[24:27]
	v_mfma_f32_16x16x32_f16 v[16:19], v[176:179], v[208:211], v[16:19]
	v_mfma_f32_16x16x32_f16 v[8:11], v[184:187], v[208:211], v[8:11]
	v_mfma_f32_16x16x32_f16 v[4:7], v[176:179], v[216:219], v[4:7]
	v_mfma_f32_16x16x32_f16 v[0:3], v[184:187], v[216:219], v[0:3]
	v_mfma_f32_16x16x32_f16 v[48:51], v[180:183], v[196:199], v[48:51]
	v_mfma_f32_16x16x32_f16 v[40:43], v[188:191], v[196:199], v[40:43]
	v_mfma_f32_16x16x32_f16 v[32:35], v[180:183], v[204:207], v[32:35]
	v_mfma_f32_16x16x32_f16 v[24:27], v[188:191], v[204:207], v[24:27]
	v_mfma_f32_16x16x32_f16 v[16:19], v[180:183], v[212:215], v[16:19]
	v_mfma_f32_16x16x32_f16 v[8:11], v[188:191], v[212:215], v[8:11]
	v_mfma_f32_16x16x32_f16 v[4:7], v[180:183], v[220:223], v[4:7]
	v_mfma_f32_16x16x32_f16 v[0:3], v[188:191], v[220:223], v[0:3]
	s_barrier
	s_add_i32 s54, s54, 2
	s_add_u32 s44, s44, 0x100
	s_addc_u32 s45, s45, 0
	s_add_u32 s52, s52, 0x100
	s_addc_u32 s53, s53, 0
	s_cmp_gt_u32 s54, 13
	s_cbranch_scc0 .LBB0_589
	s_and_b64 vcc, exec, s[8:9]
	s_cbranch_vccz .LBB0_592
	s_barrier

.LBB0_609:
	ds_read_b128 v[156:159], v152
	ds_read_b128 v[160:163], v152 offset:1024
	ds_read_b128 v[164:167], v152 offset:2048
	ds_read_b128 v[172:175], v152 offset:3072
	ds_read_b128 v[176:179], v153
	ds_read_b128 v[180:183], v153 offset:1024
	ds_read_b128 v[184:187], v153 offset:2048
	ds_read_b128 v[188:191], v153 offset:3072
	s_add_u32 s2, s44, 0xfffc0080
	s_addc_u32 s3, s45, -1
	s_cmp_eq_u32 s53, 12
	s_cselect_b32 s47, s27, s3
	s_cselect_b32 s46, s49, s2
	s_cselect_b32 s55, s25, s52
	s_cselect_b32 s54, s50, s51
	v_lshl_add_u64 v[168:169], s[44:45], 0, v[142:143]
	s_add_i32 m0, s15, 0xc000
	ds_read_b128 v[192:195], v154
	ds_read_b128 v[196:199], v154 offset:1024
	ds_read_b128 v[200:203], v154 offset:2048
	ds_read_b128 v[204:207], v154 offset:3072
	ds_read_b128 v[208:211], v154 offset:4096
	ds_read_b128 v[212:215], v154 offset:5120
	ds_read_b128 v[216:219], v154 offset:6144
	ds_read_b128 v[220:223], v154 offset:7168
	global_load_lds_dwordx4 v[168:169], off
	v_lshl_add_u64 v[168:169], s[44:45], 0, v[144:145]
	s_add_i32 m0, s15, 0xe000
	s_nop 0
	global_load_lds_dwordx4 v[168:169], off
	s_waitcnt vmcnt(8)
	s_waitcnt lgkmcnt(0)
	v_mfma_f32_16x16x32_f16 v[124:127], v[156:159], v[192:195], v[124:127]
	v_mfma_f32_16x16x32_f16 v[120:123], v[164:167], v[192:195], v[120:123]
	v_mfma_f32_16x16x32_f16 v[116:119], v[156:159], v[200:203], v[116:119]
	v_mfma_f32_16x16x32_f16 v[112:115], v[164:167], v[200:203], v[112:115]
	s_barrier
	s_waitcnt lgkmcnt(0)
	v_mfma_f32_16x16x32_f16 v[100:103], v[156:159], v[208:211], v[100:103]
	v_mfma_f32_16x16x32_f16 v[96:99], v[164:167], v[208:211], v[96:99]
	v_mfma_f32_16x16x32_f16 v[84:87], v[156:159], v[216:219], v[84:87]
	v_mfma_f32_16x16x32_f16 v[80:83], v[164:167], v[216:219], v[80:83]
	v_mfma_f32_16x16x32_f16 v[124:127], v[160:163], v[196:199], v[124:127]
	v_mfma_f32_16x16x32_f16 v[120:123], v[172:175], v[196:199], v[120:123]
	v_mfma_f32_16x16x32_f16 v[116:119], v[160:163], v[204:207], v[116:119]
	v_mfma_f32_16x16x32_f16 v[112:115], v[172:175], v[204:207], v[112:115]
	v_mfma_f32_16x16x32_f16 v[100:103], v[160:163], v[212:215], v[100:103]
	v_mfma_f32_16x16x32_f16 v[96:99], v[172:175], v[212:215], v[96:99]
	v_mfma_f32_16x16x32_f16 v[84:87], v[160:163], v[220:223], v[84:87]
	v_mfma_f32_16x16x32_f16 v[80:83], v[172:175], v[220:223], v[80:83]
	v_mfma_f32_16x16x32_f16 v[108:111], v[176:179], v[192:195], v[108:111]
	v_mfma_f32_16x16x32_f16 v[104:107], v[184:187], v[192:195], v[104:107]
	v_mfma_f32_16x16x32_f16 v[92:95], v[176:179], v[200:203], v[92:95]
	v_mfma_f32_16x16x32_f16 v[88:91], v[184:187], v[200:203], v[88:91]
	v_mfma_f32_16x16x32_f16 v[76:79], v[176:179], v[208:211], v[76:79]
	v_mfma_f32_16x16x32_f16 v[72:75], v[184:187], v[208:211], v[72:75]
	v_mfma_f32_16x16x32_f16 v[68:71], v[176:179], v[216:219], v[68:71]
	v_mfma_f32_16x16x32_f16 v[64:67], v[184:187], v[216:219], v[64:67]
	v_mfma_f32_16x16x32_f16 v[108:111], v[180:183], v[196:199], v[108:111]
	v_mfma_f32_16x16x32_f16 v[104:107], v[188:191], v[196:199], v[104:107]
	v_mfma_f32_16x16x32_f16 v[92:95], v[180:183], v[204:207], v[92:95]
	v_mfma_f32_16x16x32_f16 v[88:91], v[188:191], v[204:207], v[88:91]
	v_mfma_f32_16x16x32_f16 v[76:79], v[180:183], v[212:215], v[76:79]
	v_mfma_f32_16x16x32_f16 v[72:75], v[188:191], v[212:215], v[72:75]
	v_mfma_f32_16x16x32_f16 v[68:71], v[180:183], v[220:223], v[68:71]
	v_mfma_f32_16x16x32_f16 v[64:67], v[188:191], v[220:223], v[64:67]
	s_barrier
	s_add_i32 s2, s21, s14
	v_lshl_add_u64 v[168:169], s[54:55], 0, v[134:135]
	s_mov_b32 m0, s2
	ds_read_b128 v[192:195], v154 offset:16384
	ds_read_b128 v[196:199], v154 offset:17408
	ds_read_b128 v[200:203], v154 offset:18432
	ds_read_b128 v[204:207], v154 offset:19456
	ds_read_b128 v[208:211], v154 offset:20480
	ds_read_b128 v[212:215], v154 offset:21504
	ds_read_b128 v[216:219], v154 offset:22528
	ds_read_b128 v[220:223], v154 offset:23552
	global_load_lds_dwordx4 v[168:169], off
	v_lshl_add_u64 v[224:225], s[54:55], 0, v[128:129]
	s_add_i32 m0, s2, 0x2000
	s_add_i32 s2, s28, s14
	global_load_lds_dwordx4 v[224:225], off
	v_lshl_add_u64 v[226:227], s[54:55], 0, v[136:137]
	s_mov_b32 m0, s2
	v_lshl_add_u64 v[228:229], s[54:55], 0, v[130:131]
	global_load_lds_dwordx4 v[226:227], off
	s_add_i32 m0, s2, 0x2000
	v_lshl_add_u64 v[230:231], s[46:47], 0, v[138:139]
	global_load_lds_dwordx4 v[228:229], off
	s_mov_b32 m0, s15
	v_lshl_add_u64 v[232:233], s[46:47], 0, v[132:133]
	global_load_lds_dwordx4 v[230:231], off
	s_mov_b32 m0, s16
	s_nop 0
	global_load_lds_dwordx4 v[232:233], off
	s_waitcnt vmcnt(8)
	s_waitcnt lgkmcnt(0)
	v_mfma_f32_16x16x32_f16 v[60:63], v[156:159], v[192:195], v[60:63]
	v_mfma_f32_16x16x32_f16 v[56:59], v[164:167], v[192:195], v[56:59]
	v_mfma_f32_16x16x32_f16 v[52:55], v[156:159], v[200:203], v[52:55]
	v_mfma_f32_16x16x32_f16 v[48:51], v[164:167], v[200:203], v[48:51]
	s_barrier
	s_waitcnt lgkmcnt(0)
	v_mfma_f32_16x16x32_f16 v[36:39], v[156:159], v[208:211], v[36:39]
	v_mfma_f32_16x16x32_f16 v[32:35], v[164:167], v[208:211], v[32:35]
	v_mfma_f32_16x16x32_f16 v[20:23], v[156:159], v[216:219], v[20:23]
	v_mfma_f32_16x16x32_f16 v[16:19], v[164:167], v[216:219], v[16:19]
	v_mfma_f32_16x16x32_f16 v[60:63], v[160:163], v[196:199], v[60:63]
	v_mfma_f32_16x16x32_f16 v[56:59], v[172:175], v[196:199], v[56:59]
	v_mfma_f32_16x16x32_f16 v[52:55], v[160:163], v[204:207], v[52:55]
	v_mfma_f32_16x16x32_f16 v[48:51], v[172:175], v[204:207], v[48:51]
	v_mfma_f32_16x16x32_f16 v[36:39], v[160:163], v[212:215], v[36:39]
	v_mfma_f32_16x16x32_f16 v[32:35], v[172:175], v[212:215], v[32:35]
	v_mfma_f32_16x16x32_f16 v[20:23], v[160:163], v[220:223], v[20:23]
	v_mfma_f32_16x16x32_f16 v[16:19], v[172:175], v[220:223], v[16:19]
	v_mfma_f32_16x16x32_f16 v[44:47], v[176:179], v[192:195], v[44:47]
	v_mfma_f32_16x16x32_f16 v[40:43], v[184:187], v[192:195], v[40:43]
	v_mfma_f32_16x16x32_f16 v[28:31], v[176:179], v[200:203], v[28:31]
	v_mfma_f32_16x16x32_f16 v[24:27], v[184:187], v[200:203], v[24:27]
	v_mfma_f32_16x16x32_f16 v[12:15], v[176:179], v[208:211], v[12:15]
	v_mfma_f32_16x16x32_f16 v[8:11], v[184:187], v[208:211], v[8:11]
	v_mfma_f32_16x16x32_f16 v[4:7], v[176:179], v[216:219], v[4:7]
	v_mfma_f32_16x16x32_f16 v[0:3], v[184:187], v[216:219], v[0:3]
	v_mfma_f32_16x16x32_f16 v[44:47], v[180:183], v[196:199], v[44:47]
	v_mfma_f32_16x16x32_f16 v[40:43], v[188:191], v[196:199], v[40:43]
	v_mfma_f32_16x16x32_f16 v[28:31], v[180:183], v[204:207], v[28:31]
	v_mfma_f32_16x16x32_f16 v[24:27], v[188:191], v[204:207], v[24:27]
	v_mfma_f32_16x16x32_f16 v[12:15], v[180:183], v[212:215], v[12:15]
	v_mfma_f32_16x16x32_f16 v[8:11], v[188:191], v[212:215], v[8:11]
	v_mfma_f32_16x16x32_f16 v[4:7], v[180:183], v[220:223], v[4:7]
	v_mfma_f32_16x16x32_f16 v[0:3], v[188:191], v[220:223], v[0:3]
	s_barrier
	s_add_i32 s2, 0, 0x18000
	v_add_u32_e32 v155, s2, v151
	s_add_i32 s3, 0, 0x1c000
	ds_read_b128 v[156:159], v155
	ds_read_b128 v[160:163], v155 offset:1024
	ds_read_b128 v[164:167], v155 offset:2048
	ds_read_b128 v[172:175], v155 offset:3072
	v_add_u32_e32 v155, s3, v151
	ds_read_b128 v[176:179], v155
	ds_read_b128 v[180:183], v155 offset:1024
	ds_read_b128 v[184:187], v155 offset:2048
	ds_read_b128 v[188:191], v155 offset:3072
	s_add_u32 s46, s46, 0x40000
	s_addc_u32 s47, s47, 0
	s_mov_b32 m0, s17
	v_lshl_add_u64 v[234:235], s[46:47], 0, v[138:139]
	ds_read_b128 v[192:195], v154 offset:32768
	ds_read_b128 v[196:199], v154 offset:33792
	ds_read_b128 v[200:203], v154 offset:34816
	ds_read_b128 v[204:207], v154 offset:35840
	ds_read_b128 v[208:211], v154 offset:36864
	ds_read_b128 v[212:215], v154 offset:37888
	ds_read_b128 v[216:219], v154 offset:38912
	ds_read_b128 v[220:223], v154 offset:39936
	global_load_lds_dwordx4 v[234:235], off
	v_lshl_add_u64 v[234:235], s[46:47], 0, v[132:133]
	s_mov_b32 m0, s18
	s_nop 0
	global_load_lds_dwordx4 v[234:235], off
	s_waitcnt vmcnt(8)
	s_waitcnt lgkmcnt(0)
	v_mfma_f32_16x16x32_f16 v[124:127], v[156:159], v[192:195], v[124:127]
	v_mfma_f32_16x16x32_f16 v[120:123], v[164:167], v[192:195], v[120:123]
	v_mfma_f32_16x16x32_f16 v[116:119], v[156:159], v[200:203], v[116:119]
	v_mfma_f32_16x16x32_f16 v[112:115], v[164:167], v[200:203], v[112:115]
	s_barrier
	s_waitcnt lgkmcnt(0)
	v_mfma_f32_16x16x32_f16 v[100:103], v[156:159], v[208:211], v[100:103]
	v_mfma_f32_16x16x32_f16 v[96:99], v[164:167], v[208:211], v[96:99]
	v_mfma_f32_16x16x32_f16 v[84:87], v[156:159], v[216:219], v[84:87]
	v_mfma_f32_16x16x32_f16 v[80:83], v[164:167], v[216:219], v[80:83]
	v_mfma_f32_16x16x32_f16 v[124:127], v[160:163], v[196:199], v[124:127]
	v_mfma_f32_16x16x32_f16 v[120:123], v[172:175], v[196:199], v[120:123]
	v_mfma_f32_16x16x32_f16 v[116:119], v[160:163], v[204:207], v[116:119]
	v_mfma_f32_16x16x32_f16 v[112:115], v[172:175], v[204:207], v[112:115]
	v_mfma_f32_16x16x32_f16 v[100:103], v[160:163], v[212:215], v[100:103]
	v_mfma_f32_16x16x32_f16 v[96:99], v[172:175], v[212:215], v[96:99]
	v_mfma_f32_16x16x32_f16 v[84:87], v[160:163], v[220:223], v[84:87]
	v_mfma_f32_16x16x32_f16 v[80:83], v[172:175], v[220:223], v[80:83]
	v_mfma_f32_16x16x32_f16 v[108:111], v[176:179], v[192:195], v[108:111]
	v_mfma_f32_16x16x32_f16 v[104:107], v[184:187], v[192:195], v[104:107]
	v_mfma_f32_16x16x32_f16 v[92:95], v[176:179], v[200:203], v[92:95]
	v_mfma_f32_16x16x32_f16 v[88:91], v[184:187], v[200:203], v[88:91]
	v_mfma_f32_16x16x32_f16 v[76:79], v[176:179], v[208:211], v[76:79]
	v_mfma_f32_16x16x32_f16 v[72:75], v[184:187], v[208:211], v[72:75]
	v_mfma_f32_16x16x32_f16 v[68:71], v[176:179], v[216:219], v[68:71]
	v_mfma_f32_16x16x32_f16 v[64:67], v[184:187], v[216:219], v[64:67]
	v_mfma_f32_16x16x32_f16 v[108:111], v[180:183], v[196:199], v[108:111]
	v_mfma_f32_16x16x32_f16 v[104:107], v[188:191], v[196:199], v[104:107]
	v_mfma_f32_16x16x32_f16 v[92:95], v[180:183], v[204:207], v[92:95]
	v_mfma_f32_16x16x32_f16 v[88:91], v[188:191], v[204:207], v[88:91]
	v_mfma_f32_16x16x32_f16 v[76:79], v[180:183], v[212:215], v[76:79]
	v_mfma_f32_16x16x32_f16 v[72:75], v[188:191], v[212:215], v[72:75]
	v_mfma_f32_16x16x32_f16 v[68:71], v[180:183], v[220:223], v[68:71]
	v_mfma_f32_16x16x32_f16 v[64:67], v[188:191], v[220:223], v[64:67]
	s_barrier
	s_add_i32 s2, s2, s14
	v_lshl_add_u64 v[168:169], v[168:169], 0, s[8:9]
	s_mov_b32 m0, s2
	ds_read_b128 v[192:195], v154 offset:49152
	ds_read_b128 v[196:199], v154 offset:50176
	ds_read_b128 v[200:203], v154 offset:51200
	ds_read_b128 v[204:207], v154 offset:52224
	ds_read_b128 v[208:211], v154 offset:53248
	ds_read_b128 v[212:215], v154 offset:54272
	ds_read_b128 v[216:219], v154 offset:55296
	ds_read_b128 v[220:223], v154 offset:56320
	global_load_lds_dwordx4 v[168:169], off
	v_lshl_add_u64 v[168:169], v[224:225], 0, s[8:9]
	s_add_i32 m0, s2, 0x2000
	s_add_i32 s2, s3, s14
	global_load_lds_dwordx4 v[168:169], off
	v_lshl_add_u64 v[168:169], v[226:227], 0, s[8:9]
	s_mov_b32 m0, s2
	s_nop 0
	global_load_lds_dwordx4 v[168:169], off
	v_lshl_add_u64 v[168:169], v[228:229], 0, s[8:9]
	s_add_i32 m0, s2, 0x2000
	s_nop 0
	global_load_lds_dwordx4 v[168:169], off
	v_lshl_add_u64 v[168:169], v[230:231], 0, s[8:9]
	s_mov_b32 m0, s19
	s_nop 0
	global_load_lds_dwordx4 v[168:169], off
	v_lshl_add_u64 v[168:169], v[232:233], 0, s[8:9]
	s_mov_b32 m0, s20
	s_nop 0
	global_load_lds_dwordx4 v[168:169], off
	s_waitcnt vmcnt(8)
	s_waitcnt lgkmcnt(0)
	v_mfma_f32_16x16x32_f16 v[60:63], v[156:159], v[192:195], v[60:63]
	v_mfma_f32_16x16x32_f16 v[56:59], v[164:167], v[192:195], v[56:59]
	v_mfma_f32_16x16x32_f16 v[52:55], v[156:159], v[200:203], v[52:55]
	v_mfma_f32_16x16x32_f16 v[48:51], v[164:167], v[200:203], v[48:51]
	s_barrier
	s_waitcnt lgkmcnt(0)
	v_mfma_f32_16x16x32_f16 v[36:39], v[156:159], v[208:211], v[36:39]
	v_mfma_f32_16x16x32_f16 v[32:35], v[164:167], v[208:211], v[32:35]
	v_mfma_f32_16x16x32_f16 v[20:23], v[156:159], v[216:219], v[20:23]
	v_mfma_f32_16x16x32_f16 v[16:19], v[164:167], v[216:219], v[16:19]
	v_mfma_f32_16x16x32_f16 v[60:63], v[160:163], v[196:199], v[60:63]
	v_mfma_f32_16x16x32_f16 v[56:59], v[172:175], v[196:199], v[56:59]
	v_mfma_f32_16x16x32_f16 v[52:55], v[160:163], v[204:207], v[52:55]
	v_mfma_f32_16x16x32_f16 v[48:51], v[172:175], v[204:207], v[48:51]
	v_mfma_f32_16x16x32_f16 v[36:39], v[160:163], v[212:215], v[36:39]
	v_mfma_f32_16x16x32_f16 v[32:35], v[172:175], v[212:215], v[32:35]
	v_mfma_f32_16x16x32_f16 v[20:23], v[160:163], v[220:223], v[20:23]
	v_mfma_f32_16x16x32_f16 v[16:19], v[172:175], v[220:223], v[16:19]
	v_mfma_f32_16x16x32_f16 v[44:47], v[176:179], v[192:195], v[44:47]
	v_mfma_f32_16x16x32_f16 v[40:43], v[184:187], v[192:195], v[40:43]
	v_mfma_f32_16x16x32_f16 v[28:31], v[176:179], v[200:203], v[28:31]
	v_mfma_f32_16x16x32_f16 v[24:27], v[184:187], v[200:203], v[24:27]
	v_mfma_f32_16x16x32_f16 v[12:15], v[176:179], v[208:211], v[12:15]
	v_mfma_f32_16x16x32_f16 v[8:11], v[184:187], v[208:211], v[8:11]
	v_mfma_f32_16x16x32_f16 v[4:7], v[176:179], v[216:219], v[4:7]
	v_mfma_f32_16x16x32_f16 v[0:3], v[184:187], v[216:219], v[0:3]
	v_mfma_f32_16x16x32_f16 v[44:47], v[180:183], v[196:199], v[44:47]
	v_mfma_f32_16x16x32_f16 v[40:43], v[188:191], v[196:199], v[40:43]
	v_mfma_f32_16x16x32_f16 v[28:31], v[180:183], v[204:207], v[28:31]
	v_mfma_f32_16x16x32_f16 v[24:27], v[188:191], v[204:207], v[24:27]
	v_mfma_f32_16x16x32_f16 v[12:15], v[180:183], v[212:215], v[12:15]
	v_mfma_f32_16x16x32_f16 v[8:11], v[188:191], v[212:215], v[8:11]
	v_mfma_f32_16x16x32_f16 v[4:7], v[180:183], v[220:223], v[4:7]
	v_mfma_f32_16x16x32_f16 v[0:3], v[188:191], v[220:223], v[0:3]
	s_barrier
	s_add_i32 s53, s53, 2
	s_add_u32 s44, s44, 0x100
	s_addc_u32 s45, s45, 0
	s_add_u32 s51, s51, 0x100
	s_addc_u32 s52, s52, 0
	s_cmp_gt_u32 s53, 13
	s_cbranch_scc0 .LBB0_609
	s_and_b64 vcc, exec, s[22:23]
	s_cbranch_vccz .LBB0_612
	s_barrier

.LBB0_629:
	ds_read_b128 v[156:159], v152
	ds_read_b128 v[160:163], v152 offset:1024
	ds_read_b128 v[164:167], v152 offset:2048
	ds_read_b128 v[172:175], v152 offset:3072
	ds_read_b128 v[176:179], v153
	ds_read_b128 v[180:183], v153 offset:1024
	ds_read_b128 v[184:187], v153 offset:2048
	ds_read_b128 v[188:191], v153 offset:3072
	s_add_u32 s2, s48, 0xfffc0080
	s_addc_u32 s3, s49, -1
	s_cmp_eq_u32 s55, 12
	s_cselect_b32 s51, s27, s3
	s_cselect_b32 s50, s35, s2
	s_cselect_b32 s57, s31, s54
	s_cselect_b32 s56, s52, s53
	v_lshl_add_u64 v[168:169], s[48:49], 0, v[142:143]
	s_add_i32 m0, s15, 0xc000
	ds_read_b128 v[192:195], v154
	ds_read_b128 v[196:199], v154 offset:1024
	ds_read_b128 v[200:203], v154 offset:2048
	ds_read_b128 v[204:207], v154 offset:3072
	ds_read_b128 v[208:211], v154 offset:4096
	ds_read_b128 v[212:215], v154 offset:5120
	ds_read_b128 v[216:219], v154 offset:6144
	ds_read_b128 v[220:223], v154 offset:7168
	global_load_lds_dwordx4 v[168:169], off
	v_lshl_add_u64 v[168:169], s[48:49], 0, v[144:145]
	s_add_i32 m0, s15, 0xe000
	s_nop 0
	global_load_lds_dwordx4 v[168:169], off
	s_waitcnt vmcnt(8)
	s_waitcnt lgkmcnt(0)
	v_mfma_f32_16x16x32_f16 v[124:127], v[156:159], v[192:195], v[124:127]
	v_mfma_f32_16x16x32_f16 v[120:123], v[164:167], v[192:195], v[120:123]
	v_mfma_f32_16x16x32_f16 v[116:119], v[156:159], v[200:203], v[116:119]
	v_mfma_f32_16x16x32_f16 v[108:111], v[164:167], v[200:203], v[108:111]
	s_barrier
	s_waitcnt lgkmcnt(0)
	v_mfma_f32_16x16x32_f16 v[100:103], v[156:159], v[208:211], v[100:103]
	v_mfma_f32_16x16x32_f16 v[92:95], v[164:167], v[208:211], v[92:95]
	v_mfma_f32_16x16x32_f16 v[84:87], v[156:159], v[216:219], v[84:87]
	v_mfma_f32_16x16x32_f16 v[76:79], v[164:167], v[216:219], v[76:79]
	v_mfma_f32_16x16x32_f16 v[124:127], v[160:163], v[196:199], v[124:127]
	v_mfma_f32_16x16x32_f16 v[120:123], v[172:175], v[196:199], v[120:123]
	v_mfma_f32_16x16x32_f16 v[116:119], v[160:163], v[204:207], v[116:119]
	v_mfma_f32_16x16x32_f16 v[108:111], v[172:175], v[204:207], v[108:111]
	v_mfma_f32_16x16x32_f16 v[100:103], v[160:163], v[212:215], v[100:103]
	v_mfma_f32_16x16x32_f16 v[92:95], v[172:175], v[212:215], v[92:95]
	v_mfma_f32_16x16x32_f16 v[84:87], v[160:163], v[220:223], v[84:87]
	v_mfma_f32_16x16x32_f16 v[76:79], v[172:175], v[220:223], v[76:79]
	v_mfma_f32_16x16x32_f16 v[112:115], v[176:179], v[192:195], v[112:115]
	v_mfma_f32_16x16x32_f16 v[104:107], v[184:187], v[192:195], v[104:107]
	v_mfma_f32_16x16x32_f16 v[96:99], v[176:179], v[200:203], v[96:99]
	v_mfma_f32_16x16x32_f16 v[88:91], v[184:187], v[200:203], v[88:91]
	v_mfma_f32_16x16x32_f16 v[80:83], v[176:179], v[208:211], v[80:83]
	v_mfma_f32_16x16x32_f16 v[72:75], v[184:187], v[208:211], v[72:75]
	v_mfma_f32_16x16x32_f16 v[68:71], v[176:179], v[216:219], v[68:71]
	v_mfma_f32_16x16x32_f16 v[64:67], v[184:187], v[216:219], v[64:67]
	v_mfma_f32_16x16x32_f16 v[112:115], v[180:183], v[196:199], v[112:115]
	v_mfma_f32_16x16x32_f16 v[104:107], v[188:191], v[196:199], v[104:107]
	v_mfma_f32_16x16x32_f16 v[96:99], v[180:183], v[204:207], v[96:99]
	v_mfma_f32_16x16x32_f16 v[88:91], v[188:191], v[204:207], v[88:91]
	v_mfma_f32_16x16x32_f16 v[80:83], v[180:183], v[212:215], v[80:83]
	v_mfma_f32_16x16x32_f16 v[72:75], v[188:191], v[212:215], v[72:75]
	v_mfma_f32_16x16x32_f16 v[68:71], v[180:183], v[220:223], v[68:71]
	v_mfma_f32_16x16x32_f16 v[64:67], v[188:191], v[220:223], v[64:67]
	s_barrier
	s_add_i32 s2, s21, s14
	v_lshl_add_u64 v[168:169], s[56:57], 0, v[136:137]
	s_mov_b32 m0, s2
	ds_read_b128 v[192:195], v154 offset:16384
	ds_read_b128 v[196:199], v154 offset:17408
	ds_read_b128 v[200:203], v154 offset:18432
	ds_read_b128 v[204:207], v154 offset:19456
	ds_read_b128 v[208:211], v154 offset:20480
	ds_read_b128 v[212:215], v154 offset:21504
	ds_read_b128 v[216:219], v154 offset:22528
	ds_read_b128 v[220:223], v154 offset:23552
	global_load_lds_dwordx4 v[168:169], off
	v_lshl_add_u64 v[224:225], s[56:57], 0, v[130:131]
	s_add_i32 m0, s2, 0x2000
	s_add_i32 s2, s28, s14
	global_load_lds_dwordx4 v[224:225], off
	v_lshl_add_u64 v[226:227], s[56:57], 0, v[134:135]
	s_mov_b32 m0, s2
	v_lshl_add_u64 v[228:229], s[56:57], 0, v[128:129]
	global_load_lds_dwordx4 v[226:227], off
	s_add_i32 m0, s2, 0x2000
	v_lshl_add_u64 v[230:231], s[50:51], 0, v[138:139]
	global_load_lds_dwordx4 v[228:229], off
	s_mov_b32 m0, s15
	v_lshl_add_u64 v[232:233], s[50:51], 0, v[132:133]
	global_load_lds_dwordx4 v[230:231], off
	s_mov_b32 m0, s16
	s_nop 0
	global_load_lds_dwordx4 v[232:233], off
	s_waitcnt vmcnt(8)
	s_waitcnt lgkmcnt(0)
	v_mfma_f32_16x16x32_f16 v[60:63], v[156:159], v[192:195], v[60:63]
	v_mfma_f32_16x16x32_f16 v[56:59], v[164:167], v[192:195], v[56:59]
	v_mfma_f32_16x16x32_f16 v[52:55], v[156:159], v[200:203], v[52:55]
	v_mfma_f32_16x16x32_f16 v[48:51], v[164:167], v[200:203], v[48:51]
	s_barrier
	s_waitcnt lgkmcnt(0)
	v_mfma_f32_16x16x32_f16 v[36:39], v[156:159], v[208:211], v[36:39]
	v_mfma_f32_16x16x32_f16 v[32:35], v[164:167], v[208:211], v[32:35]
	v_mfma_f32_16x16x32_f16 v[20:23], v[156:159], v[216:219], v[20:23]
	v_mfma_f32_16x16x32_f16 v[16:19], v[164:167], v[216:219], v[16:19]
	v_mfma_f32_16x16x32_f16 v[60:63], v[160:163], v[196:199], v[60:63]
	v_mfma_f32_16x16x32_f16 v[56:59], v[172:175], v[196:199], v[56:59]
	v_mfma_f32_16x16x32_f16 v[52:55], v[160:163], v[204:207], v[52:55]
	v_mfma_f32_16x16x32_f16 v[48:51], v[172:175], v[204:207], v[48:51]
	v_mfma_f32_16x16x32_f16 v[36:39], v[160:163], v[212:215], v[36:39]
	v_mfma_f32_16x16x32_f16 v[32:35], v[172:175], v[212:215], v[32:35]
	v_mfma_f32_16x16x32_f16 v[20:23], v[160:163], v[220:223], v[20:23]
	v_mfma_f32_16x16x32_f16 v[16:19], v[172:175], v[220:223], v[16:19]
	v_mfma_f32_16x16x32_f16 v[44:47], v[176:179], v[192:195], v[44:47]
	v_mfma_f32_16x16x32_f16 v[40:43], v[184:187], v[192:195], v[40:43]
	v_mfma_f32_16x16x32_f16 v[28:31], v[176:179], v[200:203], v[28:31]
	v_mfma_f32_16x16x32_f16 v[24:27], v[184:187], v[200:203], v[24:27]
	v_mfma_f32_16x16x32_f16 v[12:15], v[176:179], v[208:211], v[12:15]
	v_mfma_f32_16x16x32_f16 v[8:11], v[184:187], v[208:211], v[8:11]
	v_mfma_f32_16x16x32_f16 v[4:7], v[176:179], v[216:219], v[4:7]
	v_mfma_f32_16x16x32_f16 v[0:3], v[184:187], v[216:219], v[0:3]
	v_mfma_f32_16x16x32_f16 v[44:47], v[180:183], v[196:199], v[44:47]
	v_mfma_f32_16x16x32_f16 v[40:43], v[188:191], v[196:199], v[40:43]
	v_mfma_f32_16x16x32_f16 v[28:31], v[180:183], v[204:207], v[28:31]
	v_mfma_f32_16x16x32_f16 v[24:27], v[188:191], v[204:207], v[24:27]
	v_mfma_f32_16x16x32_f16 v[12:15], v[180:183], v[212:215], v[12:15]
	v_mfma_f32_16x16x32_f16 v[8:11], v[188:191], v[212:215], v[8:11]
	v_mfma_f32_16x16x32_f16 v[4:7], v[180:183], v[220:223], v[4:7]
	v_mfma_f32_16x16x32_f16 v[0:3], v[188:191], v[220:223], v[0:3]
	s_barrier
	s_add_i32 s2, 0, 0x18000
	v_add_u32_e32 v155, s2, v151
	s_add_i32 s3, 0, 0x1c000
	ds_read_b128 v[156:159], v155
	ds_read_b128 v[160:163], v155 offset:1024
	ds_read_b128 v[164:167], v155 offset:2048
	ds_read_b128 v[172:175], v155 offset:3072
	v_add_u32_e32 v155, s3, v151
	ds_read_b128 v[176:179], v155
	ds_read_b128 v[180:183], v155 offset:1024
	ds_read_b128 v[184:187], v155 offset:2048
	ds_read_b128 v[188:191], v155 offset:3072
	s_add_u32 s50, s50, 0x40000
	s_addc_u32 s51, s51, 0
	s_mov_b32 m0, s17
	v_lshl_add_u64 v[234:235], s[50:51], 0, v[138:139]
	ds_read_b128 v[192:195], v154 offset:32768
	ds_read_b128 v[196:199], v154 offset:33792
	ds_read_b128 v[200:203], v154 offset:34816
	ds_read_b128 v[204:207], v154 offset:35840
	ds_read_b128 v[208:211], v154 offset:36864
	ds_read_b128 v[212:215], v154 offset:37888
	ds_read_b128 v[216:219], v154 offset:38912
	ds_read_b128 v[220:223], v154 offset:39936
	global_load_lds_dwordx4 v[234:235], off
	v_lshl_add_u64 v[234:235], s[50:51], 0, v[132:133]
	s_mov_b32 m0, s18
	s_nop 0
	global_load_lds_dwordx4 v[234:235], off
	s_waitcnt vmcnt(8)
	s_waitcnt lgkmcnt(0)
	v_mfma_f32_16x16x32_f16 v[124:127], v[156:159], v[192:195], v[124:127]
	v_mfma_f32_16x16x32_f16 v[120:123], v[164:167], v[192:195], v[120:123]
	v_mfma_f32_16x16x32_f16 v[116:119], v[156:159], v[200:203], v[116:119]
	v_mfma_f32_16x16x32_f16 v[108:111], v[164:167], v[200:203], v[108:111]
	s_barrier
	s_waitcnt lgkmcnt(0)
	v_mfma_f32_16x16x32_f16 v[100:103], v[156:159], v[208:211], v[100:103]
	v_mfma_f32_16x16x32_f16 v[92:95], v[164:167], v[208:211], v[92:95]
	v_mfma_f32_16x16x32_f16 v[84:87], v[156:159], v[216:219], v[84:87]
	v_mfma_f32_16x16x32_f16 v[76:79], v[164:167], v[216:219], v[76:79]
	v_mfma_f32_16x16x32_f16 v[124:127], v[160:163], v[196:199], v[124:127]
	v_mfma_f32_16x16x32_f16 v[120:123], v[172:175], v[196:199], v[120:123]
	v_mfma_f32_16x16x32_f16 v[116:119], v[160:163], v[204:207], v[116:119]
	v_mfma_f32_16x16x32_f16 v[108:111], v[172:175], v[204:207], v[108:111]
	v_mfma_f32_16x16x32_f16 v[100:103], v[160:163], v[212:215], v[100:103]
	v_mfma_f32_16x16x32_f16 v[92:95], v[172:175], v[212:215], v[92:95]
	v_mfma_f32_16x16x32_f16 v[84:87], v[160:163], v[220:223], v[84:87]
	v_mfma_f32_16x16x32_f16 v[76:79], v[172:175], v[220:223], v[76:79]
	v_mfma_f32_16x16x32_f16 v[112:115], v[176:179], v[192:195], v[112:115]
	v_mfma_f32_16x16x32_f16 v[104:107], v[184:187], v[192:195], v[104:107]
	v_mfma_f32_16x16x32_f16 v[96:99], v[176:179], v[200:203], v[96:99]
	v_mfma_f32_16x16x32_f16 v[88:91], v[184:187], v[200:203], v[88:91]
	v_mfma_f32_16x16x32_f16 v[80:83], v[176:179], v[208:211], v[80:83]
	v_mfma_f32_16x16x32_f16 v[72:75], v[184:187], v[208:211], v[72:75]
	v_mfma_f32_16x16x32_f16 v[68:71], v[176:179], v[216:219], v[68:71]
	v_mfma_f32_16x16x32_f16 v[64:67], v[184:187], v[216:219], v[64:67]
	v_mfma_f32_16x16x32_f16 v[112:115], v[180:183], v[196:199], v[112:115]
	v_mfma_f32_16x16x32_f16 v[104:107], v[188:191], v[196:199], v[104:107]
	v_mfma_f32_16x16x32_f16 v[96:99], v[180:183], v[204:207], v[96:99]
	v_mfma_f32_16x16x32_f16 v[88:91], v[188:191], v[204:207], v[88:91]
	v_mfma_f32_16x16x32_f16 v[80:83], v[180:183], v[212:215], v[80:83]
	v_mfma_f32_16x16x32_f16 v[72:75], v[188:191], v[212:215], v[72:75]
	v_mfma_f32_16x16x32_f16 v[68:71], v[180:183], v[220:223], v[68:71]
	v_mfma_f32_16x16x32_f16 v[64:67], v[188:191], v[220:223], v[64:67]
	s_barrier
	s_add_i32 s2, s2, s14
	v_lshl_add_u64 v[168:169], v[168:169], 0, s[8:9]
	s_mov_b32 m0, s2
	ds_read_b128 v[192:195], v154 offset:49152
	ds_read_b128 v[196:199], v154 offset:50176
	ds_read_b128 v[200:203], v154 offset:51200
	ds_read_b128 v[204:207], v154 offset:52224
	ds_read_b128 v[208:211], v154 offset:53248
	ds_read_b128 v[212:215], v154 offset:54272
	ds_read_b128 v[216:219], v154 offset:55296
	ds_read_b128 v[220:223], v154 offset:56320
	global_load_lds_dwordx4 v[168:169], off
	v_lshl_add_u64 v[168:169], v[224:225], 0, s[8:9]
	s_add_i32 m0, s2, 0x2000
	s_add_i32 s2, s3, s14
	global_load_lds_dwordx4 v[168:169], off
	v_lshl_add_u64 v[168:169], v[226:227], 0, s[8:9]
	s_mov_b32 m0, s2
	s_nop 0
	global_load_lds_dwordx4 v[168:169], off
	v_lshl_add_u64 v[168:169], v[228:229], 0, s[8:9]
	s_add_i32 m0, s2, 0x2000
	s_nop 0
	global_load_lds_dwordx4 v[168:169], off
	v_lshl_add_u64 v[168:169], v[230:231], 0, s[8:9]
	s_mov_b32 m0, s19
	s_nop 0
	global_load_lds_dwordx4 v[168:169], off
	v_lshl_add_u64 v[168:169], v[232:233], 0, s[8:9]
	s_mov_b32 m0, s20
	s_nop 0
	global_load_lds_dwordx4 v[168:169], off
	s_waitcnt vmcnt(8)
	s_waitcnt lgkmcnt(0)
	v_mfma_f32_16x16x32_f16 v[60:63], v[156:159], v[192:195], v[60:63]
	v_mfma_f32_16x16x32_f16 v[56:59], v[164:167], v[192:195], v[56:59]
	v_mfma_f32_16x16x32_f16 v[52:55], v[156:159], v[200:203], v[52:55]
	v_mfma_f32_16x16x32_f16 v[48:51], v[164:167], v[200:203], v[48:51]
	s_barrier
	s_waitcnt lgkmcnt(0)
	v_mfma_f32_16x16x32_f16 v[36:39], v[156:159], v[208:211], v[36:39]
	v_mfma_f32_16x16x32_f16 v[32:35], v[164:167], v[208:211], v[32:35]
	v_mfma_f32_16x16x32_f16 v[20:23], v[156:159], v[216:219], v[20:23]
	v_mfma_f32_16x16x32_f16 v[16:19], v[164:167], v[216:219], v[16:19]
	v_mfma_f32_16x16x32_f16 v[60:63], v[160:163], v[196:199], v[60:63]
	v_mfma_f32_16x16x32_f16 v[56:59], v[172:175], v[196:199], v[56:59]
	v_mfma_f32_16x16x32_f16 v[52:55], v[160:163], v[204:207], v[52:55]
	v_mfma_f32_16x16x32_f16 v[48:51], v[172:175], v[204:207], v[48:51]
	v_mfma_f32_16x16x32_f16 v[36:39], v[160:163], v[212:215], v[36:39]
	v_mfma_f32_16x16x32_f16 v[32:35], v[172:175], v[212:215], v[32:35]
	v_mfma_f32_16x16x32_f16 v[20:23], v[160:163], v[220:223], v[20:23]
	v_mfma_f32_16x16x32_f16 v[16:19], v[172:175], v[220:223], v[16:19]
	v_mfma_f32_16x16x32_f16 v[44:47], v[176:179], v[192:195], v[44:47]
	v_mfma_f32_16x16x32_f16 v[40:43], v[184:187], v[192:195], v[40:43]
	v_mfma_f32_16x16x32_f16 v[28:31], v[176:179], v[200:203], v[28:31]
	v_mfma_f32_16x16x32_f16 v[24:27], v[184:187], v[200:203], v[24:27]
	v_mfma_f32_16x16x32_f16 v[12:15], v[176:179], v[208:211], v[12:15]
	v_mfma_f32_16x16x32_f16 v[8:11], v[184:187], v[208:211], v[8:11]
	v_mfma_f32_16x16x32_f16 v[4:7], v[176:179], v[216:219], v[4:7]
	v_mfma_f32_16x16x32_f16 v[0:3], v[184:187], v[216:219], v[0:3]
	v_mfma_f32_16x16x32_f16 v[44:47], v[180:183], v[196:199], v[44:47]
	v_mfma_f32_16x16x32_f16 v[40:43], v[188:191], v[196:199], v[40:43]
	v_mfma_f32_16x16x32_f16 v[28:31], v[180:183], v[204:207], v[28:31]
	v_mfma_f32_16x16x32_f16 v[24:27], v[188:191], v[204:207], v[24:27]
	v_mfma_f32_16x16x32_f16 v[12:15], v[180:183], v[212:215], v[12:15]
	v_mfma_f32_16x16x32_f16 v[8:11], v[188:191], v[212:215], v[8:11]
	v_mfma_f32_16x16x32_f16 v[4:7], v[180:183], v[220:223], v[4:7]
	v_mfma_f32_16x16x32_f16 v[0:3], v[188:191], v[220:223], v[0:3]
	s_barrier
	s_add_i32 s55, s55, 2
	s_add_u32 s48, s48, 0x100
	s_addc_u32 s49, s49, 0
	s_add_u32 s53, s53, 0x100
	s_addc_u32 s54, s54, 0
	s_cmp_gt_u32 s55, 13
	s_cbranch_scc0 .LBB0_629
	s_and_b64 vcc, exec, s[22:23]
	s_cbranch_vccz .LBB0_632
	s_barrier

.LBB0_649:
	ds_read_b128 v[160:163], v156
	ds_read_b128 v[164:167], v156 offset:1024
	ds_read_b128 v[172:175], v156 offset:2048
	ds_read_b128 v[176:179], v156 offset:3072
	ds_read_b128 v[180:183], v157
	ds_read_b128 v[184:187], v157 offset:1024
	ds_read_b128 v[188:191], v157 offset:2048
	ds_read_b128 v[192:195], v157 offset:3072
	s_add_u32 s2, s44, 0xfffc0080
	s_addc_u32 s3, s45, -1
	s_cmp_eq_u32 s52, 12
	s_cselect_b32 s47, s27, s3
	s_cselect_b32 s46, s48, s2
	s_cselect_b32 s55, s25, s51
	s_cselect_b32 s54, s49, s50
	v_lshl_add_u64 v[168:169], s[44:45], 0, v[142:143]
	s_add_i32 m0, s15, 0xc000
	ds_read_b128 v[196:199], v158
	ds_read_b128 v[200:203], v158 offset:1024
	ds_read_b128 v[204:207], v158 offset:2048
	ds_read_b128 v[208:211], v158 offset:3072
	ds_read_b128 v[212:215], v158 offset:4096
	ds_read_b128 v[216:219], v158 offset:5120
	ds_read_b128 v[220:223], v158 offset:6144
	ds_read_b128 v[224:227], v158 offset:7168
	global_load_lds_dwordx4 v[168:169], off
	v_lshl_add_u64 v[168:169], s[44:45], 0, v[144:145]
	s_add_i32 m0, s15, 0xe000
	s_nop 0
	global_load_lds_dwordx4 v[168:169], off
	s_waitcnt vmcnt(8)
	s_waitcnt lgkmcnt(0)
	v_mfma_f32_16x16x32_f16 v[124:127], v[160:163], v[196:199], v[124:127]
	v_mfma_f32_16x16x32_f16 v[120:123], v[172:175], v[196:199], v[120:123]
	v_mfma_f32_16x16x32_f16 v[116:119], v[160:163], v[204:207], v[116:119]
	v_mfma_f32_16x16x32_f16 v[108:111], v[172:175], v[204:207], v[108:111]
	s_barrier
	s_waitcnt lgkmcnt(0)
	v_mfma_f32_16x16x32_f16 v[100:103], v[160:163], v[212:215], v[100:103]
	v_mfma_f32_16x16x32_f16 v[92:95], v[172:175], v[212:215], v[92:95]
	v_mfma_f32_16x16x32_f16 v[84:87], v[160:163], v[220:223], v[84:87]
	v_mfma_f32_16x16x32_f16 v[76:79], v[172:175], v[220:223], v[76:79]
	v_mfma_f32_16x16x32_f16 v[124:127], v[164:167], v[200:203], v[124:127]
	v_mfma_f32_16x16x32_f16 v[120:123], v[176:179], v[200:203], v[120:123]
	v_mfma_f32_16x16x32_f16 v[116:119], v[164:167], v[208:211], v[116:119]
	v_mfma_f32_16x16x32_f16 v[108:111], v[176:179], v[208:211], v[108:111]
	v_mfma_f32_16x16x32_f16 v[100:103], v[164:167], v[216:219], v[100:103]
	v_mfma_f32_16x16x32_f16 v[92:95], v[176:179], v[216:219], v[92:95]
	v_mfma_f32_16x16x32_f16 v[84:87], v[164:167], v[224:227], v[84:87]
	v_mfma_f32_16x16x32_f16 v[76:79], v[176:179], v[224:227], v[76:79]
	v_mfma_f32_16x16x32_f16 v[112:115], v[180:183], v[196:199], v[112:115]
	v_mfma_f32_16x16x32_f16 v[104:107], v[188:191], v[196:199], v[104:107]
	v_mfma_f32_16x16x32_f16 v[96:99], v[180:183], v[204:207], v[96:99]
	v_mfma_f32_16x16x32_f16 v[88:91], v[188:191], v[204:207], v[88:91]
	v_mfma_f32_16x16x32_f16 v[80:83], v[180:183], v[212:215], v[80:83]
	v_mfma_f32_16x16x32_f16 v[72:75], v[188:191], v[212:215], v[72:75]
	v_mfma_f32_16x16x32_f16 v[68:71], v[180:183], v[220:223], v[68:71]
	v_mfma_f32_16x16x32_f16 v[64:67], v[188:191], v[220:223], v[64:67]
	v_mfma_f32_16x16x32_f16 v[112:115], v[184:187], v[200:203], v[112:115]
	v_mfma_f32_16x16x32_f16 v[104:107], v[192:195], v[200:203], v[104:107]
	v_mfma_f32_16x16x32_f16 v[96:99], v[184:187], v[208:211], v[96:99]
	v_mfma_f32_16x16x32_f16 v[88:91], v[192:195], v[208:211], v[88:91]
	v_mfma_f32_16x16x32_f16 v[80:83], v[184:187], v[216:219], v[80:83]
	v_mfma_f32_16x16x32_f16 v[72:75], v[192:195], v[216:219], v[72:75]
	v_mfma_f32_16x16x32_f16 v[68:71], v[184:187], v[224:227], v[68:71]
	v_mfma_f32_16x16x32_f16 v[64:67], v[192:195], v[224:227], v[64:67]
	s_barrier
	s_add_i32 s2, s21, s14
	v_lshl_add_u64 v[168:169], s[54:55], 0, v[136:137]
	s_mov_b32 m0, s2
	ds_read_b128 v[196:199], v158 offset:16384
	ds_read_b128 v[200:203], v158 offset:17408
	ds_read_b128 v[204:207], v158 offset:18432
	ds_read_b128 v[208:211], v158 offset:19456
	ds_read_b128 v[212:215], v158 offset:20480
	ds_read_b128 v[216:219], v158 offset:21504
	ds_read_b128 v[220:223], v158 offset:22528
	ds_read_b128 v[224:227], v158 offset:23552
	global_load_lds_dwordx4 v[168:169], off
	v_lshl_add_u64 v[228:229], s[54:55], 0, v[130:131]
	s_add_i32 m0, s2, 0x2000
	s_add_i32 s2, s28, s14
	global_load_lds_dwordx4 v[228:229], off
	v_lshl_add_u64 v[230:231], s[54:55], 0, v[134:135]
	s_mov_b32 m0, s2
	v_lshl_add_u64 v[232:233], s[54:55], 0, v[128:129]
	global_load_lds_dwordx4 v[230:231], off
	s_add_i32 m0, s2, 0x2000
	v_lshl_add_u64 v[234:235], s[46:47], 0, v[138:139]
	global_load_lds_dwordx4 v[232:233], off
	s_mov_b32 m0, s15
	v_lshl_add_u64 v[236:237], s[46:47], 0, v[132:133]
	global_load_lds_dwordx4 v[234:235], off
	s_mov_b32 m0, s16
	s_nop 0
	global_load_lds_dwordx4 v[236:237], off
	s_waitcnt vmcnt(8)
	s_waitcnt lgkmcnt(0)
	v_mfma_f32_16x16x32_f16 v[60:63], v[160:163], v[196:199], v[60:63]
	v_mfma_f32_16x16x32_f16 v[56:59], v[172:175], v[196:199], v[56:59]
	v_mfma_f32_16x16x32_f16 v[52:55], v[160:163], v[204:207], v[52:55]
	v_mfma_f32_16x16x32_f16 v[48:51], v[172:175], v[204:207], v[48:51]
	s_barrier
	s_waitcnt lgkmcnt(0)
	v_mfma_f32_16x16x32_f16 v[36:39], v[160:163], v[212:215], v[36:39]
	v_mfma_f32_16x16x32_f16 v[32:35], v[172:175], v[212:215], v[32:35]
	v_mfma_f32_16x16x32_f16 v[20:23], v[160:163], v[220:223], v[20:23]
	v_mfma_f32_16x16x32_f16 v[16:19], v[172:175], v[220:223], v[16:19]
	v_mfma_f32_16x16x32_f16 v[60:63], v[164:167], v[200:203], v[60:63]
	v_mfma_f32_16x16x32_f16 v[56:59], v[176:179], v[200:203], v[56:59]
	v_mfma_f32_16x16x32_f16 v[52:55], v[164:167], v[208:211], v[52:55]
	v_mfma_f32_16x16x32_f16 v[48:51], v[176:179], v[208:211], v[48:51]
	v_mfma_f32_16x16x32_f16 v[36:39], v[164:167], v[216:219], v[36:39]
	v_mfma_f32_16x16x32_f16 v[32:35], v[176:179], v[216:219], v[32:35]
	v_mfma_f32_16x16x32_f16 v[20:23], v[164:167], v[224:227], v[20:23]
	v_mfma_f32_16x16x32_f16 v[16:19], v[176:179], v[224:227], v[16:19]
	v_mfma_f32_16x16x32_f16 v[44:47], v[180:183], v[196:199], v[44:47]
	v_mfma_f32_16x16x32_f16 v[40:43], v[188:191], v[196:199], v[40:43]
	v_mfma_f32_16x16x32_f16 v[28:31], v[180:183], v[204:207], v[28:31]
	v_mfma_f32_16x16x32_f16 v[24:27], v[188:191], v[204:207], v[24:27]
	v_mfma_f32_16x16x32_f16 v[12:15], v[180:183], v[212:215], v[12:15]
	v_mfma_f32_16x16x32_f16 v[8:11], v[188:191], v[212:215], v[8:11]
	v_mfma_f32_16x16x32_f16 v[4:7], v[180:183], v[220:223], v[4:7]
	v_mfma_f32_16x16x32_f16 v[0:3], v[188:191], v[220:223], v[0:3]
	v_mfma_f32_16x16x32_f16 v[44:47], v[184:187], v[200:203], v[44:47]
	v_mfma_f32_16x16x32_f16 v[40:43], v[192:195], v[200:203], v[40:43]
	v_mfma_f32_16x16x32_f16 v[28:31], v[184:187], v[208:211], v[28:31]
	v_mfma_f32_16x16x32_f16 v[24:27], v[192:195], v[208:211], v[24:27]
	v_mfma_f32_16x16x32_f16 v[12:15], v[184:187], v[216:219], v[12:15]
	v_mfma_f32_16x16x32_f16 v[8:11], v[192:195], v[216:219], v[8:11]
	v_mfma_f32_16x16x32_f16 v[4:7], v[184:187], v[224:227], v[4:7]
	v_mfma_f32_16x16x32_f16 v[0:3], v[192:195], v[224:227], v[0:3]
	s_barrier
	s_add_i32 s2, 0, 0x18000
	v_add_u32_e32 v151, s2, v155
	s_add_i32 s3, 0, 0x1c000
	ds_read_b128 v[160:163], v151
	ds_read_b128 v[164:167], v151 offset:1024
	ds_read_b128 v[172:175], v151 offset:2048
	ds_read_b128 v[176:179], v151 offset:3072
	v_add_u32_e32 v151, s3, v155
	ds_read_b128 v[180:183], v151
	ds_read_b128 v[184:187], v151 offset:1024
	ds_read_b128 v[188:191], v151 offset:2048
	ds_read_b128 v[192:195], v151 offset:3072
	s_add_u32 s46, s46, 0x40000
	s_addc_u32 s47, s47, 0
	s_mov_b32 m0, s17
	v_lshl_add_u64 v[238:239], s[46:47], 0, v[138:139]
	ds_read_b128 v[196:199], v158 offset:32768
	ds_read_b128 v[200:203], v158 offset:33792
	ds_read_b128 v[204:207], v158 offset:34816
	ds_read_b128 v[208:211], v158 offset:35840
	ds_read_b128 v[212:215], v158 offset:36864
	ds_read_b128 v[216:219], v158 offset:37888
	ds_read_b128 v[220:223], v158 offset:38912
	ds_read_b128 v[224:227], v158 offset:39936
	global_load_lds_dwordx4 v[238:239], off
	v_lshl_add_u64 v[238:239], s[46:47], 0, v[132:133]
	s_mov_b32 m0, s18
	s_nop 0
	global_load_lds_dwordx4 v[238:239], off
	s_waitcnt vmcnt(8)
	s_waitcnt lgkmcnt(0)
	v_mfma_f32_16x16x32_f16 v[124:127], v[160:163], v[196:199], v[124:127]
	v_mfma_f32_16x16x32_f16 v[120:123], v[172:175], v[196:199], v[120:123]
	v_mfma_f32_16x16x32_f16 v[116:119], v[160:163], v[204:207], v[116:119]
	v_mfma_f32_16x16x32_f16 v[108:111], v[172:175], v[204:207], v[108:111]
	s_barrier
	s_waitcnt lgkmcnt(0)
	v_mfma_f32_16x16x32_f16 v[100:103], v[160:163], v[212:215], v[100:103]
	v_mfma_f32_16x16x32_f16 v[92:95], v[172:175], v[212:215], v[92:95]
	v_mfma_f32_16x16x32_f16 v[84:87], v[160:163], v[220:223], v[84:87]
	v_mfma_f32_16x16x32_f16 v[76:79], v[172:175], v[220:223], v[76:79]
	v_mfma_f32_16x16x32_f16 v[124:127], v[164:167], v[200:203], v[124:127]
	v_mfma_f32_16x16x32_f16 v[120:123], v[176:179], v[200:203], v[120:123]
	v_mfma_f32_16x16x32_f16 v[116:119], v[164:167], v[208:211], v[116:119]
	v_mfma_f32_16x16x32_f16 v[108:111], v[176:179], v[208:211], v[108:111]
	v_mfma_f32_16x16x32_f16 v[100:103], v[164:167], v[216:219], v[100:103]
	v_mfma_f32_16x16x32_f16 v[92:95], v[176:179], v[216:219], v[92:95]
	v_mfma_f32_16x16x32_f16 v[84:87], v[164:167], v[224:227], v[84:87]
	v_mfma_f32_16x16x32_f16 v[76:79], v[176:179], v[224:227], v[76:79]
	v_mfma_f32_16x16x32_f16 v[112:115], v[180:183], v[196:199], v[112:115]
	v_mfma_f32_16x16x32_f16 v[104:107], v[188:191], v[196:199], v[104:107]
	v_mfma_f32_16x16x32_f16 v[96:99], v[180:183], v[204:207], v[96:99]
	v_mfma_f32_16x16x32_f16 v[88:91], v[188:191], v[204:207], v[88:91]
	v_mfma_f32_16x16x32_f16 v[80:83], v[180:183], v[212:215], v[80:83]
	v_mfma_f32_16x16x32_f16 v[72:75], v[188:191], v[212:215], v[72:75]
	v_mfma_f32_16x16x32_f16 v[68:71], v[180:183], v[220:223], v[68:71]
	v_mfma_f32_16x16x32_f16 v[64:67], v[188:191], v[220:223], v[64:67]
	v_mfma_f32_16x16x32_f16 v[112:115], v[184:187], v[200:203], v[112:115]
	v_mfma_f32_16x16x32_f16 v[104:107], v[192:195], v[200:203], v[104:107]
	v_mfma_f32_16x16x32_f16 v[96:99], v[184:187], v[208:211], v[96:99]
	v_mfma_f32_16x16x32_f16 v[88:91], v[192:195], v[208:211], v[88:91]
	v_mfma_f32_16x16x32_f16 v[80:83], v[184:187], v[216:219], v[80:83]
	v_mfma_f32_16x16x32_f16 v[72:75], v[192:195], v[216:219], v[72:75]
	v_mfma_f32_16x16x32_f16 v[68:71], v[184:187], v[224:227], v[68:71]
	v_mfma_f32_16x16x32_f16 v[64:67], v[192:195], v[224:227], v[64:67]
	s_barrier
	s_add_i32 s2, s2, s14
	v_lshl_add_u64 v[168:169], v[168:169], 0, s[10:11]
	s_mov_b32 m0, s2
	ds_read_b128 v[196:199], v158 offset:49152
	ds_read_b128 v[200:203], v158 offset:50176
	ds_read_b128 v[204:207], v158 offset:51200
	ds_read_b128 v[208:211], v158 offset:52224
	ds_read_b128 v[212:215], v158 offset:53248
	ds_read_b128 v[216:219], v158 offset:54272
	ds_read_b128 v[220:223], v158 offset:55296
	ds_read_b128 v[224:227], v158 offset:56320
	global_load_lds_dwordx4 v[168:169], off
	v_lshl_add_u64 v[168:169], v[228:229], 0, s[10:11]
	s_add_i32 m0, s2, 0x2000
	s_add_i32 s2, s3, s14
	global_load_lds_dwordx4 v[168:169], off
	v_lshl_add_u64 v[168:169], v[230:231], 0, s[10:11]
	s_mov_b32 m0, s2
	s_nop 0
	global_load_lds_dwordx4 v[168:169], off
	v_lshl_add_u64 v[168:169], v[232:233], 0, s[10:11]
	s_add_i32 m0, s2, 0x2000
	s_nop 0
	global_load_lds_dwordx4 v[168:169], off
	v_lshl_add_u64 v[168:169], v[234:235], 0, s[10:11]
	s_mov_b32 m0, s19
	s_nop 0
	global_load_lds_dwordx4 v[168:169], off
	v_lshl_add_u64 v[168:169], v[236:237], 0, s[10:11]
	s_mov_b32 m0, s20
	s_nop 0
	global_load_lds_dwordx4 v[168:169], off
	s_waitcnt vmcnt(8)
	s_waitcnt lgkmcnt(0)
	v_mfma_f32_16x16x32_f16 v[60:63], v[160:163], v[196:199], v[60:63]
	v_mfma_f32_16x16x32_f16 v[56:59], v[172:175], v[196:199], v[56:59]
	v_mfma_f32_16x16x32_f16 v[52:55], v[160:163], v[204:207], v[52:55]
	v_mfma_f32_16x16x32_f16 v[48:51], v[172:175], v[204:207], v[48:51]
	s_barrier
	s_waitcnt lgkmcnt(0)
	v_mfma_f32_16x16x32_f16 v[36:39], v[160:163], v[212:215], v[36:39]
	v_mfma_f32_16x16x32_f16 v[32:35], v[172:175], v[212:215], v[32:35]
	v_mfma_f32_16x16x32_f16 v[20:23], v[160:163], v[220:223], v[20:23]
	v_mfma_f32_16x16x32_f16 v[16:19], v[172:175], v[220:223], v[16:19]
	v_mfma_f32_16x16x32_f16 v[60:63], v[164:167], v[200:203], v[60:63]
	v_mfma_f32_16x16x32_f16 v[56:59], v[176:179], v[200:203], v[56:59]
	v_mfma_f32_16x16x32_f16 v[52:55], v[164:167], v[208:211], v[52:55]
	v_mfma_f32_16x16x32_f16 v[48:51], v[176:179], v[208:211], v[48:51]
	v_mfma_f32_16x16x32_f16 v[36:39], v[164:167], v[216:219], v[36:39]
	v_mfma_f32_16x16x32_f16 v[32:35], v[176:179], v[216:219], v[32:35]
	v_mfma_f32_16x16x32_f16 v[20:23], v[164:167], v[224:227], v[20:23]
	v_mfma_f32_16x16x32_f16 v[16:19], v[176:179], v[224:227], v[16:19]
	v_mfma_f32_16x16x32_f16 v[44:47], v[180:183], v[196:199], v[44:47]
	v_mfma_f32_16x16x32_f16 v[40:43], v[188:191], v[196:199], v[40:43]
	v_mfma_f32_16x16x32_f16 v[28:31], v[180:183], v[204:207], v[28:31]
	v_mfma_f32_16x16x32_f16 v[24:27], v[188:191], v[204:207], v[24:27]
	v_mfma_f32_16x16x32_f16 v[12:15], v[180:183], v[212:215], v[12:15]
	v_mfma_f32_16x16x32_f16 v[8:11], v[188:191], v[212:215], v[8:11]
	v_mfma_f32_16x16x32_f16 v[4:7], v[180:183], v[220:223], v[4:7]
	v_mfma_f32_16x16x32_f16 v[0:3], v[188:191], v[220:223], v[0:3]
	v_mfma_f32_16x16x32_f16 v[44:47], v[184:187], v[200:203], v[44:47]
	v_mfma_f32_16x16x32_f16 v[40:43], v[192:195], v[200:203], v[40:43]
	v_mfma_f32_16x16x32_f16 v[28:31], v[184:187], v[208:211], v[28:31]
	v_mfma_f32_16x16x32_f16 v[24:27], v[192:195], v[208:211], v[24:27]
	v_mfma_f32_16x16x32_f16 v[12:15], v[184:187], v[216:219], v[12:15]
	v_mfma_f32_16x16x32_f16 v[8:11], v[192:195], v[216:219], v[8:11]
	v_mfma_f32_16x16x32_f16 v[4:7], v[184:187], v[224:227], v[4:7]
	v_mfma_f32_16x16x32_f16 v[0:3], v[192:195], v[224:227], v[0:3]
	s_barrier
	s_add_i32 s52, s52, 2
	s_add_u32 s44, s44, 0x100
	s_addc_u32 s45, s45, 0
	s_add_u32 s50, s50, 0x100
	s_addc_u32 s51, s51, 0
	s_cmp_gt_u32 s52, 13
	s_cbranch_scc0 .LBB0_649
	s_and_b64 vcc, exec, s[22:23]
	s_cbranch_vccz .LBB0_652
	s_barrier

.LBB0_673:
	s_add_u32 s23, s54, 0xfffc0080
	s_addc_u32 s24, s55, -1
	s_add_i32 s26, 0, 0x10000
	s_cmp_eq_u32 s21, 12
	s_cselect_b32 s57, s15, s24
	s_cselect_b32 s56, s16, s23
	v_add_u32_e32 v149, s26, v147
	s_cselect_b32 s25, s17, s20
	s_cselect_b32 s24, s18, s19
	s_add_i32 s23, 0, 0x14000
	ds_read_b128 v[150:153], v149
	ds_read_b128 v[184:187], v149 offset:1024
	ds_read_b128 v[188:191], v149 offset:2048
	ds_read_b128 v[192:195], v149 offset:3072
	v_add_u32_e32 v149, s23, v147
	ds_read_b128 v[196:199], v149
	ds_read_b128 v[200:203], v149 offset:1024
	ds_read_b128 v[204:207], v149 offset:2048
	ds_read_b128 v[208:211], v149 offset:3072
	v_lshl_add_u64 v[154:155], s[54:55], 0, v[142:143]
	s_add_i32 m0, s1, 0xc000
	ds_read_b128 v[212:215], v148
	ds_read_b128 v[216:219], v148 offset:1024
	ds_read_b128 v[220:223], v148 offset:2048
	ds_read_b128 v[224:227], v148 offset:3072
	ds_read_b128 v[228:231], v148 offset:4096
	ds_read_b128 v[232:235], v148 offset:5120
	ds_read_b128 v[236:239], v148 offset:6144
	ds_read_b128 v[240:243], v148 offset:7168
	global_load_lds_dwordx4 v[154:155], off
	v_lshl_add_u64 v[154:155], s[54:55], 0, v[144:145]
	s_add_i32 m0, s1, 0xe000
	s_nop 0
	global_load_lds_dwordx4 v[154:155], off
	s_waitcnt vmcnt(8)
	s_waitcnt lgkmcnt(0)
	v_mfma_f32_16x16x32_f16 v[128:131], v[150:153], v[212:215], v[128:131]
	v_mfma_f32_16x16x32_f16 v[124:127], v[188:191], v[212:215], v[124:127]
	v_mfma_f32_16x16x32_f16 v[120:123], v[150:153], v[220:223], v[120:123]
	v_mfma_f32_16x16x32_f16 v[112:115], v[188:191], v[220:223], v[112:115]
	s_barrier
	s_waitcnt lgkmcnt(0)
	v_mfma_f32_16x16x32_f16 v[104:107], v[150:153], v[228:231], v[104:107]
	v_mfma_f32_16x16x32_f16 v[100:103], v[188:191], v[228:231], v[100:103]
	v_mfma_f32_16x16x32_f16 v[88:91], v[150:153], v[236:239], v[88:91]
	v_mfma_f32_16x16x32_f16 v[84:87], v[188:191], v[236:239], v[84:87]
	v_mfma_f32_16x16x32_f16 v[128:131], v[184:187], v[216:219], v[128:131]
	v_mfma_f32_16x16x32_f16 v[124:127], v[192:195], v[216:219], v[124:127]
	v_mfma_f32_16x16x32_f16 v[120:123], v[184:187], v[224:227], v[120:123]
	v_mfma_f32_16x16x32_f16 v[112:115], v[192:195], v[224:227], v[112:115]
	v_mfma_f32_16x16x32_f16 v[104:107], v[184:187], v[232:235], v[104:107]
	v_mfma_f32_16x16x32_f16 v[100:103], v[192:195], v[232:235], v[100:103]
	v_mfma_f32_16x16x32_f16 v[88:91], v[184:187], v[240:243], v[88:91]
	v_mfma_f32_16x16x32_f16 v[84:87], v[192:195], v[240:243], v[84:87]
	v_mfma_f32_16x16x32_f16 v[116:119], v[196:199], v[212:215], v[116:119]
	v_mfma_f32_16x16x32_f16 v[108:111], v[204:207], v[212:215], v[108:111]
	v_mfma_f32_16x16x32_f16 v[96:99], v[196:199], v[220:223], v[96:99]
	v_mfma_f32_16x16x32_f16 v[92:95], v[204:207], v[220:223], v[92:95]
	v_mfma_f32_16x16x32_f16 v[80:83], v[196:199], v[228:231], v[80:83]
	v_mfma_f32_16x16x32_f16 v[76:79], v[204:207], v[228:231], v[76:79]
	v_mfma_f32_16x16x32_f16 v[72:75], v[196:199], v[236:239], v[72:75]
	v_mfma_f32_16x16x32_f16 v[68:71], v[204:207], v[236:239], v[68:71]
	v_mfma_f32_16x16x32_f16 v[116:119], v[200:203], v[216:219], v[116:119]
	v_mfma_f32_16x16x32_f16 v[108:111], v[208:211], v[216:219], v[108:111]
	v_mfma_f32_16x16x32_f16 v[96:99], v[200:203], v[224:227], v[96:99]
	v_mfma_f32_16x16x32_f16 v[92:95], v[208:211], v[224:227], v[92:95]
	v_mfma_f32_16x16x32_f16 v[80:83], v[200:203], v[232:235], v[80:83]
	v_mfma_f32_16x16x32_f16 v[76:79], v[208:211], v[232:235], v[76:79]
	v_mfma_f32_16x16x32_f16 v[72:75], v[200:203], v[240:243], v[72:75]
	v_mfma_f32_16x16x32_f16 v[68:71], v[208:211], v[240:243], v[68:71]
	s_barrier
	s_add_i32 s26, s26, s0
	v_lshl_add_u64 v[154:155], s[24:25], 0, v[136:137]
	s_mov_b32 m0, s26
	ds_read_b128 v[212:215], v148 offset:16384
	ds_read_b128 v[216:219], v148 offset:17408
	ds_read_b128 v[220:223], v148 offset:18432
	ds_read_b128 v[224:227], v148 offset:19456
	ds_read_b128 v[228:231], v148 offset:20480
	ds_read_b128 v[232:235], v148 offset:21504
	ds_read_b128 v[236:239], v148 offset:22528
	ds_read_b128 v[240:243], v148 offset:23552
	global_load_lds_dwordx4 v[154:155], off
	v_lshl_add_u64 v[168:169], s[24:25], 0, v[0:1]
	s_add_i32 m0, s26, 0x2000
	s_add_i32 s23, s23, s0
	global_load_lds_dwordx4 v[168:169], off
	v_lshl_add_u64 v[244:245], s[24:25], 0, v[138:139]
	s_mov_b32 m0, s23
	v_lshl_add_u64 v[246:247], s[24:25], 0, v[132:133]
	global_load_lds_dwordx4 v[244:245], off
	s_add_i32 m0, s23, 0x2000
	v_lshl_add_u64 v[248:249], s[56:57], 0, v[140:141]
	global_load_lds_dwordx4 v[246:247], off
	s_mov_b32 m0, s1
	v_lshl_add_u64 v[250:251], s[56:57], 0, v[134:135]
	global_load_lds_dwordx4 v[248:249], off
	s_mov_b32 m0, s2
	s_nop 0
	global_load_lds_dwordx4 v[250:251], off
	s_waitcnt vmcnt(8)
	s_waitcnt lgkmcnt(0)
	v_mfma_f32_16x16x32_f16 v[64:67], v[150:153], v[212:215], v[64:67]
	v_mfma_f32_16x16x32_f16 v[60:63], v[188:191], v[212:215], v[60:63]
	v_mfma_f32_16x16x32_f16 v[56:59], v[150:153], v[220:223], v[56:59]
	v_mfma_f32_16x16x32_f16 v[52:55], v[188:191], v[220:223], v[52:55]
	s_barrier
	s_waitcnt lgkmcnt(0)
	v_mfma_f32_16x16x32_f16 v[40:43], v[150:153], v[228:231], v[40:43]
	v_mfma_f32_16x16x32_f16 v[36:39], v[188:191], v[228:231], v[36:39]
	v_mfma_f32_16x16x32_f16 v[24:27], v[150:153], v[236:239], v[24:27]
	v_mfma_f32_16x16x32_f16 v[20:23], v[188:191], v[236:239], v[20:23]
	v_mfma_f32_16x16x32_f16 v[64:67], v[184:187], v[216:219], v[64:67]
	v_mfma_f32_16x16x32_f16 v[60:63], v[192:195], v[216:219], v[60:63]
	v_mfma_f32_16x16x32_f16 v[56:59], v[184:187], v[224:227], v[56:59]
	v_mfma_f32_16x16x32_f16 v[52:55], v[192:195], v[224:227], v[52:55]
	v_mfma_f32_16x16x32_f16 v[40:43], v[184:187], v[232:235], v[40:43]
	v_mfma_f32_16x16x32_f16 v[36:39], v[192:195], v[232:235], v[36:39]
	v_mfma_f32_16x16x32_f16 v[24:27], v[184:187], v[240:243], v[24:27]
	v_mfma_f32_16x16x32_f16 v[20:23], v[192:195], v[240:243], v[20:23]
	v_mfma_f32_16x16x32_f16 v[48:51], v[196:199], v[212:215], v[48:51]
	v_mfma_f32_16x16x32_f16 v[44:47], v[204:207], v[212:215], v[44:47]
	v_mfma_f32_16x16x32_f16 v[32:35], v[196:199], v[220:223], v[32:35]
	v_mfma_f32_16x16x32_f16 v[28:31], v[204:207], v[220:223], v[28:31]
	v_mfma_f32_16x16x32_f16 v[16:19], v[196:199], v[228:231], v[16:19]
	v_mfma_f32_16x16x32_f16 v[12:15], v[204:207], v[228:231], v[12:15]
	v_mfma_f32_16x16x32_f16 v[8:11], v[196:199], v[236:239], v[8:11]
	v_mfma_f32_16x16x32_f16 v[4:7], v[204:207], v[236:239], v[4:7]
	v_mfma_f32_16x16x32_f16 v[48:51], v[200:203], v[216:219], v[48:51]
	v_mfma_f32_16x16x32_f16 v[44:47], v[208:211], v[216:219], v[44:47]
	v_mfma_f32_16x16x32_f16 v[32:35], v[200:203], v[224:227], v[32:35]
	v_mfma_f32_16x16x32_f16 v[28:31], v[208:211], v[224:227], v[28:31]
	v_mfma_f32_16x16x32_f16 v[16:19], v[200:203], v[232:235], v[16:19]
	v_mfma_f32_16x16x32_f16 v[12:15], v[208:211], v[232:235], v[12:15]
	v_mfma_f32_16x16x32_f16 v[8:11], v[200:203], v[240:243], v[8:11]
	v_mfma_f32_16x16x32_f16 v[4:7], v[208:211], v[240:243], v[4:7]
	s_barrier
	s_add_i32 s23, 0, 0x18000
	v_add_u32_e32 v149, s23, v147
	s_add_i32 s26, 0, 0x1c000
	ds_read_b128 v[150:153], v149
	ds_read_b128 v[184:187], v149 offset:1024
	ds_read_b128 v[188:191], v149 offset:2048
	ds_read_b128 v[192:195], v149 offset:3072
	v_add_u32_e32 v149, s26, v147
	ds_read_b128 v[196:199], v149
	ds_read_b128 v[200:203], v149 offset:1024
	ds_read_b128 v[204:207], v149 offset:2048
	ds_read_b128 v[208:211], v149 offset:3072
	s_add_u32 s24, s56, 0x40000
	s_addc_u32 s25, s57, 0
	s_mov_b32 m0, s3
	v_lshl_add_u64 v[178:179], s[24:25], 0, v[140:141]
	ds_read_b128 v[212:215], v148 offset:32768
	ds_read_b128 v[216:219], v148 offset:33792
	ds_read_b128 v[220:223], v148 offset:34816
	ds_read_b128 v[224:227], v148 offset:35840
	ds_read_b128 v[228:231], v148 offset:36864
	ds_read_b128 v[232:235], v148 offset:37888
	ds_read_b128 v[236:239], v148 offset:38912
	ds_read_b128 v[240:243], v148 offset:39936
	global_load_lds_dwordx4 v[178:179], off
	v_lshl_add_u64 v[178:179], s[24:25], 0, v[134:135]
	s_mov_b32 m0, s4
	s_nop 0
	global_load_lds_dwordx4 v[178:179], off
	s_waitcnt vmcnt(8)
	s_waitcnt lgkmcnt(0)
	v_mfma_f32_16x16x32_f16 v[128:131], v[150:153], v[212:215], v[128:131]
	v_mfma_f32_16x16x32_f16 v[124:127], v[188:191], v[212:215], v[124:127]
	v_mfma_f32_16x16x32_f16 v[120:123], v[150:153], v[220:223], v[120:123]
	v_mfma_f32_16x16x32_f16 v[112:115], v[188:191], v[220:223], v[112:115]
	s_barrier
	s_waitcnt lgkmcnt(0)
	v_mfma_f32_16x16x32_f16 v[104:107], v[150:153], v[228:231], v[104:107]
	v_mfma_f32_16x16x32_f16 v[100:103], v[188:191], v[228:231], v[100:103]
	v_mfma_f32_16x16x32_f16 v[88:91], v[150:153], v[236:239], v[88:91]
	v_mfma_f32_16x16x32_f16 v[84:87], v[188:191], v[236:239], v[84:87]
	v_mfma_f32_16x16x32_f16 v[128:131], v[184:187], v[216:219], v[128:131]
	v_mfma_f32_16x16x32_f16 v[124:127], v[192:195], v[216:219], v[124:127]
	v_mfma_f32_16x16x32_f16 v[120:123], v[184:187], v[224:227], v[120:123]
	v_mfma_f32_16x16x32_f16 v[112:115], v[192:195], v[224:227], v[112:115]
	v_mfma_f32_16x16x32_f16 v[104:107], v[184:187], v[232:235], v[104:107]
	v_mfma_f32_16x16x32_f16 v[100:103], v[192:195], v[232:235], v[100:103]
	v_mfma_f32_16x16x32_f16 v[88:91], v[184:187], v[240:243], v[88:91]
	v_mfma_f32_16x16x32_f16 v[84:87], v[192:195], v[240:243], v[84:87]
	v_mfma_f32_16x16x32_f16 v[116:119], v[196:199], v[212:215], v[116:119]
	v_mfma_f32_16x16x32_f16 v[108:111], v[204:207], v[212:215], v[108:111]
	v_mfma_f32_16x16x32_f16 v[96:99], v[196:199], v[220:223], v[96:99]
	v_mfma_f32_16x16x32_f16 v[92:95], v[204:207], v[220:223], v[92:95]
	v_mfma_f32_16x16x32_f16 v[80:83], v[196:199], v[228:231], v[80:83]
	v_mfma_f32_16x16x32_f16 v[76:79], v[204:207], v[228:231], v[76:79]
	v_mfma_f32_16x16x32_f16 v[72:75], v[196:199], v[236:239], v[72:75]
	v_mfma_f32_16x16x32_f16 v[68:71], v[204:207], v[236:239], v[68:71]
	v_mfma_f32_16x16x32_f16 v[116:119], v[200:203], v[216:219], v[116:119]
	v_mfma_f32_16x16x32_f16 v[108:111], v[208:211], v[216:219], v[108:111]
	v_mfma_f32_16x16x32_f16 v[96:99], v[200:203], v[224:227], v[96:99]
	v_mfma_f32_16x16x32_f16 v[92:95], v[208:211], v[224:227], v[92:95]
	v_mfma_f32_16x16x32_f16 v[80:83], v[200:203], v[232:235], v[80:83]
	v_mfma_f32_16x16x32_f16 v[76:79], v[208:211], v[232:235], v[76:79]
	v_mfma_f32_16x16x32_f16 v[72:75], v[200:203], v[240:243], v[72:75]
	v_mfma_f32_16x16x32_f16 v[68:71], v[208:211], v[240:243], v[68:71]
	s_barrier
	s_add_i32 s23, s23, s0
	v_lshl_add_u64 v[154:155], v[154:155], 0, s[72:73]
	s_mov_b32 m0, s23
	ds_read_b128 v[212:215], v148 offset:49152
	ds_read_b128 v[216:219], v148 offset:50176
	ds_read_b128 v[220:223], v148 offset:51200
	ds_read_b128 v[224:227], v148 offset:52224
	ds_read_b128 v[228:231], v148 offset:53248
	ds_read_b128 v[232:235], v148 offset:54272
	ds_read_b128 v[236:239], v148 offset:55296
	ds_read_b128 v[240:243], v148 offset:56320
	global_load_lds_dwordx4 v[154:155], off
	v_lshl_add_u64 v[154:155], v[168:169], 0, s[72:73]
	s_add_i32 m0, s23, 0x2000
	s_add_i32 s23, s26, s0
	global_load_lds_dwordx4 v[154:155], off
	v_lshl_add_u64 v[154:155], v[244:245], 0, s[72:73]
	s_mov_b32 m0, s23
	s_nop 0
	global_load_lds_dwordx4 v[154:155], off
	v_lshl_add_u64 v[154:155], v[246:247], 0, s[72:73]
	s_add_i32 m0, s23, 0x2000
	s_nop 0
	global_load_lds_dwordx4 v[154:155], off
	v_lshl_add_u64 v[154:155], v[248:249], 0, s[72:73]
	s_mov_b32 m0, s10
	s_nop 0
	global_load_lds_dwordx4 v[154:155], off
	v_lshl_add_u64 v[154:155], v[250:251], 0, s[72:73]
	s_mov_b32 m0, s11
	s_nop 0
	global_load_lds_dwordx4 v[154:155], off
	s_waitcnt vmcnt(8)
	s_waitcnt lgkmcnt(0)
	v_mfma_f32_16x16x32_f16 v[64:67], v[150:153], v[212:215], v[64:67]
	v_mfma_f32_16x16x32_f16 v[60:63], v[188:191], v[212:215], v[60:63]
	v_mfma_f32_16x16x32_f16 v[56:59], v[150:153], v[220:223], v[56:59]
	v_mfma_f32_16x16x32_f16 v[52:55], v[188:191], v[220:223], v[52:55]
	s_barrier
	s_waitcnt lgkmcnt(0)
	v_mfma_f32_16x16x32_f16 v[40:43], v[150:153], v[228:231], v[40:43]
	v_mfma_f32_16x16x32_f16 v[36:39], v[188:191], v[228:231], v[36:39]
	v_mfma_f32_16x16x32_f16 v[24:27], v[150:153], v[236:239], v[24:27]
	v_mfma_f32_16x16x32_f16 v[20:23], v[188:191], v[236:239], v[20:23]
	v_mfma_f32_16x16x32_f16 v[64:67], v[184:187], v[216:219], v[64:67]
	v_mfma_f32_16x16x32_f16 v[60:63], v[192:195], v[216:219], v[60:63]
	v_mfma_f32_16x16x32_f16 v[56:59], v[184:187], v[224:227], v[56:59]
	v_mfma_f32_16x16x32_f16 v[52:55], v[192:195], v[224:227], v[52:55]
	v_mfma_f32_16x16x32_f16 v[40:43], v[184:187], v[232:235], v[40:43]
	v_mfma_f32_16x16x32_f16 v[36:39], v[192:195], v[232:235], v[36:39]
	v_mfma_f32_16x16x32_f16 v[24:27], v[184:187], v[240:243], v[24:27]
	v_mfma_f32_16x16x32_f16 v[20:23], v[192:195], v[240:243], v[20:23]
	v_mfma_f32_16x16x32_f16 v[48:51], v[196:199], v[212:215], v[48:51]
	v_mfma_f32_16x16x32_f16 v[44:47], v[204:207], v[212:215], v[44:47]
	v_mfma_f32_16x16x32_f16 v[32:35], v[196:199], v[220:223], v[32:35]
	v_mfma_f32_16x16x32_f16 v[28:31], v[204:207], v[220:223], v[28:31]
	v_mfma_f32_16x16x32_f16 v[16:19], v[196:199], v[228:231], v[16:19]
	v_mfma_f32_16x16x32_f16 v[12:15], v[204:207], v[228:231], v[12:15]
	v_mfma_f32_16x16x32_f16 v[8:11], v[196:199], v[236:239], v[8:11]
	v_mfma_f32_16x16x32_f16 v[4:7], v[204:207], v[236:239], v[4:7]
	v_mfma_f32_16x16x32_f16 v[48:51], v[200:203], v[216:219], v[48:51]
	v_mfma_f32_16x16x32_f16 v[44:47], v[208:211], v[216:219], v[44:47]
	v_mfma_f32_16x16x32_f16 v[32:35], v[200:203], v[224:227], v[32:35]
	v_mfma_f32_16x16x32_f16 v[28:31], v[208:211], v[224:227], v[28:31]
	v_mfma_f32_16x16x32_f16 v[16:19], v[200:203], v[232:235], v[16:19]
	v_mfma_f32_16x16x32_f16 v[12:15], v[208:211], v[232:235], v[12:15]
	v_mfma_f32_16x16x32_f16 v[8:11], v[200:203], v[240:243], v[8:11]
	v_mfma_f32_16x16x32_f16 v[4:7], v[208:211], v[240:243], v[4:7]
	s_barrier
	s_add_i32 s21, s21, 2
	s_add_u32 s54, s54, 0x100
	s_addc_u32 s55, s55, 0
	s_add_u32 s19, s19, 0x100
	s_addc_u32 s20, s20, 0
	s_cmp_gt_u32 s21, 13
	s_cbranch_scc0 .LBB0_673
	s_and_b64 vcc, exec, s[44:45]
	s_cbranch_vccz .LBB0_676
	s_barrier

.LBB0_734:
	s_or_b64 exec, exec, s[6:7]
	v_readlane_b32 s0, v254, 56
	v_readlane_b32 s1, v254, 57
	s_mov_b64 s[6:7], -1
	s_and_b64 vcc, exec, s[0:1]
	s_waitcnt lgkmcnt(0)
	s_barrier
	s_cbranch_vccz .LBB0_759
	v_mov_b32_e32 v0, v170
	v_readlane_b32 s1, v253, 39
	v_readfirstlane_b32 s0, v0
	s_ashr_i32 s4, s0, 6
	s_lshl_b32 s0, s4, 4
	v_and_b32_e32 v61, 15, v0
	s_add_i32 s1, s0, s1
	v_or_b32_e32 v26, s1, v61
	v_ashrrev_i32_e32 v27, 31, v26
	v_readlane_b32 s2, v253, 8
	v_lshlrev_b64 v[4:5], 7, v[26:27]
	v_readlane_b32 s3, v253, 9
	v_and_b32_e32 v2, 48, v0
	s_cmp_gt_i32 s4, 3
	v_lshl_add_u64 v[4:5], s[2:3], 0, v[4:5]
	v_lshl_add_u64 v[4:5], v[4:5], 0, v[2:3]
	global_load_dwordx4 v[8:11], v[4:5], off
	s_nop 0
	global_load_dwordx4 v[4:7], v[4:5], off offset:64
	s_cbranch_scc1 .LBB0_737
.LBB0_737:
	s_add_i32 s5, s4, 8
	s_lshl_b32 s7, s4, 1
	s_lshl_b32 s1, s4, 3
	s_lshl_b32 s2, s4, 10
	s_lshl_b32 s3, s5, 3
	s_lshl_b32 s10, s5, 10
	s_lshl_b32 s11, s4, 2
	s_lshl_b32 s12, s5, 2
	s_and_b32 s13, s0, 0x70
	s_add_i32 s8, s7, 2
	s_add_i32 s9, s7, 4
	s_add_i32 s14, s7, 6
	s_add_i32 s5, s5, s4
	s_add_i32 s15, s7, 10
	s_add_i32 s16, s7, 12
	s_add_i32 s17, s7, 14
	s_cmp_gt_u32 s7, 0xffffffef
	s_mov_b32 s94, 0x8000
	s_cselect_b32 s6, s94, 0x10000
	s_mov_b32 s29, 0x18000
	s_cselect_b32 s18, 0x18000, 0
	s_cselect_b32 s39, 0, 0x8000
	v_writelane_b32 v255, s6, 24
	s_cselect_b32 s6, 0x10000, s29
	s_cmp_lt_u32 s17, 16
	v_writelane_b32 v255, s6, 40
	s_cselect_b32 s21, 0x18000, 0
	s_cselect_b32 s30, 0, 0x8000
	s_cselect_b32 s46, s94, 0x10000
	s_cselect_b32 s6, 0x10000, s29
	s_cmp_lt_u32 s16, 16
	v_writelane_b32 v254, s6, 58
	s_cselect_b32 s25, 0x18000, 0
	s_cselect_b32 s28, 0, 0x8000
	s_cselect_b32 s45, s94, 0x10000
	s_cselect_b32 s6, 0x10000, s29
	s_cmp_lt_u32 s15, 16
	v_writelane_b32 v254, s6, 59
	s_cselect_b32 s35, 0x18000, 0
	s_cselect_b32 s36, 0, 0x8000
	s_cselect_b32 s44, s94, 0x10000
	s_cselect_b32 s6, 0x10000, s29
	s_cmp_lt_u32 s5, 16
	s_cselect_b32 s37, 0x18000, 0
	s_cselect_b32 s47, 0, 0x8000
	s_cselect_b32 s48, s94, 0x10000
	s_cselect_b32 s49, 0x10000, s29
	s_cmp_lt_u32 s14, 16
	s_cselect_b32 s31, 0x18000, 0
	s_cselect_b32 s50, 0, 0x8000
	s_cselect_b32 s51, s94, 0x10000
	s_cselect_b32 s52, 0x10000, s29
	s_cmp_lt_u32 s9, 16
	s_cselect_b32 s34, 0x18000, 0
	s_cselect_b32 s55, 0, 0x8000
	s_cselect_b32 s56, s94, 0x10000
	s_cselect_b32 s57, 0x10000, s29
	s_cmp_lt_u32 s8, 16
	s_cselect_b32 s26, 0x18000, 0
	s_cselect_b32 s58, 0, 0x8000
	s_cselect_b32 s59, s94, 0x10000
	s_cselect_b32 s60, 0x10000, s29
	s_cmp_lt_u32 s7, 16
	s_cselect_b32 s27, 0x18000, 0
	s_cselect_b32 s61, 0, 0x8000
	s_cselect_b32 s62, s94, 0x10000
	s_cselect_b32 vcc_lo, 0x10000, s29
	s_cmp_gt_i32 s4, -1
	s_cselect_b32 s64, 0x10000, s94
	s_cselect_b32 vcc_hi, s29, 0x10000
	s_cmp_gt_i32 s4, 0
	s_cselect_b32 s38, 0, 0x18000
	s_cselect_b32 s63, 0x8000, 0
	s_cselect_b32 s66, 0x10000, s94
	s_cselect_b32 s24, s29, 0x10000
	s_cmp_gt_i32 s4, 1
	s_cselect_b32 s53, 0, 0x18000
	s_cselect_b32 s65, 0x8000, 0
	s_cselect_b32 s68, 0x10000, s94
	s_cselect_b32 s80, s29, 0x10000
	s_cmp_gt_i32 s4, 2
	s_cselect_b32 s54, 0, 0x18000
	s_cselect_b32 s67, 0x8000, 0
	s_cselect_b32 s71, 0x10000, s94
	s_cselect_b32 s82, s29, 0x10000
	s_cmp_gt_i32 s4, 3
	s_cselect_b32 s69, 0, 0x18000
	s_cselect_b32 s70, 0x8000, 0
	s_cselect_b32 s75, 0x10000, s94
	s_cselect_b32 s83, s29, 0x10000
	s_cmp_gt_i32 s4, 4
	s_cselect_b32 s74, 0, 0x18000
	s_cselect_b32 s76, 0x8000, 0
	s_cselect_b32 s77, 0x10000, s94
	s_cselect_b32 s84, s29, 0x10000
	s_cmp_gt_i32 s4, 5
	s_cselect_b32 s78, 0, 0x18000
	s_cselect_b32 s85, 0x8000, 0
	s_cselect_b32 s92, 0x10000, s94
	s_cselect_b32 s86, s29, 0x10000
	s_cmp_gt_i32 s4, 6
	s_cselect_b32 s87, 0, 0x18000
	s_cselect_b32 s88, 0x8000, 0
	s_cselect_b32 s91, 0x10000, s94
	s_cselect_b32 s97, s29, 0x10000
	s_cmp_gt_i32 s4, 7
	v_writelane_b32 v255, s6, 25
	s_cselect_b32 s90, 0, 0x18000
	s_cselect_b32 s93, 0x8000, 0
	s_cselect_b32 s94, 0x10000, s94
	s_cselect_b32 s6, s29, 0x10000
	s_add_i32 s27, s27, 0
	v_writelane_b32 v253, s27, 4
	s_add_i32 s26, s26, 0
	v_writelane_b32 v253, s26, 1
	s_and_b32 s26, s7, 14
	s_add_i32 s7, s34, 0
	v_writelane_b32 v253, s7, 13
	s_add_i32 s7, s31, 0
	v_writelane_b32 v253, s7, 2
	s_add_i32 s7, s37, 0
	v_writelane_b32 v255, s7, 6
	s_add_i32 s7, s35, 0
	v_writelane_b32 v255, s7, 7
	s_and_b32 s37, s5, 14
	s_add_i32 s5, s25, 0
	v_writelane_b32 v255, s5, 8
	s_add_i32 s5, s21, 0
	v_writelane_b32 v255, s5, 9
	s_add_i32 s5, s18, 0
	v_writelane_b32 v255, s5, 10
	s_add_i32 s5, s93, 0
	v_writelane_b32 v255, s5, 11
	s_add_i32 s5, s88, 0
	v_writelane_b32 v255, s5, 12
	s_add_i32 s5, s85, 0
	v_writelane_b32 v255, s5, 13
	s_add_i32 s5, s76, 0
	v_writelane_b32 v255, s5, 14
	s_add_i32 s5, s70, 0
	v_writelane_b32 v255, s5, 15
	s_add_i32 s5, s67, 0
	v_writelane_b32 v255, s5, 16
	s_add_i32 s5, s65, 0
	v_writelane_b32 v255, s5, 17
	s_add_i32 s5, s63, 0
	v_writelane_b32 v255, s5, 18
	s_add_i32 s5, s0, 16
	v_writelane_b32 v255, s5, 34
	s_and_b32 s65, s5, 0x70
	s_add_i32 s5, s0, 32
	v_writelane_b32 v255, s5, 35
	s_and_b32 s67, s5, 0x70
	s_add_i32 s5, s0, 48
	s_add_i32 s29, s69, 0
	v_writelane_b32 v255, s5, 36
	s_and_b32 s69, s5, 0x70
	s_add_i32 s5, s0, 0x50
	s_add_i32 s95, s74, 0
	s_add_i32 s20, s38, 0
	s_ashr_i32 s38, s4, 31
	v_writelane_b32 v255, s5, 37
	s_and_b32 s74, s5, 0x70
	s_add_i32 s5, s0, 0x60
	s_and_b32 s38, s38, 0x18000
	v_writelane_b32 v255, s5, 38
	s_and_b32 s76, s5, 0x70
	s_add_i32 s5, s0, 0x70
	s_add_i32 s79, s90, 0
	s_add_i32 s87, s87, 0
	s_add_i32 s89, s78, 0
	s_add_i32 s96, s54, 0
	s_add_i32 s19, s53, 0
	s_add_i32 s23, s38, 0
	s_and_b32 s27, s8, 14
	s_and_b32 s31, s9, 14
	s_and_b32 s34, s14, 14
	s_and_b32 s38, s15, 14
	s_and_b32 s53, s16, 14
	s_and_b32 s54, s17, 14
	s_xor_b32 s70, s13, 64
	s_and_b32 s78, s5, 0x70
	s_cmp_lt_i32 s4, 0
	s_cselect_b32 s4, 0, 0x8000
	v_writelane_b32 v255, s5, 39
	s_add_i32 s4, s4, 0
	v_writelane_b32 v255, s4, 19
	s_add_i32 s4, s61, 0
	v_writelane_b32 v255, s4, 20
	s_add_i32 s4, s58, 0
	v_writelane_b32 v255, s4, 21
	s_add_i32 s4, s55, 0
	v_writelane_b32 v255, s4, 22
	s_add_i32 s4, s50, 0
	v_writelane_b32 v255, s4, 23
	s_add_i32 s4, s47, 0
	v_writelane_b32 v255, s4, 28
	s_add_i32 s4, s36, 0
	v_writelane_b32 v255, s4, 29
	s_add_i32 s4, s28, 0
	v_writelane_b32 v255, s4, 30
	s_add_i32 s4, s30, 0
	v_writelane_b32 v255, s4, 31
	s_add_i32 s4, s39, 0
	v_bfe_u32 v63, v0, 4, 2
	v_writelane_b32 v255, s4, 32
	v_readlane_b32 s4, v253, 8
	v_lshlrev_b32_e32 v2, 3, v63
	v_readlane_b32 s5, v253, 9
	s_add_i32 s16, s6, 0
	s_add_i32 s36, s52, 0
	v_lshl_add_u64 v[22:23], s[4:5], 0, v[2:3]
	s_add_i32 s4, s94, 0
	v_writelane_b32 v255, s4, 33
	s_add_i32 s88, s66, 0
	v_readlane_b32 s6, v255, 25
	s_add_i32 s52, s6, 0
	v_readlane_b32 s6, v254, 59
	s_add_i32 s55, s6, 0
	v_readlane_b32 s6, v254, 58
	s_add_i32 s66, s56, 0
	s_add_i32 s56, s6, 0
	v_readlane_b32 s6, v255, 40
	s_add_i32 s35, s57, 0
	s_add_i32 s57, s6, 0
	v_readlane_b32 s6, v253, 36
	v_and_b32_e32 v62, 63, v0
	v_readlane_b32 s7, v255, 24
	v_mov_b32_e32 v27, s6
	v_readlane_b32 s6, v254, 17
	v_lshlrev_b32_e32 v20, 2, v63
	s_add_i32 s91, s91, 0
	s_add_i32 s92, s92, 0
	s_add_i32 s93, s77, 0
	s_add_i32 s94, s75, 0
	s_add_i32 s63, s71, 0
	s_add_i32 s85, s68, 0
	s_add_i32 s4, s64, 0
	s_add_i32 s5, s62, 0
	s_add_i32 s64, s59, 0
	s_add_i32 s68, s51, 0
	s_add_i32 s71, s48, 0
	s_add_i32 s75, s44, 0
	s_add_i32 s77, s45, 0
	s_add_i32 s14, s46, 0
	s_add_i32 s15, s7, 0
	s_add_i32 s17, s97, 0
	s_add_i32 s18, s86, 0
	s_add_i32 s97, s84, 0
	s_mov_b32 s84, s87
	s_add_i32 s90, s83, 0
	s_add_i32 s21, s82, 0
	s_add_i32 s80, s80, 0
	s_add_i32 s24, s24, 0
	s_add_i32 s25, vcc_hi, 0
	s_add_i32 s28, vcc_lo, 0
	s_add_i32 s30, s60, 0
	s_add_i32 s39, s49, 0
	v_mov_b32_e32 v2, 0
	v_mov_b32_e32 v28, 0
	s_mov_b32 s59, 0
	s_add_i32 s58, s0, s6
	v_cmp_gt_u32_e64 s[6:7], 16, v62
	s_mov_b64 s[46:47], 0
	s_mov_b64 s[44:45], -1
	v_readlane_b32 s48, v254, 15
	s_mov_b32 s8, 0
	v_readlane_b32 s49, v254, 16

.Lat738_i3_nomask:
	v_max3_f32 v245, v44, v45, v46
	v_max3_f32 v245, v245, v47, v48
	v_max3_f32 v245, v245, v49, v50
	v_max3_f32 v245, v245, v51, v52
	v_max3_f32 v245, v245, v53, v54
	v_max3_f32 v245, v245, v55, v56
	v_max3_f32 v245, v245, v57, v58
	v_max3_f32 v245, v245, v59, v60
	v_max3_f32 v245, v245, v61, v62
	v_max3_f32 v245, v245, v63, v64
	v_max3_f32 v245, v245, v65, v66
	v_max3_f32 v245, v245, v67, v68
	v_max3_f32 v245, v245, v69, v70
	v_max3_f32 v245, v245, v71, v72
	v_max3_f32 v245, v245, v73, v74
	v_max3_f32 v245, v245, v75, v76
	v_max3_f32 v245, v245, v77, v78
	v_max_f32_e32 v245, v245, v79
	v_mov_b32_e32 v148, v245
	s_nop 1
	v_permlane16_swap_b32 v245, v148
	v_max_f32_e32 v245, v245, v148
	v_mov_b32_e32 v148, v245
	s_nop 1
	v_permlane32_swap_b32 v245, v148
	v_max_f32_e32 v245, v245, v148
	v_sub_f32_e32 v44, v44, v245
	v_sub_f32_e32 v45, v45, v245
	v_sub_f32_e32 v46, v46, v245
	v_sub_f32_e32 v47, v47, v245
	v_exp_f32_e32 v44, v44
	v_exp_f32_e32 v45, v45
	v_exp_f32_e32 v46, v46
	v_exp_f32_e32 v47, v47
	v_sub_f32_e32 v48, v48, v245
	v_sub_f32_e32 v49, v49, v245
	v_sub_f32_e32 v50, v50, v245
	v_sub_f32_e32 v51, v51, v245
	v_exp_f32_e32 v48, v48
	v_exp_f32_e32 v49, v49
	v_exp_f32_e32 v50, v50
	v_exp_f32_e32 v51, v51
	v_mov_b32_e32 v149, v44
	v_mov_b32_e32 v150, v45
	v_mov_b32_e32 v151, v46
	v_mov_b32_e32 v152, v47
	v_cvt_pk_bf16_f32 v44, v44, v45
	v_cvt_pk_bf16_f32 v45, v46, v47
	v_sub_f32_e32 v52, v52, v245
	v_sub_f32_e32 v53, v53, v245
	v_sub_f32_e32 v54, v54, v245
	v_sub_f32_e32 v55, v55, v245
	v_exp_f32_e32 v52, v52
	v_exp_f32_e32 v53, v53
	v_exp_f32_e32 v54, v54
	v_exp_f32_e32 v55, v55
	v_add_f32_e32 v149, v149, v48
	v_add_f32_e32 v150, v150, v49
	v_add_f32_e32 v151, v151, v50
	v_add_f32_e32 v152, v152, v51
	v_cvt_pk_bf16_f32 v46, v48, v49
	v_cvt_pk_bf16_f32 v47, v50, v51
	v_sub_f32_e32 v56, v56, v245
	v_sub_f32_e32 v57, v57, v245
	v_sub_f32_e32 v58, v58, v245
	v_sub_f32_e32 v59, v59, v245
	v_exp_f32_e32 v56, v56
	v_exp_f32_e32 v57, v57
	v_exp_f32_e32 v58, v58
	v_exp_f32_e32 v59, v59
	v_add_f32_e32 v149, v149, v52
	v_add_f32_e32 v150, v150, v53
	v_add_f32_e32 v151, v151, v54
	v_add_f32_e32 v152, v152, v55
	v_cvt_pk_bf16_f32 v52, v52, v53
	v_cvt_pk_bf16_f32 v53, v54, v55
	v_sub_f32_e32 v60, v60, v245
	v_sub_f32_e32 v61, v61, v245
	v_sub_f32_e32 v62, v62, v245
	v_sub_f32_e32 v63, v63, v245
	v_exp_f32_e32 v60, v60
	v_exp_f32_e32 v61, v61
	v_exp_f32_e32 v62, v62
	v_exp_f32_e32 v63, v63
	v_add_f32_e32 v149, v149, v56
	v_add_f32_e32 v150, v150, v57
	v_add_f32_e32 v151, v151, v58
	v_add_f32_e32 v152, v152, v59
	v_cvt_pk_bf16_f32 v54, v56, v57
	v_cvt_pk_bf16_f32 v55, v58, v59
	v_sub_f32_e32 v64, v64, v245
	v_sub_f32_e32 v65, v65, v245
	v_sub_f32_e32 v66, v66, v245
	v_sub_f32_e32 v67, v67, v245
	v_exp_f32_e32 v64, v64
	v_exp_f32_e32 v65, v65
	v_exp_f32_e32 v66, v66
	v_exp_f32_e32 v67, v67
	v_add_f32_e32 v149, v149, v60
	v_add_f32_e32 v150, v150, v61
	v_add_f32_e32 v151, v151, v62
	v_add_f32_e32 v152, v152, v63
	v_cvt_pk_bf16_f32 v60, v60, v61
	v_cvt_pk_bf16_f32 v61, v62, v63
	v_sub_f32_e32 v68, v68, v245
	v_sub_f32_e32 v69, v69, v245
	v_sub_f32_e32 v70, v70, v245
	v_sub_f32_e32 v71, v71, v245
	v_exp_f32_e32 v68, v68
	v_exp_f32_e32 v69, v69
	v_exp_f32_e32 v70, v70
	v_exp_f32_e32 v71, v71
	v_add_f32_e32 v149, v149, v64
	v_add_f32_e32 v150, v150, v65
	v_add_f32_e32 v151, v151, v66
	v_add_f32_e32 v152, v152, v67
	v_cvt_pk_bf16_f32 v62, v64, v65
	v_cvt_pk_bf16_f32 v63, v66, v67
	v_sub_f32_e32 v72, v72, v245
	v_sub_f32_e32 v73, v73, v245
	v_sub_f32_e32 v74, v74, v245
	v_sub_f32_e32 v75, v75, v245
	v_exp_f32_e32 v72, v72
	v_exp_f32_e32 v73, v73
	v_exp_f32_e32 v74, v74
	v_exp_f32_e32 v75, v75
	v_add_f32_e32 v149, v149, v68
	v_add_f32_e32 v150, v150, v69
	v_add_f32_e32 v151, v151, v70
	v_add_f32_e32 v152, v152, v71
	v_cvt_pk_bf16_f32 v68, v68, v69
	v_cvt_pk_bf16_f32 v69, v70, v71
	v_sub_f32_e32 v76, v76, v245
	v_sub_f32_e32 v77, v77, v245
	v_sub_f32_e32 v78, v78, v245
	v_sub_f32_e32 v79, v79, v245
	v_exp_f32_e32 v76, v76
	v_exp_f32_e32 v77, v77
	v_exp_f32_e32 v78, v78
	v_exp_f32_e32 v79, v79
	v_add_f32_e32 v149, v149, v72
	v_add_f32_e32 v150, v150, v73
	v_add_f32_e32 v151, v151, v74
	v_add_f32_e32 v152, v152, v75
	v_cvt_pk_bf16_f32 v70, v72, v73
	v_cvt_pk_bf16_f32 v71, v74, v75
	s_nop 0
	v_add_f32_e32 v149, v149, v76
	v_add_f32_e32 v150, v150, v77
	v_add_f32_e32 v151, v151, v78
	v_add_f32_e32 v152, v152, v79
	v_cvt_pk_bf16_f32 v76, v76, v77
	v_cvt_pk_bf16_f32 v77, v78, v79
	v_mov_b32_e32 v78, 0
	v_mov_b32_e32 v79, 0
	v_add_f32_e32 v149, v149, v150
	v_add_f32_e32 v151, v151, v152
	v_add_f32_e32 v246, v149, v151
	s_waitcnt lgkmcnt(0)
	v_mfma_f32_16x16x32_bf16 v[80:83], v[4:7], v[44:47], 0
	v_mfma_f32_16x16x32_bf16 v[84:87], v[8:11], v[44:47], 0
	v_mfma_f32_16x16x32_bf16 v[88:91], v[12:15], v[44:47], 0
	v_mfma_f32_16x16x32_bf16 v[92:95], v[16:19], v[44:47], 0
	ds_read_b64 v[4:5], v225 offset:32768
	ds_read_b64 v[8:9], v225 offset:36864
	ds_read_b64 v[12:13], v225 offset:40960
	ds_read_b64 v[16:17], v225 offset:45056
	ds_read_b64 v[6:7], v226 offset:32768
	ds_read_b64 v[10:11], v226 offset:36864
	ds_read_b64 v[14:15], v226 offset:40960
	ds_read_b64 v[18:19], v226 offset:45056
	v_mfma_f32_16x16x32_bf16 v[80:83], v[20:23], v[52:55], v[80:83]
	v_mfma_f32_16x16x32_bf16 v[84:87], v[24:27], v[52:55], v[84:87]
	v_mfma_f32_16x16x32_bf16 v[88:91], v[28:31], v[52:55], v[88:91]
	v_mfma_f32_16x16x32_bf16 v[92:95], v[32:35], v[52:55], v[92:95]
	ds_read_b64 v[20:21], v227 offset:32768
	ds_read_b64 v[24:25], v227 offset:36864
	ds_read_b64 v[28:29], v227 offset:40960
	ds_read_b64 v[32:33], v227 offset:45056
	ds_read_b64 v[22:23], v228 offset:32768
	ds_read_b64 v[26:27], v228 offset:36864
	ds_read_b64 v[30:31], v228 offset:40960
	ds_read_b64 v[34:35], v228 offset:45056
	s_waitcnt lgkmcnt(8)
	v_mfma_f32_16x16x32_bf16 v[80:83], v[4:7], v[60:63], v[80:83]
	v_mfma_f32_16x16x32_bf16 v[84:87], v[8:11], v[60:63], v[84:87]
	v_mfma_f32_16x16x32_bf16 v[88:91], v[12:15], v[60:63], v[88:91]
	v_mfma_f32_16x16x32_bf16 v[92:95], v[16:19], v[60:63], v[92:95]
	ds_read_b64 v[4:5], v229 offset:32768
	ds_read_b64 v[8:9], v229 offset:36864
	ds_read_b64 v[12:13], v229 offset:40960
	ds_read_b64 v[16:17], v229 offset:45056
	v_mov_b32_e32 v6, 0
	v_mov_b32_e32 v7, 0
	v_mov_b32_e32 v10, 0
	v_mov_b32_e32 v11, 0
	v_mov_b32_e32 v14, 0
	v_mov_b32_e32 v15, 0
	v_mov_b32_e32 v18, 0
	v_mov_b32_e32 v19, 0
	s_waitcnt lgkmcnt(4)
	v_mfma_f32_16x16x32_bf16 v[80:83], v[20:23], v[68:71], v[80:83]
	v_mfma_f32_16x16x32_bf16 v[84:87], v[24:27], v[68:71], v[84:87]
	v_mfma_f32_16x16x32_bf16 v[88:91], v[28:31], v[68:71], v[88:91]
	v_mfma_f32_16x16x32_bf16 v[92:95], v[32:35], v[68:71], v[92:95]
	s_waitcnt lgkmcnt(0)
	v_mfma_f32_16x16x32_bf16 v[80:83], v[4:7], v[76:79], v[80:83]
	v_mfma_f32_16x16x32_bf16 v[84:87], v[8:11], v[76:79], v[84:87]
	v_mfma_f32_16x16x32_bf16 v[88:91], v[12:15], v[76:79], v[88:91]
	v_mfma_f32_16x16x32_bf16 v[92:95], v[16:19], v[76:79], v[92:95]
	v_mov_b32_e32 v148, v246
	s_nop 1
	v_permlane16_swap_b32 v246, v148
	v_add_f32_e32 v246, v246, v148
	v_mov_b32_e32 v148, v246
	s_nop 1
	v_permlane32_swap_b32 v246, v148
	v_add_f32_e32 v246, v246, v148
	v_rcp_f32_e32 v149, v246
	v_log_f32_e32 v150, v246
	s_nop 0
	v_add_f32_e32 v151, v245, v150
	v_mul_f32_e32 v151, 0x3f317218, v151
	v_mov_b32_e32 v140, v151
	v_mul_f32_e32 v80, v80, v149
	v_mul_f32_e32 v81, v81, v149
	v_mul_f32_e32 v82, v82, v149
	v_mul_f32_e32 v83, v83, v149
	v_mul_f32_e32 v84, v84, v149
	v_mul_f32_e32 v85, v85, v149
	v_mul_f32_e32 v86, v86, v149
	v_mul_f32_e32 v87, v87, v149
	v_mul_f32_e32 v88, v88, v149
	v_mul_f32_e32 v89, v89, v149
	v_mul_f32_e32 v90, v90, v149
	v_mul_f32_e32 v91, v91, v149
	v_mul_f32_e32 v92, v92, v149
	v_mul_f32_e32 v93, v93, v149
	v_mul_f32_e32 v94, v94, v149
	v_mul_f32_e32 v95, v95, v149
	v_cvt_pk_bf16_f32 v132, v80, v81
	v_cvt_pk_bf16_f32 v133, v82, v83
	v_cvt_pk_bf16_f32 v134, v84, v85
	v_cvt_pk_bf16_f32 v135, v86, v87
	v_cvt_pk_bf16_f32 v136, v88, v89
	v_cvt_pk_bf16_f32 v137, v90, v91
	v_cvt_pk_bf16_f32 v138, v92, v93
	v_cvt_pk_bf16_f32 v139, v94, v95
	s_mov_b64 s[26:27], s[86:87]
	s_mov_b64 s[28:29], s[88:89]
	s_mov_b64 s[86:87], s[12:13]
	s_mov_b64 s[88:89], s[14:15]
	s_mov_b32 s4, s83
	s_mov_b32 s5, s84
	s_add_u32 s7, s7, 1
	s_cmp_lt_u32 s7, 2
	s_cbranch_scc1 .Lat738_loop
	global_store_dwordx2 v237, v[132:133], s[26:27]
	global_store_dwordx2 v237, v[134:135], s[26:27] offset:32
	global_store_dwordx2 v237, v[136:137], s[26:27] offset:64
	global_store_dwordx2 v237, v[138:139], s[26:27] offset:96
	s_mov_b64 s[90:91], exec
	s_mov_b64 exec, 0xffff
	global_store_dword v238, v140, s[28:29]
	s_mov_b64 exec, s[90:91]
	s_mov_b64 s[0:1], s[42:43]
	v_writelane_b32 v253, s0, 4
	s_waitcnt vmcnt(0)
	v_readlane_b32 s34, v252, 27
	v_readlane_b32 s36, v252, 29
	v_writelane_b32 v253, s1, 5
	v_readlane_b32 s70, v252, 31
	v_readlane_b32 s56, v253, 19
	v_readlane_b32 s16, v253, 21
	v_readlane_b32 s74, v252, 33
	v_readlane_b32 s76, v252, 35
	v_readlane_b32 s78, v252, 37
	s_mov_b64 s[6:7], 0
	v_readlane_b32 s85, v253, 23
	v_readlane_b32 s92, v253, 24
	v_readlane_b32 s35, v252, 28
	v_readlane_b32 s57, v253, 20
	v_readlane_b32 s17, v253, 22
	v_readlane_b32 s37, v252, 30
	v_readlane_b32 s71, v252, 32
	v_readlane_b32 s75, v252, 34
	v_readlane_b32 s77, v252, 36
	v_readlane_b32 s79, v252, 38
	s_barrier
	v_readlane_b32 s93, v253, 25

.LBB0_765:
	v_mov_b32_e32 v0, v170
	v_readlane_b32 s6, v253, 49
	v_readfirstlane_b32 s0, v0
	v_and_b32_e32 v63, 63, v0
	s_ashr_i32 s2, s0, 6
	v_mov_b32_e32 v1, v63
	s_lshl_b32 s0, s2, 3
	s_waitcnt vmcnt(2)
	v_ashrrev_i32_e32 v6, 3, v1
	v_add_u32_e32 v4, s0, v6
	v_lshrrev_b32_e32 v2, 1, v4
	v_xor_b32_e32 v2, v2, v1
	v_ashrrev_i32_e32 v5, 31, v4
	v_lshlrev_b64 v[4:5], 7, v[4:5]
	v_readlane_b32 s7, v253, 50
	v_lshlrev_b32_e32 v2, 4, v2
	s_lshl_b32 s35, s2, 10
	s_add_i32 s4, 0, 0x18000
	v_lshl_add_u64 v[4:5], s[6:7], 0, v[4:5]
	v_and_b32_e32 v2, 0x70, v2
	s_add_i32 s3, s4, s35
	s_add_i32 s5, s2, 8
	v_lshl_add_u64 v[4:5], v[4:5], 0, v[2:3]
	v_writelane_b32 v253, s3, 4
	s_mov_b32 m0, s3
	s_bitset0_b32 m0, 16
	s_bitset1_b32 m0, 14
	s_lshl_b32 s3, s5, 3
	global_load_lds_dwordx4 v[4:5], off nt
	v_add_u32_e32 v4, s3, v6
	v_lshrrev_b32_e32 v2, 1, v4
	v_xor_b32_e32 v2, v2, v1
	v_ashrrev_i32_e32 v5, 31, v4
	v_lshlrev_b64 v[4:5], 7, v[4:5]
	v_lshlrev_b32_e32 v2, 4, v2
	s_lshl_b32 s10, s5, 10
	v_lshl_add_u64 v[4:5], s[6:7], 0, v[4:5]
	v_and_b32_e32 v2, 0x70, v2
	s_add_i32 s4, s4, s10
	v_lshl_add_u64 v[4:5], v[4:5], 0, v[2:3]
	s_mov_b32 m0, s4
	s_bitset0_b32 m0, 16
	s_bitset1_b32 m0, 14
	v_ashrrev_i32_e32 v6, 4, v1
	s_lshl_b32 s12, s2, 2
	v_writelane_b32 v253, s4, 1
	global_load_lds_dwordx4 v[4:5], off nt
	v_add_u32_e32 v4, s12, v6
	v_xor_b32_e32 v2, v4, v1
	v_ashrrev_i32_e32 v5, 31, v4
	v_readlane_b32 s6, v253, 32
	v_lshlrev_b64 v[4:5], 15, v[4:5]
	v_readlane_b32 s7, v253, 33
	v_lshlrev_b32_e32 v2, 4, v2
	s_add_i32 s4, 0, 0x1c000
	v_lshl_add_u64 v[4:5], s[6:7], 0, v[4:5]
	v_and_b32_e32 v2, 0xf0, v2
	s_add_i32 s8, s4, s35
	v_lshl_add_u64 v[4:5], v[4:5], 0, v[2:3]
	s_mov_b32 m0, s8
	s_lshl_b32 s14, s5, 2
	global_load_lds_dwordx4 v[4:5], off nt
	v_add_u32_e32 v4, s14, v6
	v_xor_b32_e32 v1, v4, v1
	v_ashrrev_i32_e32 v5, 31, v4
	v_lshlrev_b64 v[4:5], 15, v[4:5]
	v_lshlrev_b32_e32 v1, 4, v1
	v_lshl_add_u64 v[4:5], s[6:7], 0, v[4:5]
	v_and_b32_e32 v2, 0xf0, v1
	s_add_i32 s4, s4, s10
	v_lshl_add_u64 v[4:5], v[4:5], 0, v[2:3]
	s_mov_b32 m0, s4
	v_mov_b32_e32 v1, v63
	global_load_lds_dwordx4 v[4:5], off nt
	v_writelane_b32 v253, s8, 13
	v_ashrrev_i32_e32 v6, 3, v1
	v_add_u32_e32 v4, s0, v6
	v_writelane_b32 v253, s4, 2
	v_lshrrev_b32_e32 v2, 1, v4
	v_xor_b32_e32 v2, v2, v1
	v_ashrrev_i32_e32 v5, 31, v4
	v_readlane_b32 s4, v253, 54
	v_lshlrev_b64 v[4:5], 7, v[4:5]
	v_readlane_b32 s5, v253, 55
	v_lshlrev_b32_e32 v2, 4, v2
	v_and_b32_e32 v2, 0x70, v2
	v_lshl_add_u64 v[4:5], s[4:5], 0, v[4:5]
	s_add_i32 s16, s35, 0
	v_lshl_add_u64 v[4:5], v[4:5], 0, v[2:3]
	s_mov_b32 m0, s16
	s_add_i32 s17, s10, 0
	global_load_lds_dwordx4 v[4:5], off nt
	v_add_u32_e32 v4, s3, v6
	v_lshrrev_b32_e32 v2, 1, v4
	v_xor_b32_e32 v2, v2, v1
	v_ashrrev_i32_e32 v5, 31, v4
	v_lshlrev_b64 v[4:5], 7, v[4:5]
	v_lshlrev_b32_e32 v2, 4, v2
	v_lshl_add_u64 v[4:5], s[4:5], 0, v[4:5]
	v_and_b32_e32 v2, 0x70, v2
	v_lshl_add_u64 v[4:5], v[4:5], 0, v[2:3]
	s_mov_b32 m0, s17
	v_ashrrev_i32_e32 v6, 4, v1
	global_load_lds_dwordx4 v[4:5], off nt
	v_add_u32_e32 v4, s12, v6
	v_xor_b32_e32 v2, v4, v1
	v_ashrrev_i32_e32 v5, 31, v4
	v_readlane_b32 s4, v253, 37
	v_lshlrev_b64 v[4:5], 15, v[4:5]
	v_readlane_b32 s5, v253, 38
	v_lshlrev_b32_e32 v2, 4, v2
	v_and_b32_e32 v2, 0xf0, v2
	v_lshl_add_u64 v[4:5], s[4:5], 0, v[4:5]
	s_add_i32 s6, s16, 0x4000
	v_lshl_add_u64 v[4:5], v[4:5], 0, v[2:3]
	s_mov_b32 m0, s6
	s_bitset0_b32 m0, 14
	s_bitset1_b32 m0, 16
	v_writelane_b32 v254, s6, 58
	global_load_lds_dwordx4 v[4:5], off nt
	v_add_u32_e32 v4, s14, v6
	v_ashrrev_i32_e32 v5, 31, v4
	v_xor_b32_e32 v1, v4, v1
	v_lshlrev_b64 v[4:5], 15, v[4:5]
	v_lshl_add_u64 v[4:5], s[4:5], 0, v[4:5]
	s_add_i32 s4, s17, 0x4000
	v_and_b32_e32 v64, 15, v0
	v_lshlrev_b32_e32 v1, 4, v1
	v_writelane_b32 v254, s4, 59
	s_mov_b32 m0, s4
	s_bitset0_b32 m0, 14
	s_bitset1_b32 m0, 16
	v_readlane_b32 s4, v253, 56
	v_and_b32_e32 v2, 0xf0, v1
	s_lshl_b32 s87, s2, 4
	v_or_b32_e32 v1, s4, v64
	v_add_u32_e32 v28, s87, v1
	v_lshl_add_u64 v[4:5], v[4:5], 0, v[2:3]
	v_ashrrev_i32_e32 v29, 31, v28
	v_readlane_b32 s4, v253, 8
	global_load_lds_dwordx4 v[4:5], off nt
	v_lshlrev_b64 v[4:5], 7, v[28:29]
	v_readlane_b32 s5, v253, 9
	v_and_b32_e32 v2, 48, v0
	s_cmp_gt_i32 s2, 3
	v_lshl_add_u64 v[4:5], s[4:5], 0, v[4:5]
	v_lshl_add_u64 v[4:5], v[4:5], 0, v[2:3]
	global_load_dwordx4 v[8:11], v[4:5], off
	s_nop 0
	global_load_dwordx4 v[4:7], v[4:5], off offset:64
	s_cbranch_scc1 .LBB0_767
.LBB0_767:
	v_readlane_b32 s4, v254, 17
	s_lshl_b32 s5, s2, 1
	s_add_i32 s21, s87, s4
	s_and_b32 s23, s87, 0x70
	s_add_i32 s6, s5, 2
	s_add_i32 s7, s5, 4
	s_add_i32 s8, s5, 6
	s_add_i32 s9, s5, 8
	s_add_i32 s11, s5, 10
	s_add_i32 s13, s5, 12
	s_add_i32 s15, s5, 14
	s_cmp_gt_u32 s5, 0xffffffef
	s_mov_b32 s29, 0x8000
	s_cselect_b32 s1, s29, 0x10000
	s_mov_b32 s20, 0x18000
	s_cselect_b32 s18, 0x18000, 0
	s_cselect_b32 s63, 0, 0x8000
	v_writelane_b32 v254, s1, 60
	s_cselect_b32 s1, 0x10000, s20
	s_cmp_lt_u32 s15, 16
	v_writelane_b32 v254, s1, 61
	s_cselect_b32 s1, s29, 0x10000
	s_cselect_b32 s24, 0x18000, 0
	s_cselect_b32 s48, 0, 0x8000
	v_writelane_b32 v254, s1, 62
	s_cselect_b32 s1, 0x10000, s20
	s_cmp_lt_u32 s13, 16
	v_writelane_b32 v254, s1, 63
	s_cselect_b32 s1, s29, 0x10000
	s_cselect_b32 s27, 0x18000, 0
	s_cselect_b32 s46, 0, 0x8000
	v_writelane_b32 v255, s1, 0
	s_cselect_b32 s1, 0x10000, s20
	s_cmp_lt_u32 s11, 16
	v_writelane_b32 v255, s1, 1
	s_cselect_b32 s1, s29, 0x10000
	s_cselect_b32 s36, 0x18000, 0
	s_cselect_b32 s45, 0, 0x8000
	v_writelane_b32 v255, s1, 2
	s_cselect_b32 s1, 0x10000, s20
	s_cmp_lt_u32 s9, 16
	v_writelane_b32 v255, s1, 3
	s_cselect_b32 s39, 0x18000, 0
	s_cselect_b32 s47, 0, 0x8000
	s_cselect_b32 s49, s29, 0x10000
	s_cselect_b32 s1, 0x10000, s20
	s_cmp_lt_u32 s8, 16
	v_writelane_b32 v255, s1, 4
	s_cselect_b32 s50, 0x18000, 0
	s_cselect_b32 s51, 0, 0x8000
	s_cselect_b32 s54, s29, 0x10000
	s_cselect_b32 s1, 0x10000, s20
	s_cmp_lt_u32 s7, 16
	s_cselect_b32 s55, 0x18000, 0
	s_cselect_b32 s58, 0, 0x8000
	s_cselect_b32 s59, s29, 0x10000
	s_cselect_b32 s66, 0x10000, s20
	s_cmp_lt_u32 s6, 16
	s_cselect_b32 s52, 0x18000, 0
	s_cselect_b32 s62, 0, 0x8000
	s_cselect_b32 s67, s29, 0x10000
	s_cselect_b32 s68, 0x10000, s20
	s_cmp_lt_u32 s5, 16
	s_cselect_b32 s53, 0x18000, 0
	s_cselect_b32 s69, 0, 0x8000
	s_cselect_b32 s70, s29, 0x10000
	s_cselect_b32 s71, 0x10000, s20
	s_cmp_gt_i32 s2, -1
	s_cselect_b32 s74, 0x10000, s29
	s_cselect_b32 s75, s20, 0x10000
	s_cmp_gt_i32 s2, 0
	s_cselect_b32 s56, 0, 0x18000
	s_cselect_b32 s76, 0x8000, 0
	s_cselect_b32 vcc_lo, 0x10000, s29
	s_cselect_b32 vcc_hi, s20, 0x10000
	s_cmp_gt_i32 s2, 1
	s_cselect_b32 s57, 0, 0x18000
	s_cselect_b32 s77, 0x8000, 0
	s_cselect_b32 s85, 0x10000, s29
	s_cselect_b32 s44, s20, 0x10000
	s_cmp_gt_i32 s2, 2
	s_cselect_b32 s60, 0, 0x18000
	s_cselect_b32 s78, 0x8000, 0
	s_cselect_b32 s83, 0x10000, s29
	s_cselect_b32 s88, s20, 0x10000
	s_cmp_gt_i32 s2, 3
	s_cselect_b32 s61, 0, 0x18000
	s_cselect_b32 s79, 0x8000, 0
	s_cselect_b32 s80, 0x10000, s29
	s_cselect_b32 s89, s20, 0x10000
	s_cmp_gt_i32 s2, 4
	s_cselect_b32 s64, 0, 0x18000
	s_cselect_b32 s82, 0x8000, 0
	s_cselect_b32 s90, 0x10000, s29
	s_cselect_b32 s91, s20, 0x10000
	s_cmp_gt_i32 s2, 5
	s_cselect_b32 s65, 0, 0x18000
	s_cselect_b32 s84, 0x8000, 0
	s_cselect_b32 s92, 0x10000, s29
	s_cselect_b32 s4, s20, 0x10000
	s_cmp_gt_i32 s2, 6
	s_cselect_b32 s30, 0, 0x18000
	s_cselect_b32 s86, 0x8000, 0
	s_cselect_b32 s94, 0x10000, s29
	s_cselect_b32 s95, s20, 0x10000
	s_cmp_gt_i32 s2, 7
	s_cselect_b32 s26, 0, 0x18000
	s_cselect_b32 s96, 0x8000, 0
	s_cselect_b32 s97, 0x10000, s29
	s_cselect_b32 s20, s20, 0x10000
	s_add_i32 s38, s56, 0
	s_ashr_i32 s56, s2, 31
	s_and_b32 s56, s56, 0x18000
	v_writelane_b32 v255, s1, 5
	s_add_i32 s56, s56, 0
	v_writelane_b32 v255, s56, 6
	s_add_i32 s53, s53, 0
	v_writelane_b32 v255, s53, 7
	s_add_i32 s52, s52, 0
	v_writelane_b32 v255, s52, 8
	s_and_b32 s52, s5, 14
	s_add_i32 s5, s55, 0
	v_writelane_b32 v255, s5, 9
	s_add_i32 s5, s50, 0
	v_writelane_b32 v255, s5, 10
	s_add_i32 s5, s39, 0
	v_writelane_b32 v255, s5, 11
	s_add_i32 s5, s36, 0
	v_writelane_b32 v255, s5, 12
	s_add_i32 s5, s27, 0
	v_writelane_b32 v255, s5, 13
	s_add_i32 s5, s24, 0
	v_writelane_b32 v255, s5, 14
	s_add_i32 s5, s18, 0
	v_writelane_b32 v255, s5, 15
	s_add_i32 s5, s96, 0
	v_writelane_b32 v255, s5, 16
	s_add_i32 s5, s86, 0
	v_writelane_b32 v255, s5, 17
	s_add_i32 s5, s84, 0
	v_writelane_b32 v255, s5, 18
	s_add_i32 s5, s82, 0
	v_writelane_b32 v255, s5, 19
	s_add_i32 s5, s79, 0
	v_writelane_b32 v255, s5, 20
	s_add_i32 s5, s78, 0
	v_writelane_b32 v255, s5, 21
	s_add_i32 s5, s77, 0
	v_writelane_b32 v255, s5, 22
	s_add_i32 s5, s76, 0
	v_writelane_b32 v255, s5, 23
	s_add_i32 s5, s87, 48
	v_writelane_b32 v255, s5, 24
	s_and_b32 s78, s5, 0x70
	s_add_i32 s5, s87, 0x50
	v_writelane_b32 v255, s5, 25
	s_and_b32 s82, s5, 0x70
	s_add_i32 s5, s87, 0x60
	s_add_i32 s93, s87, 16
	s_add_i32 s19, s87, 32
	v_writelane_b32 v255, s5, 26
	s_and_b32 s84, s5, 0x70
	s_add_i32 s5, s87, 0x70
	s_add_i32 s29, s26, 0
	s_and_b32 s26, s93, 0x70
	s_add_i32 s1, s30, 0
	s_and_b32 s30, s19, 0x70
	s_add_i32 s25, s65, 0
	s_add_i32 s28, s64, 0
	s_add_i32 s31, s61, 0
	s_add_i32 s34, s60, 0
	s_add_i32 s37, s57, 0
	s_and_b32 s53, s6, 14
	s_and_b32 s56, s7, 14
	s_and_b32 s57, s8, 14
	s_and_b32 s60, s9, 14
	s_and_b32 s61, s11, 14
	s_and_b32 s64, s13, 14
	s_and_b32 s65, s15, 14
	s_xor_b32 s79, s23, 64
	s_and_b32 s86, s5, 0x70
	s_cmp_lt_i32 s2, 0
	s_cselect_b32 s2, 0, 0x8000
	v_writelane_b32 v255, s5, 27
	s_add_i32 s2, s2, 0
	v_writelane_b32 v255, s2, 28
	s_add_i32 s2, s69, 0
	v_writelane_b32 v255, s2, 29
	s_add_i32 s2, s62, 0
	v_writelane_b32 v255, s2, 30
	s_add_i32 s2, s58, 0
	v_writelane_b32 v255, s2, 31
	s_add_i32 s2, s51, 0
	v_writelane_b32 v255, s2, 32
	s_add_i32 s2, s47, 0
	v_writelane_b32 v255, s2, 33
	s_add_i32 s2, s45, 0
	v_writelane_b32 v255, s2, 34
	s_add_i32 s2, s46, 0
	v_writelane_b32 v255, s2, 35
	s_add_i32 s2, s48, 0
	v_writelane_b32 v255, s2, 36
	s_add_i32 s2, s63, 0
	v_writelane_b32 v255, s2, 37
	s_add_i32 s2, s97, 0
	v_writelane_b32 v255, s2, 38
	s_add_i32 s2, s94, 0
	v_writelane_b32 v255, s2, 39
	s_add_i32 s2, s92, 0
	v_writelane_b32 v254, s2, 54
	s_add_i32 s2, s90, 0
	v_writelane_b32 v255, s2, 40
	s_add_i32 s77, s4, 0
	v_readlane_b32 s4, v255, 5
	s_add_i32 s63, s66, 0
	s_add_i32 s66, s4, 0
	v_readlane_b32 s4, v255, 4
	s_add_i32 s11, s67, 0
	s_add_i32 s67, s4, 0
	v_readlane_b32 s4, v255, 3
	v_readlane_b32 s5, v255, 2
	s_add_i32 s62, s68, 0
	s_add_i32 s68, s4, 0
	v_readlane_b32 s4, v255, 1
	s_add_i32 s27, s5, 0
	v_readlane_b32 s5, v255, 0
	s_add_i32 s69, s4, 0
	v_readlane_b32 s4, v254, 63
	v_bfe_u32 v65, v0, 4, 2
	v_readlane_b32 s6, v253, 8
	s_add_i32 s2, s70, 0
	s_add_i32 s96, s5, 0
	v_readlane_b32 s5, v254, 62
	s_add_i32 s70, s4, 0
	v_readlane_b32 s4, v254, 61
	v_lshlrev_b32_e32 v2, 3, v65
	v_readlane_b32 s7, v253, 9
	s_add_i32 s13, s59, 0
	s_add_i32 s97, s5, 0
	v_readlane_b32 s5, v254, 60
	s_add_i32 s59, s71, 0
	s_add_i32 s71, s4, 0
	v_readlane_b32 s4, v253, 36
	v_lshlrev_b32_e32 v20, 2, v65
	v_lshl_add_u64 v[22:23], s[6:7], 0, v[2:3]
	s_mov_b32 s92, s29
	s_add_i32 s80, s80, 0
	s_add_i32 s83, s83, 0
	s_add_i32 s85, s85, 0
	s_add_i32 s18, vcc_lo, 0
	s_add_i32 s76, s74, 0
	s_add_i32 s15, s54, 0
	s_add_i32 s24, s49, 0
	s_add_i32 s94, s5, 0
	s_add_i32 s36, s20, 0
	s_add_i32 s95, s95, 0
	s_add_i32 s39, s91, 0
	s_add_i32 s50, s89, 0
	s_add_i32 s51, s88, 0
	s_add_i32 s54, s44, 0
	s_add_i32 s55, vcc_hi, 0
	s_add_i32 s58, s75, 0
	v_mov_b32_e32 v2, 0
	v_mov_b32_e32 v29, s4
	v_mov_b32_e32 v30, 0
	s_mov_b32 s74, 0
	v_cmp_gt_u32_e64 s[4:5], 16, v63
	s_mov_b64 s[44:45], 0
	s_mov_b64 s[8:9], -1
	v_readlane_b32 s46, v254, 15
	s_mov_b32 s6, 0
	v_readlane_b32 s47, v254, 16

.Lat768_i3_nomask:
	v_max3_f32 v245, v44, v45, v46
	v_max3_f32 v245, v245, v47, v48
	v_max3_f32 v245, v245, v49, v50
	v_max3_f32 v245, v245, v51, v52
	v_max3_f32 v245, v245, v53, v54
	v_max3_f32 v245, v245, v55, v56
	v_max3_f32 v245, v245, v57, v58
	v_max3_f32 v245, v245, v59, v60
	v_max3_f32 v245, v245, v61, v62
	v_max3_f32 v245, v245, v63, v64
	v_max3_f32 v245, v245, v65, v66
	v_max3_f32 v245, v245, v67, v68
	v_max3_f32 v245, v245, v69, v70
	v_max3_f32 v245, v245, v71, v72
	v_max3_f32 v245, v245, v73, v74
	v_max3_f32 v245, v245, v75, v76
	v_max3_f32 v245, v245, v77, v78
	v_max_f32_e32 v245, v245, v79
	v_mov_b32_e32 v148, v245
	s_nop 1
	v_permlane16_swap_b32 v245, v148
	v_max_f32_e32 v245, v245, v148
	v_mov_b32_e32 v148, v245
	s_nop 1
	v_permlane32_swap_b32 v245, v148
	v_max_f32_e32 v245, v245, v148
	v_sub_f32_e32 v44, v44, v245
	v_sub_f32_e32 v45, v45, v245
	v_sub_f32_e32 v46, v46, v245
	v_sub_f32_e32 v47, v47, v245
	v_exp_f32_e32 v44, v44
	v_exp_f32_e32 v45, v45
	v_exp_f32_e32 v46, v46
	v_exp_f32_e32 v47, v47
	v_sub_f32_e32 v48, v48, v245
	v_sub_f32_e32 v49, v49, v245
	v_sub_f32_e32 v50, v50, v245
	v_sub_f32_e32 v51, v51, v245
	v_exp_f32_e32 v48, v48
	v_exp_f32_e32 v49, v49
	v_exp_f32_e32 v50, v50
	v_exp_f32_e32 v51, v51
	v_mov_b32_e32 v149, v44
	v_mov_b32_e32 v150, v45
	v_mov_b32_e32 v151, v46
	v_mov_b32_e32 v152, v47
	v_cvt_pk_bf16_f32 v44, v44, v45
	v_cvt_pk_bf16_f32 v45, v46, v47
	v_sub_f32_e32 v52, v52, v245
	v_sub_f32_e32 v53, v53, v245
	v_sub_f32_e32 v54, v54, v245
	v_sub_f32_e32 v55, v55, v245
	v_exp_f32_e32 v52, v52
	v_exp_f32_e32 v53, v53
	v_exp_f32_e32 v54, v54
	v_exp_f32_e32 v55, v55
	v_add_f32_e32 v149, v149, v48
	v_add_f32_e32 v150, v150, v49
	v_add_f32_e32 v151, v151, v50
	v_add_f32_e32 v152, v152, v51
	v_cvt_pk_bf16_f32 v46, v48, v49
	v_cvt_pk_bf16_f32 v47, v50, v51
	v_sub_f32_e32 v56, v56, v245
	v_sub_f32_e32 v57, v57, v245
	v_sub_f32_e32 v58, v58, v245
	v_sub_f32_e32 v59, v59, v245
	v_exp_f32_e32 v56, v56
	v_exp_f32_e32 v57, v57
	v_exp_f32_e32 v58, v58
	v_exp_f32_e32 v59, v59
	v_add_f32_e32 v149, v149, v52
	v_add_f32_e32 v150, v150, v53
	v_add_f32_e32 v151, v151, v54
	v_add_f32_e32 v152, v152, v55
	v_cvt_pk_bf16_f32 v52, v52, v53
	v_cvt_pk_bf16_f32 v53, v54, v55
	v_sub_f32_e32 v60, v60, v245
	v_sub_f32_e32 v61, v61, v245
	v_sub_f32_e32 v62, v62, v245
	v_sub_f32_e32 v63, v63, v245
	v_exp_f32_e32 v60, v60
	v_exp_f32_e32 v61, v61
	v_exp_f32_e32 v62, v62
	v_exp_f32_e32 v63, v63
	v_add_f32_e32 v149, v149, v56
	v_add_f32_e32 v150, v150, v57
	v_add_f32_e32 v151, v151, v58
	v_add_f32_e32 v152, v152, v59
	v_cvt_pk_bf16_f32 v54, v56, v57
	v_cvt_pk_bf16_f32 v55, v58, v59
	v_sub_f32_e32 v64, v64, v245
	v_sub_f32_e32 v65, v65, v245
	v_sub_f32_e32 v66, v66, v245
	v_sub_f32_e32 v67, v67, v245
	v_exp_f32_e32 v64, v64
	v_exp_f32_e32 v65, v65
	v_exp_f32_e32 v66, v66
	v_exp_f32_e32 v67, v67
	v_add_f32_e32 v149, v149, v60
	v_add_f32_e32 v150, v150, v61
	v_add_f32_e32 v151, v151, v62
	v_add_f32_e32 v152, v152, v63
	v_cvt_pk_bf16_f32 v60, v60, v61
	v_cvt_pk_bf16_f32 v61, v62, v63
	v_sub_f32_e32 v68, v68, v245
	v_sub_f32_e32 v69, v69, v245
	v_sub_f32_e32 v70, v70, v245
	v_sub_f32_e32 v71, v71, v245
	v_exp_f32_e32 v68, v68
	v_exp_f32_e32 v69, v69
	v_exp_f32_e32 v70, v70
	v_exp_f32_e32 v71, v71
	v_add_f32_e32 v149, v149, v64
	v_add_f32_e32 v150, v150, v65
	v_add_f32_e32 v151, v151, v66
	v_add_f32_e32 v152, v152, v67
	v_cvt_pk_bf16_f32 v62, v64, v65
	v_cvt_pk_bf16_f32 v63, v66, v67
	v_sub_f32_e32 v72, v72, v245
	v_sub_f32_e32 v73, v73, v245
	v_sub_f32_e32 v74, v74, v245
	v_sub_f32_e32 v75, v75, v245
	v_exp_f32_e32 v72, v72
	v_exp_f32_e32 v73, v73
	v_exp_f32_e32 v74, v74
	v_exp_f32_e32 v75, v75
	v_add_f32_e32 v149, v149, v68
	v_add_f32_e32 v150, v150, v69
	v_add_f32_e32 v151, v151, v70
	v_add_f32_e32 v152, v152, v71
	v_cvt_pk_bf16_f32 v68, v68, v69
	v_cvt_pk_bf16_f32 v69, v70, v71
	v_sub_f32_e32 v76, v76, v245
	v_sub_f32_e32 v77, v77, v245
	v_sub_f32_e32 v78, v78, v245
	v_sub_f32_e32 v79, v79, v245
	v_exp_f32_e32 v76, v76
	v_exp_f32_e32 v77, v77
	v_exp_f32_e32 v78, v78
	v_exp_f32_e32 v79, v79
	v_add_f32_e32 v149, v149, v72
	v_add_f32_e32 v150, v150, v73
	v_add_f32_e32 v151, v151, v74
	v_add_f32_e32 v152, v152, v75
	v_cvt_pk_bf16_f32 v70, v72, v73
	v_cvt_pk_bf16_f32 v71, v74, v75
	s_nop 0
	v_add_f32_e32 v149, v149, v76
	v_add_f32_e32 v150, v150, v77
	v_add_f32_e32 v151, v151, v78
	v_add_f32_e32 v152, v152, v79
	v_cvt_pk_bf16_f32 v76, v76, v77
	v_cvt_pk_bf16_f32 v77, v78, v79
	v_mov_b32_e32 v78, 0
	v_mov_b32_e32 v79, 0
	v_add_f32_e32 v149, v149, v150
	v_add_f32_e32 v151, v151, v152
	v_add_f32_e32 v246, v149, v151
	s_waitcnt lgkmcnt(0)
	v_mfma_f32_16x16x32_bf16 v[80:83], v[4:7], v[44:47], 0
	v_mfma_f32_16x16x32_bf16 v[84:87], v[8:11], v[44:47], 0
	v_mfma_f32_16x16x32_bf16 v[88:91], v[12:15], v[44:47], 0
	v_mfma_f32_16x16x32_bf16 v[92:95], v[16:19], v[44:47], 0
	ds_read_b64 v[4:5], v225 offset:32768
	ds_read_b64 v[8:9], v225 offset:36864
	ds_read_b64 v[12:13], v225 offset:40960
	ds_read_b64 v[16:17], v225 offset:45056
	ds_read_b64 v[6:7], v226 offset:32768
	ds_read_b64 v[10:11], v226 offset:36864
	ds_read_b64 v[14:15], v226 offset:40960
	ds_read_b64 v[18:19], v226 offset:45056
	v_mfma_f32_16x16x32_bf16 v[80:83], v[20:23], v[52:55], v[80:83]
	v_mfma_f32_16x16x32_bf16 v[84:87], v[24:27], v[52:55], v[84:87]
	v_mfma_f32_16x16x32_bf16 v[88:91], v[28:31], v[52:55], v[88:91]
	v_mfma_f32_16x16x32_bf16 v[92:95], v[32:35], v[52:55], v[92:95]
	ds_read_b64 v[20:21], v227 offset:32768
	ds_read_b64 v[24:25], v227 offset:36864
	ds_read_b64 v[28:29], v227 offset:40960
	ds_read_b64 v[32:33], v227 offset:45056
	ds_read_b64 v[22:23], v228 offset:32768
	ds_read_b64 v[26:27], v228 offset:36864
	ds_read_b64 v[30:31], v228 offset:40960
	ds_read_b64 v[34:35], v228 offset:45056
	s_waitcnt lgkmcnt(8)
	v_mfma_f32_16x16x32_bf16 v[80:83], v[4:7], v[60:63], v[80:83]
	v_mfma_f32_16x16x32_bf16 v[84:87], v[8:11], v[60:63], v[84:87]
	v_mfma_f32_16x16x32_bf16 v[88:91], v[12:15], v[60:63], v[88:91]
	v_mfma_f32_16x16x32_bf16 v[92:95], v[16:19], v[60:63], v[92:95]
	ds_read_b64 v[4:5], v229 offset:32768
	ds_read_b64 v[8:9], v229 offset:36864
	ds_read_b64 v[12:13], v229 offset:40960
	ds_read_b64 v[16:17], v229 offset:45056
	v_mov_b32_e32 v6, 0
	v_mov_b32_e32 v7, 0
	v_mov_b32_e32 v10, 0
	v_mov_b32_e32 v11, 0
	v_mov_b32_e32 v14, 0
	v_mov_b32_e32 v15, 0
	v_mov_b32_e32 v18, 0
	v_mov_b32_e32 v19, 0
	s_waitcnt lgkmcnt(4)
	v_mfma_f32_16x16x32_bf16 v[80:83], v[20:23], v[68:71], v[80:83]
	v_mfma_f32_16x16x32_bf16 v[84:87], v[24:27], v[68:71], v[84:87]
	v_mfma_f32_16x16x32_bf16 v[88:91], v[28:31], v[68:71], v[88:91]
	v_mfma_f32_16x16x32_bf16 v[92:95], v[32:35], v[68:71], v[92:95]
	s_waitcnt lgkmcnt(0)
	v_mfma_f32_16x16x32_bf16 v[80:83], v[4:7], v[76:79], v[80:83]
	v_mfma_f32_16x16x32_bf16 v[84:87], v[8:11], v[76:79], v[84:87]
	v_mfma_f32_16x16x32_bf16 v[88:91], v[12:15], v[76:79], v[88:91]
	v_mfma_f32_16x16x32_bf16 v[92:95], v[16:19], v[76:79], v[92:95]
	v_mov_b32_e32 v148, v246
	s_nop 1
	v_permlane16_swap_b32 v246, v148
	v_add_f32_e32 v246, v246, v148
	v_mov_b32_e32 v148, v246
	s_nop 1
	v_permlane32_swap_b32 v246, v148
	v_add_f32_e32 v246, v246, v148
	v_rcp_f32_e32 v149, v246
	v_log_f32_e32 v150, v246
	s_nop 0
	v_add_f32_e32 v151, v245, v150
	v_mul_f32_e32 v151, 0x3f317218, v151
	v_mov_b32_e32 v140, v151
	v_mul_f32_e32 v80, v80, v149
	v_mul_f32_e32 v81, v81, v149
	v_mul_f32_e32 v82, v82, v149
	v_mul_f32_e32 v83, v83, v149
	v_mul_f32_e32 v84, v84, v149
	v_mul_f32_e32 v85, v85, v149
	v_mul_f32_e32 v86, v86, v149
	v_mul_f32_e32 v87, v87, v149
	v_mul_f32_e32 v88, v88, v149
	v_mul_f32_e32 v89, v89, v149
	v_mul_f32_e32 v90, v90, v149
	v_mul_f32_e32 v91, v91, v149
	v_mul_f32_e32 v92, v92, v149
	v_mul_f32_e32 v93, v93, v149
	v_mul_f32_e32 v94, v94, v149
	v_mul_f32_e32 v95, v95, v149
	v_cvt_pk_bf16_f32 v132, v80, v81
	v_cvt_pk_bf16_f32 v133, v82, v83
	v_cvt_pk_bf16_f32 v134, v84, v85
	v_cvt_pk_bf16_f32 v135, v86, v87
	v_cvt_pk_bf16_f32 v136, v88, v89
	v_cvt_pk_bf16_f32 v137, v90, v91
	v_cvt_pk_bf16_f32 v138, v92, v93
	v_cvt_pk_bf16_f32 v139, v94, v95
	s_mov_b64 s[26:27], s[86:87]
	s_mov_b64 s[28:29], s[88:89]
	s_mov_b64 s[86:87], s[12:13]
	s_mov_b64 s[88:89], s[14:15]
	s_mov_b32 s4, s83
	s_mov_b32 s5, s84
	s_add_u32 s7, s7, 1
	s_cmp_lt_u32 s7, 2
	s_cbranch_scc1 .Lat768_loop
	global_store_dwordx2 v237, v[132:133], s[26:27]
	global_store_dwordx2 v237, v[134:135], s[26:27] offset:32
	global_store_dwordx2 v237, v[136:137], s[26:27] offset:64
	global_store_dwordx2 v237, v[138:139], s[26:27] offset:96
	s_mov_b64 s[90:91], exec
	s_mov_b64 exec, 0xffff
	global_store_dword v238, v140, s[28:29]
	s_mov_b64 exec, s[90:91]
	v_readlane_b32 s0, v253, 62
	v_readlane_b32 s1, v253, 63
	s_waitcnt vmcnt(0)
	v_readlane_b32 s34, v252, 27
	v_writelane_b32 v253, s0, 4
	v_readlane_b32 s36, v252, 29
	v_readlane_b32 s70, v252, 31
	v_writelane_b32 v253, s1, 5
	v_readlane_b32 s74, v252, 33
	v_readlane_b32 s56, v253, 19
	v_readlane_b32 s16, v253, 21
	v_readlane_b32 s76, v252, 35
	v_readlane_b32 s78, v252, 37
	s_barrier
	v_readlane_b32 s35, v252, 28
	v_readlane_b32 s57, v253, 20
	v_readlane_b32 s17, v253, 22
	v_readlane_b32 s37, v252, 30
	v_readlane_b32 s71, v252, 32
	v_readlane_b32 s75, v252, 34
	v_readlane_b32 s77, v252, 36
	v_readlane_b32 s79, v252, 38

.LBB0_841:
	s_or_b64 exec, exec, s[4:5]
	s_waitcnt lgkmcnt(0)
	v_mov_b32_e32 v0, v170
	s_barrier
	v_readlane_b32 s1, v253, 61
	v_readfirstlane_b32 s0, v0
	s_ashr_i32 s4, s0, 6
	v_and_b32_e32 v77, 15, v0
	s_lshl_b32 s0, s4, 4
	v_or_b32_e32 v1, s0, v77
	v_lshl_add_u32 v24, v1, 2, s1
	v_ashrrev_i32_e32 v25, 31, v24
	v_readlane_b32 s2, v254, 0
	v_lshlrev_b64 v[12:13], 7, v[24:25]
	v_readlane_b32 s3, v254, 1
	v_bfe_u32 v78, v0, 4, 2
	v_lshlrev_b32_e32 v2, 3, v78
	v_lshl_add_u64 v[4:5], s[2:3], 0, v[12:13]
	v_readlane_b32 s2, v253, 6
	v_readlane_b32 s3, v253, 7
	v_and_b32_e32 v6, 48, v0
	v_mov_b32_e32 v7, v3
	v_lshl_add_u64 v[14:15], v[24:25], 2, s[2:3]
	v_readlane_b32 s2, v253, 8
	v_readlane_b32 s3, v253, 9
	v_lshl_add_u64 v[4:5], v[4:5], 0, v[6:7]
	global_load_dwordx4 v[8:11], v[4:5], off
	s_nop 0
	global_load_dwordx4 v[4:7], v[4:5], off offset:64
	v_lshl_add_u64 v[12:13], s[2:3], 0, v[12:13]
	v_lshl_add_u64 v[12:13], v[12:13], 0, v[2:3]
	global_load_dword v25, v[14:15], off
	global_load_dwordx2 v[32:33], v[12:13], off
	global_load_dwordx2 v[30:31], v[12:13], off offset:32
	global_load_dwordx2 v[28:29], v[12:13], off offset:64
	global_load_dwordx2 v[26:27], v[12:13], off offset:96
	s_cmp_gt_i32 s4, 3
	s_cbranch_scc1 .LBB0_843
.LBB0_843:
	s_add_i32 s5, s4, 8
	s_lshl_b32 s6, s4, 1
	s_lshl_b32 s1, s4, 3
	s_lshl_b32 s2, s4, 10
	s_lshl_b32 s3, s5, 3
	s_lshl_b32 s8, s5, 10
	s_lshl_b32 s9, s4, 2
	s_lshl_b32 s10, s5, 2
	s_and_b32 s11, s0, 0x70
	s_add_i32 s7, s6, 2
	s_add_i32 s12, s6, 4
	s_add_i32 s13, s6, 6
	s_add_i32 s14, s5, s4
	s_add_i32 s15, s6, 10
	s_add_i32 s16, s6, 12
	s_add_i32 s17, s6, 14
	s_cmp_gt_u32 s6, 0xffffffef
	s_mov_b32 s94, 0x8000
	s_mov_b32 s29, 0x18000
	s_cselect_b32 s18, 0x18000, 0
	s_cselect_b32 s19, 0, 0x8000
	s_cselect_b32 s20, s94, 0x10000
	s_cselect_b32 s5, 0x10000, s29
	s_cmp_lt_u32 s17, 16
	s_cselect_b32 s21, 0x18000, 0
	s_cselect_b32 s23, 0, 0x8000
	s_cselect_b32 s24, s94, 0x10000
	s_cselect_b32 s44, 0x10000, s29
	s_cmp_lt_u32 s16, 16
	s_cselect_b32 s27, 0x18000, 0
	s_cselect_b32 s28, 0, 0x8000
	s_cselect_b32 s34, s94, 0x10000
	s_cselect_b32 s45, 0x10000, s29
	s_cmp_lt_u32 s15, 16
	s_cselect_b32 s35, 0x18000, 0
	s_cselect_b32 s38, 0, 0x8000
	s_cselect_b32 s39, s94, 0x10000
	s_cselect_b32 s46, 0x10000, s29
	s_cmp_lt_u32 s14, 16
	s_cselect_b32 s36, 0x18000, 0
	s_cselect_b32 s47, 0, 0x8000
	s_cselect_b32 s48, s94, 0x10000
	s_cselect_b32 s49, 0x10000, s29
	s_cmp_lt_u32 s13, 16
	s_cselect_b32 s30, 0x18000, 0
	s_cselect_b32 s50, 0, 0x8000
	s_cselect_b32 s51, s94, 0x10000
	s_cselect_b32 s52, 0x10000, s29
	s_cmp_lt_u32 s12, 16
	s_cselect_b32 s31, 0x18000, 0
	s_cselect_b32 s53, 0, 0x8000
	s_cselect_b32 s56, s94, 0x10000
	s_cselect_b32 s58, 0x10000, s29
	s_cmp_lt_u32 s7, 16
	s_cselect_b32 s25, 0x18000, 0
	s_cselect_b32 s57, 0, 0x8000
	s_cselect_b32 s59, s94, 0x10000
	s_cselect_b32 s60, 0x10000, s29
	s_cmp_lt_u32 s6, 16
	s_cselect_b32 s26, 0x18000, 0
	s_cselect_b32 s61, 0, 0x8000
	s_cselect_b32 s63, s94, 0x10000
	s_cselect_b32 s64, 0x10000, s29
	s_cmp_gt_i32 s4, -1
	s_cselect_b32 s65, 0x10000, s94
	s_cselect_b32 s67, s29, 0x10000
	s_cmp_gt_i32 s4, 0
	s_cselect_b32 s37, 0, 0x18000
	s_cselect_b32 s66, 0x8000, 0
	s_cselect_b32 s68, 0x10000, s94
	s_cselect_b32 s84, s29, 0x10000
	s_cmp_gt_i32 s4, 1
	s_cselect_b32 s54, 0, 0x18000
	s_cselect_b32 s69, 0x8000, 0
	s_cselect_b32 s71, 0x10000, s94
	s_cselect_b32 s85, s29, 0x10000
	s_cmp_gt_i32 s4, 2
	s_cselect_b32 s55, 0, 0x18000
	s_cselect_b32 s70, 0x8000, 0
	s_cselect_b32 s76, 0x10000, s94
	s_cselect_b32 s86, s29, 0x10000
	s_cmp_gt_i32 s4, 3
	s_cselect_b32 s74, 0, 0x18000
	s_cselect_b32 s75, 0x8000, 0
	s_cselect_b32 s78, 0x10000, s94
	s_cselect_b32 s87, s29, 0x10000
	s_cmp_gt_i32 s4, 4
	s_cselect_b32 s77, 0, 0x18000
	s_cselect_b32 s79, 0x8000, 0
	s_cselect_b32 s80, 0x10000, s94
	s_cselect_b32 vcc_lo, s29, 0x10000
	s_cmp_gt_i32 s4, 5
	s_cselect_b32 s83, 0, 0x18000
	s_cselect_b32 s88, 0x8000, 0
	s_cselect_b32 s96, 0x10000, s94
	s_cselect_b32 vcc_hi, s29, 0x10000
	s_cmp_gt_i32 s4, 6
	s_cselect_b32 s89, 0, 0x18000
	s_cselect_b32 s90, 0x8000, 0
	s_cselect_b32 s95, 0x10000, s94
	s_cselect_b32 s91, s29, 0x10000
	s_cmp_gt_i32 s4, 7
	v_writelane_b32 v255, s5, 24
	s_cselect_b32 s92, 0, 0x18000
	s_cselect_b32 s93, 0x8000, 0
	s_cselect_b32 s94, 0x10000, s94
	s_cselect_b32 s5, s29, 0x10000
	s_add_i32 s74, s74, 0
	v_writelane_b32 v255, s74, 6
	s_add_i32 s55, s55, 0
	v_writelane_b32 v255, s55, 7
	s_add_i32 s54, s54, 0
	v_writelane_b32 v255, s54, 8
	s_add_i32 s37, s37, 0
	v_writelane_b32 v255, s37, 9
	s_ashr_i32 s37, s4, 31
	s_and_b32 s37, s37, 0x18000
	s_add_i32 s37, s37, 0
	v_writelane_b32 v255, s37, 10
	s_add_i32 s26, s26, 0
	v_writelane_b32 v255, s26, 11
	s_add_i32 s25, s25, 0
	v_writelane_b32 v255, s25, 12
	s_and_b32 s25, s6, 14
	s_add_i32 s6, s31, 0
	v_writelane_b32 v255, s6, 13
	s_add_i32 s6, s30, 0
	v_writelane_b32 v255, s6, 14
	s_add_i32 s6, s36, 0
	v_writelane_b32 v255, s6, 15
	s_add_i32 s6, s35, 0
	v_writelane_b32 v255, s6, 16
	s_add_i32 s6, s27, 0
	v_writelane_b32 v255, s6, 17
	s_add_i32 s6, s21, 0
	v_writelane_b32 v255, s6, 18
	s_add_i32 s6, s18, 0
	v_writelane_b32 v255, s6, 19
	s_add_i32 s6, s93, 0
	v_writelane_b32 v255, s6, 20
	s_add_i32 s6, s90, 0
	v_writelane_b32 v255, s6, 21
	s_add_i32 s6, s88, 0
	v_writelane_b32 v255, s6, 22
	s_add_i32 s6, s79, 0
	v_writelane_b32 v255, s6, 23
	s_add_i32 s6, s75, 0
	v_writelane_b32 v255, s6, 28
	s_add_i32 s6, s70, 0
	v_writelane_b32 v255, s6, 29
	s_add_i32 s6, s69, 0
	v_writelane_b32 v255, s6, 30
	s_add_i32 s6, s66, 0
	s_add_i32 s89, s89, 0
	v_writelane_b32 v255, s6, 31
	s_add_i32 s6, s0, 32
	v_writelane_b32 v253, s89, 1
	s_add_i32 s83, s83, 0
	v_writelane_b32 v255, s6, 39
	s_and_b32 s70, s6, 0x70
	s_add_i32 s6, s0, 48
	v_writelane_b32 v253, s83, 13
	s_add_i32 s77, s77, 0
	v_writelane_b32 v254, s6, 54
	s_and_b32 s74, s6, 0x70
	s_add_i32 s6, s0, 0x50
	v_writelane_b32 v253, s77, 2
	v_writelane_b32 v255, s6, 40
	s_and_b32 s77, s6, 0x70
	s_add_i32 s6, s0, 0x60
	s_add_i32 s29, s0, 16
	v_writelane_b32 v254, s6, 58
	s_and_b32 s79, s6, 0x70
	s_add_i32 s6, s0, 0x70
	s_add_i32 s97, s92, 0
	s_and_b32 s26, s7, 14
	s_and_b32 s30, s12, 14
	s_and_b32 s31, s13, 14
	s_and_b32 s36, s14, 14
	s_and_b32 s37, s15, 14
	s_and_b32 s54, s16, 14
	s_and_b32 s55, s17, 14
	s_and_b32 s66, s29, 0x70
	s_xor_b32 s75, s11, 64
	s_and_b32 s83, s6, 0x70
	s_cmp_lt_i32 s4, 0
	s_cselect_b32 s4, 0, 0x8000
	s_add_i32 s4, s4, 0
	v_writelane_b32 v255, s4, 32
	s_add_i32 s4, s61, 0
	v_writelane_b32 v255, s4, 33
	s_add_i32 s4, s57, 0
	v_writelane_b32 v255, s4, 34
	s_add_i32 s4, s53, 0
	v_writelane_b32 v255, s4, 35
	s_add_i32 s4, s50, 0
	v_writelane_b32 v255, s4, 36
	s_add_i32 s4, s47, 0
	v_writelane_b32 v255, s4, 37
	s_add_i32 s4, s38, 0
	v_writelane_b32 v254, s6, 59
	v_and_b32_e32 v79, 63, v0
	v_lshlrev_b32_e32 v0, 2, v78
	v_writelane_b32 v255, s4, 38
	v_readlane_b32 s6, v253, 8
	v_lshlrev_b32_e32 v20, 1, v0
	v_mov_b32_e32 v21, v3
	v_readlane_b32 s7, v253, 9
	v_readlane_b32 s4, v255, 24
	s_add_i32 s88, s28, 0
	s_add_i32 s92, s23, 0
	s_add_i32 s93, s19, 0
	v_lshl_add_u64 v[22:23], s[6:7], 0, v[20:21]
	s_add_i32 s94, s94, 0
	s_add_i32 s95, s95, 0
	s_add_i32 s96, s96, 0
	s_add_i32 s89, s80, 0
	s_add_i32 s13, s78, 0
	s_add_i32 s69, s76, 0
	s_add_i32 s71, s71, 0
	s_add_i32 s76, s68, 0
	s_add_i32 s78, s65, 0
	s_add_i32 s80, s63, 0
	s_add_i32 s12, s59, 0
	s_add_i32 s14, s56, 0
	s_add_i32 s15, s51, 0
	s_add_i32 s16, s48, 0
	s_add_i32 s17, s39, 0
	s_add_i32 s18, s34, 0
	s_add_i32 s19, s24, 0
	s_add_i32 s20, s20, 0
	s_add_i32 s21, s5, 0
	s_add_i32 s23, s91, 0
	s_add_i32 s24, vcc_hi, 0
	s_add_i32 s27, vcc_lo, 0
	s_add_i32 s28, s87, 0
	s_add_i32 s34, s86, 0
	s_add_i32 s35, s85, 0
	s_add_i32 s38, s84, 0
	s_add_i32 s39, s67, 0
	s_add_i32 s56, s64, 0
	s_add_i32 s57, s60, 0
	s_add_i32 s58, s58, 0
	s_add_i32 s59, s52, 0
	s_add_i32 s60, s49, 0
	s_add_i32 s61, s46, 0
	s_add_i32 s63, s45, 0
	s_add_i32 s64, s44, 0
	s_add_i32 s65, s4, 0
	v_mov_b32_e32 v2, 0
	v_mov_b32_e32 v58, 0
	v_mov_b32_e32 v34, 0
	s_mov_b32 s84, 0
	v_cmp_gt_u32_e64 s[4:5], 16, v79
	s_mov_b64 s[50:51], 0
	s_mov_b64 s[44:45], -1
	v_readlane_b32 s48, v254, 15
	s_mov_b32 s6, 0
	v_readlane_b32 s49, v254, 16

.Lat844_i3_nomask:
	v_max3_f32 v245, v44, v45, v46
	v_max3_f32 v245, v245, v47, v48
	v_max3_f32 v245, v245, v49, v50
	v_max3_f32 v245, v245, v51, v52
	v_max3_f32 v245, v245, v53, v54
	v_max3_f32 v245, v245, v55, v56
	v_max3_f32 v245, v245, v57, v58
	v_max3_f32 v245, v245, v59, v60
	v_max3_f32 v245, v245, v61, v62
	v_max3_f32 v245, v245, v63, v64
	v_max3_f32 v245, v245, v65, v66
	v_max3_f32 v245, v245, v67, v68
	v_max3_f32 v245, v245, v69, v70
	v_max3_f32 v245, v245, v71, v72
	v_max3_f32 v245, v245, v73, v74
	v_max3_f32 v245, v245, v75, v76
	v_max3_f32 v245, v245, v77, v78
	v_max_f32_e32 v245, v245, v79
	v_mov_b32_e32 v148, v245
	s_nop 1
	v_permlane16_swap_b32 v245, v148
	v_max_f32_e32 v245, v245, v148
	v_mov_b32_e32 v148, v245
	s_nop 1
	v_permlane32_swap_b32 v245, v148
	v_max_f32_e32 v245, v245, v148
	v_sub_f32_e32 v44, v44, v245
	v_sub_f32_e32 v45, v45, v245
	v_sub_f32_e32 v46, v46, v245
	v_sub_f32_e32 v47, v47, v245
	v_exp_f32_e32 v44, v44
	v_exp_f32_e32 v45, v45
	v_exp_f32_e32 v46, v46
	v_exp_f32_e32 v47, v47
	v_sub_f32_e32 v48, v48, v245
	v_sub_f32_e32 v49, v49, v245
	v_sub_f32_e32 v50, v50, v245
	v_sub_f32_e32 v51, v51, v245
	v_exp_f32_e32 v48, v48
	v_exp_f32_e32 v49, v49
	v_exp_f32_e32 v50, v50
	v_exp_f32_e32 v51, v51
	v_mov_b32_e32 v149, v44
	v_mov_b32_e32 v150, v45
	v_mov_b32_e32 v151, v46
	v_mov_b32_e32 v152, v47
	v_cvt_pk_bf16_f32 v44, v44, v45
	v_cvt_pk_bf16_f32 v45, v46, v47
	v_sub_f32_e32 v52, v52, v245
	v_sub_f32_e32 v53, v53, v245
	v_sub_f32_e32 v54, v54, v245
	v_sub_f32_e32 v55, v55, v245
	v_exp_f32_e32 v52, v52
	v_exp_f32_e32 v53, v53
	v_exp_f32_e32 v54, v54
	v_exp_f32_e32 v55, v55
	v_add_f32_e32 v149, v149, v48
	v_add_f32_e32 v150, v150, v49
	v_add_f32_e32 v151, v151, v50
	v_add_f32_e32 v152, v152, v51
	v_cvt_pk_bf16_f32 v46, v48, v49
	v_cvt_pk_bf16_f32 v47, v50, v51
	v_sub_f32_e32 v56, v56, v245
	v_sub_f32_e32 v57, v57, v245
	v_sub_f32_e32 v58, v58, v245
	v_sub_f32_e32 v59, v59, v245
	v_exp_f32_e32 v56, v56
	v_exp_f32_e32 v57, v57
	v_exp_f32_e32 v58, v58
	v_exp_f32_e32 v59, v59
	v_add_f32_e32 v149, v149, v52
	v_add_f32_e32 v150, v150, v53
	v_add_f32_e32 v151, v151, v54
	v_add_f32_e32 v152, v152, v55
	v_cvt_pk_bf16_f32 v52, v52, v53
	v_cvt_pk_bf16_f32 v53, v54, v55
	v_sub_f32_e32 v60, v60, v245
	v_sub_f32_e32 v61, v61, v245
	v_sub_f32_e32 v62, v62, v245
	v_sub_f32_e32 v63, v63, v245
	v_exp_f32_e32 v60, v60
	v_exp_f32_e32 v61, v61
	v_exp_f32_e32 v62, v62
	v_exp_f32_e32 v63, v63
	v_add_f32_e32 v149, v149, v56
	v_add_f32_e32 v150, v150, v57
	v_add_f32_e32 v151, v151, v58
	v_add_f32_e32 v152, v152, v59
	v_cvt_pk_bf16_f32 v54, v56, v57
	v_cvt_pk_bf16_f32 v55, v58, v59
	v_sub_f32_e32 v64, v64, v245
	v_sub_f32_e32 v65, v65, v245
	v_sub_f32_e32 v66, v66, v245
	v_sub_f32_e32 v67, v67, v245
	v_exp_f32_e32 v64, v64
	v_exp_f32_e32 v65, v65
	v_exp_f32_e32 v66, v66
	v_exp_f32_e32 v67, v67
	v_add_f32_e32 v149, v149, v60
	v_add_f32_e32 v150, v150, v61
	v_add_f32_e32 v151, v151, v62
	v_add_f32_e32 v152, v152, v63
	v_cvt_pk_bf16_f32 v60, v60, v61
	v_cvt_pk_bf16_f32 v61, v62, v63
	v_sub_f32_e32 v68, v68, v245
	v_sub_f32_e32 v69, v69, v245
	v_sub_f32_e32 v70, v70, v245
	v_sub_f32_e32 v71, v71, v245
	v_exp_f32_e32 v68, v68
	v_exp_f32_e32 v69, v69
	v_exp_f32_e32 v70, v70
	v_exp_f32_e32 v71, v71
	v_add_f32_e32 v149, v149, v64
	v_add_f32_e32 v150, v150, v65
	v_add_f32_e32 v151, v151, v66
	v_add_f32_e32 v152, v152, v67
	v_cvt_pk_bf16_f32 v62, v64, v65
	v_cvt_pk_bf16_f32 v63, v66, v67
	v_sub_f32_e32 v72, v72, v245
	v_sub_f32_e32 v73, v73, v245
	v_sub_f32_e32 v74, v74, v245
	v_sub_f32_e32 v75, v75, v245
	v_exp_f32_e32 v72, v72
	v_exp_f32_e32 v73, v73
	v_exp_f32_e32 v74, v74
	v_exp_f32_e32 v75, v75
	v_add_f32_e32 v149, v149, v68
	v_add_f32_e32 v150, v150, v69
	v_add_f32_e32 v151, v151, v70
	v_add_f32_e32 v152, v152, v71
	v_cvt_pk_bf16_f32 v68, v68, v69
	v_cvt_pk_bf16_f32 v69, v70, v71
	v_sub_f32_e32 v76, v76, v245
	v_sub_f32_e32 v77, v77, v245
	v_sub_f32_e32 v78, v78, v245
	v_sub_f32_e32 v79, v79, v245
	v_exp_f32_e32 v76, v76
	v_exp_f32_e32 v77, v77
	v_exp_f32_e32 v78, v78
	v_exp_f32_e32 v79, v79
	v_add_f32_e32 v149, v149, v72
	v_add_f32_e32 v150, v150, v73
	v_add_f32_e32 v151, v151, v74
	v_add_f32_e32 v152, v152, v75
	v_cvt_pk_bf16_f32 v70, v72, v73
	v_cvt_pk_bf16_f32 v71, v74, v75
	s_nop 0
	v_add_f32_e32 v149, v149, v76
	v_add_f32_e32 v150, v150, v77
	v_add_f32_e32 v151, v151, v78
	v_add_f32_e32 v152, v152, v79
	v_cvt_pk_bf16_f32 v76, v76, v77
	v_cvt_pk_bf16_f32 v77, v78, v79
	v_mov_b32_e32 v78, 0
	v_mov_b32_e32 v79, 0
	v_add_f32_e32 v149, v149, v150
	v_add_f32_e32 v151, v151, v152
	v_add_f32_e32 v246, v149, v151
	s_waitcnt lgkmcnt(0)
	v_mfma_f32_16x16x32_bf16 v[80:83], v[4:7], v[44:47], 0
	v_mfma_f32_16x16x32_bf16 v[84:87], v[8:11], v[44:47], 0
	v_mfma_f32_16x16x32_bf16 v[88:91], v[12:15], v[44:47], 0
	v_mfma_f32_16x16x32_bf16 v[92:95], v[16:19], v[44:47], 0
	ds_read_b64 v[4:5], v225 offset:32768
	ds_read_b64 v[8:9], v225 offset:36864
	ds_read_b64 v[12:13], v225 offset:40960
	ds_read_b64 v[16:17], v225 offset:45056
	ds_read_b64 v[6:7], v226 offset:32768
	ds_read_b64 v[10:11], v226 offset:36864
	ds_read_b64 v[14:15], v226 offset:40960
	ds_read_b64 v[18:19], v226 offset:45056
	v_mfma_f32_16x16x32_bf16 v[80:83], v[20:23], v[52:55], v[80:83]
	v_mfma_f32_16x16x32_bf16 v[84:87], v[24:27], v[52:55], v[84:87]
	v_mfma_f32_16x16x32_bf16 v[88:91], v[28:31], v[52:55], v[88:91]
	v_mfma_f32_16x16x32_bf16 v[92:95], v[32:35], v[52:55], v[92:95]
	ds_read_b64 v[20:21], v227 offset:32768
	ds_read_b64 v[24:25], v227 offset:36864
	ds_read_b64 v[28:29], v227 offset:40960
	ds_read_b64 v[32:33], v227 offset:45056
	ds_read_b64 v[22:23], v228 offset:32768
	ds_read_b64 v[26:27], v228 offset:36864
	ds_read_b64 v[30:31], v228 offset:40960
	ds_read_b64 v[34:35], v228 offset:45056
	s_waitcnt lgkmcnt(8)
	v_mfma_f32_16x16x32_bf16 v[80:83], v[4:7], v[60:63], v[80:83]
	v_mfma_f32_16x16x32_bf16 v[84:87], v[8:11], v[60:63], v[84:87]
	v_mfma_f32_16x16x32_bf16 v[88:91], v[12:15], v[60:63], v[88:91]
	v_mfma_f32_16x16x32_bf16 v[92:95], v[16:19], v[60:63], v[92:95]
	ds_read_b64 v[4:5], v229 offset:32768
	ds_read_b64 v[8:9], v229 offset:36864
	ds_read_b64 v[12:13], v229 offset:40960
	ds_read_b64 v[16:17], v229 offset:45056
	v_mov_b32_e32 v6, 0
	v_mov_b32_e32 v7, 0
	v_mov_b32_e32 v10, 0
	v_mov_b32_e32 v11, 0
	v_mov_b32_e32 v14, 0
	v_mov_b32_e32 v15, 0
	v_mov_b32_e32 v18, 0
	v_mov_b32_e32 v19, 0
	s_waitcnt lgkmcnt(4)
	v_mfma_f32_16x16x32_bf16 v[80:83], v[20:23], v[68:71], v[80:83]
	v_mfma_f32_16x16x32_bf16 v[84:87], v[24:27], v[68:71], v[84:87]
	v_mfma_f32_16x16x32_bf16 v[88:91], v[28:31], v[68:71], v[88:91]
	v_mfma_f32_16x16x32_bf16 v[92:95], v[32:35], v[68:71], v[92:95]
	s_waitcnt lgkmcnt(0)
	v_mfma_f32_16x16x32_bf16 v[80:83], v[4:7], v[76:79], v[80:83]
	v_mfma_f32_16x16x32_bf16 v[84:87], v[8:11], v[76:79], v[84:87]
	v_mfma_f32_16x16x32_bf16 v[88:91], v[12:15], v[76:79], v[88:91]
	v_mfma_f32_16x16x32_bf16 v[92:95], v[16:19], v[76:79], v[92:95]
	v_mov_b32_e32 v148, v246
	s_nop 1
	v_permlane16_swap_b32 v246, v148
	v_add_f32_e32 v246, v246, v148
	v_mov_b32_e32 v148, v246
	s_nop 1
	v_permlane32_swap_b32 v246, v148
	v_add_f32_e32 v246, v246, v148
	v_rcp_f32_e32 v149, v246
	v_log_f32_e32 v150, v246
	s_nop 0
	v_add_f32_e32 v151, v245, v150
	v_mul_f32_e32 v151, 0x3f317218, v151
	v_max_f32_e32 v152, v121, v151
	v_sub_f32_e32 v153, v121, v152
	v_sub_f32_e32 v154, v151, v152
	v_mul_f32_e32 v153, 0x3fb8aa3b, v153
	v_mul_f32_e32 v154, 0x3fb8aa3b, v154
	v_exp_f32_e32 v153, v153
	v_exp_f32_e32 v154, v154
	s_nop 0
	v_add_f32_e32 v155, v153, v154
	v_rcp_f32_e32 v146, v155
	v_log_f32_e32 v150, v155
	s_nop 0
	v_mul_f32_e32 v154, v154, v146
	v_mul_f32_e32 v146, v153, v146
	v_mul_f32_e32 v147, v149, v154
	v_mul_f32_e32 v150, 0x3f317218, v150
	v_add_f32_e32 v140, v152, v150
	v_mul_f32_e32 v80, v80, v147
	v_mul_f32_e32 v81, v81, v147
	v_mul_f32_e32 v82, v82, v147
	v_mul_f32_e32 v83, v83, v147
	v_mul_f32_e32 v84, v84, v147
	v_mul_f32_e32 v85, v85, v147
	v_mul_f32_e32 v86, v86, v147
	v_mul_f32_e32 v87, v87, v147
	v_mul_f32_e32 v88, v88, v147
	v_mul_f32_e32 v89, v89, v147
	v_mul_f32_e32 v90, v90, v147
	v_mul_f32_e32 v91, v91, v147
	v_mul_f32_e32 v92, v92, v147
	v_mul_f32_e32 v93, v93, v147
	v_mul_f32_e32 v94, v94, v147
	v_mul_f32_e32 v95, v95, v147
	v_lshlrev_b32_e32 v141, 16, v122
	v_and_b32_e32 v142, 0xffff0000, v122
	v_lshlrev_b32_e32 v143, 16, v123
	v_and_b32_e32 v144, 0xffff0000, v123
	v_fmac_f32_e32 v80, v146, v141
	v_fmac_f32_e32 v81, v146, v142
	v_fmac_f32_e32 v82, v146, v143
	v_fmac_f32_e32 v83, v146, v144
	v_cvt_pk_bf16_f32 v132, v80, v81
	v_cvt_pk_bf16_f32 v133, v82, v83
	v_lshlrev_b32_e32 v141, 16, v124
	v_and_b32_e32 v142, 0xffff0000, v124
	v_lshlrev_b32_e32 v143, 16, v125
	v_and_b32_e32 v144, 0xffff0000, v125
	v_fmac_f32_e32 v84, v146, v141
	v_fmac_f32_e32 v85, v146, v142
	v_fmac_f32_e32 v86, v146, v143
	v_fmac_f32_e32 v87, v146, v144
	v_cvt_pk_bf16_f32 v134, v84, v85
	v_cvt_pk_bf16_f32 v135, v86, v87
	v_lshlrev_b32_e32 v141, 16, v126
	v_and_b32_e32 v142, 0xffff0000, v126
	v_lshlrev_b32_e32 v143, 16, v127
	v_and_b32_e32 v144, 0xffff0000, v127
	v_fmac_f32_e32 v88, v146, v141
	v_fmac_f32_e32 v89, v146, v142
	v_fmac_f32_e32 v90, v146, v143
	v_fmac_f32_e32 v91, v146, v144
	v_cvt_pk_bf16_f32 v136, v88, v89
	v_cvt_pk_bf16_f32 v137, v90, v91
	v_lshlrev_b32_e32 v141, 16, v128
	v_and_b32_e32 v142, 0xffff0000, v128
	v_lshlrev_b32_e32 v143, 16, v129
	v_and_b32_e32 v144, 0xffff0000, v129
	v_fmac_f32_e32 v92, v146, v141
	v_fmac_f32_e32 v93, v146, v142
	v_fmac_f32_e32 v94, v146, v143
	v_fmac_f32_e32 v95, v146, v144
	v_cvt_pk_bf16_f32 v138, v92, v93
	v_cvt_pk_bf16_f32 v139, v94, v95
	s_mov_b64 s[26:27], s[86:87]
	s_mov_b64 s[28:29], s[88:89]
	s_mov_b64 s[86:87], s[12:13]
	s_mov_b64 s[88:89], s[14:15]
	s_mov_b32 s4, s83
	s_mov_b32 s5, s84
	s_add_u32 s7, s7, 1
	s_cmp_lt_u32 s7, 2
	s_cbranch_scc1 .Lat844_loop
	global_store_dwordx2 v237, v[132:133], s[26:27]
	global_store_dwordx2 v237, v[134:135], s[26:27] offset:32
	global_store_dwordx2 v237, v[136:137], s[26:27] offset:64
	global_store_dwordx2 v237, v[138:139], s[26:27] offset:96
	s_mov_b64 s[90:91], exec
	s_mov_b64 exec, 0xffff
	global_store_dword v238, v140, s[28:29]
	s_mov_b64 exec, s[90:91]
	s_mov_b32 s67, 0x10000
	s_mov_b32 s68, 0x14000
	v_mov_b32_e32 v183, v239
	v_mov_b32_e32 v184, v240
	s_waitcnt vmcnt(0)
	s_barrier
	s_waitcnt vmcnt(0)
	s_barrier
	s_mov_b64 s[4:5], exec
	v_readlane_b32 s0, v252, 2
	v_readlane_b32 s30, v253, 24
	v_readlane_b32 s1, v252, 3
	v_readlane_b32 s31, v253, 25
	v_readlane_b32 s34, v253, 15
	v_readlane_b32 s36, v252, 27
	v_readlane_b32 s8, v253, 19
	v_readlane_b32 s10, v253, 21
	v_readlane_b32 s38, v252, 29
	v_readlane_b32 s60, v252, 31
	v_readlane_b32 s64, v252, 33
	v_readlane_b32 s70, v252, 35
	v_readlane_b32 s74, v252, 37
	s_and_b64 s[0:1], s[4:5], s[0:1]
	v_readlane_b32 s28, v253, 23
	v_readlane_b32 s35, v253, 16
	v_readlane_b32 s29, v252, 26
	v_readlane_b32 s31, v253, 18
	v_readlane_b32 s37, v252, 28
	v_readlane_b32 s9, v253, 20
	v_readlane_b32 s11, v253, 22
	v_readlane_b32 s39, v252, 30
	v_readlane_b32 s61, v252, 32
	v_readlane_b32 s65, v252, 34
	v_readlane_b32 s71, v252, 36
	v_readlane_b32 s75, v252, 38
	v_readlane_b32 s63, v253, 17
	s_mov_b64 exec, s[0:1]
	s_cbranch_execz .LBB0_916
	v_mov_b32_e32 v0, 0x20000
	ds_read_b64 v[0:1], v0
	s_getreg_b32 s44, hwreg(HW_REG_XCC_ID, 0, 4)
	s_lshl_b32 s44, s44, 7
	s_add_u32 s44, s44, 0xdc03600
	v_mov_b32_e32 v2, s44
	v_mov_b32_e32 v4, 1
	s_waitcnt vmcnt(0) lgkmcnt(0)
	global_atomic_add v5, v2, v4, s[42:43] sc0
	buffer_inv sc1
	s_add_u32 s100, s100, 1
	v_readfirstlane_b32 s46, v0
	v_readfirstlane_b32 s47, v1
	v_mov_b32_e32 v2, 0xdc03e00
	s_nop 3
	s_mul_i32 s48, s46, s100
	s_mul_i32 s49, s47, s100
	s_waitcnt vmcnt(1)
	v_readfirstlane_b32 s50, v5
	s_nop 3
	s_add_u32 s50, s50, 1
	s_cmp_lg_u32 s50, s48
	s_cbranch_scc1 .Lxb7_poll
	buffer_wbl2 sc1
	s_waitcnt vmcnt(0)
	global_atomic_add v2, v4, s[42:43]

.LBB0_929:
	v_add_u32_e32 v149, s67, v147
	ds_read_b128 v[150:153], v149
	ds_read_b128 v[186:189], v149 offset:1024
	ds_read_b128 v[190:193], v149 offset:2048
	ds_read_b128 v[194:197], v149 offset:3072
	v_add_u32_e32 v149, s68, v147
	ds_read_b128 v[198:201], v149
	ds_read_b128 v[202:205], v149 offset:1024
	ds_read_b128 v[206:209], v149 offset:2048
	ds_read_b128 v[210:213], v149 offset:3072
	s_add_u32 s25, s54, 0xfffc0080
	s_addc_u32 s26, s55, -1
	s_cmp_eq_u32 s24, 12
	s_cselect_b32 s57, s17, s26
	s_cselect_b32 s56, s18, s25
	s_cselect_b32 s27, s19, s23
	s_cselect_b32 s26, s20, s21
	v_lshl_add_u64 v[154:155], s[54:55], 0, v[142:143]
	s_add_i32 m0, s3, 0xc000
	ds_read_b128 v[214:217], v148
	ds_read_b128 v[218:221], v148 offset:1024
	ds_read_b128 v[222:225], v148 offset:2048
	ds_read_b128 v[226:229], v148 offset:3072
	ds_read_b128 v[230:233], v148 offset:4096
	ds_read_b128 v[234:237], v148 offset:5120
	ds_read_b128 v[238:241], v148 offset:6144
	ds_read_b128 v[242:245], v148 offset:7168
	global_load_lds_dwordx4 v[154:155], off
	v_lshl_add_u64 v[154:155], s[54:55], 0, v[144:145]
	s_add_i32 m0, s3, 0xe000
	s_nop 0
	global_load_lds_dwordx4 v[154:155], off
	s_waitcnt vmcnt(8)
	s_waitcnt lgkmcnt(0)
	v_mfma_f32_16x16x32_f16 v[128:131], v[150:153], v[214:217], v[128:131]
	v_mfma_f32_16x16x32_f16 v[124:127], v[190:193], v[214:217], v[124:127]
	v_mfma_f32_16x16x32_f16 v[116:119], v[150:153], v[222:225], v[116:119]
	v_mfma_f32_16x16x32_f16 v[108:111], v[190:193], v[222:225], v[108:111]
	s_barrier
	s_waitcnt lgkmcnt(0)
	v_mfma_f32_16x16x32_f16 v[104:107], v[150:153], v[230:233], v[104:107]
	v_mfma_f32_16x16x32_f16 v[100:103], v[190:193], v[230:233], v[100:103]
	v_mfma_f32_16x16x32_f16 v[88:91], v[150:153], v[238:241], v[88:91]
	v_mfma_f32_16x16x32_f16 v[84:87], v[190:193], v[238:241], v[84:87]
	v_mfma_f32_16x16x32_f16 v[128:131], v[186:189], v[218:221], v[128:131]
	v_mfma_f32_16x16x32_f16 v[124:127], v[194:197], v[218:221], v[124:127]
	v_mfma_f32_16x16x32_f16 v[116:119], v[186:189], v[226:229], v[116:119]
	v_mfma_f32_16x16x32_f16 v[108:111], v[194:197], v[226:229], v[108:111]
	v_mfma_f32_16x16x32_f16 v[104:107], v[186:189], v[234:237], v[104:107]
	v_mfma_f32_16x16x32_f16 v[100:103], v[194:197], v[234:237], v[100:103]
	v_mfma_f32_16x16x32_f16 v[88:91], v[186:189], v[242:245], v[88:91]
	v_mfma_f32_16x16x32_f16 v[84:87], v[194:197], v[242:245], v[84:87]
	v_mfma_f32_16x16x32_f16 v[120:123], v[198:201], v[214:217], v[120:123]
	v_mfma_f32_16x16x32_f16 v[112:115], v[206:209], v[214:217], v[112:115]
	v_mfma_f32_16x16x32_f16 v[96:99], v[198:201], v[222:225], v[96:99]
	v_mfma_f32_16x16x32_f16 v[92:95], v[206:209], v[222:225], v[92:95]
	v_mfma_f32_16x16x32_f16 v[80:83], v[198:201], v[230:233], v[80:83]
	v_mfma_f32_16x16x32_f16 v[76:79], v[206:209], v[230:233], v[76:79]
	v_mfma_f32_16x16x32_f16 v[72:75], v[198:201], v[238:241], v[72:75]
	v_mfma_f32_16x16x32_f16 v[68:71], v[206:209], v[238:241], v[68:71]
	v_mfma_f32_16x16x32_f16 v[120:123], v[202:205], v[218:221], v[120:123]
	v_mfma_f32_16x16x32_f16 v[112:115], v[210:213], v[218:221], v[112:115]
	v_mfma_f32_16x16x32_f16 v[96:99], v[202:205], v[226:229], v[96:99]
	v_mfma_f32_16x16x32_f16 v[92:95], v[210:213], v[226:229], v[92:95]
	v_mfma_f32_16x16x32_f16 v[80:83], v[202:205], v[234:237], v[80:83]
	v_mfma_f32_16x16x32_f16 v[76:79], v[210:213], v[234:237], v[76:79]
	v_mfma_f32_16x16x32_f16 v[72:75], v[202:205], v[242:245], v[72:75]
	v_mfma_f32_16x16x32_f16 v[68:71], v[210:213], v[242:245], v[68:71]
	s_barrier
	s_add_i32 s25, s67, s2
	v_lshl_add_u64 v[154:155], s[26:27], 0, v[136:137]
	s_mov_b32 m0, s25
	ds_read_b128 v[214:217], v148 offset:16384
	ds_read_b128 v[218:221], v148 offset:17408
	ds_read_b128 v[222:225], v148 offset:18432
	ds_read_b128 v[226:229], v148 offset:19456
	ds_read_b128 v[230:233], v148 offset:20480
	ds_read_b128 v[234:237], v148 offset:21504
	ds_read_b128 v[238:241], v148 offset:22528
	ds_read_b128 v[242:245], v148 offset:23552
	global_load_lds_dwordx4 v[154:155], off
	v_lshl_add_u64 v[168:169], s[26:27], 0, v[0:1]
	s_add_i32 m0, s25, 0x2000
	s_add_i32 s25, s68, s2
	global_load_lds_dwordx4 v[168:169], off
	v_lshl_add_u64 v[178:179], s[26:27], 0, v[138:139]
	s_mov_b32 m0, s25
	v_lshl_add_u64 v[246:247], s[26:27], 0, v[132:133]
	global_load_lds_dwordx4 v[178:179], off
	s_add_i32 m0, s25, 0x2000
	v_lshl_add_u64 v[248:249], s[56:57], 0, v[140:141]
	global_load_lds_dwordx4 v[246:247], off
	s_mov_b32 m0, s3
	v_lshl_add_u64 v[250:251], s[56:57], 0, v[134:135]
	global_load_lds_dwordx4 v[248:249], off
	s_mov_b32 m0, s8
	s_nop 0
	global_load_lds_dwordx4 v[250:251], off
	s_waitcnt vmcnt(8)
	s_waitcnt lgkmcnt(0)
	v_mfma_f32_16x16x32_f16 v[64:67], v[150:153], v[214:217], v[64:67]
	v_mfma_f32_16x16x32_f16 v[60:63], v[190:193], v[214:217], v[60:63]
	v_mfma_f32_16x16x32_f16 v[56:59], v[150:153], v[222:225], v[56:59]
	v_mfma_f32_16x16x32_f16 v[52:55], v[190:193], v[222:225], v[52:55]
	s_barrier
	s_waitcnt lgkmcnt(0)
	v_mfma_f32_16x16x32_f16 v[40:43], v[150:153], v[230:233], v[40:43]
	v_mfma_f32_16x16x32_f16 v[36:39], v[190:193], v[230:233], v[36:39]
	v_mfma_f32_16x16x32_f16 v[24:27], v[150:153], v[238:241], v[24:27]
	v_mfma_f32_16x16x32_f16 v[20:23], v[190:193], v[238:241], v[20:23]
	v_mfma_f32_16x16x32_f16 v[64:67], v[186:189], v[218:221], v[64:67]
	v_mfma_f32_16x16x32_f16 v[60:63], v[194:197], v[218:221], v[60:63]
	v_mfma_f32_16x16x32_f16 v[56:59], v[186:189], v[226:229], v[56:59]
	v_mfma_f32_16x16x32_f16 v[52:55], v[194:197], v[226:229], v[52:55]
	v_mfma_f32_16x16x32_f16 v[40:43], v[186:189], v[234:237], v[40:43]
	v_mfma_f32_16x16x32_f16 v[36:39], v[194:197], v[234:237], v[36:39]
	v_mfma_f32_16x16x32_f16 v[24:27], v[186:189], v[242:245], v[24:27]
	v_mfma_f32_16x16x32_f16 v[20:23], v[194:197], v[242:245], v[20:23]
	v_mfma_f32_16x16x32_f16 v[48:51], v[198:201], v[214:217], v[48:51]
	v_mfma_f32_16x16x32_f16 v[44:47], v[206:209], v[214:217], v[44:47]
	v_mfma_f32_16x16x32_f16 v[32:35], v[198:201], v[222:225], v[32:35]
	v_mfma_f32_16x16x32_f16 v[28:31], v[206:209], v[222:225], v[28:31]
	v_mfma_f32_16x16x32_f16 v[16:19], v[198:201], v[230:233], v[16:19]
	v_mfma_f32_16x16x32_f16 v[12:15], v[206:209], v[230:233], v[12:15]
	v_mfma_f32_16x16x32_f16 v[8:11], v[198:201], v[238:241], v[8:11]
	v_mfma_f32_16x16x32_f16 v[4:7], v[206:209], v[238:241], v[4:7]
	v_mfma_f32_16x16x32_f16 v[48:51], v[202:205], v[218:221], v[48:51]
	v_mfma_f32_16x16x32_f16 v[44:47], v[210:213], v[218:221], v[44:47]
	v_mfma_f32_16x16x32_f16 v[32:35], v[202:205], v[226:229], v[32:35]
	v_mfma_f32_16x16x32_f16 v[28:31], v[210:213], v[226:229], v[28:31]
	v_mfma_f32_16x16x32_f16 v[16:19], v[202:205], v[234:237], v[16:19]
	v_mfma_f32_16x16x32_f16 v[12:15], v[210:213], v[234:237], v[12:15]
	v_mfma_f32_16x16x32_f16 v[8:11], v[202:205], v[242:245], v[8:11]
	v_mfma_f32_16x16x32_f16 v[4:7], v[210:213], v[242:245], v[4:7]
	s_barrier
	v_add_u32_e32 v149, s82, v147
	ds_read_b128 v[150:153], v149
	ds_read_b128 v[186:189], v149 offset:1024
	ds_read_b128 v[190:193], v149 offset:2048
	ds_read_b128 v[194:197], v149 offset:3072
	v_add_u32_e32 v149, s62, v147
	ds_read_b128 v[198:201], v149
	ds_read_b128 v[202:205], v149 offset:1024
	ds_read_b128 v[206:209], v149 offset:2048
	ds_read_b128 v[210:213], v149 offset:3072
	s_add_u32 s26, s56, 0x40000
	s_addc_u32 s27, s57, 0
	s_mov_b32 m0, s9
	v_lshl_add_u64 v[176:177], s[26:27], 0, v[140:141]
	ds_read_b128 v[214:217], v148 offset:32768
	ds_read_b128 v[218:221], v148 offset:33792
	ds_read_b128 v[222:225], v148 offset:34816
	ds_read_b128 v[226:229], v148 offset:35840
	ds_read_b128 v[230:233], v148 offset:36864
	ds_read_b128 v[234:237], v148 offset:37888
	ds_read_b128 v[238:241], v148 offset:38912
	ds_read_b128 v[242:245], v148 offset:39936
	global_load_lds_dwordx4 v[176:177], off
	v_lshl_add_u64 v[176:177], s[26:27], 0, v[134:135]
	s_mov_b32 m0, s10
	s_nop 0
	global_load_lds_dwordx4 v[176:177], off
	s_waitcnt vmcnt(8)
	s_waitcnt lgkmcnt(0)
	v_mfma_f32_16x16x32_f16 v[128:131], v[150:153], v[214:217], v[128:131]
	v_mfma_f32_16x16x32_f16 v[124:127], v[190:193], v[214:217], v[124:127]
	v_mfma_f32_16x16x32_f16 v[116:119], v[150:153], v[222:225], v[116:119]
	v_mfma_f32_16x16x32_f16 v[108:111], v[190:193], v[222:225], v[108:111]
	s_barrier
	s_waitcnt lgkmcnt(0)
	v_mfma_f32_16x16x32_f16 v[104:107], v[150:153], v[230:233], v[104:107]
	v_mfma_f32_16x16x32_f16 v[100:103], v[190:193], v[230:233], v[100:103]
	v_mfma_f32_16x16x32_f16 v[88:91], v[150:153], v[238:241], v[88:91]
	v_mfma_f32_16x16x32_f16 v[84:87], v[190:193], v[238:241], v[84:87]
	v_mfma_f32_16x16x32_f16 v[128:131], v[186:189], v[218:221], v[128:131]
	v_mfma_f32_16x16x32_f16 v[124:127], v[194:197], v[218:221], v[124:127]
	v_mfma_f32_16x16x32_f16 v[116:119], v[186:189], v[226:229], v[116:119]
	v_mfma_f32_16x16x32_f16 v[108:111], v[194:197], v[226:229], v[108:111]
	v_mfma_f32_16x16x32_f16 v[104:107], v[186:189], v[234:237], v[104:107]
	v_mfma_f32_16x16x32_f16 v[100:103], v[194:197], v[234:237], v[100:103]
	v_mfma_f32_16x16x32_f16 v[88:91], v[186:189], v[242:245], v[88:91]
	v_mfma_f32_16x16x32_f16 v[84:87], v[194:197], v[242:245], v[84:87]
	v_mfma_f32_16x16x32_f16 v[120:123], v[198:201], v[214:217], v[120:123]
	v_mfma_f32_16x16x32_f16 v[112:115], v[206:209], v[214:217], v[112:115]
	v_mfma_f32_16x16x32_f16 v[96:99], v[198:201], v[222:225], v[96:99]
	v_mfma_f32_16x16x32_f16 v[92:95], v[206:209], v[222:225], v[92:95]
	v_mfma_f32_16x16x32_f16 v[80:83], v[198:201], v[230:233], v[80:83]
	v_mfma_f32_16x16x32_f16 v[76:79], v[206:209], v[230:233], v[76:79]
	v_mfma_f32_16x16x32_f16 v[72:75], v[198:201], v[238:241], v[72:75]
	v_mfma_f32_16x16x32_f16 v[68:71], v[206:209], v[238:241], v[68:71]
	v_mfma_f32_16x16x32_f16 v[120:123], v[202:205], v[218:221], v[120:123]
	v_mfma_f32_16x16x32_f16 v[112:115], v[210:213], v[218:221], v[112:115]
	v_mfma_f32_16x16x32_f16 v[96:99], v[202:205], v[226:229], v[96:99]
	v_mfma_f32_16x16x32_f16 v[92:95], v[210:213], v[226:229], v[92:95]
	v_mfma_f32_16x16x32_f16 v[80:83], v[202:205], v[234:237], v[80:83]
	v_mfma_f32_16x16x32_f16 v[76:79], v[210:213], v[234:237], v[76:79]
	v_mfma_f32_16x16x32_f16 v[72:75], v[202:205], v[242:245], v[72:75]
	v_mfma_f32_16x16x32_f16 v[68:71], v[210:213], v[242:245], v[68:71]
	s_barrier
	s_add_i32 s25, s82, s2
	v_lshl_add_u64 v[154:155], v[154:155], 0, s[72:73]
	s_mov_b32 m0, s25
	ds_read_b128 v[214:217], v148 offset:49152
	ds_read_b128 v[218:221], v148 offset:50176
	ds_read_b128 v[222:225], v148 offset:51200
	ds_read_b128 v[226:229], v148 offset:52224
	ds_read_b128 v[230:233], v148 offset:53248
	ds_read_b128 v[234:237], v148 offset:54272
	ds_read_b128 v[238:241], v148 offset:55296
	ds_read_b128 v[242:245], v148 offset:56320
	global_load_lds_dwordx4 v[154:155], off
	v_lshl_add_u64 v[154:155], v[168:169], 0, s[72:73]
	s_add_i32 m0, s25, 0x2000
	s_add_i32 s25, s62, s2
	global_load_lds_dwordx4 v[154:155], off
	v_lshl_add_u64 v[154:155], v[178:179], 0, s[72:73]
	s_mov_b32 m0, s25
	s_nop 0
	global_load_lds_dwordx4 v[154:155], off
	v_lshl_add_u64 v[154:155], v[246:247], 0, s[72:73]
	s_add_i32 m0, s25, 0x2000
	s_nop 0
	global_load_lds_dwordx4 v[154:155], off
	v_lshl_add_u64 v[154:155], v[248:249], 0, s[72:73]
	s_mov_b32 m0, s12
	s_nop 0
	global_load_lds_dwordx4 v[154:155], off
	v_lshl_add_u64 v[154:155], v[250:251], 0, s[72:73]
	s_mov_b32 m0, s13
	s_nop 0
	global_load_lds_dwordx4 v[154:155], off
	s_waitcnt vmcnt(8)
	s_waitcnt lgkmcnt(0)
	v_mfma_f32_16x16x32_f16 v[64:67], v[150:153], v[214:217], v[64:67]
	v_mfma_f32_16x16x32_f16 v[60:63], v[190:193], v[214:217], v[60:63]
	v_mfma_f32_16x16x32_f16 v[56:59], v[150:153], v[222:225], v[56:59]
	v_mfma_f32_16x16x32_f16 v[52:55], v[190:193], v[222:225], v[52:55]
	s_barrier
	s_waitcnt lgkmcnt(0)
	v_mfma_f32_16x16x32_f16 v[40:43], v[150:153], v[230:233], v[40:43]
	v_mfma_f32_16x16x32_f16 v[36:39], v[190:193], v[230:233], v[36:39]
	v_mfma_f32_16x16x32_f16 v[24:27], v[150:153], v[238:241], v[24:27]
	v_mfma_f32_16x16x32_f16 v[20:23], v[190:193], v[238:241], v[20:23]
	v_mfma_f32_16x16x32_f16 v[64:67], v[186:189], v[218:221], v[64:67]
	v_mfma_f32_16x16x32_f16 v[60:63], v[194:197], v[218:221], v[60:63]
	v_mfma_f32_16x16x32_f16 v[56:59], v[186:189], v[226:229], v[56:59]
	v_mfma_f32_16x16x32_f16 v[52:55], v[194:197], v[226:229], v[52:55]
	v_mfma_f32_16x16x32_f16 v[40:43], v[186:189], v[234:237], v[40:43]
	v_mfma_f32_16x16x32_f16 v[36:39], v[194:197], v[234:237], v[36:39]
	v_mfma_f32_16x16x32_f16 v[24:27], v[186:189], v[242:245], v[24:27]
	v_mfma_f32_16x16x32_f16 v[20:23], v[194:197], v[242:245], v[20:23]
	v_mfma_f32_16x16x32_f16 v[48:51], v[198:201], v[214:217], v[48:51]
	v_mfma_f32_16x16x32_f16 v[44:47], v[206:209], v[214:217], v[44:47]
	v_mfma_f32_16x16x32_f16 v[32:35], v[198:201], v[222:225], v[32:35]
	v_mfma_f32_16x16x32_f16 v[28:31], v[206:209], v[222:225], v[28:31]
	v_mfma_f32_16x16x32_f16 v[16:19], v[198:201], v[230:233], v[16:19]
	v_mfma_f32_16x16x32_f16 v[12:15], v[206:209], v[230:233], v[12:15]
	v_mfma_f32_16x16x32_f16 v[8:11], v[198:201], v[238:241], v[8:11]
	v_mfma_f32_16x16x32_f16 v[4:7], v[206:209], v[238:241], v[4:7]
	v_mfma_f32_16x16x32_f16 v[48:51], v[202:205], v[218:221], v[48:51]
	v_mfma_f32_16x16x32_f16 v[44:47], v[210:213], v[218:221], v[44:47]
	v_mfma_f32_16x16x32_f16 v[32:35], v[202:205], v[226:229], v[32:35]
	v_mfma_f32_16x16x32_f16 v[28:31], v[210:213], v[226:229], v[28:31]
	v_mfma_f32_16x16x32_f16 v[16:19], v[202:205], v[234:237], v[16:19]
	v_mfma_f32_16x16x32_f16 v[12:15], v[210:213], v[234:237], v[12:15]
	v_mfma_f32_16x16x32_f16 v[8:11], v[202:205], v[242:245], v[8:11]
	v_mfma_f32_16x16x32_f16 v[4:7], v[210:213], v[242:245], v[4:7]
	s_barrier
	s_add_i32 s24, s24, 2
	s_add_u32 s54, s54, 0x100
	s_addc_u32 s55, s55, 0
	s_add_u32 s21, s21, 0x100
	s_addc_u32 s23, s23, 0
	s_cmp_gt_u32 s24, 13
	s_cbranch_scc0 .LBB0_929
	s_and_b64 vcc, exec, s[44:45]
	s_cbranch_vccz .LBB0_932
	s_barrier

.LBB0_988:
	s_or_b64 exec, exec, s[4:5]
	s_waitcnt lgkmcnt(0)
	v_mov_b32_e32 v0, v170
	s_barrier
	v_readlane_b32 s1, v254, 18
	v_readfirstlane_b32 s0, v0
	s_ashr_i32 s0, s0, 6
	v_and_b32_e32 v85, 15, v0
	s_lshl_b32 s23, s0, 4
	v_or_b32_e32 v1, s23, v85
	v_lshl_add_u32 v60, v1, 4, s1
	v_ashrrev_i32_e32 v61, 31, v60
	v_readlane_b32 s2, v254, 0
	v_lshlrev_b64 v[12:13], 7, v[60:61]
	v_readlane_b32 s3, v254, 1
	v_bfe_u32 v86, v0, 4, 2
	v_lshlrev_b32_e32 v2, 3, v86
	v_lshl_add_u64 v[4:5], s[2:3], 0, v[12:13]
	v_readlane_b32 s2, v253, 6
	v_readlane_b32 s3, v253, 7
	v_and_b32_e32 v6, 48, v0
	v_mov_b32_e32 v7, v3
	v_lshl_add_u64 v[14:15], v[60:61], 2, s[2:3]
	v_readlane_b32 s2, v253, 8
	v_readlane_b32 s3, v253, 9
	v_lshl_add_u64 v[4:5], v[4:5], 0, v[6:7]
	global_load_dwordx4 v[8:11], v[4:5], off
	s_nop 0
	global_load_dwordx4 v[4:7], v[4:5], off offset:64
	v_lshl_add_u64 v[12:13], s[2:3], 0, v[12:13]
	v_lshl_add_u64 v[12:13], v[12:13], 0, v[2:3]
	global_load_dword v61, v[14:15], off
	global_load_dwordx2 v[68:69], v[12:13], off
	global_load_dwordx2 v[66:67], v[12:13], off offset:32
	global_load_dwordx2 v[64:65], v[12:13], off offset:64
	global_load_dwordx2 v[62:63], v[12:13], off offset:96
	s_cmp_gt_i32 s0, 3
	s_cbranch_scc1 .LBB0_990
.LBB0_990:
	s_add_i32 s1, s0, 8
	s_lshl_b32 s2, s0, 1
	s_lshl_b32 s52, s0, 3
	s_lshl_b32 s53, s0, 10
	s_lshl_b32 s54, s1, 3
	s_lshl_b32 s55, s1, 10
	s_lshl_b32 s56, s0, 2
	s_lshl_b32 s57, s1, 2
	s_and_b32 s58, s23, 0x70
	s_add_i32 s3, s2, 2
	s_add_i32 s5, s2, 4
	s_add_i32 s6, s2, 6
	s_add_i32 s1, s1, s0
	s_add_i32 s7, s2, 10
	s_add_i32 s8, s2, 12
	s_add_i32 s9, s2, 14
	s_cmp_gt_u32 s2, 0xffffffef
	s_mov_b32 s29, 0x8000
	s_mov_b32 s4, 0x18000
	s_cselect_b32 s10, 0x18000, 0
	s_cselect_b32 s12, 0, 0x8000
	s_cselect_b32 s13, s29, 0x10000
	s_cselect_b32 s11, 0x10000, s4
	s_cmp_lt_u32 s9, 16
	v_writelane_b32 v255, s11, 26
	s_cselect_b32 s11, 0x18000, 0
	s_cselect_b32 s20, 0, 0x8000
	s_cselect_b32 s21, s29, 0x10000
	s_cselect_b32 s44, 0x10000, s4
	s_cmp_lt_u32 s8, 16
	s_cselect_b32 s14, 0x18000, 0
	s_cselect_b32 s24, 0, 0x8000
	s_cselect_b32 s25, s29, 0x10000
	s_cselect_b32 s45, 0x10000, s4
	s_cmp_lt_u32 s7, 16
	s_cselect_b32 s15, 0x18000, 0
	s_cselect_b32 s26, 0, 0x8000
	s_cselect_b32 s27, s29, 0x10000
	s_cselect_b32 s46, 0x10000, s4
	s_cmp_lt_u32 s1, 16
	s_cselect_b32 s16, 0x18000, 0
	s_cselect_b32 s31, 0, 0x8000
	s_cselect_b32 s35, s29, 0x10000
	s_cselect_b32 s47, 0x10000, s4
	s_cmp_lt_u32 s6, 16
	s_cselect_b32 s17, 0x18000, 0
	s_cselect_b32 s36, 0, 0x8000
	s_cselect_b32 s37, s29, 0x10000
	s_cselect_b32 s48, 0x10000, s4
	s_cmp_lt_u32 s5, 16
	s_cselect_b32 s18, 0x18000, 0
	s_cselect_b32 s38, 0, 0x8000
	s_cselect_b32 s49, s29, 0x10000
	s_cselect_b32 s50, 0x10000, s4
	s_cmp_lt_u32 s3, 16
	s_cselect_b32 s19, 0x18000, 0
	s_cselect_b32 s51, 0, 0x8000
	s_cselect_b32 s61, s29, 0x10000
	s_cselect_b32 s63, 0x10000, s4
	s_cmp_lt_u32 s2, 16
	s_cselect_b32 s28, 0x18000, 0
	s_cselect_b32 s59, 0, 0x8000
	s_cselect_b32 s60, s29, 0x10000
	s_cselect_b32 s64, 0x10000, s4
	s_cmp_gt_i32 s0, -1
	s_cselect_b32 s71, 0x10000, s29
	s_cselect_b32 s78, s4, 0x10000
	s_cmp_gt_i32 s0, 0
	s_cselect_b32 s30, 0, 0x18000
	s_cselect_b32 s65, 0x8000, 0
	s_cselect_b32 s74, 0x10000, s29
	s_cselect_b32 s79, s4, 0x10000
	s_cmp_gt_i32 s0, 1
	s_cselect_b32 s34, 0, 0x18000
	s_cselect_b32 s66, 0x8000, 0
	s_cselect_b32 s77, 0x10000, s29
	s_cselect_b32 s83, s4, 0x10000
	s_cmp_gt_i32 s0, 2
	s_cselect_b32 s39, 0, 0x18000
	s_cselect_b32 s69, 0x8000, 0
	s_cselect_b32 s84, 0x10000, s29
	s_cselect_b32 s88, s4, 0x10000
	s_cmp_gt_i32 s0, 3
	s_cselect_b32 s70, 0, 0x18000
	s_cselect_b32 s80, 0x8000, 0
	s_cselect_b32 s87, 0x10000, s29
	s_cselect_b32 s89, s4, 0x10000
	s_cmp_gt_i32 s0, 4
	s_cselect_b32 s75, 0, 0x18000
	s_cselect_b32 s90, 0x8000, 0
	s_cselect_b32 s91, 0x10000, s29
	s_cselect_b32 s94, s4, 0x10000
	s_cmp_gt_i32 s0, 5
	s_cselect_b32 s76, 0, 0x18000
	s_cselect_b32 s92, 0x8000, 0
	s_cselect_b32 s93, 0x10000, s29
	s_cselect_b32 s95, s4, 0x10000
	s_cmp_gt_i32 s0, 6
	s_cselect_b32 s85, 0, 0x18000
	s_cselect_b32 s96, 0x8000, 0
	s_cselect_b32 s97, 0x10000, s29
	s_cselect_b32 vcc_lo, s4, 0x10000
	s_cmp_gt_i32 s0, 7
	s_cselect_b32 s86, 0, 0x18000
	s_cselect_b32 vcc_hi, 0x8000, 0
	s_cselect_b32 s29, 0x10000, s29
	s_cselect_b32 s4, s4, 0x10000
	s_add_i32 s75, s75, 0
	v_writelane_b32 v255, s75, 6
	s_add_i32 s70, s70, 0
	v_writelane_b32 v255, s70, 7
	s_add_i32 s39, s39, 0
	v_writelane_b32 v255, s39, 8
	s_add_i32 s34, s34, 0
	v_writelane_b32 v255, s34, 9
	s_add_i32 s30, s30, 0
	v_writelane_b32 v255, s30, 10
	s_ashr_i32 s30, s0, 31
	s_and_b32 s30, s30, 0x18000
	s_add_i32 s30, s30, 0
	v_writelane_b32 v255, s30, 11
	s_add_i32 s28, s28, 0
	v_writelane_b32 v255, s28, 12
	s_add_i32 s19, s19, 0
	v_writelane_b32 v255, s19, 13
	s_and_b32 s39, s2, 14
	s_add_i32 s2, s18, 0
	v_writelane_b32 v255, s2, 14
	s_add_i32 s2, s17, 0
	v_writelane_b32 v255, s2, 15
	s_add_i32 s2, s16, 0
	v_writelane_b32 v255, s2, 16
	s_add_i32 s2, s15, 0
	v_writelane_b32 v255, s2, 17
	s_and_b32 s75, s1, 14
	s_add_i32 s1, s14, 0
	v_writelane_b32 v255, s1, 18
	s_add_i32 s1, s11, 0
	v_writelane_b32 v255, s1, 19
	s_add_i32 s1, s10, 0
	v_writelane_b32 v255, s1, 20
	s_add_i32 s1, vcc_hi, 0
	v_writelane_b32 v255, s1, 21
	s_add_i32 s1, s96, 0
	v_writelane_b32 v255, s1, 22
	s_add_i32 s1, s92, 0
	v_writelane_b32 v255, s1, 23
	s_add_i32 s1, s90, 0
	s_add_i32 s86, s86, 0
	v_writelane_b32 v255, s1, 28
	s_add_i32 s1, s80, 0
	v_writelane_b32 v253, s86, 1
	s_add_i32 s85, s85, 0
	v_writelane_b32 v255, s1, 29
	s_add_i32 s1, s69, 0
	s_add_i32 s86, s23, 16
	v_writelane_b32 v253, s85, 13
	s_add_i32 s76, s76, 0
	v_writelane_b32 v255, s1, 30
	s_add_i32 s1, s66, 0
	s_add_i32 s2, s23, 32
	s_add_i32 s19, s23, 48
	s_add_i32 s80, s23, 0x50
	s_add_i32 s17, s23, 0x60
	s_add_i32 s14, s23, 0x70
	v_writelane_b32 v253, s76, 2
	s_and_b32 s70, s3, 14
	s_and_b32 s85, s5, 14
	s_and_b32 s34, s6, 14
	s_and_b32 s76, s7, 14
	s_and_b32 s11, s8, 14
	s_and_b32 s30, s9, 14
	v_writelane_b32 v255, s1, 31
	s_add_i32 s1, s65, 0
	s_and_b32 s3, s86, 0x70
	s_and_b32 s18, s2, 0x70
	s_and_b32 s65, s19, 0x70
	s_xor_b32 s66, s58, 64
	s_and_b32 s16, s80, 0x70
	s_and_b32 s28, s17, 0x70
	s_and_b32 s15, s14, 0x70
	s_add_i32 s69, s23, 64
	s_cmp_lt_i32 s0, 0
	s_cselect_b32 s0, 0, 0x8000
	v_writelane_b32 v255, s1, 32
	s_add_i32 s0, s0, 0
	v_writelane_b32 v255, s0, 33
	s_add_i32 s0, s59, 0
	v_writelane_b32 v255, s0, 34
	s_add_i32 s0, s51, 0
	v_writelane_b32 v255, s0, 35
	s_add_i32 s0, s38, 0
	v_writelane_b32 v255, s0, 36
	s_add_i32 s0, s36, 0
	v_writelane_b32 v255, s0, 37
	s_add_i32 s0, s31, 0
	v_writelane_b32 v255, s0, 38
	s_add_i32 s0, s26, 0
	v_writelane_b32 v255, s0, 39
	s_add_i32 s0, s24, 0
	v_writelane_b32 v254, s0, 54
	s_add_i32 s0, s20, 0
	v_writelane_b32 v255, s0, 40
	s_add_i32 s0, s12, 0
	v_and_b32_e32 v87, 63, v0
	v_lshlrev_b32_e32 v0, 2, v86
	v_writelane_b32 v254, s0, 58
	v_readlane_b32 s0, v253, 8
	v_lshlrev_b32_e32 v56, 1, v0
	v_mov_b32_e32 v57, v3
	v_readlane_b32 s1, v253, 9
	s_add_i32 s92, s91, 0
	s_add_i32 s59, s84, 0
	v_lshl_add_u64 v[58:59], s[0:1], 0, v[56:57]
	s_add_i32 s0, s29, 0
	v_writelane_b32 v254, s0, 59
	s_add_i32 s0, s97, 0
	v_writelane_b32 v255, s0, 24
	s_add_i32 s0, s93, 0
	v_writelane_b32 v255, s0, 25
	s_add_i32 s0, s35, 0
	s_add_i32 s35, s4, 0
	v_readlane_b32 s4, v255, 26
	s_add_i32 s93, s87, 0
	s_add_i32 s87, s77, 0
	s_add_i32 s90, s74, 0
	s_add_i32 s91, s71, 0
	s_add_i32 s60, s60, 0
	s_add_i32 s61, s61, 0
	s_add_i32 s36, s49, 0
	s_add_i32 s37, s37, 0
	s_add_i32 s1, s27, 0
	s_add_i32 s38, s25, 0
	s_add_i32 s71, s21, 0
	s_add_i32 s84, s13, 0
	s_add_i32 s74, vcc_lo, 0
	s_add_i32 s77, s95, 0
	s_add_i32 s10, s94, 0
	s_add_i32 s31, s89, 0
	s_add_i32 s26, s88, 0
	s_add_i32 s27, s83, 0
	s_add_i32 s12, s79, 0
	s_add_i32 s13, s78, 0
	s_add_i32 s24, s64, 0
	s_add_i32 s25, s63, 0
	s_add_i32 s63, s50, 0
	s_add_i32 s64, s48, 0
	s_add_i32 s20, s47, 0
	s_add_i32 s21, s46, 0
	s_add_i32 s78, s45, 0
	s_add_i32 s79, s44, 0
	s_add_i32 s83, s4, 0
	v_mov_b32_e32 v2, 0
	v_mov_b32_e32 v20, 0
	s_mov_b32 s89, 0
	s_add_i32 s88, s23, 0x80
	v_cmp_gt_u32_e64 s[4:5], 16, v87
	s_mov_b64 s[50:51], 0
	s_mov_b64 s[44:45], -1
	v_readlane_b32 s48, v254, 15
	s_mov_b32 s6, 0
	v_readlane_b32 s49, v254, 16

.Lat991_i3_nomask:
	v_max3_f32 v245, v44, v45, v46
	v_max3_f32 v245, v245, v47, v48
	v_max3_f32 v245, v245, v49, v50
	v_max3_f32 v245, v245, v51, v52
	v_max3_f32 v245, v245, v53, v54
	v_max3_f32 v245, v245, v55, v56
	v_max3_f32 v245, v245, v57, v58
	v_max3_f32 v245, v245, v59, v60
	v_max3_f32 v245, v245, v61, v62
	v_max3_f32 v245, v245, v63, v64
	v_max3_f32 v245, v245, v65, v66
	v_max3_f32 v245, v245, v67, v68
	v_max3_f32 v245, v245, v69, v70
	v_max3_f32 v245, v245, v71, v72
	v_max3_f32 v245, v245, v73, v74
	v_max3_f32 v245, v245, v75, v76
	v_max3_f32 v245, v245, v77, v78
	v_max_f32_e32 v245, v245, v79
	v_mov_b32_e32 v148, v245
	s_nop 1
	v_permlane16_swap_b32 v245, v148
	v_max_f32_e32 v245, v245, v148
	v_mov_b32_e32 v148, v245
	s_nop 1
	v_permlane32_swap_b32 v245, v148
	v_max_f32_e32 v245, v245, v148
	v_sub_f32_e32 v44, v44, v245
	v_sub_f32_e32 v45, v45, v245
	v_sub_f32_e32 v46, v46, v245
	v_sub_f32_e32 v47, v47, v245
	v_exp_f32_e32 v44, v44
	v_exp_f32_e32 v45, v45
	v_exp_f32_e32 v46, v46
	v_exp_f32_e32 v47, v47
	v_sub_f32_e32 v48, v48, v245
	v_sub_f32_e32 v49, v49, v245
	v_sub_f32_e32 v50, v50, v245
	v_sub_f32_e32 v51, v51, v245
	v_exp_f32_e32 v48, v48
	v_exp_f32_e32 v49, v49
	v_exp_f32_e32 v50, v50
	v_exp_f32_e32 v51, v51
	v_mov_b32_e32 v149, v44
	v_mov_b32_e32 v150, v45
	v_mov_b32_e32 v151, v46
	v_mov_b32_e32 v152, v47
	v_cvt_pk_bf16_f32 v44, v44, v45
	v_cvt_pk_bf16_f32 v45, v46, v47
	v_sub_f32_e32 v52, v52, v245
	v_sub_f32_e32 v53, v53, v245
	v_sub_f32_e32 v54, v54, v245
	v_sub_f32_e32 v55, v55, v245
	v_exp_f32_e32 v52, v52
	v_exp_f32_e32 v53, v53
	v_exp_f32_e32 v54, v54
	v_exp_f32_e32 v55, v55
	v_add_f32_e32 v149, v149, v48
	v_add_f32_e32 v150, v150, v49
	v_add_f32_e32 v151, v151, v50
	v_add_f32_e32 v152, v152, v51
	v_cvt_pk_bf16_f32 v46, v48, v49
	v_cvt_pk_bf16_f32 v47, v50, v51
	v_sub_f32_e32 v56, v56, v245
	v_sub_f32_e32 v57, v57, v245
	v_sub_f32_e32 v58, v58, v245
	v_sub_f32_e32 v59, v59, v245
	v_exp_f32_e32 v56, v56
	v_exp_f32_e32 v57, v57
	v_exp_f32_e32 v58, v58
	v_exp_f32_e32 v59, v59
	v_add_f32_e32 v149, v149, v52
	v_add_f32_e32 v150, v150, v53
	v_add_f32_e32 v151, v151, v54
	v_add_f32_e32 v152, v152, v55
	v_cvt_pk_bf16_f32 v52, v52, v53
	v_cvt_pk_bf16_f32 v53, v54, v55
	v_sub_f32_e32 v60, v60, v245
	v_sub_f32_e32 v61, v61, v245
	v_sub_f32_e32 v62, v62, v245
	v_sub_f32_e32 v63, v63, v245
	v_exp_f32_e32 v60, v60
	v_exp_f32_e32 v61, v61
	v_exp_f32_e32 v62, v62
	v_exp_f32_e32 v63, v63
	v_add_f32_e32 v149, v149, v56
	v_add_f32_e32 v150, v150, v57
	v_add_f32_e32 v151, v151, v58
	v_add_f32_e32 v152, v152, v59
	v_cvt_pk_bf16_f32 v54, v56, v57
	v_cvt_pk_bf16_f32 v55, v58, v59
	v_sub_f32_e32 v64, v64, v245
	v_sub_f32_e32 v65, v65, v245
	v_sub_f32_e32 v66, v66, v245
	v_sub_f32_e32 v67, v67, v245
	v_exp_f32_e32 v64, v64
	v_exp_f32_e32 v65, v65
	v_exp_f32_e32 v66, v66
	v_exp_f32_e32 v67, v67
	v_add_f32_e32 v149, v149, v60
	v_add_f32_e32 v150, v150, v61
	v_add_f32_e32 v151, v151, v62
	v_add_f32_e32 v152, v152, v63
	v_cvt_pk_bf16_f32 v60, v60, v61
	v_cvt_pk_bf16_f32 v61, v62, v63
	v_sub_f32_e32 v68, v68, v245
	v_sub_f32_e32 v69, v69, v245
	v_sub_f32_e32 v70, v70, v245
	v_sub_f32_e32 v71, v71, v245
	v_exp_f32_e32 v68, v68
	v_exp_f32_e32 v69, v69
	v_exp_f32_e32 v70, v70
	v_exp_f32_e32 v71, v71
	v_add_f32_e32 v149, v149, v64
	v_add_f32_e32 v150, v150, v65
	v_add_f32_e32 v151, v151, v66
	v_add_f32_e32 v152, v152, v67
	v_cvt_pk_bf16_f32 v62, v64, v65
	v_cvt_pk_bf16_f32 v63, v66, v67
	v_sub_f32_e32 v72, v72, v245
	v_sub_f32_e32 v73, v73, v245
	v_sub_f32_e32 v74, v74, v245
	v_sub_f32_e32 v75, v75, v245
	v_exp_f32_e32 v72, v72
	v_exp_f32_e32 v73, v73
	v_exp_f32_e32 v74, v74
	v_exp_f32_e32 v75, v75
	v_add_f32_e32 v149, v149, v68
	v_add_f32_e32 v150, v150, v69
	v_add_f32_e32 v151, v151, v70
	v_add_f32_e32 v152, v152, v71
	v_cvt_pk_bf16_f32 v68, v68, v69
	v_cvt_pk_bf16_f32 v69, v70, v71
	v_sub_f32_e32 v76, v76, v245
	v_sub_f32_e32 v77, v77, v245
	v_sub_f32_e32 v78, v78, v245
	v_sub_f32_e32 v79, v79, v245
	v_exp_f32_e32 v76, v76
	v_exp_f32_e32 v77, v77
	v_exp_f32_e32 v78, v78
	v_exp_f32_e32 v79, v79
	v_add_f32_e32 v149, v149, v72
	v_add_f32_e32 v150, v150, v73
	v_add_f32_e32 v151, v151, v74
	v_add_f32_e32 v152, v152, v75
	v_cvt_pk_bf16_f32 v70, v72, v73
	v_cvt_pk_bf16_f32 v71, v74, v75
	s_nop 0
	v_add_f32_e32 v149, v149, v76
	v_add_f32_e32 v150, v150, v77
	v_add_f32_e32 v151, v151, v78
	v_add_f32_e32 v152, v152, v79
	v_cvt_pk_bf16_f32 v76, v76, v77
	v_cvt_pk_bf16_f32 v77, v78, v79
	v_mov_b32_e32 v78, 0
	v_mov_b32_e32 v79, 0
	v_add_f32_e32 v149, v149, v150
	v_add_f32_e32 v151, v151, v152
	v_add_f32_e32 v246, v149, v151
	s_waitcnt lgkmcnt(0)
	v_mfma_f32_16x16x32_bf16 v[80:83], v[4:7], v[44:47], 0
	v_mfma_f32_16x16x32_bf16 v[84:87], v[8:11], v[44:47], 0
	v_mfma_f32_16x16x32_bf16 v[88:91], v[12:15], v[44:47], 0
	v_mfma_f32_16x16x32_bf16 v[92:95], v[16:19], v[44:47], 0
	ds_read_b64 v[4:5], v225 offset:32768
	ds_read_b64 v[8:9], v225 offset:36864
	ds_read_b64 v[12:13], v225 offset:40960
	ds_read_b64 v[16:17], v225 offset:45056
	ds_read_b64 v[6:7], v226 offset:32768
	ds_read_b64 v[10:11], v226 offset:36864
	ds_read_b64 v[14:15], v226 offset:40960
	ds_read_b64 v[18:19], v226 offset:45056
	v_mfma_f32_16x16x32_bf16 v[80:83], v[20:23], v[52:55], v[80:83]
	v_mfma_f32_16x16x32_bf16 v[84:87], v[24:27], v[52:55], v[84:87]
	v_mfma_f32_16x16x32_bf16 v[88:91], v[28:31], v[52:55], v[88:91]
	v_mfma_f32_16x16x32_bf16 v[92:95], v[32:35], v[52:55], v[92:95]
	ds_read_b64 v[20:21], v227 offset:32768
	ds_read_b64 v[24:25], v227 offset:36864
	ds_read_b64 v[28:29], v227 offset:40960
	ds_read_b64 v[32:33], v227 offset:45056
	ds_read_b64 v[22:23], v228 offset:32768
	ds_read_b64 v[26:27], v228 offset:36864
	ds_read_b64 v[30:31], v228 offset:40960
	ds_read_b64 v[34:35], v228 offset:45056
	s_waitcnt lgkmcnt(8)
	v_mfma_f32_16x16x32_bf16 v[80:83], v[4:7], v[60:63], v[80:83]
	v_mfma_f32_16x16x32_bf16 v[84:87], v[8:11], v[60:63], v[84:87]
	v_mfma_f32_16x16x32_bf16 v[88:91], v[12:15], v[60:63], v[88:91]
	v_mfma_f32_16x16x32_bf16 v[92:95], v[16:19], v[60:63], v[92:95]
	ds_read_b64 v[4:5], v229 offset:32768
	ds_read_b64 v[8:9], v229 offset:36864
	ds_read_b64 v[12:13], v229 offset:40960
	ds_read_b64 v[16:17], v229 offset:45056
	v_mov_b32_e32 v6, 0
	v_mov_b32_e32 v7, 0
	v_mov_b32_e32 v10, 0
	v_mov_b32_e32 v11, 0
	v_mov_b32_e32 v14, 0
	v_mov_b32_e32 v15, 0
	v_mov_b32_e32 v18, 0
	v_mov_b32_e32 v19, 0
	s_waitcnt lgkmcnt(4)
	v_mfma_f32_16x16x32_bf16 v[80:83], v[20:23], v[68:71], v[80:83]
	v_mfma_f32_16x16x32_bf16 v[84:87], v[24:27], v[68:71], v[84:87]
	v_mfma_f32_16x16x32_bf16 v[88:91], v[28:31], v[68:71], v[88:91]
	v_mfma_f32_16x16x32_bf16 v[92:95], v[32:35], v[68:71], v[92:95]
	s_waitcnt lgkmcnt(0)
	v_mfma_f32_16x16x32_bf16 v[80:83], v[4:7], v[76:79], v[80:83]
	v_mfma_f32_16x16x32_bf16 v[84:87], v[8:11], v[76:79], v[84:87]
	v_mfma_f32_16x16x32_bf16 v[88:91], v[12:15], v[76:79], v[88:91]
	v_mfma_f32_16x16x32_bf16 v[92:95], v[16:19], v[76:79], v[92:95]
	v_mov_b32_e32 v148, v246
	s_nop 1
	v_permlane16_swap_b32 v246, v148
	v_add_f32_e32 v246, v246, v148
	v_mov_b32_e32 v148, v246
	s_nop 1
	v_permlane32_swap_b32 v246, v148
	v_add_f32_e32 v246, v246, v148
	v_rcp_f32_e32 v149, v246
	v_log_f32_e32 v150, v246
	s_nop 0
	v_add_f32_e32 v151, v245, v150
	v_mul_f32_e32 v151, 0x3f317218, v151
	v_max_f32_e32 v152, v121, v151
	v_sub_f32_e32 v153, v121, v152
	v_sub_f32_e32 v154, v151, v152
	v_mul_f32_e32 v153, 0x3fb8aa3b, v153
	v_mul_f32_e32 v154, 0x3fb8aa3b, v154
	v_exp_f32_e32 v153, v153
	v_exp_f32_e32 v154, v154
	s_nop 0
	v_add_f32_e32 v155, v153, v154
	v_rcp_f32_e32 v146, v155
	v_log_f32_e32 v150, v155
	s_nop 0
	v_mul_f32_e32 v154, v154, v146
	v_mul_f32_e32 v146, v153, v146
	v_mul_f32_e32 v147, v149, v154
	v_mul_f32_e32 v150, 0x3f317218, v150
	v_add_f32_e32 v140, v152, v150
	v_mul_f32_e32 v80, v80, v147
	v_mul_f32_e32 v81, v81, v147
	v_mul_f32_e32 v82, v82, v147
	v_mul_f32_e32 v83, v83, v147
	v_mul_f32_e32 v84, v84, v147
	v_mul_f32_e32 v85, v85, v147
	v_mul_f32_e32 v86, v86, v147
	v_mul_f32_e32 v87, v87, v147
	v_mul_f32_e32 v88, v88, v147
	v_mul_f32_e32 v89, v89, v147
	v_mul_f32_e32 v90, v90, v147
	v_mul_f32_e32 v91, v91, v147
	v_mul_f32_e32 v92, v92, v147
	v_mul_f32_e32 v93, v93, v147
	v_mul_f32_e32 v94, v94, v147
	v_mul_f32_e32 v95, v95, v147
	v_lshlrev_b32_e32 v141, 16, v122
	v_and_b32_e32 v142, 0xffff0000, v122
	v_lshlrev_b32_e32 v143, 16, v123
	v_and_b32_e32 v144, 0xffff0000, v123
	v_fmac_f32_e32 v80, v146, v141
	v_fmac_f32_e32 v81, v146, v142
	v_fmac_f32_e32 v82, v146, v143
	v_fmac_f32_e32 v83, v146, v144
	v_cvt_pk_bf16_f32 v132, v80, v81
	v_cvt_pk_bf16_f32 v133, v82, v83
	v_lshlrev_b32_e32 v141, 16, v124
	v_and_b32_e32 v142, 0xffff0000, v124
	v_lshlrev_b32_e32 v143, 16, v125
	v_and_b32_e32 v144, 0xffff0000, v125
	v_fmac_f32_e32 v84, v146, v141
	v_fmac_f32_e32 v85, v146, v142
	v_fmac_f32_e32 v86, v146, v143
	v_fmac_f32_e32 v87, v146, v144
	v_cvt_pk_bf16_f32 v134, v84, v85
	v_cvt_pk_bf16_f32 v135, v86, v87
	v_lshlrev_b32_e32 v141, 16, v126
	v_and_b32_e32 v142, 0xffff0000, v126
	v_lshlrev_b32_e32 v143, 16, v127
	v_and_b32_e32 v144, 0xffff0000, v127
	v_fmac_f32_e32 v88, v146, v141
	v_fmac_f32_e32 v89, v146, v142
	v_fmac_f32_e32 v90, v146, v143
	v_fmac_f32_e32 v91, v146, v144
	v_cvt_pk_bf16_f32 v136, v88, v89
	v_cvt_pk_bf16_f32 v137, v90, v91
	v_lshlrev_b32_e32 v141, 16, v128
	v_and_b32_e32 v142, 0xffff0000, v128
	v_lshlrev_b32_e32 v143, 16, v129
	v_and_b32_e32 v144, 0xffff0000, v129
	v_fmac_f32_e32 v92, v146, v141
	v_fmac_f32_e32 v93, v146, v142
	v_fmac_f32_e32 v94, v146, v143
	v_fmac_f32_e32 v95, v146, v144
	v_cvt_pk_bf16_f32 v138, v92, v93
	v_cvt_pk_bf16_f32 v139, v94, v95
	s_mov_b64 s[26:27], s[86:87]
	s_mov_b64 s[28:29], s[88:89]
	s_mov_b64 s[86:87], s[12:13]
	s_mov_b64 s[88:89], s[14:15]
	s_mov_b32 s4, s83
	s_mov_b32 s5, s84
	s_add_u32 s7, s7, 1
	s_cmp_lt_u32 s7, 2
	s_cbranch_scc1 .Lat991_loop
	global_store_dwordx2 v237, v[132:133], s[26:27]
	global_store_dwordx2 v237, v[134:135], s[26:27] offset:32
	global_store_dwordx2 v237, v[136:137], s[26:27] offset:64
	global_store_dwordx2 v237, v[138:139], s[26:27] offset:96
	s_mov_b64 s[90:91], exec
	s_mov_b64 exec, 0xffff
	global_store_dword v238, v140, s[28:29]
	s_mov_b64 exec, s[90:91]
	s_waitcnt vmcnt(0)
	s_barrier
	s_waitcnt vmcnt(0)
	s_barrier
	s_mov_b64 s[4:5], exec
	v_readlane_b32 s0, v252, 2
	v_readlane_b32 s1, v252, 3
	v_readlane_b32 s64, v253, 15
	v_readlane_b32 s34, v252, 27
	v_readlane_b32 s56, v253, 19
	v_readlane_b32 s16, v253, 21
	v_readlane_b32 s36, v252, 29
	v_readlane_b32 s70, v252, 31
	v_readlane_b32 s74, v252, 33
	v_readlane_b32 s76, v252, 35
	v_readlane_b32 s78, v252, 37
	s_and_b64 s[0:1], s[4:5], s[0:1]
	v_readlane_b32 s85, v253, 23
	v_readlane_b32 s92, v253, 24
	v_readlane_b32 s65, v253, 16
	v_readlane_b32 s63, v252, 26
	v_readlane_b32 s66, v253, 18
	v_readlane_b32 s35, v252, 28
	v_readlane_b32 s57, v253, 20
	v_readlane_b32 s17, v253, 22
	v_readlane_b32 s37, v252, 30
	v_readlane_b32 s71, v252, 32
	v_readlane_b32 s75, v252, 34
	v_readlane_b32 s77, v252, 36
	v_readlane_b32 s79, v252, 38
	v_readlane_b32 s93, v253, 25
	s_mov_b64 exec, s[0:1]
	s_cbranch_execz .LBB0_1061
	v_mov_b32_e32 v0, 0x20000
	ds_read_b64 v[0:1], v0
	s_getreg_b32 s44, hwreg(HW_REG_XCC_ID, 0, 4)
	s_lshl_b32 s44, s44, 7
	s_add_u32 s44, s44, 0xdc03600
	v_mov_b32_e32 v2, s44
	v_mov_b32_e32 v4, 1
	s_waitcnt vmcnt(0) lgkmcnt(0)
	global_atomic_add v5, v2, v4, s[42:43] sc0
	buffer_inv sc1
	s_add_u32 s100, s100, 1
	v_readfirstlane_b32 s46, v0
	v_readfirstlane_b32 s47, v1
	v_mov_b32_e32 v2, 0xdc03e00
	s_nop 3
	s_mul_i32 s48, s46, s100
	s_mul_i32 s49, s47, s100
	s_waitcnt vmcnt(1)
	v_readfirstlane_b32 s50, v5
	s_nop 3
	s_add_u32 s50, s50, 1
	s_cmp_lg_u32 s50, s48
	s_cbranch_scc1 .Lxb9_poll
	buffer_wbl2 sc1
	s_waitcnt vmcnt(0)
	global_atomic_add v2, v4, s[42:43]

.LBB0_1074:
	v_add_u32_e32 v2, s67, v186
	ds_read_b128 v[132:135], v2
	ds_read_b128 v[150:153], v2 offset:1024
	ds_read_b128 v[188:191], v2 offset:2048
	ds_read_b128 v[192:195], v2 offset:3072
	v_add_u32_e32 v2, s68, v186
	ds_read_b128 v[196:199], v2
	ds_read_b128 v[200:203], v2 offset:1024
	ds_read_b128 v[204:207], v2 offset:2048
	ds_read_b128 v[208:211], v2 offset:3072
	s_add_u32 s13, s54, 0xfffc0080
	s_addc_u32 s14, s55, -1
	s_cmp_eq_u32 s12, 12
	s_cselect_b32 s57, s2, s14
	s_cselect_b32 s56, s3, s13
	s_cselect_b32 s15, s8, s11
	s_cselect_b32 s14, s9, s10
	v_lshl_add_u64 v[154:155], s[54:55], 0, v[146:147]
	s_add_i32 m0, s60, 0xc000
	ds_read_b128 v[212:215], v187
	ds_read_b128 v[216:219], v187 offset:1024
	ds_read_b128 v[220:223], v187 offset:2048
	ds_read_b128 v[224:227], v187 offset:3072
	ds_read_b128 v[228:231], v187 offset:4096
	ds_read_b128 v[232:235], v187 offset:5120
	ds_read_b128 v[236:239], v187 offset:6144
	ds_read_b128 v[240:243], v187 offset:7168
	global_load_lds_dwordx4 v[154:155], off
	v_lshl_add_u64 v[154:155], s[54:55], 0, v[148:149]
	s_add_i32 m0, s60, 0xe000
	s_nop 0
	global_load_lds_dwordx4 v[154:155], off
	s_waitcnt vmcnt(8)
	s_waitcnt lgkmcnt(0)
	v_mfma_f32_16x16x32_f16 v[128:131], v[132:135], v[212:215], v[128:131]
	v_mfma_f32_16x16x32_f16 v[124:127], v[188:191], v[212:215], v[124:127]
	v_mfma_f32_16x16x32_f16 v[112:115], v[132:135], v[220:223], v[112:115]
	v_mfma_f32_16x16x32_f16 v[108:111], v[188:191], v[220:223], v[108:111]
	s_barrier
	s_waitcnt lgkmcnt(0)
	v_mfma_f32_16x16x32_f16 v[96:99], v[132:135], v[228:231], v[96:99]
	v_mfma_f32_16x16x32_f16 v[92:95], v[188:191], v[228:231], v[92:95]
	v_mfma_f32_16x16x32_f16 v[80:83], v[132:135], v[236:239], v[80:83]
	v_mfma_f32_16x16x32_f16 v[76:79], v[188:191], v[236:239], v[76:79]
	v_mfma_f32_16x16x32_f16 v[128:131], v[150:153], v[216:219], v[128:131]
	v_mfma_f32_16x16x32_f16 v[124:127], v[192:195], v[216:219], v[124:127]
	v_mfma_f32_16x16x32_f16 v[112:115], v[150:153], v[224:227], v[112:115]
	v_mfma_f32_16x16x32_f16 v[108:111], v[192:195], v[224:227], v[108:111]
	v_mfma_f32_16x16x32_f16 v[96:99], v[150:153], v[232:235], v[96:99]
	v_mfma_f32_16x16x32_f16 v[92:95], v[192:195], v[232:235], v[92:95]
	v_mfma_f32_16x16x32_f16 v[80:83], v[150:153], v[240:243], v[80:83]
	v_mfma_f32_16x16x32_f16 v[76:79], v[192:195], v[240:243], v[76:79]
	v_mfma_f32_16x16x32_f16 v[120:123], v[196:199], v[212:215], v[120:123]
	v_mfma_f32_16x16x32_f16 v[116:119], v[204:207], v[212:215], v[116:119]
	v_mfma_f32_16x16x32_f16 v[104:107], v[196:199], v[220:223], v[104:107]
	v_mfma_f32_16x16x32_f16 v[100:103], v[204:207], v[220:223], v[100:103]
	v_mfma_f32_16x16x32_f16 v[88:91], v[196:199], v[228:231], v[88:91]
	v_mfma_f32_16x16x32_f16 v[84:87], v[204:207], v[228:231], v[84:87]
	v_mfma_f32_16x16x32_f16 v[72:75], v[196:199], v[236:239], v[72:75]
	v_mfma_f32_16x16x32_f16 v[68:71], v[204:207], v[236:239], v[68:71]
	v_mfma_f32_16x16x32_f16 v[120:123], v[200:203], v[216:219], v[120:123]
	v_mfma_f32_16x16x32_f16 v[116:119], v[208:211], v[216:219], v[116:119]
	v_mfma_f32_16x16x32_f16 v[104:107], v[200:203], v[224:227], v[104:107]
	v_mfma_f32_16x16x32_f16 v[100:103], v[208:211], v[224:227], v[100:103]
	v_mfma_f32_16x16x32_f16 v[88:91], v[200:203], v[232:235], v[88:91]
	v_mfma_f32_16x16x32_f16 v[84:87], v[208:211], v[232:235], v[84:87]
	v_mfma_f32_16x16x32_f16 v[72:75], v[200:203], v[240:243], v[72:75]
	v_mfma_f32_16x16x32_f16 v[68:71], v[208:211], v[240:243], v[68:71]
	s_barrier
	s_add_i32 s13, s67, s59
	v_lshl_add_u64 v[154:155], s[14:15], 0, v[140:141]
	s_mov_b32 m0, s13
	ds_read_b128 v[212:215], v187 offset:16384
	ds_read_b128 v[216:219], v187 offset:17408
	ds_read_b128 v[220:223], v187 offset:18432
	ds_read_b128 v[224:227], v187 offset:19456
	ds_read_b128 v[228:231], v187 offset:20480
	ds_read_b128 v[232:235], v187 offset:21504
	ds_read_b128 v[236:239], v187 offset:22528
	ds_read_b128 v[240:243], v187 offset:23552
	global_load_lds_dwordx4 v[154:155], off
	v_lshl_add_u64 v[168:169], s[14:15], 0, v[0:1]
	s_add_i32 m0, s13, 0x2000
	s_add_i32 s13, s68, s59
	global_load_lds_dwordx4 v[168:169], off
	v_lshl_add_u64 v[176:177], s[14:15], 0, v[142:143]
	s_mov_b32 m0, s13
	v_lshl_add_u64 v[178:179], s[14:15], 0, v[136:137]
	global_load_lds_dwordx4 v[176:177], off
	s_add_i32 m0, s13, 0x2000
	v_lshl_add_u64 v[244:245], s[56:57], 0, v[144:145]
	global_load_lds_dwordx4 v[178:179], off
	s_mov_b32 m0, s60
	v_lshl_add_u64 v[246:247], s[56:57], 0, v[138:139]
	global_load_lds_dwordx4 v[244:245], off
	s_mov_b32 m0, s61
	s_nop 0
	global_load_lds_dwordx4 v[246:247], off
	s_waitcnt vmcnt(8)
	s_waitcnt lgkmcnt(0)
	v_mfma_f32_16x16x32_f16 v[64:67], v[132:135], v[212:215], v[64:67]
	v_mfma_f32_16x16x32_f16 v[60:63], v[188:191], v[212:215], v[60:63]
	v_mfma_f32_16x16x32_f16 v[48:51], v[132:135], v[220:223], v[48:51]
	v_mfma_f32_16x16x32_f16 v[44:47], v[188:191], v[220:223], v[44:47]
	s_barrier
	s_waitcnt lgkmcnt(0)
	v_mfma_f32_16x16x32_f16 v[32:35], v[132:135], v[228:231], v[32:35]
	v_mfma_f32_16x16x32_f16 v[28:31], v[188:191], v[228:231], v[28:31]
	v_mfma_f32_16x16x32_f16 v[16:19], v[132:135], v[236:239], v[16:19]
	v_mfma_f32_16x16x32_f16 v[12:15], v[188:191], v[236:239], v[12:15]
	v_mfma_f32_16x16x32_f16 v[64:67], v[150:153], v[216:219], v[64:67]
	v_mfma_f32_16x16x32_f16 v[60:63], v[192:195], v[216:219], v[60:63]
	v_mfma_f32_16x16x32_f16 v[48:51], v[150:153], v[224:227], v[48:51]
	v_mfma_f32_16x16x32_f16 v[44:47], v[192:195], v[224:227], v[44:47]
	v_mfma_f32_16x16x32_f16 v[32:35], v[150:153], v[232:235], v[32:35]
	v_mfma_f32_16x16x32_f16 v[28:31], v[192:195], v[232:235], v[28:31]
	v_mfma_f32_16x16x32_f16 v[16:19], v[150:153], v[240:243], v[16:19]
	v_mfma_f32_16x16x32_f16 v[12:15], v[192:195], v[240:243], v[12:15]
	v_mfma_f32_16x16x32_f16 v[56:59], v[196:199], v[212:215], v[56:59]
	v_mfma_f32_16x16x32_f16 v[52:55], v[204:207], v[212:215], v[52:55]
	v_mfma_f32_16x16x32_f16 v[40:43], v[196:199], v[220:223], v[40:43]
	v_mfma_f32_16x16x32_f16 v[36:39], v[204:207], v[220:223], v[36:39]
	v_mfma_f32_16x16x32_f16 v[24:27], v[196:199], v[228:231], v[24:27]
	v_mfma_f32_16x16x32_f16 v[20:23], v[204:207], v[228:231], v[20:23]
	v_mfma_f32_16x16x32_f16 v[8:11], v[196:199], v[236:239], v[8:11]
	v_mfma_f32_16x16x32_f16 v[4:7], v[204:207], v[236:239], v[4:7]
	v_mfma_f32_16x16x32_f16 v[56:59], v[200:203], v[216:219], v[56:59]
	v_mfma_f32_16x16x32_f16 v[52:55], v[208:211], v[216:219], v[52:55]
	v_mfma_f32_16x16x32_f16 v[40:43], v[200:203], v[224:227], v[40:43]
	v_mfma_f32_16x16x32_f16 v[36:39], v[208:211], v[224:227], v[36:39]
	v_mfma_f32_16x16x32_f16 v[24:27], v[200:203], v[232:235], v[24:27]
	v_mfma_f32_16x16x32_f16 v[20:23], v[208:211], v[232:235], v[20:23]
	v_mfma_f32_16x16x32_f16 v[8:11], v[200:203], v[240:243], v[8:11]
	v_mfma_f32_16x16x32_f16 v[4:7], v[208:211], v[240:243], v[4:7]
	s_barrier
	v_add_u32_e32 v2, s82, v186
	ds_read_b128 v[132:135], v2
	ds_read_b128 v[150:153], v2 offset:1024
	ds_read_b128 v[188:191], v2 offset:2048
	ds_read_b128 v[192:195], v2 offset:3072
	v_add_u32_e32 v2, s62, v186
	ds_read_b128 v[196:199], v2
	ds_read_b128 v[200:203], v2 offset:1024
	ds_read_b128 v[204:207], v2 offset:2048
	ds_read_b128 v[208:211], v2 offset:3072
	s_add_u32 s14, s56, 0x40000
	s_addc_u32 s15, s57, 0
	s_mov_b32 m0, s90
	v_lshl_add_u64 v[248:249], s[14:15], 0, v[144:145]
	ds_read_b128 v[212:215], v187 offset:32768
	ds_read_b128 v[216:219], v187 offset:33792
	ds_read_b128 v[220:223], v187 offset:34816
	ds_read_b128 v[224:227], v187 offset:35840
	ds_read_b128 v[228:231], v187 offset:36864
	ds_read_b128 v[232:235], v187 offset:37888
	ds_read_b128 v[236:239], v187 offset:38912
	ds_read_b128 v[240:243], v187 offset:39936
	global_load_lds_dwordx4 v[248:249], off
	v_lshl_add_u64 v[248:249], s[14:15], 0, v[138:139]
	s_mov_b32 m0, s91
	s_nop 0
	global_load_lds_dwordx4 v[248:249], off
	s_waitcnt vmcnt(8)
	s_waitcnt lgkmcnt(0)
	v_mfma_f32_16x16x32_f16 v[128:131], v[132:135], v[212:215], v[128:131]
	v_mfma_f32_16x16x32_f16 v[124:127], v[188:191], v[212:215], v[124:127]
	v_mfma_f32_16x16x32_f16 v[112:115], v[132:135], v[220:223], v[112:115]
	v_mfma_f32_16x16x32_f16 v[108:111], v[188:191], v[220:223], v[108:111]
	s_barrier
	s_waitcnt lgkmcnt(0)
	v_mfma_f32_16x16x32_f16 v[96:99], v[132:135], v[228:231], v[96:99]
	v_mfma_f32_16x16x32_f16 v[92:95], v[188:191], v[228:231], v[92:95]
	v_mfma_f32_16x16x32_f16 v[80:83], v[132:135], v[236:239], v[80:83]
	v_mfma_f32_16x16x32_f16 v[76:79], v[188:191], v[236:239], v[76:79]
	v_mfma_f32_16x16x32_f16 v[128:131], v[150:153], v[216:219], v[128:131]
	v_mfma_f32_16x16x32_f16 v[124:127], v[192:195], v[216:219], v[124:127]
	v_mfma_f32_16x16x32_f16 v[112:115], v[150:153], v[224:227], v[112:115]
	v_mfma_f32_16x16x32_f16 v[108:111], v[192:195], v[224:227], v[108:111]
	v_mfma_f32_16x16x32_f16 v[96:99], v[150:153], v[232:235], v[96:99]
	v_mfma_f32_16x16x32_f16 v[92:95], v[192:195], v[232:235], v[92:95]
	v_mfma_f32_16x16x32_f16 v[80:83], v[150:153], v[240:243], v[80:83]
	v_mfma_f32_16x16x32_f16 v[76:79], v[192:195], v[240:243], v[76:79]
	v_mfma_f32_16x16x32_f16 v[120:123], v[196:199], v[212:215], v[120:123]
	v_mfma_f32_16x16x32_f16 v[116:119], v[204:207], v[212:215], v[116:119]
	v_mfma_f32_16x16x32_f16 v[104:107], v[196:199], v[220:223], v[104:107]
	v_mfma_f32_16x16x32_f16 v[100:103], v[204:207], v[220:223], v[100:103]
	v_mfma_f32_16x16x32_f16 v[88:91], v[196:199], v[228:231], v[88:91]
	v_mfma_f32_16x16x32_f16 v[84:87], v[204:207], v[228:231], v[84:87]
	v_mfma_f32_16x16x32_f16 v[72:75], v[196:199], v[236:239], v[72:75]
	v_mfma_f32_16x16x32_f16 v[68:71], v[204:207], v[236:239], v[68:71]
	v_mfma_f32_16x16x32_f16 v[120:123], v[200:203], v[216:219], v[120:123]
	v_mfma_f32_16x16x32_f16 v[116:119], v[208:211], v[216:219], v[116:119]
	v_mfma_f32_16x16x32_f16 v[104:107], v[200:203], v[224:227], v[104:107]
	v_mfma_f32_16x16x32_f16 v[100:103], v[208:211], v[224:227], v[100:103]
	v_mfma_f32_16x16x32_f16 v[88:91], v[200:203], v[232:235], v[88:91]
	v_mfma_f32_16x16x32_f16 v[84:87], v[208:211], v[232:235], v[84:87]
	v_mfma_f32_16x16x32_f16 v[72:75], v[200:203], v[240:243], v[72:75]
	v_mfma_f32_16x16x32_f16 v[68:71], v[208:211], v[240:243], v[68:71]
	s_barrier
	s_add_i32 s13, s82, s59
	v_lshl_add_u64 v[154:155], v[154:155], 0, s[72:73]
	s_mov_b32 m0, s13
	ds_read_b128 v[212:215], v187 offset:49152
	ds_read_b128 v[216:219], v187 offset:50176
	ds_read_b128 v[220:223], v187 offset:51200
	ds_read_b128 v[224:227], v187 offset:52224
	ds_read_b128 v[228:231], v187 offset:53248
	ds_read_b128 v[232:235], v187 offset:54272
	ds_read_b128 v[236:239], v187 offset:55296
	ds_read_b128 v[240:243], v187 offset:56320
	global_load_lds_dwordx4 v[154:155], off
	v_lshl_add_u64 v[154:155], v[168:169], 0, s[72:73]
	s_add_i32 m0, s13, 0x2000
	s_add_i32 s13, s62, s59
	global_load_lds_dwordx4 v[154:155], off
	v_lshl_add_u64 v[154:155], v[176:177], 0, s[72:73]
	s_mov_b32 m0, s13
	s_nop 0
	global_load_lds_dwordx4 v[154:155], off
	v_lshl_add_u64 v[154:155], v[178:179], 0, s[72:73]
	s_add_i32 m0, s13, 0x2000
	s_nop 0
	global_load_lds_dwordx4 v[154:155], off
	v_lshl_add_u64 v[154:155], v[244:245], 0, s[72:73]
	s_mov_b32 m0, s7
	s_nop 0
	global_load_lds_dwordx4 v[154:155], off
	v_lshl_add_u64 v[154:155], v[246:247], 0, s[72:73]
	s_mov_b32 m0, s86
	s_nop 0
	global_load_lds_dwordx4 v[154:155], off
	s_waitcnt vmcnt(8)
	s_waitcnt lgkmcnt(0)
	v_mfma_f32_16x16x32_f16 v[64:67], v[132:135], v[212:215], v[64:67]
	v_mfma_f32_16x16x32_f16 v[60:63], v[188:191], v[212:215], v[60:63]
	v_mfma_f32_16x16x32_f16 v[48:51], v[132:135], v[220:223], v[48:51]
	v_mfma_f32_16x16x32_f16 v[44:47], v[188:191], v[220:223], v[44:47]
	s_barrier
	s_waitcnt lgkmcnt(0)
	v_mfma_f32_16x16x32_f16 v[32:35], v[132:135], v[228:231], v[32:35]
	v_mfma_f32_16x16x32_f16 v[28:31], v[188:191], v[228:231], v[28:31]
	v_mfma_f32_16x16x32_f16 v[16:19], v[132:135], v[236:239], v[16:19]
	v_mfma_f32_16x16x32_f16 v[12:15], v[188:191], v[236:239], v[12:15]
	v_mfma_f32_16x16x32_f16 v[64:67], v[150:153], v[216:219], v[64:67]
	v_mfma_f32_16x16x32_f16 v[60:63], v[192:195], v[216:219], v[60:63]
	v_mfma_f32_16x16x32_f16 v[48:51], v[150:153], v[224:227], v[48:51]
	v_mfma_f32_16x16x32_f16 v[44:47], v[192:195], v[224:227], v[44:47]
	v_mfma_f32_16x16x32_f16 v[32:35], v[150:153], v[232:235], v[32:35]
	v_mfma_f32_16x16x32_f16 v[28:31], v[192:195], v[232:235], v[28:31]
	v_mfma_f32_16x16x32_f16 v[16:19], v[150:153], v[240:243], v[16:19]
	v_mfma_f32_16x16x32_f16 v[12:15], v[192:195], v[240:243], v[12:15]
	v_mfma_f32_16x16x32_f16 v[56:59], v[196:199], v[212:215], v[56:59]
	v_mfma_f32_16x16x32_f16 v[52:55], v[204:207], v[212:215], v[52:55]
	v_mfma_f32_16x16x32_f16 v[40:43], v[196:199], v[220:223], v[40:43]
	v_mfma_f32_16x16x32_f16 v[36:39], v[204:207], v[220:223], v[36:39]
	v_mfma_f32_16x16x32_f16 v[24:27], v[196:199], v[228:231], v[24:27]
	v_mfma_f32_16x16x32_f16 v[20:23], v[204:207], v[228:231], v[20:23]
	v_mfma_f32_16x16x32_f16 v[8:11], v[196:199], v[236:239], v[8:11]
	v_mfma_f32_16x16x32_f16 v[4:7], v[204:207], v[236:239], v[4:7]
	v_mfma_f32_16x16x32_f16 v[56:59], v[200:203], v[216:219], v[56:59]
	v_mfma_f32_16x16x32_f16 v[52:55], v[208:211], v[216:219], v[52:55]
	v_mfma_f32_16x16x32_f16 v[40:43], v[200:203], v[224:227], v[40:43]
	v_mfma_f32_16x16x32_f16 v[36:39], v[208:211], v[224:227], v[36:39]
	v_mfma_f32_16x16x32_f16 v[24:27], v[200:203], v[232:235], v[24:27]
	v_mfma_f32_16x16x32_f16 v[20:23], v[208:211], v[232:235], v[20:23]
	v_mfma_f32_16x16x32_f16 v[8:11], v[200:203], v[240:243], v[8:11]
	v_mfma_f32_16x16x32_f16 v[4:7], v[208:211], v[240:243], v[4:7]
	s_barrier
	s_add_i32 s12, s12, 2
	s_add_u32 s54, s54, 0x100
	s_addc_u32 s55, s55, 0
	s_add_u32 s10, s10, 0x100
	s_addc_u32 s11, s11, 0
	s_cmp_gt_u32 s12, 13
	s_cbranch_scc0 .LBB0_1074
	s_and_b64 vcc, exec, s[44:45]
	s_cbranch_vccz .LBB0_1077
	s_barrier

.LBB0_1145:
	v_add_u32_e32 v157, s67, v146
	ds_read_b128 v[148:151], v157
	ds_read_b128 v[152:155], v157 offset:1024
	ds_read_b128 v[186:189], v157 offset:2048
	ds_read_b128 v[190:193], v157 offset:3072
	v_add_u32_e32 v157, s68, v146
	s_add_u32 s28, s54, vcc_lo
	ds_read_b128 v[194:197], v157
	ds_read_b128 v[198:201], v157 offset:1024
	ds_read_b128 v[202:205], v157 offset:2048
	ds_read_b128 v[206:209], v157 offset:3072
	s_addc_u32 s29, s55, vcc_hi
	s_add_u32 s28, s28, 0x100
	s_addc_u32 s29, s29, 0
	s_add_u32 s30, s19, vcc_lo
	s_addc_u32 s31, s20, vcc_hi
	s_cmpk_eq_i32 vcc_lo, 0x700
	s_cselect_b32 s61, s21, s29
	s_cselect_b32 s60, s24, s28
	s_cselect_b32 s31, s25, s31
	s_cselect_b32 s30, s26, s30
	v_lshl_add_u64 v[168:169], v[140:141], 0, vcc
	s_add_i32 m0, s10, 0xc000
	ds_read_b128 v[210:213], v147
	ds_read_b128 v[214:217], v147 offset:1024
	ds_read_b128 v[218:221], v147 offset:2048
	ds_read_b128 v[222:225], v147 offset:3072
	ds_read_b128 v[226:229], v147 offset:4096
	ds_read_b128 v[230:233], v147 offset:5120
	ds_read_b128 v[234:237], v147 offset:6144
	ds_read_b128 v[238:241], v147 offset:7168
	global_load_lds_dwordx4 v[168:169], off
	v_lshl_add_u64 v[168:169], v[142:143], 0, vcc
	s_add_i32 m0, s10, 0xe000
	s_nop 0
	global_load_lds_dwordx4 v[168:169], off
	s_waitcnt vmcnt(8)
	s_waitcnt lgkmcnt(0)
	v_mfma_f32_16x16x32_bf16 v[36:39], v[148:151], v[210:213], v[36:39]
	v_mfma_f32_16x16x32_bf16 v[20:23], v[186:189], v[210:213], v[20:23]
	v_mfma_f32_16x16x32_bf16 v[40:43], v[148:151], v[218:221], v[40:43]
	v_mfma_f32_16x16x32_bf16 v[24:27], v[186:189], v[218:221], v[24:27]
	s_barrier
	s_waitcnt lgkmcnt(0)
	v_mfma_f32_16x16x32_bf16 v[100:103], v[148:151], v[226:229], v[100:103]
	v_mfma_f32_16x16x32_bf16 v[84:87], v[186:189], v[226:229], v[84:87]
	v_mfma_f32_16x16x32_bf16 v[104:107], v[148:151], v[234:237], v[104:107]
	v_mfma_f32_16x16x32_bf16 v[88:91], v[186:189], v[234:237], v[88:91]
	v_mfma_f32_16x16x32_bf16 v[36:39], v[152:155], v[214:217], v[36:39]
	v_mfma_f32_16x16x32_bf16 v[20:23], v[190:193], v[214:217], v[20:23]
	v_mfma_f32_16x16x32_bf16 v[40:43], v[152:155], v[222:225], v[40:43]
	v_mfma_f32_16x16x32_bf16 v[24:27], v[190:193], v[222:225], v[24:27]
	v_mfma_f32_16x16x32_bf16 v[100:103], v[152:155], v[230:233], v[100:103]
	v_mfma_f32_16x16x32_bf16 v[84:87], v[190:193], v[230:233], v[84:87]
	v_mfma_f32_16x16x32_bf16 v[104:107], v[152:155], v[238:241], v[104:107]
	v_mfma_f32_16x16x32_bf16 v[88:91], v[190:193], v[238:241], v[88:91]
	v_mfma_f32_16x16x32_bf16 v[12:15], v[194:197], v[210:213], v[12:15]
	v_mfma_f32_16x16x32_bf16 v[4:7], v[202:205], v[210:213], v[4:7]
	v_mfma_f32_16x16x32_bf16 v[16:19], v[194:197], v[218:221], v[16:19]
	v_mfma_f32_16x16x32_bf16 v[8:11], v[202:205], v[218:221], v[8:11]
	v_mfma_f32_16x16x32_bf16 v[64:67], v[194:197], v[226:229], v[64:67]
	v_mfma_f32_16x16x32_bf16 v[32:35], v[202:205], v[226:229], v[32:35]
	v_mfma_f32_16x16x32_bf16 v[68:71], v[194:197], v[234:237], v[68:71]
	v_mfma_f32_16x16x32_bf16 v[28:31], v[202:205], v[234:237], v[28:31]
	v_mfma_f32_16x16x32_bf16 v[12:15], v[198:201], v[214:217], v[12:15]
	v_mfma_f32_16x16x32_bf16 v[4:7], v[206:209], v[214:217], v[4:7]
	v_mfma_f32_16x16x32_bf16 v[16:19], v[198:201], v[222:225], v[16:19]
	v_mfma_f32_16x16x32_bf16 v[8:11], v[206:209], v[222:225], v[8:11]
	v_mfma_f32_16x16x32_bf16 v[64:67], v[198:201], v[230:233], v[64:67]
	v_mfma_f32_16x16x32_bf16 v[32:35], v[206:209], v[230:233], v[32:35]
	v_mfma_f32_16x16x32_bf16 v[68:71], v[198:201], v[238:241], v[68:71]
	v_mfma_f32_16x16x32_bf16 v[28:31], v[206:209], v[238:241], v[28:31]
	s_barrier
	s_add_i32 s28, s67, s9
	v_lshl_add_u64 v[168:169], s[30:31], 0, v[2:3]
	s_mov_b32 m0, s28
	ds_read_b128 v[210:213], v147 offset:16384
	ds_read_b128 v[214:217], v147 offset:17408
	ds_read_b128 v[218:221], v147 offset:18432
	ds_read_b128 v[222:225], v147 offset:19456
	ds_read_b128 v[226:229], v147 offset:20480
	ds_read_b128 v[230:233], v147 offset:21504
	ds_read_b128 v[234:237], v147 offset:22528
	ds_read_b128 v[238:241], v147 offset:23552
	global_load_lds_dwordx4 v[168:169], off
	v_lshl_add_u64 v[176:177], s[30:31], 0, v[0:1]
	s_add_i32 m0, s28, 0x2000
	s_add_i32 s28, s68, s9
	global_load_lds_dwordx4 v[176:177], off
	v_lshl_add_u64 v[178:179], s[30:31], 0, v[134:135]
	s_mov_b32 m0, s28
	v_lshl_add_u64 v[242:243], s[30:31], 0, v[132:133]
	global_load_lds_dwordx4 v[178:179], off
	s_add_i32 m0, s28, 0x2000
	v_lshl_add_u64 v[244:245], s[60:61], 0, v[2:3]
	global_load_lds_dwordx4 v[242:243], off
	s_mov_b32 m0, s10
	v_lshl_add_u64 v[246:247], s[60:61], 0, v[0:1]
	global_load_lds_dwordx4 v[244:245], off
	s_mov_b32 m0, s11
	s_nop 0
	global_load_lds_dwordx4 v[246:247], off
	s_waitcnt vmcnt(8)
	s_waitcnt lgkmcnt(0)
	v_mfma_f32_16x16x32_bf16 v[128:131], v[148:151], v[210:213], v[128:131]
	v_mfma_f32_16x16x32_bf16 v[124:127], v[186:189], v[210:213], v[124:127]
	v_mfma_f32_16x16x32_bf16 v[120:123], v[148:151], v[218:221], v[120:123]
	v_mfma_f32_16x16x32_bf16 v[116:119], v[186:189], v[218:221], v[116:119]
	s_barrier
	s_waitcnt lgkmcnt(0)
	v_mfma_f32_16x16x32_bf16 v[80:83], v[148:151], v[226:229], v[80:83]
	v_mfma_f32_16x16x32_bf16 v[76:79], v[186:189], v[226:229], v[76:79]
	v_mfma_f32_16x16x32_bf16 v[72:75], v[148:151], v[234:237], v[72:75]
	v_mfma_f32_16x16x32_bf16 v[60:63], v[186:189], v[234:237], v[60:63]
	v_mfma_f32_16x16x32_bf16 v[128:131], v[152:155], v[214:217], v[128:131]
	v_mfma_f32_16x16x32_bf16 v[124:127], v[190:193], v[214:217], v[124:127]
	v_mfma_f32_16x16x32_bf16 v[120:123], v[152:155], v[222:225], v[120:123]
	v_mfma_f32_16x16x32_bf16 v[116:119], v[190:193], v[222:225], v[116:119]
	v_mfma_f32_16x16x32_bf16 v[80:83], v[152:155], v[230:233], v[80:83]
	v_mfma_f32_16x16x32_bf16 v[76:79], v[190:193], v[230:233], v[76:79]
	v_mfma_f32_16x16x32_bf16 v[72:75], v[152:155], v[238:241], v[72:75]
	v_mfma_f32_16x16x32_bf16 v[60:63], v[190:193], v[238:241], v[60:63]
	v_mfma_f32_16x16x32_bf16 v[108:111], v[194:197], v[210:213], v[108:111]
	v_mfma_f32_16x16x32_bf16 v[92:95], v[202:205], v[210:213], v[92:95]
	v_mfma_f32_16x16x32_bf16 v[112:115], v[194:197], v[218:221], v[112:115]
	v_mfma_f32_16x16x32_bf16 v[96:99], v[202:205], v[218:221], v[96:99]
	v_mfma_f32_16x16x32_bf16 v[56:59], v[194:197], v[226:229], v[56:59]
	v_mfma_f32_16x16x32_bf16 v[52:55], v[202:205], v[226:229], v[52:55]
	v_mfma_f32_16x16x32_bf16 v[48:51], v[194:197], v[234:237], v[48:51]
	v_mfma_f32_16x16x32_bf16 v[44:47], v[202:205], v[234:237], v[44:47]
	v_mfma_f32_16x16x32_bf16 v[108:111], v[198:201], v[214:217], v[108:111]
	v_mfma_f32_16x16x32_bf16 v[92:95], v[206:209], v[214:217], v[92:95]
	v_mfma_f32_16x16x32_bf16 v[112:115], v[198:201], v[222:225], v[112:115]
	v_mfma_f32_16x16x32_bf16 v[96:99], v[206:209], v[222:225], v[96:99]
	v_mfma_f32_16x16x32_bf16 v[56:59], v[198:201], v[230:233], v[56:59]
	v_mfma_f32_16x16x32_bf16 v[52:55], v[206:209], v[230:233], v[52:55]
	v_mfma_f32_16x16x32_bf16 v[48:51], v[198:201], v[238:241], v[48:51]
	v_mfma_f32_16x16x32_bf16 v[44:47], v[206:209], v[238:241], v[44:47]
	s_barrier
	v_add_u32_e32 v157, s82, v146
	ds_read_b128 v[148:151], v157
	ds_read_b128 v[152:155], v157 offset:1024
	ds_read_b128 v[186:189], v157 offset:2048
	ds_read_b128 v[190:193], v157 offset:3072
	v_add_u32_e32 v157, s62, v146
	ds_read_b128 v[194:197], v157
	ds_read_b128 v[198:201], v157 offset:1024
	ds_read_b128 v[202:205], v157 offset:2048
	ds_read_b128 v[206:209], v157 offset:3072
	s_add_u32 s30, s60, 0x40000
	s_addc_u32 s31, s61, 0
	s_mov_b32 m0, s12
	v_lshl_add_u64 v[248:249], s[30:31], 0, v[2:3]
	ds_read_b128 v[210:213], v147 offset:32768
	ds_read_b128 v[214:217], v147 offset:33792
	ds_read_b128 v[218:221], v147 offset:34816
	ds_read_b128 v[222:225], v147 offset:35840
	ds_read_b128 v[226:229], v147 offset:36864
	ds_read_b128 v[230:233], v147 offset:37888
	ds_read_b128 v[234:237], v147 offset:38912
	ds_read_b128 v[238:241], v147 offset:39936
	global_load_lds_dwordx4 v[248:249], off
	v_lshl_add_u64 v[248:249], s[30:31], 0, v[0:1]
	s_mov_b32 m0, s13
	s_nop 0
	global_load_lds_dwordx4 v[248:249], off
	s_waitcnt vmcnt(8)
	s_waitcnt lgkmcnt(0)
	v_mfma_f32_16x16x32_bf16 v[36:39], v[148:151], v[210:213], v[36:39]
	v_mfma_f32_16x16x32_bf16 v[20:23], v[186:189], v[210:213], v[20:23]
	v_mfma_f32_16x16x32_bf16 v[40:43], v[148:151], v[218:221], v[40:43]
	v_mfma_f32_16x16x32_bf16 v[24:27], v[186:189], v[218:221], v[24:27]
	s_barrier
	s_waitcnt lgkmcnt(0)
	v_mfma_f32_16x16x32_bf16 v[100:103], v[148:151], v[226:229], v[100:103]
	v_mfma_f32_16x16x32_bf16 v[84:87], v[186:189], v[226:229], v[84:87]
	v_mfma_f32_16x16x32_bf16 v[104:107], v[148:151], v[234:237], v[104:107]
	v_mfma_f32_16x16x32_bf16 v[88:91], v[186:189], v[234:237], v[88:91]
	v_mfma_f32_16x16x32_bf16 v[36:39], v[152:155], v[214:217], v[36:39]
	v_mfma_f32_16x16x32_bf16 v[20:23], v[190:193], v[214:217], v[20:23]
	v_mfma_f32_16x16x32_bf16 v[40:43], v[152:155], v[222:225], v[40:43]
	v_mfma_f32_16x16x32_bf16 v[24:27], v[190:193], v[222:225], v[24:27]
	v_mfma_f32_16x16x32_bf16 v[100:103], v[152:155], v[230:233], v[100:103]
	v_mfma_f32_16x16x32_bf16 v[84:87], v[190:193], v[230:233], v[84:87]
	v_mfma_f32_16x16x32_bf16 v[104:107], v[152:155], v[238:241], v[104:107]
	v_mfma_f32_16x16x32_bf16 v[88:91], v[190:193], v[238:241], v[88:91]
	v_mfma_f32_16x16x32_bf16 v[12:15], v[194:197], v[210:213], v[12:15]
	v_mfma_f32_16x16x32_bf16 v[4:7], v[202:205], v[210:213], v[4:7]
	v_mfma_f32_16x16x32_bf16 v[16:19], v[194:197], v[218:221], v[16:19]
	v_mfma_f32_16x16x32_bf16 v[8:11], v[202:205], v[218:221], v[8:11]
	v_mfma_f32_16x16x32_bf16 v[64:67], v[194:197], v[226:229], v[64:67]
	v_mfma_f32_16x16x32_bf16 v[32:35], v[202:205], v[226:229], v[32:35]
	v_mfma_f32_16x16x32_bf16 v[68:71], v[194:197], v[234:237], v[68:71]
	v_mfma_f32_16x16x32_bf16 v[28:31], v[202:205], v[234:237], v[28:31]
	v_mfma_f32_16x16x32_bf16 v[12:15], v[198:201], v[214:217], v[12:15]
	v_mfma_f32_16x16x32_bf16 v[4:7], v[206:209], v[214:217], v[4:7]
	v_mfma_f32_16x16x32_bf16 v[16:19], v[198:201], v[222:225], v[16:19]
	v_mfma_f32_16x16x32_bf16 v[8:11], v[206:209], v[222:225], v[8:11]
	v_mfma_f32_16x16x32_bf16 v[64:67], v[198:201], v[230:233], v[64:67]
	v_mfma_f32_16x16x32_bf16 v[32:35], v[206:209], v[230:233], v[32:35]
	v_mfma_f32_16x16x32_bf16 v[68:71], v[198:201], v[238:241], v[68:71]
	v_mfma_f32_16x16x32_bf16 v[28:31], v[206:209], v[238:241], v[28:31]
	s_barrier
	s_add_i32 s28, s82, s9
	v_lshl_add_u64 v[168:169], v[168:169], 0, s[72:73]
	s_mov_b32 m0, s28
	ds_read_b128 v[210:213], v147 offset:49152
	ds_read_b128 v[214:217], v147 offset:50176
	ds_read_b128 v[218:221], v147 offset:51200
	ds_read_b128 v[222:225], v147 offset:52224
	ds_read_b128 v[226:229], v147 offset:53248
	ds_read_b128 v[230:233], v147 offset:54272
	ds_read_b128 v[234:237], v147 offset:55296
	ds_read_b128 v[238:241], v147 offset:56320
	global_load_lds_dwordx4 v[168:169], off
	v_lshl_add_u64 v[168:169], v[176:177], 0, s[72:73]
	s_add_i32 m0, s28, 0x2000
	s_add_i32 s28, s62, s9
	global_load_lds_dwordx4 v[168:169], off
	v_lshl_add_u64 v[168:169], v[178:179], 0, s[72:73]
	s_mov_b32 m0, s28
	s_nop 0
	global_load_lds_dwordx4 v[168:169], off
	v_lshl_add_u64 v[168:169], v[242:243], 0, s[72:73]
	s_add_i32 m0, s28, 0x2000
	s_nop 0
	global_load_lds_dwordx4 v[168:169], off
	v_lshl_add_u64 v[168:169], v[244:245], 0, s[72:73]
	s_mov_b32 m0, s15
	s_nop 0
	global_load_lds_dwordx4 v[168:169], off
	v_lshl_add_u64 v[168:169], v[246:247], 0, s[72:73]
	s_mov_b32 m0, s16
	s_nop 0
	global_load_lds_dwordx4 v[168:169], off
	s_waitcnt vmcnt(8)
	s_waitcnt lgkmcnt(0)
	v_mfma_f32_16x16x32_bf16 v[128:131], v[148:151], v[210:213], v[128:131]
	v_mfma_f32_16x16x32_bf16 v[124:127], v[186:189], v[210:213], v[124:127]
	v_mfma_f32_16x16x32_bf16 v[120:123], v[148:151], v[218:221], v[120:123]
	v_mfma_f32_16x16x32_bf16 v[116:119], v[186:189], v[218:221], v[116:119]
	s_barrier
	s_waitcnt lgkmcnt(0)
	v_mfma_f32_16x16x32_bf16 v[80:83], v[148:151], v[226:229], v[80:83]
	v_mfma_f32_16x16x32_bf16 v[76:79], v[186:189], v[226:229], v[76:79]
	v_mfma_f32_16x16x32_bf16 v[72:75], v[148:151], v[234:237], v[72:75]
	v_mfma_f32_16x16x32_bf16 v[60:63], v[186:189], v[234:237], v[60:63]
	v_mfma_f32_16x16x32_bf16 v[128:131], v[152:155], v[214:217], v[128:131]
	v_mfma_f32_16x16x32_bf16 v[124:127], v[190:193], v[214:217], v[124:127]
	v_mfma_f32_16x16x32_bf16 v[120:123], v[152:155], v[222:225], v[120:123]
	v_mfma_f32_16x16x32_bf16 v[116:119], v[190:193], v[222:225], v[116:119]
	v_mfma_f32_16x16x32_bf16 v[80:83], v[152:155], v[230:233], v[80:83]
	v_mfma_f32_16x16x32_bf16 v[76:79], v[190:193], v[230:233], v[76:79]
	v_mfma_f32_16x16x32_bf16 v[72:75], v[152:155], v[238:241], v[72:75]
	v_mfma_f32_16x16x32_bf16 v[60:63], v[190:193], v[238:241], v[60:63]
	v_mfma_f32_16x16x32_bf16 v[108:111], v[194:197], v[210:213], v[108:111]
	v_mfma_f32_16x16x32_bf16 v[92:95], v[202:205], v[210:213], v[92:95]
	v_mfma_f32_16x16x32_bf16 v[112:115], v[194:197], v[218:221], v[112:115]
	v_mfma_f32_16x16x32_bf16 v[96:99], v[202:205], v[218:221], v[96:99]
	v_mfma_f32_16x16x32_bf16 v[56:59], v[194:197], v[226:229], v[56:59]
	v_mfma_f32_16x16x32_bf16 v[52:55], v[202:205], v[226:229], v[52:55]
	v_mfma_f32_16x16x32_bf16 v[48:51], v[194:197], v[234:237], v[48:51]
	v_mfma_f32_16x16x32_bf16 v[44:47], v[202:205], v[234:237], v[44:47]
	v_mfma_f32_16x16x32_bf16 v[108:111], v[198:201], v[214:217], v[108:111]
	v_mfma_f32_16x16x32_bf16 v[92:95], v[206:209], v[214:217], v[92:95]
	v_mfma_f32_16x16x32_bf16 v[112:115], v[198:201], v[222:225], v[112:115]
	v_mfma_f32_16x16x32_bf16 v[96:99], v[206:209], v[222:225], v[96:99]
	v_mfma_f32_16x16x32_bf16 v[56:59], v[198:201], v[230:233], v[56:59]
	v_mfma_f32_16x16x32_bf16 v[52:55], v[206:209], v[230:233], v[52:55]
	v_mfma_f32_16x16x32_bf16 v[48:51], v[198:201], v[238:241], v[48:51]
	v_mfma_f32_16x16x32_bf16 v[44:47], v[206:209], v[238:241], v[44:47]
	s_barrier
	s_add_i32 s27, s27, 2
	s_add_u32 vcc_lo, vcc_lo, 0x100
	s_addc_u32 vcc_hi, vcc_hi, 0
	s_cmp_gt_u32 s27, 13
	s_cbranch_scc0 .LBB0_1145
	s_and_b64 vcc, exec, s[48:49]
	s_cbranch_vccz .LBB0_1148
	s_barrier

.LBB0_1201:
	v_add_u32_e32 v157, s67, v146
	ds_read_b128 v[148:151], v157
	ds_read_b128 v[152:155], v157 offset:1024
	ds_read_b128 v[186:189], v157 offset:2048
	ds_read_b128 v[190:193], v157 offset:3072
	v_add_u32_e32 v157, s68, v146
	s_add_u32 s28, s54, vcc_lo
	ds_read_b128 v[194:197], v157
	ds_read_b128 v[198:201], v157 offset:1024
	ds_read_b128 v[202:205], v157 offset:2048
	ds_read_b128 v[206:209], v157 offset:3072
	s_addc_u32 s29, s55, vcc_hi
	s_add_u32 s28, s28, 0x100
	s_addc_u32 s29, s29, 0
	s_add_u32 s30, s19, vcc_lo
	s_addc_u32 s31, s20, vcc_hi
	s_cmpk_eq_i32 vcc_lo, 0x700
	s_cselect_b32 s59, s21, s29
	s_cselect_b32 s58, s24, s28
	s_cselect_b32 s31, s25, s31
	s_cselect_b32 s30, s26, s30
	v_lshl_add_u64 v[168:169], v[140:141], 0, vcc
	s_add_i32 m0, s10, 0xc000
	ds_read_b128 v[210:213], v147
	ds_read_b128 v[214:217], v147 offset:1024
	ds_read_b128 v[218:221], v147 offset:2048
	ds_read_b128 v[222:225], v147 offset:3072
	ds_read_b128 v[226:229], v147 offset:4096
	ds_read_b128 v[230:233], v147 offset:5120
	ds_read_b128 v[234:237], v147 offset:6144
	ds_read_b128 v[238:241], v147 offset:7168
	global_load_lds_dwordx4 v[168:169], off
	v_lshl_add_u64 v[168:169], v[142:143], 0, vcc
	s_add_i32 m0, s10, 0xe000
	s_nop 0
	global_load_lds_dwordx4 v[168:169], off
	s_waitcnt vmcnt(8)
	s_waitcnt lgkmcnt(0)
	v_mfma_f32_16x16x32_bf16 v[36:39], v[148:151], v[210:213], v[36:39]
	v_mfma_f32_16x16x32_bf16 v[24:27], v[186:189], v[210:213], v[24:27]
	v_mfma_f32_16x16x32_bf16 v[40:43], v[148:151], v[218:221], v[40:43]
	v_mfma_f32_16x16x32_bf16 v[20:23], v[186:189], v[218:221], v[20:23]
	s_barrier
	s_waitcnt lgkmcnt(0)
	v_mfma_f32_16x16x32_bf16 v[100:103], v[148:151], v[226:229], v[100:103]
	v_mfma_f32_16x16x32_bf16 v[88:91], v[186:189], v[226:229], v[88:91]
	v_mfma_f32_16x16x32_bf16 v[104:107], v[148:151], v[234:237], v[104:107]
	v_mfma_f32_16x16x32_bf16 v[84:87], v[186:189], v[234:237], v[84:87]
	v_mfma_f32_16x16x32_bf16 v[36:39], v[152:155], v[214:217], v[36:39]
	v_mfma_f32_16x16x32_bf16 v[24:27], v[190:193], v[214:217], v[24:27]
	v_mfma_f32_16x16x32_bf16 v[40:43], v[152:155], v[222:225], v[40:43]
	v_mfma_f32_16x16x32_bf16 v[20:23], v[190:193], v[222:225], v[20:23]
	v_mfma_f32_16x16x32_bf16 v[100:103], v[152:155], v[230:233], v[100:103]
	v_mfma_f32_16x16x32_bf16 v[88:91], v[190:193], v[230:233], v[88:91]
	v_mfma_f32_16x16x32_bf16 v[104:107], v[152:155], v[238:241], v[104:107]
	v_mfma_f32_16x16x32_bf16 v[84:87], v[190:193], v[238:241], v[84:87]
	v_mfma_f32_16x16x32_bf16 v[16:19], v[194:197], v[210:213], v[16:19]
	v_mfma_f32_16x16x32_bf16 v[8:11], v[202:205], v[210:213], v[8:11]
	v_mfma_f32_16x16x32_bf16 v[12:15], v[194:197], v[218:221], v[12:15]
	v_mfma_f32_16x16x32_bf16 v[4:7], v[202:205], v[218:221], v[4:7]
	v_mfma_f32_16x16x32_bf16 v[52:55], v[194:197], v[226:229], v[52:55]
	v_mfma_f32_16x16x32_bf16 v[32:35], v[202:205], v[226:229], v[32:35]
	v_mfma_f32_16x16x32_bf16 v[48:51], v[194:197], v[234:237], v[48:51]
	v_mfma_f32_16x16x32_bf16 v[28:31], v[202:205], v[234:237], v[28:31]
	v_mfma_f32_16x16x32_bf16 v[16:19], v[198:201], v[214:217], v[16:19]
	v_mfma_f32_16x16x32_bf16 v[8:11], v[206:209], v[214:217], v[8:11]
	v_mfma_f32_16x16x32_bf16 v[12:15], v[198:201], v[222:225], v[12:15]
	v_mfma_f32_16x16x32_bf16 v[4:7], v[206:209], v[222:225], v[4:7]
	v_mfma_f32_16x16x32_bf16 v[52:55], v[198:201], v[230:233], v[52:55]
	v_mfma_f32_16x16x32_bf16 v[32:35], v[206:209], v[230:233], v[32:35]
	v_mfma_f32_16x16x32_bf16 v[48:51], v[198:201], v[238:241], v[48:51]
	v_mfma_f32_16x16x32_bf16 v[28:31], v[206:209], v[238:241], v[28:31]
	s_barrier
	s_add_i32 s28, s67, s9
	v_lshl_add_u64 v[168:169], s[30:31], 0, v[2:3]
	s_mov_b32 m0, s28
	ds_read_b128 v[210:213], v147 offset:16384
	ds_read_b128 v[214:217], v147 offset:17408
	ds_read_b128 v[218:221], v147 offset:18432
	ds_read_b128 v[222:225], v147 offset:19456
	ds_read_b128 v[226:229], v147 offset:20480
	ds_read_b128 v[230:233], v147 offset:21504
	ds_read_b128 v[234:237], v147 offset:22528
	ds_read_b128 v[238:241], v147 offset:23552
	global_load_lds_dwordx4 v[168:169], off
	v_lshl_add_u64 v[176:177], s[30:31], 0, v[132:133]
	s_add_i32 m0, s28, 0x2000
	s_add_i32 s28, s68, s9
	global_load_lds_dwordx4 v[176:177], off
	v_lshl_add_u64 v[178:179], s[30:31], 0, v[134:135]
	s_mov_b32 m0, s28
	v_lshl_add_u64 v[242:243], s[30:31], 0, v[0:1]
	global_load_lds_dwordx4 v[178:179], off
	s_add_i32 m0, s28, 0x2000
	v_lshl_add_u64 v[244:245], s[58:59], 0, v[2:3]
	global_load_lds_dwordx4 v[242:243], off
	s_mov_b32 m0, s10
	v_lshl_add_u64 v[246:247], s[58:59], 0, v[132:133]
	global_load_lds_dwordx4 v[244:245], off
	s_mov_b32 m0, s11
	s_nop 0
	global_load_lds_dwordx4 v[246:247], off
	s_waitcnt vmcnt(8)
	s_waitcnt lgkmcnt(0)
	v_mfma_f32_16x16x32_bf16 v[128:131], v[148:151], v[210:213], v[128:131]
	v_mfma_f32_16x16x32_bf16 v[124:127], v[186:189], v[210:213], v[124:127]
	v_mfma_f32_16x16x32_bf16 v[120:123], v[148:151], v[218:221], v[120:123]
	v_mfma_f32_16x16x32_bf16 v[116:119], v[186:189], v[218:221], v[116:119]
	s_barrier
	s_waitcnt lgkmcnt(0)
	v_mfma_f32_16x16x32_bf16 v[80:83], v[148:151], v[226:229], v[80:83]
	v_mfma_f32_16x16x32_bf16 v[76:79], v[186:189], v[226:229], v[76:79]
	v_mfma_f32_16x16x32_bf16 v[72:75], v[148:151], v[234:237], v[72:75]
	v_mfma_f32_16x16x32_bf16 v[68:71], v[186:189], v[234:237], v[68:71]
	v_mfma_f32_16x16x32_bf16 v[128:131], v[152:155], v[214:217], v[128:131]
	v_mfma_f32_16x16x32_bf16 v[124:127], v[190:193], v[214:217], v[124:127]
	v_mfma_f32_16x16x32_bf16 v[120:123], v[152:155], v[222:225], v[120:123]
	v_mfma_f32_16x16x32_bf16 v[116:119], v[190:193], v[222:225], v[116:119]
	v_mfma_f32_16x16x32_bf16 v[80:83], v[152:155], v[230:233], v[80:83]
	v_mfma_f32_16x16x32_bf16 v[76:79], v[190:193], v[230:233], v[76:79]
	v_mfma_f32_16x16x32_bf16 v[72:75], v[152:155], v[238:241], v[72:75]
	v_mfma_f32_16x16x32_bf16 v[68:71], v[190:193], v[238:241], v[68:71]
	v_mfma_f32_16x16x32_bf16 v[112:115], v[194:197], v[210:213], v[112:115]
	v_mfma_f32_16x16x32_bf16 v[96:99], v[202:205], v[210:213], v[96:99]
	v_mfma_f32_16x16x32_bf16 v[108:111], v[194:197], v[218:221], v[108:111]
	v_mfma_f32_16x16x32_bf16 v[92:95], v[202:205], v[218:221], v[92:95]
	v_mfma_f32_16x16x32_bf16 v[64:67], v[194:197], v[226:229], v[64:67]
	v_mfma_f32_16x16x32_bf16 v[60:63], v[202:205], v[226:229], v[60:63]
	v_mfma_f32_16x16x32_bf16 v[56:59], v[194:197], v[234:237], v[56:59]
	v_mfma_f32_16x16x32_bf16 v[44:47], v[202:205], v[234:237], v[44:47]
	v_mfma_f32_16x16x32_bf16 v[112:115], v[198:201], v[214:217], v[112:115]
	v_mfma_f32_16x16x32_bf16 v[96:99], v[206:209], v[214:217], v[96:99]
	v_mfma_f32_16x16x32_bf16 v[108:111], v[198:201], v[222:225], v[108:111]
	v_mfma_f32_16x16x32_bf16 v[92:95], v[206:209], v[222:225], v[92:95]
	v_mfma_f32_16x16x32_bf16 v[64:67], v[198:201], v[230:233], v[64:67]
	v_mfma_f32_16x16x32_bf16 v[60:63], v[206:209], v[230:233], v[60:63]
	v_mfma_f32_16x16x32_bf16 v[56:59], v[198:201], v[238:241], v[56:59]
	v_mfma_f32_16x16x32_bf16 v[44:47], v[206:209], v[238:241], v[44:47]
	s_barrier
	v_add_u32_e32 v157, s82, v146
	ds_read_b128 v[148:151], v157
	ds_read_b128 v[152:155], v157 offset:1024
	ds_read_b128 v[186:189], v157 offset:2048
	ds_read_b128 v[190:193], v157 offset:3072
	v_add_u32_e32 v157, s62, v146
	ds_read_b128 v[194:197], v157
	ds_read_b128 v[198:201], v157 offset:1024
	ds_read_b128 v[202:205], v157 offset:2048
	ds_read_b128 v[206:209], v157 offset:3072
	s_add_u32 s30, s58, 0x40000
	s_addc_u32 s31, s59, 0
	s_mov_b32 m0, s12
	v_lshl_add_u64 v[248:249], s[30:31], 0, v[2:3]
	ds_read_b128 v[210:213], v147 offset:32768
	ds_read_b128 v[214:217], v147 offset:33792
	ds_read_b128 v[218:221], v147 offset:34816
	ds_read_b128 v[222:225], v147 offset:35840
	ds_read_b128 v[226:229], v147 offset:36864
	ds_read_b128 v[230:233], v147 offset:37888
	ds_read_b128 v[234:237], v147 offset:38912
	ds_read_b128 v[238:241], v147 offset:39936
	global_load_lds_dwordx4 v[248:249], off
	v_lshl_add_u64 v[248:249], s[30:31], 0, v[132:133]
	s_mov_b32 m0, s13
	s_nop 0
	global_load_lds_dwordx4 v[248:249], off
	s_waitcnt vmcnt(8)
	s_waitcnt lgkmcnt(0)
	v_mfma_f32_16x16x32_bf16 v[36:39], v[148:151], v[210:213], v[36:39]
	v_mfma_f32_16x16x32_bf16 v[24:27], v[186:189], v[210:213], v[24:27]
	v_mfma_f32_16x16x32_bf16 v[40:43], v[148:151], v[218:221], v[40:43]
	v_mfma_f32_16x16x32_bf16 v[20:23], v[186:189], v[218:221], v[20:23]
	s_barrier
	s_waitcnt lgkmcnt(0)
	v_mfma_f32_16x16x32_bf16 v[100:103], v[148:151], v[226:229], v[100:103]
	v_mfma_f32_16x16x32_bf16 v[88:91], v[186:189], v[226:229], v[88:91]
	v_mfma_f32_16x16x32_bf16 v[104:107], v[148:151], v[234:237], v[104:107]
	v_mfma_f32_16x16x32_bf16 v[84:87], v[186:189], v[234:237], v[84:87]
	v_mfma_f32_16x16x32_bf16 v[36:39], v[152:155], v[214:217], v[36:39]
	v_mfma_f32_16x16x32_bf16 v[24:27], v[190:193], v[214:217], v[24:27]
	v_mfma_f32_16x16x32_bf16 v[40:43], v[152:155], v[222:225], v[40:43]
	v_mfma_f32_16x16x32_bf16 v[20:23], v[190:193], v[222:225], v[20:23]
	v_mfma_f32_16x16x32_bf16 v[100:103], v[152:155], v[230:233], v[100:103]
	v_mfma_f32_16x16x32_bf16 v[88:91], v[190:193], v[230:233], v[88:91]
	v_mfma_f32_16x16x32_bf16 v[104:107], v[152:155], v[238:241], v[104:107]
	v_mfma_f32_16x16x32_bf16 v[84:87], v[190:193], v[238:241], v[84:87]
	v_mfma_f32_16x16x32_bf16 v[16:19], v[194:197], v[210:213], v[16:19]
	v_mfma_f32_16x16x32_bf16 v[8:11], v[202:205], v[210:213], v[8:11]
	v_mfma_f32_16x16x32_bf16 v[12:15], v[194:197], v[218:221], v[12:15]
	v_mfma_f32_16x16x32_bf16 v[4:7], v[202:205], v[218:221], v[4:7]
	v_mfma_f32_16x16x32_bf16 v[52:55], v[194:197], v[226:229], v[52:55]
	v_mfma_f32_16x16x32_bf16 v[32:35], v[202:205], v[226:229], v[32:35]
	v_mfma_f32_16x16x32_bf16 v[48:51], v[194:197], v[234:237], v[48:51]
	v_mfma_f32_16x16x32_bf16 v[28:31], v[202:205], v[234:237], v[28:31]
	v_mfma_f32_16x16x32_bf16 v[16:19], v[198:201], v[214:217], v[16:19]
	v_mfma_f32_16x16x32_bf16 v[8:11], v[206:209], v[214:217], v[8:11]
	v_mfma_f32_16x16x32_bf16 v[12:15], v[198:201], v[222:225], v[12:15]
	v_mfma_f32_16x16x32_bf16 v[4:7], v[206:209], v[222:225], v[4:7]
	v_mfma_f32_16x16x32_bf16 v[52:55], v[198:201], v[230:233], v[52:55]
	v_mfma_f32_16x16x32_bf16 v[32:35], v[206:209], v[230:233], v[32:35]
	v_mfma_f32_16x16x32_bf16 v[48:51], v[198:201], v[238:241], v[48:51]
	v_mfma_f32_16x16x32_bf16 v[28:31], v[206:209], v[238:241], v[28:31]
	s_barrier
	s_add_i32 s28, s82, s9
	v_lshl_add_u64 v[168:169], v[168:169], 0, s[72:73]
	s_mov_b32 m0, s28
	ds_read_b128 v[210:213], v147 offset:49152
	ds_read_b128 v[214:217], v147 offset:50176
	ds_read_b128 v[218:221], v147 offset:51200
	ds_read_b128 v[222:225], v147 offset:52224
	ds_read_b128 v[226:229], v147 offset:53248
	ds_read_b128 v[230:233], v147 offset:54272
	ds_read_b128 v[234:237], v147 offset:55296
	ds_read_b128 v[238:241], v147 offset:56320
	global_load_lds_dwordx4 v[168:169], off
	v_lshl_add_u64 v[168:169], v[176:177], 0, s[72:73]
	s_add_i32 m0, s28, 0x2000
	s_add_i32 s28, s62, s9
	global_load_lds_dwordx4 v[168:169], off
	v_lshl_add_u64 v[168:169], v[178:179], 0, s[72:73]
	s_mov_b32 m0, s28
	s_nop 0
	global_load_lds_dwordx4 v[168:169], off
	v_lshl_add_u64 v[168:169], v[242:243], 0, s[72:73]
	s_add_i32 m0, s28, 0x2000
	s_nop 0
	global_load_lds_dwordx4 v[168:169], off
	v_lshl_add_u64 v[168:169], v[244:245], 0, s[72:73]
	s_mov_b32 m0, s15
	s_nop 0
	global_load_lds_dwordx4 v[168:169], off
	v_lshl_add_u64 v[168:169], v[246:247], 0, s[72:73]
	s_mov_b32 m0, s16
	s_nop 0
	global_load_lds_dwordx4 v[168:169], off
	s_waitcnt vmcnt(8)
	s_waitcnt lgkmcnt(0)
	v_mfma_f32_16x16x32_bf16 v[128:131], v[148:151], v[210:213], v[128:131]
	v_mfma_f32_16x16x32_bf16 v[124:127], v[186:189], v[210:213], v[124:127]
	v_mfma_f32_16x16x32_bf16 v[120:123], v[148:151], v[218:221], v[120:123]
	v_mfma_f32_16x16x32_bf16 v[116:119], v[186:189], v[218:221], v[116:119]
	s_barrier
	s_waitcnt lgkmcnt(0)
	v_mfma_f32_16x16x32_bf16 v[80:83], v[148:151], v[226:229], v[80:83]
	v_mfma_f32_16x16x32_bf16 v[76:79], v[186:189], v[226:229], v[76:79]
	v_mfma_f32_16x16x32_bf16 v[72:75], v[148:151], v[234:237], v[72:75]
	v_mfma_f32_16x16x32_bf16 v[68:71], v[186:189], v[234:237], v[68:71]
	v_mfma_f32_16x16x32_bf16 v[128:131], v[152:155], v[214:217], v[128:131]
	v_mfma_f32_16x16x32_bf16 v[124:127], v[190:193], v[214:217], v[124:127]
	v_mfma_f32_16x16x32_bf16 v[120:123], v[152:155], v[222:225], v[120:123]
	v_mfma_f32_16x16x32_bf16 v[116:119], v[190:193], v[222:225], v[116:119]
	v_mfma_f32_16x16x32_bf16 v[80:83], v[152:155], v[230:233], v[80:83]
	v_mfma_f32_16x16x32_bf16 v[76:79], v[190:193], v[230:233], v[76:79]
	v_mfma_f32_16x16x32_bf16 v[72:75], v[152:155], v[238:241], v[72:75]
	v_mfma_f32_16x16x32_bf16 v[68:71], v[190:193], v[238:241], v[68:71]
	v_mfma_f32_16x16x32_bf16 v[112:115], v[194:197], v[210:213], v[112:115]
	v_mfma_f32_16x16x32_bf16 v[96:99], v[202:205], v[210:213], v[96:99]
	v_mfma_f32_16x16x32_bf16 v[108:111], v[194:197], v[218:221], v[108:111]
	v_mfma_f32_16x16x32_bf16 v[92:95], v[202:205], v[218:221], v[92:95]
	v_mfma_f32_16x16x32_bf16 v[64:67], v[194:197], v[226:229], v[64:67]
	v_mfma_f32_16x16x32_bf16 v[60:63], v[202:205], v[226:229], v[60:63]
	v_mfma_f32_16x16x32_bf16 v[56:59], v[194:197], v[234:237], v[56:59]
	v_mfma_f32_16x16x32_bf16 v[44:47], v[202:205], v[234:237], v[44:47]
	v_mfma_f32_16x16x32_bf16 v[112:115], v[198:201], v[214:217], v[112:115]
	v_mfma_f32_16x16x32_bf16 v[96:99], v[206:209], v[214:217], v[96:99]
	v_mfma_f32_16x16x32_bf16 v[108:111], v[198:201], v[222:225], v[108:111]
	v_mfma_f32_16x16x32_bf16 v[92:95], v[206:209], v[222:225], v[92:95]
	v_mfma_f32_16x16x32_bf16 v[64:67], v[198:201], v[230:233], v[64:67]
	v_mfma_f32_16x16x32_bf16 v[60:63], v[206:209], v[230:233], v[60:63]
	v_mfma_f32_16x16x32_bf16 v[56:59], v[198:201], v[238:241], v[56:59]
	v_mfma_f32_16x16x32_bf16 v[44:47], v[206:209], v[238:241], v[44:47]
	s_barrier
	s_add_i32 s27, s27, 2
	s_add_u32 vcc_lo, vcc_lo, 0x100
	s_addc_u32 vcc_hi, vcc_hi, 0
	s_cmp_gt_u32 s27, 13
	s_cbranch_scc0 .LBB0_1201
	s_and_b64 vcc, exec, s[48:49]
	s_cbranch_vccz .LBB0_1204
	s_barrier
